# K-loops: dropped the redundant lgkmcnt(0) behind each pre-MFMA barrier and the setprio 0/1 flip in the middle of each 32-MFMA block (on top of the early L1 invalidate)
# speedup vs baseline: 1.0023x; 1.0023x over previous
.LBB0_164:
	s_add_i32 s51, s51, 2
	v_add_u32_e32 v146, s33, v179
	v_add_u32_e32 v162, s36, v179
	s_add_u32 s3, s6, s10
	ds_read_b128 v[54:57], v146
	ds_read_b128 v[58:61], v146 offset:1024
	ds_read_b128 v[62:65], v146 offset:2048
	ds_read_b128 v[146:149], v146 offset:3072
	ds_read_b128 v[150:153], v162
	ds_read_b128 v[154:157], v162 offset:1024
	ds_read_b128 v[158:161], v162 offset:2048
	ds_read_b128 v[162:165], v162 offset:3072
	s_addc_u32 s24, s7, s11
	s_add_u32 s3, s3, 0x100
	s_addc_u32 s24, s24, 0
	s_add_u32 s25, s49, s10
	s_addc_u32 s26, s50, s11
	s_cmpk_eq_i32 s10, 0x700
	s_cselect_b32 s77, s75, s26
	s_cselect_b32 s76, s74, s25
	s_cselect_b32 s79, s73, s24
	s_cselect_b32 s78, s72, s3
	v_lshl_add_u64 v[206:207], v[52:53], 0, s[10:11]
	s_add_i32 s3, s20, 0x8000
	v_lshl_add_u64 v[244:245], v[206:207], 0, s[42:43]
	s_mov_b32 m0, s3
	ds_read_b128 v[212:215], v209
	ds_read_b128 v[216:219], v209 offset:1024
	ds_read_b128 v[220:223], v209 offset:2048
	ds_read_b128 v[224:227], v209 offset:3072
	ds_read_b128 v[228:231], v209 offset:4096
	ds_read_b128 v[232:235], v209 offset:5120
	ds_read_b128 v[236:239], v209 offset:6144
	ds_read_b128 v[240:243], v209 offset:7168
	global_load_lds_dwordx4 v[244:245], off
	v_lshl_add_u64 v[244:245], v[50:51], 0, s[10:11]
	s_add_i32 s80, s20, 0xa000
	v_lshl_add_u64 v[246:247], v[244:245], 0, s[42:43]
	s_mov_b32 m0, s80
	s_add_i32 s61, s20, 0xc000
	global_load_lds_dwordx4 v[246:247], off
	v_lshl_add_u64 v[206:207], v[206:207], 0, s[44:45]
	s_mov_b32 m0, s61
	s_add_i32 s71, s20, 0xe000
	global_load_lds_dwordx4 v[206:207], off
	v_lshl_add_u64 v[206:207], v[244:245], 0, s[44:45]
	s_mov_b32 m0, s71
	s_nop 0
	global_load_lds_dwordx4 v[206:207], off
	s_waitcnt vmcnt(8)
	s_waitcnt lgkmcnt(0)
	s_barrier
	s_setprio 1
	v_mfma_f32_16x16x32_bf16 v[142:145], v[54:57], v[212:215], v[142:145]
	v_mfma_f32_16x16x32_bf16 v[138:141], v[62:65], v[212:215], v[138:141]
	v_mfma_f32_16x16x32_bf16 v[126:129], v[54:57], v[220:223], v[126:129]
	v_mfma_f32_16x16x32_bf16 v[122:125], v[62:65], v[220:223], v[122:125]
	v_mfma_f32_16x16x32_bf16 v[110:113], v[54:57], v[228:231], v[110:113]
	v_mfma_f32_16x16x32_bf16 v[106:109], v[62:65], v[228:231], v[106:109]
	v_mfma_f32_16x16x32_bf16 v[94:97], v[54:57], v[236:239], v[94:97]
	v_mfma_f32_16x16x32_bf16 v[90:93], v[62:65], v[236:239], v[90:93]
	v_mfma_f32_16x16x32_bf16 v[142:145], v[58:61], v[216:219], v[142:145]
	v_mfma_f32_16x16x32_bf16 v[138:141], v[146:149], v[216:219], v[138:141]
	v_mfma_f32_16x16x32_bf16 v[126:129], v[58:61], v[224:227], v[126:129]
	v_mfma_f32_16x16x32_bf16 v[122:125], v[146:149], v[224:227], v[122:125]
	v_mfma_f32_16x16x32_bf16 v[110:113], v[58:61], v[232:235], v[110:113]
	v_mfma_f32_16x16x32_bf16 v[106:109], v[146:149], v[232:235], v[106:109]
	v_mfma_f32_16x16x32_bf16 v[94:97], v[58:61], v[240:243], v[94:97]
	v_mfma_f32_16x16x32_bf16 v[90:93], v[146:149], v[240:243], v[90:93]
	v_mfma_f32_16x16x32_bf16 v[134:137], v[150:153], v[212:215], v[134:137]
	v_mfma_f32_16x16x32_bf16 v[130:133], v[158:161], v[212:215], v[130:133]
	v_mfma_f32_16x16x32_bf16 v[118:121], v[150:153], v[220:223], v[118:121]
	v_mfma_f32_16x16x32_bf16 v[114:117], v[158:161], v[220:223], v[114:117]
	v_mfma_f32_16x16x32_bf16 v[102:105], v[150:153], v[228:231], v[102:105]
	v_mfma_f32_16x16x32_bf16 v[98:101], v[158:161], v[228:231], v[98:101]
	v_mfma_f32_16x16x32_bf16 v[86:89], v[150:153], v[236:239], v[86:89]
	v_mfma_f32_16x16x32_bf16 v[82:85], v[158:161], v[236:239], v[82:85]
	v_mfma_f32_16x16x32_bf16 v[134:137], v[154:157], v[216:219], v[134:137]
	v_mfma_f32_16x16x32_bf16 v[130:133], v[162:165], v[216:219], v[130:133]
	v_mfma_f32_16x16x32_bf16 v[118:121], v[154:157], v[224:227], v[118:121]
	v_mfma_f32_16x16x32_bf16 v[114:117], v[162:165], v[224:227], v[114:117]
	v_mfma_f32_16x16x32_bf16 v[102:105], v[154:157], v[232:235], v[102:105]
	v_mfma_f32_16x16x32_bf16 v[98:101], v[162:165], v[232:235], v[98:101]
	v_mfma_f32_16x16x32_bf16 v[86:89], v[154:157], v[240:243], v[86:89]
	v_mfma_f32_16x16x32_bf16 v[82:85], v[162:165], v[240:243], v[82:85]
	s_setprio 0
	s_barrier
	s_add_i32 s24, s33, s19
	v_lshl_add_u64 v[206:207], s[76:77], 0, v[168:169]
	s_mov_b32 m0, s24
	ds_read_b128 v[212:215], v209 offset:16384
	ds_read_b128 v[216:219], v209 offset:17408
	ds_read_b128 v[220:223], v209 offset:18432
	ds_read_b128 v[224:227], v209 offset:19456
	ds_read_b128 v[228:231], v209 offset:20480
	ds_read_b128 v[232:235], v209 offset:21504
	ds_read_b128 v[236:239], v209 offset:22528
	ds_read_b128 v[240:243], v209 offset:23552
	global_load_lds_dwordx4 v[206:207], off
	s_add_i32 m0, s24, 0x2000
	s_add_u32 s24, s76, 0x40000
	v_lshl_add_u64 v[244:245], s[76:77], 0, v[172:173]
	s_addc_u32 s25, s77, 0
	s_add_i32 s26, s36, s19
	global_load_lds_dwordx4 v[244:245], off
	v_lshl_add_u64 v[246:247], s[24:25], 0, v[168:169]
	s_mov_b32 m0, s26
	s_nop 0
	global_load_lds_dwordx4 v[246:247], off
	v_lshl_add_u64 v[246:247], s[24:25], 0, v[172:173]
	s_add_i32 m0, s26, 0x2000
	s_nop 0
	global_load_lds_dwordx4 v[246:247], off
	s_waitcnt vmcnt(4)
	s_waitcnt lgkmcnt(0)
	s_barrier
	s_setprio 1
	v_mfma_f32_16x16x32_bf16 v[78:81], v[54:57], v[212:215], v[78:81]
	v_mfma_f32_16x16x32_bf16 v[74:77], v[62:65], v[212:215], v[74:77]
	v_mfma_f32_16x16x32_bf16 v[46:49], v[54:57], v[220:223], v[46:49]
	v_mfma_f32_16x16x32_bf16 v[42:45], v[62:65], v[220:223], v[42:45]
	v_mfma_f32_16x16x32_bf16 v[30:33], v[54:57], v[228:231], v[30:33]
	v_mfma_f32_16x16x32_bf16 v[26:29], v[62:65], v[228:231], v[26:29]
	v_mfma_f32_16x16x32_bf16 v[14:17], v[54:57], v[236:239], v[14:17]
	v_mfma_f32_16x16x32_bf16 v[10:13], v[62:65], v[236:239], v[10:13]
	v_mfma_f32_16x16x32_bf16 v[78:81], v[58:61], v[216:219], v[78:81]
	v_mfma_f32_16x16x32_bf16 v[74:77], v[146:149], v[216:219], v[74:77]
	v_mfma_f32_16x16x32_bf16 v[46:49], v[58:61], v[224:227], v[46:49]
	v_mfma_f32_16x16x32_bf16 v[42:45], v[146:149], v[224:227], v[42:45]
	v_mfma_f32_16x16x32_bf16 v[30:33], v[58:61], v[232:235], v[30:33]
	v_mfma_f32_16x16x32_bf16 v[26:29], v[146:149], v[232:235], v[26:29]
	v_mfma_f32_16x16x32_bf16 v[14:17], v[58:61], v[240:243], v[14:17]
	v_mfma_f32_16x16x32_bf16 v[10:13], v[146:149], v[240:243], v[10:13]
	v_mfma_f32_16x16x32_bf16 v[38:41], v[150:153], v[220:223], v[38:41]
	v_mfma_f32_16x16x32_bf16 v[34:37], v[158:161], v[220:223], v[34:37]
	v_mfma_f32_16x16x32_bf16 v[22:25], v[150:153], v[228:231], v[22:25]
	v_mfma_f32_16x16x32_bf16 v[18:21], v[158:161], v[228:231], v[18:21]
	v_mfma_f32_16x16x32_bf16 v[6:9], v[150:153], v[236:239], v[6:9]
	v_mfma_f32_16x16x32_bf16 v[2:5], v[158:161], v[236:239], v[2:5]
	v_mfma_f32_16x16x32_bf16 v[54:57], v[150:153], v[212:215], v[70:73]
	v_mfma_f32_16x16x32_bf16 v[58:61], v[158:161], v[212:215], v[66:69]
	v_mfma_f32_16x16x32_bf16 v[38:41], v[154:157], v[224:227], v[38:41]
	v_mfma_f32_16x16x32_bf16 v[34:37], v[162:165], v[224:227], v[34:37]
	v_mfma_f32_16x16x32_bf16 v[22:25], v[154:157], v[232:235], v[22:25]
	v_mfma_f32_16x16x32_bf16 v[18:21], v[162:165], v[232:235], v[18:21]
	v_mfma_f32_16x16x32_bf16 v[6:9], v[154:157], v[240:243], v[6:9]
	v_mfma_f32_16x16x32_bf16 v[2:5], v[162:165], v[240:243], v[2:5]
	v_mfma_f32_16x16x32_bf16 v[54:57], v[154:157], v[216:219], v[54:57]
	v_mfma_f32_16x16x32_bf16 v[58:61], v[162:165], v[216:219], v[58:61]
	s_setprio 0
	s_barrier
	s_add_i32 s26, 0, 0x18000
	s_add_i32 s27, 0, 0x1c000
	v_add_u32_e32 v146, s26, v179
	v_add_u32_e32 v162, s27, v179
	ds_read_b128 v[62:65], v146
	ds_read_b128 v[66:69], v146 offset:1024
	ds_read_b128 v[70:73], v146 offset:2048
	ds_read_b128 v[146:149], v146 offset:3072
	ds_read_b128 v[150:153], v162
	ds_read_b128 v[154:157], v162 offset:1024
	ds_read_b128 v[158:161], v162 offset:2048
	ds_read_b128 v[162:165], v162 offset:3072
	s_mov_b32 m0, s20
	v_lshl_add_u64 v[246:247], s[78:79], 0, v[166:167]
	s_add_u32 s24, s78, 0x40000
	ds_read_b128 v[212:215], v209 offset:32768
	ds_read_b128 v[216:219], v209 offset:33792
	ds_read_b128 v[220:223], v209 offset:34816
	ds_read_b128 v[224:227], v209 offset:35840
	ds_read_b128 v[228:231], v209 offset:36864
	ds_read_b128 v[232:235], v209 offset:37888
	ds_read_b128 v[236:239], v209 offset:38912
	ds_read_b128 v[240:243], v209 offset:39936
	global_load_lds_dwordx4 v[246:247], off
	v_lshl_add_u64 v[246:247], s[78:79], 0, v[170:171]
	s_mov_b32 m0, s21
	s_addc_u32 s25, s79, 0
	global_load_lds_dwordx4 v[246:247], off
	v_lshl_add_u64 v[246:247], s[24:25], 0, v[166:167]
	s_mov_b32 m0, s22
	s_nop 0
	global_load_lds_dwordx4 v[246:247], off
	v_lshl_add_u64 v[246:247], s[24:25], 0, v[170:171]
	s_mov_b32 m0, s23
	s_nop 0
	global_load_lds_dwordx4 v[246:247], off
	s_waitcnt vmcnt(8)
	s_waitcnt lgkmcnt(0)
	s_barrier
	s_setprio 1
	v_mfma_f32_16x16x32_bf16 v[142:145], v[62:65], v[212:215], v[142:145]
	v_mfma_f32_16x16x32_bf16 v[138:141], v[70:73], v[212:215], v[138:141]
	v_mfma_f32_16x16x32_bf16 v[126:129], v[62:65], v[220:223], v[126:129]
	v_mfma_f32_16x16x32_bf16 v[122:125], v[70:73], v[220:223], v[122:125]
	v_mfma_f32_16x16x32_bf16 v[110:113], v[62:65], v[228:231], v[110:113]
	v_mfma_f32_16x16x32_bf16 v[106:109], v[70:73], v[228:231], v[106:109]
	v_mfma_f32_16x16x32_bf16 v[94:97], v[62:65], v[236:239], v[94:97]
	v_mfma_f32_16x16x32_bf16 v[90:93], v[70:73], v[236:239], v[90:93]
	v_mfma_f32_16x16x32_bf16 v[142:145], v[66:69], v[216:219], v[142:145]
	v_mfma_f32_16x16x32_bf16 v[138:141], v[146:149], v[216:219], v[138:141]
	v_mfma_f32_16x16x32_bf16 v[126:129], v[66:69], v[224:227], v[126:129]
	v_mfma_f32_16x16x32_bf16 v[122:125], v[146:149], v[224:227], v[122:125]
	v_mfma_f32_16x16x32_bf16 v[110:113], v[66:69], v[232:235], v[110:113]
	v_mfma_f32_16x16x32_bf16 v[106:109], v[146:149], v[232:235], v[106:109]
	v_mfma_f32_16x16x32_bf16 v[94:97], v[66:69], v[240:243], v[94:97]
	v_mfma_f32_16x16x32_bf16 v[90:93], v[146:149], v[240:243], v[90:93]
	v_mfma_f32_16x16x32_bf16 v[134:137], v[150:153], v[212:215], v[134:137]
	v_mfma_f32_16x16x32_bf16 v[130:133], v[158:161], v[212:215], v[130:133]
	v_mfma_f32_16x16x32_bf16 v[118:121], v[150:153], v[220:223], v[118:121]
	v_mfma_f32_16x16x32_bf16 v[114:117], v[158:161], v[220:223], v[114:117]
	v_mfma_f32_16x16x32_bf16 v[102:105], v[150:153], v[228:231], v[102:105]
	v_mfma_f32_16x16x32_bf16 v[98:101], v[158:161], v[228:231], v[98:101]
	v_mfma_f32_16x16x32_bf16 v[86:89], v[150:153], v[236:239], v[86:89]
	v_mfma_f32_16x16x32_bf16 v[82:85], v[158:161], v[236:239], v[82:85]
	v_mfma_f32_16x16x32_bf16 v[134:137], v[154:157], v[216:219], v[134:137]
	v_mfma_f32_16x16x32_bf16 v[130:133], v[162:165], v[216:219], v[130:133]
	v_mfma_f32_16x16x32_bf16 v[118:121], v[154:157], v[224:227], v[118:121]
	v_mfma_f32_16x16x32_bf16 v[114:117], v[162:165], v[224:227], v[114:117]
	v_mfma_f32_16x16x32_bf16 v[102:105], v[154:157], v[232:235], v[102:105]
	v_mfma_f32_16x16x32_bf16 v[98:101], v[162:165], v[232:235], v[98:101]
	v_mfma_f32_16x16x32_bf16 v[86:89], v[154:157], v[240:243], v[86:89]
	v_mfma_f32_16x16x32_bf16 v[82:85], v[162:165], v[240:243], v[82:85]
	s_setprio 0
	s_barrier
	s_add_i32 s24, s26, s19
	v_lshl_add_u64 v[206:207], v[206:207], 0, s[42:43]
	s_mov_b32 m0, s24
	ds_read_b128 v[212:215], v209 offset:49152
	ds_read_b128 v[216:219], v209 offset:50176
	ds_read_b128 v[220:223], v209 offset:51200
	ds_read_b128 v[224:227], v209 offset:52224
	ds_read_b128 v[228:231], v209 offset:53248
	ds_read_b128 v[232:235], v209 offset:54272
	ds_read_b128 v[236:239], v209 offset:55296
	ds_read_b128 v[240:243], v209 offset:56320
	global_load_lds_dwordx4 v[206:207], off
	s_add_i32 m0, s24, 0x2000
	s_add_u32 s24, s76, 0x40080
	v_lshl_add_u64 v[206:207], v[244:245], 0, s[42:43]
	s_addc_u32 s25, s77, 0
	s_add_i32 s26, s27, s19
	global_load_lds_dwordx4 v[206:207], off
	v_lshl_add_u64 v[206:207], s[24:25], 0, v[168:169]
	s_mov_b32 m0, s26
	s_nop 0
	global_load_lds_dwordx4 v[206:207], off
	v_lshl_add_u64 v[206:207], s[24:25], 0, v[172:173]
	s_add_i32 m0, s26, 0x2000
	s_nop 0
	global_load_lds_dwordx4 v[206:207], off
	s_waitcnt vmcnt(4)
	s_waitcnt lgkmcnt(0)
	s_barrier
	s_setprio 1
	v_mfma_f32_16x16x32_bf16 v[78:81], v[62:65], v[212:215], v[78:81]
	v_mfma_f32_16x16x32_bf16 v[74:77], v[70:73], v[212:215], v[74:77]
	v_mfma_f32_16x16x32_bf16 v[46:49], v[62:65], v[220:223], v[46:49]
	v_mfma_f32_16x16x32_bf16 v[42:45], v[70:73], v[220:223], v[42:45]
	v_mfma_f32_16x16x32_bf16 v[30:33], v[62:65], v[228:231], v[30:33]
	v_mfma_f32_16x16x32_bf16 v[26:29], v[70:73], v[228:231], v[26:29]
	v_mfma_f32_16x16x32_bf16 v[14:17], v[62:65], v[236:239], v[14:17]
	v_mfma_f32_16x16x32_bf16 v[10:13], v[70:73], v[236:239], v[10:13]
	v_mfma_f32_16x16x32_bf16 v[78:81], v[66:69], v[216:219], v[78:81]
	v_mfma_f32_16x16x32_bf16 v[74:77], v[146:149], v[216:219], v[74:77]
	v_mfma_f32_16x16x32_bf16 v[46:49], v[66:69], v[224:227], v[46:49]
	v_mfma_f32_16x16x32_bf16 v[42:45], v[146:149], v[224:227], v[42:45]
	v_mfma_f32_16x16x32_bf16 v[30:33], v[66:69], v[232:235], v[30:33]
	v_mfma_f32_16x16x32_bf16 v[26:29], v[146:149], v[232:235], v[26:29]
	v_mfma_f32_16x16x32_bf16 v[14:17], v[66:69], v[240:243], v[14:17]
	v_mfma_f32_16x16x32_bf16 v[10:13], v[146:149], v[240:243], v[10:13]
	v_mfma_f32_16x16x32_bf16 v[54:57], v[150:153], v[212:215], v[54:57]
	v_mfma_f32_16x16x32_bf16 v[70:73], v[154:157], v[216:219], v[54:57]
	v_mfma_f32_16x16x32_bf16 v[54:57], v[158:161], v[212:215], v[58:61]
	v_mfma_f32_16x16x32_bf16 v[38:41], v[150:153], v[220:223], v[38:41]
	v_mfma_f32_16x16x32_bf16 v[34:37], v[158:161], v[220:223], v[34:37]
	v_mfma_f32_16x16x32_bf16 v[22:25], v[150:153], v[228:231], v[22:25]
	v_mfma_f32_16x16x32_bf16 v[18:21], v[158:161], v[228:231], v[18:21]
	v_mfma_f32_16x16x32_bf16 v[6:9], v[150:153], v[236:239], v[6:9]
	v_mfma_f32_16x16x32_bf16 v[2:5], v[158:161], v[236:239], v[2:5]
	v_mfma_f32_16x16x32_bf16 v[66:69], v[162:165], v[216:219], v[54:57]
	v_mfma_f32_16x16x32_bf16 v[38:41], v[154:157], v[224:227], v[38:41]
	v_mfma_f32_16x16x32_bf16 v[34:37], v[162:165], v[224:227], v[34:37]
	v_mfma_f32_16x16x32_bf16 v[22:25], v[154:157], v[232:235], v[22:25]
	v_mfma_f32_16x16x32_bf16 v[18:21], v[162:165], v[232:235], v[18:21]
	v_mfma_f32_16x16x32_bf16 v[6:9], v[154:157], v[240:243], v[6:9]
	v_mfma_f32_16x16x32_bf16 v[2:5], v[162:165], v[240:243], v[2:5]
	s_setprio 0
	s_barrier
	s_add_u32 s10, s10, 0x100
	s_addc_u32 s11, s11, 0
	s_cmp_ge_u32 s51, s9
	s_cbranch_scc0 .LBB0_164
	s_and_b64 vcc, exec, s[4:5]
	s_cbranch_vccz .LBB0_167
	v_add_u32_e32 v204, 0, v179
	v_add_u32_e32 v62, 0x10000, v204
	v_add_u32_e32 v158, 0x14000, v204
	ds_read_b128 v[50:53], v62
	ds_read_b128 v[54:57], v62 offset:1024
	ds_read_b128 v[58:61], v62 offset:2048
	ds_read_b128 v[62:65], v62 offset:3072
	ds_read_b128 v[146:149], v158
	ds_read_b128 v[150:153], v158 offset:1024
	ds_read_b128 v[154:157], v158 offset:2048
	ds_read_b128 v[158:161], v158 offset:3072
	v_lshl_add_u64 v[206:207], s[6:7], 0, v[166:167]
	s_mov_b32 m0, s3
	v_lshl_add_u64 v[206:207], v[206:207], 0, s[58:59]
	ds_read_b128 v[162:165], v209
	ds_read_b128 v[212:215], v209 offset:1024
	ds_read_b128 v[216:219], v209 offset:2048
	ds_read_b128 v[220:223], v209 offset:3072
	ds_read_b128 v[224:227], v209 offset:4096
	ds_read_b128 v[228:231], v209 offset:5120
	ds_read_b128 v[232:235], v209 offset:6144
	ds_read_b128 v[236:239], v209 offset:7168
	global_load_lds_dwordx4 v[206:207], off
	v_lshl_add_u64 v[206:207], s[6:7], 0, v[170:171]
	s_add_u32 s4, s6, 0x40780
	v_lshl_add_u64 v[206:207], v[206:207], 0, s[58:59]
	s_mov_b32 m0, s80
	s_addc_u32 s5, s7, 0
	global_load_lds_dwordx4 v[206:207], off
	v_lshl_add_u64 v[206:207], s[4:5], 0, v[166:167]
	s_mov_b32 m0, s61
	s_nop 0
	global_load_lds_dwordx4 v[206:207], off
	v_lshl_add_u64 v[206:207], s[4:5], 0, v[170:171]
	s_mov_b32 m0, s71
	s_nop 0
	global_load_lds_dwordx4 v[206:207], off
	s_waitcnt vmcnt(8)
	s_waitcnt lgkmcnt(0)
	s_barrier
	s_setprio 1
	v_mfma_f32_16x16x32_bf16 v[142:145], v[50:53], v[162:165], v[142:145]
	v_mfma_f32_16x16x32_bf16 v[138:141], v[58:61], v[162:165], v[138:141]
	v_mfma_f32_16x16x32_bf16 v[126:129], v[50:53], v[216:219], v[126:129]
	v_mfma_f32_16x16x32_bf16 v[122:125], v[58:61], v[216:219], v[122:125]
	v_mfma_f32_16x16x32_bf16 v[110:113], v[50:53], v[224:227], v[110:113]
	v_mfma_f32_16x16x32_bf16 v[106:109], v[58:61], v[224:227], v[106:109]
	v_mfma_f32_16x16x32_bf16 v[94:97], v[50:53], v[232:235], v[94:97]
	v_mfma_f32_16x16x32_bf16 v[90:93], v[58:61], v[232:235], v[90:93]
	v_mfma_f32_16x16x32_bf16 v[142:145], v[54:57], v[212:215], v[142:145]
	v_mfma_f32_16x16x32_bf16 v[138:141], v[62:65], v[212:215], v[138:141]
	v_mfma_f32_16x16x32_bf16 v[126:129], v[54:57], v[220:223], v[126:129]
	v_mfma_f32_16x16x32_bf16 v[122:125], v[62:65], v[220:223], v[122:125]
	v_mfma_f32_16x16x32_bf16 v[110:113], v[54:57], v[228:231], v[110:113]
	v_mfma_f32_16x16x32_bf16 v[106:109], v[62:65], v[228:231], v[106:109]
	v_mfma_f32_16x16x32_bf16 v[94:97], v[54:57], v[236:239], v[94:97]
	v_mfma_f32_16x16x32_bf16 v[90:93], v[62:65], v[236:239], v[90:93]
	v_mfma_f32_16x16x32_bf16 v[134:137], v[146:149], v[162:165], v[134:137]
	v_mfma_f32_16x16x32_bf16 v[130:133], v[154:157], v[162:165], v[130:133]
	v_mfma_f32_16x16x32_bf16 v[118:121], v[146:149], v[216:219], v[118:121]
	v_mfma_f32_16x16x32_bf16 v[114:117], v[154:157], v[216:219], v[114:117]
	v_mfma_f32_16x16x32_bf16 v[102:105], v[146:149], v[224:227], v[102:105]
	v_mfma_f32_16x16x32_bf16 v[98:101], v[154:157], v[224:227], v[98:101]
	v_mfma_f32_16x16x32_bf16 v[86:89], v[146:149], v[232:235], v[86:89]
	v_mfma_f32_16x16x32_bf16 v[82:85], v[154:157], v[232:235], v[82:85]
	v_mfma_f32_16x16x32_bf16 v[134:137], v[150:153], v[212:215], v[134:137]
	v_mfma_f32_16x16x32_bf16 v[130:133], v[158:161], v[212:215], v[130:133]
	v_mfma_f32_16x16x32_bf16 v[118:121], v[150:153], v[220:223], v[118:121]
	v_mfma_f32_16x16x32_bf16 v[114:117], v[158:161], v[220:223], v[114:117]
	v_mfma_f32_16x16x32_bf16 v[102:105], v[150:153], v[228:231], v[102:105]
	v_mfma_f32_16x16x32_bf16 v[98:101], v[158:161], v[228:231], v[98:101]
	v_mfma_f32_16x16x32_bf16 v[86:89], v[150:153], v[236:239], v[86:89]
	v_mfma_f32_16x16x32_bf16 v[82:85], v[158:161], v[236:239], v[82:85]
	s_setprio 0
	s_barrier
	ds_read_b128 v[162:165], v209 offset:16384
	ds_read_b128 v[212:215], v209 offset:17408
	ds_read_b128 v[216:219], v209 offset:18432
	ds_read_b128 v[220:223], v209 offset:19456
	ds_read_b128 v[224:227], v209 offset:20480
	ds_read_b128 v[228:231], v209 offset:21504
	ds_read_b128 v[232:235], v209 offset:22528
	ds_read_b128 v[236:239], v209 offset:23552
	s_waitcnt vmcnt(0)
	s_waitcnt lgkmcnt(0)
	s_barrier
	s_setprio 1
	v_mfma_f32_16x16x32_bf16 v[78:81], v[50:53], v[162:165], v[78:81]
	v_mfma_f32_16x16x32_bf16 v[74:77], v[58:61], v[162:165], v[74:77]
	v_mfma_f32_16x16x32_bf16 v[46:49], v[50:53], v[216:219], v[46:49]
	v_mfma_f32_16x16x32_bf16 v[42:45], v[58:61], v[216:219], v[42:45]
	v_mfma_f32_16x16x32_bf16 v[30:33], v[50:53], v[224:227], v[30:33]
	v_mfma_f32_16x16x32_bf16 v[26:29], v[58:61], v[224:227], v[26:29]
	v_mfma_f32_16x16x32_bf16 v[14:17], v[50:53], v[232:235], v[14:17]
	v_mfma_f32_16x16x32_bf16 v[10:13], v[58:61], v[232:235], v[10:13]
	v_mfma_f32_16x16x32_bf16 v[78:81], v[54:57], v[212:215], v[78:81]
	v_mfma_f32_16x16x32_bf16 v[74:77], v[62:65], v[212:215], v[74:77]
	v_mfma_f32_16x16x32_bf16 v[46:49], v[54:57], v[220:223], v[46:49]
	v_mfma_f32_16x16x32_bf16 v[42:45], v[62:65], v[220:223], v[42:45]
	v_mfma_f32_16x16x32_bf16 v[30:33], v[54:57], v[228:231], v[30:33]
	v_mfma_f32_16x16x32_bf16 v[26:29], v[62:65], v[228:231], v[26:29]
	v_mfma_f32_16x16x32_bf16 v[14:17], v[54:57], v[236:239], v[14:17]
	v_mfma_f32_16x16x32_bf16 v[10:13], v[62:65], v[236:239], v[10:13]
	v_mfma_f32_16x16x32_bf16 v[38:41], v[146:149], v[216:219], v[38:41]
	v_mfma_f32_16x16x32_bf16 v[34:37], v[154:157], v[216:219], v[34:37]
	v_mfma_f32_16x16x32_bf16 v[22:25], v[146:149], v[224:227], v[22:25]
	v_mfma_f32_16x16x32_bf16 v[18:21], v[154:157], v[224:227], v[18:21]
	v_mfma_f32_16x16x32_bf16 v[6:9], v[146:149], v[232:235], v[6:9]
	v_mfma_f32_16x16x32_bf16 v[2:5], v[154:157], v[232:235], v[2:5]
	v_mfma_f32_16x16x32_bf16 v[50:53], v[146:149], v[162:165], v[70:73]
	v_mfma_f32_16x16x32_bf16 v[54:57], v[154:157], v[162:165], v[66:69]
	v_mfma_f32_16x16x32_bf16 v[38:41], v[150:153], v[220:223], v[38:41]
	v_mfma_f32_16x16x32_bf16 v[34:37], v[158:161], v[220:223], v[34:37]
	v_mfma_f32_16x16x32_bf16 v[22:25], v[150:153], v[228:231], v[22:25]
	v_mfma_f32_16x16x32_bf16 v[18:21], v[158:161], v[228:231], v[18:21]
	v_mfma_f32_16x16x32_bf16 v[6:9], v[150:153], v[236:239], v[6:9]
	v_mfma_f32_16x16x32_bf16 v[2:5], v[158:161], v[236:239], v[2:5]
	v_mfma_f32_16x16x32_bf16 v[50:53], v[150:153], v[212:215], v[50:53]
	v_mfma_f32_16x16x32_bf16 v[54:57], v[158:161], v[212:215], v[54:57]
	s_setprio 0
	s_barrier
	v_add_u32_e32 v70, 0x18000, v204
	v_add_u32_e32 v158, 0x1c000, v204
	ds_read_b128 v[58:61], v70
	ds_read_b128 v[62:65], v70 offset:1024
	ds_read_b128 v[66:69], v70 offset:2048
	ds_read_b128 v[70:73], v70 offset:3072
	ds_read_b128 v[146:149], v158
	ds_read_b128 v[150:153], v158 offset:1024
	ds_read_b128 v[154:157], v158 offset:2048
	ds_read_b128 v[158:161], v158 offset:3072
	ds_read_b128 v[162:165], v209 offset:32768
	ds_read_b128 v[212:215], v209 offset:33792
	ds_read_b128 v[216:219], v209 offset:34816
	ds_read_b128 v[220:223], v209 offset:35840
	ds_read_b128 v[224:227], v209 offset:36864
	ds_read_b128 v[228:231], v209 offset:37888
	ds_read_b128 v[232:235], v209 offset:38912
	ds_read_b128 v[236:239], v209 offset:39936
	s_waitcnt lgkmcnt(0)
	s_barrier
	s_setprio 1
	v_mfma_f32_16x16x32_bf16 v[142:145], v[58:61], v[162:165], v[142:145]
	v_mfma_f32_16x16x32_bf16 v[138:141], v[66:69], v[162:165], v[138:141]
	v_mfma_f32_16x16x32_bf16 v[126:129], v[58:61], v[216:219], v[126:129]
	v_mfma_f32_16x16x32_bf16 v[122:125], v[66:69], v[216:219], v[122:125]
	v_mfma_f32_16x16x32_bf16 v[110:113], v[58:61], v[224:227], v[110:113]
	v_mfma_f32_16x16x32_bf16 v[106:109], v[66:69], v[224:227], v[106:109]
	v_mfma_f32_16x16x32_bf16 v[94:97], v[58:61], v[232:235], v[94:97]
	v_mfma_f32_16x16x32_bf16 v[90:93], v[66:69], v[232:235], v[90:93]
	v_mfma_f32_16x16x32_bf16 v[142:145], v[62:65], v[212:215], v[142:145]
	v_mfma_f32_16x16x32_bf16 v[138:141], v[70:73], v[212:215], v[138:141]
	v_mfma_f32_16x16x32_bf16 v[126:129], v[62:65], v[220:223], v[126:129]
	v_mfma_f32_16x16x32_bf16 v[122:125], v[70:73], v[220:223], v[122:125]
	v_mfma_f32_16x16x32_bf16 v[110:113], v[62:65], v[228:231], v[110:113]
	v_mfma_f32_16x16x32_bf16 v[106:109], v[70:73], v[228:231], v[106:109]
	v_mfma_f32_16x16x32_bf16 v[94:97], v[62:65], v[236:239], v[94:97]
	v_mfma_f32_16x16x32_bf16 v[90:93], v[70:73], v[236:239], v[90:93]
	v_mfma_f32_16x16x32_bf16 v[134:137], v[146:149], v[162:165], v[134:137]
	v_mfma_f32_16x16x32_bf16 v[130:133], v[154:157], v[162:165], v[130:133]
	v_mfma_f32_16x16x32_bf16 v[118:121], v[146:149], v[216:219], v[118:121]
	v_mfma_f32_16x16x32_bf16 v[114:117], v[154:157], v[216:219], v[114:117]
	v_mfma_f32_16x16x32_bf16 v[102:105], v[146:149], v[224:227], v[102:105]
	v_mfma_f32_16x16x32_bf16 v[98:101], v[154:157], v[224:227], v[98:101]
	v_mfma_f32_16x16x32_bf16 v[86:89], v[146:149], v[232:235], v[86:89]
	v_mfma_f32_16x16x32_bf16 v[82:85], v[154:157], v[232:235], v[82:85]
	v_mfma_f32_16x16x32_bf16 v[134:137], v[150:153], v[212:215], v[134:137]
	v_mfma_f32_16x16x32_bf16 v[130:133], v[158:161], v[212:215], v[130:133]
	v_mfma_f32_16x16x32_bf16 v[118:121], v[150:153], v[220:223], v[118:121]
	v_mfma_f32_16x16x32_bf16 v[114:117], v[158:161], v[220:223], v[114:117]
	v_mfma_f32_16x16x32_bf16 v[102:105], v[150:153], v[228:231], v[102:105]
	v_mfma_f32_16x16x32_bf16 v[98:101], v[158:161], v[228:231], v[98:101]
	v_mfma_f32_16x16x32_bf16 v[86:89], v[150:153], v[236:239], v[86:89]
	v_mfma_f32_16x16x32_bf16 v[82:85], v[158:161], v[236:239], v[82:85]
	s_setprio 0
	s_barrier
	ds_read_b128 v[162:165], v209 offset:49152
	ds_read_b128 v[212:215], v209 offset:50176
	ds_read_b128 v[216:219], v209 offset:51200
	ds_read_b128 v[220:223], v209 offset:52224
	ds_read_b128 v[224:227], v209 offset:53248
	ds_read_b128 v[228:231], v209 offset:54272
	ds_read_b128 v[232:235], v209 offset:55296
	ds_read_b128 v[236:239], v209 offset:56320
	s_waitcnt lgkmcnt(0)
	s_barrier
	s_setprio 1
	v_mfma_f32_16x16x32_bf16 v[78:81], v[58:61], v[162:165], v[78:81]
	v_mfma_f32_16x16x32_bf16 v[74:77], v[66:69], v[162:165], v[74:77]
	v_mfma_f32_16x16x32_bf16 v[46:49], v[58:61], v[216:219], v[46:49]
	v_mfma_f32_16x16x32_bf16 v[42:45], v[66:69], v[216:219], v[42:45]
	v_mfma_f32_16x16x32_bf16 v[30:33], v[58:61], v[224:227], v[30:33]
	v_mfma_f32_16x16x32_bf16 v[26:29], v[66:69], v[224:227], v[26:29]
	v_mfma_f32_16x16x32_bf16 v[14:17], v[58:61], v[232:235], v[14:17]
	v_mfma_f32_16x16x32_bf16 v[10:13], v[66:69], v[232:235], v[10:13]
	v_mfma_f32_16x16x32_bf16 v[78:81], v[62:65], v[212:215], v[78:81]
	v_mfma_f32_16x16x32_bf16 v[74:77], v[70:73], v[212:215], v[74:77]
	v_mfma_f32_16x16x32_bf16 v[46:49], v[62:65], v[220:223], v[46:49]
	v_mfma_f32_16x16x32_bf16 v[42:45], v[70:73], v[220:223], v[42:45]
	v_mfma_f32_16x16x32_bf16 v[30:33], v[62:65], v[228:231], v[30:33]
	v_mfma_f32_16x16x32_bf16 v[26:29], v[70:73], v[228:231], v[26:29]
	v_mfma_f32_16x16x32_bf16 v[14:17], v[62:65], v[236:239], v[14:17]
	v_mfma_f32_16x16x32_bf16 v[10:13], v[70:73], v[236:239], v[10:13]
	v_mfma_f32_16x16x32_bf16 v[50:53], v[146:149], v[162:165], v[50:53]
	v_mfma_f32_16x16x32_bf16 v[70:73], v[150:153], v[212:215], v[50:53]
	v_mfma_f32_16x16x32_bf16 v[50:53], v[154:157], v[162:165], v[54:57]
	v_mfma_f32_16x16x32_bf16 v[38:41], v[146:149], v[216:219], v[38:41]
	v_mfma_f32_16x16x32_bf16 v[34:37], v[154:157], v[216:219], v[34:37]
	v_mfma_f32_16x16x32_bf16 v[22:25], v[146:149], v[224:227], v[22:25]
	v_mfma_f32_16x16x32_bf16 v[18:21], v[154:157], v[224:227], v[18:21]
	v_mfma_f32_16x16x32_bf16 v[6:9], v[146:149], v[232:235], v[6:9]
	v_mfma_f32_16x16x32_bf16 v[2:5], v[154:157], v[232:235], v[2:5]
	v_mfma_f32_16x16x32_bf16 v[66:69], v[158:161], v[212:215], v[50:53]
	v_mfma_f32_16x16x32_bf16 v[38:41], v[150:153], v[220:223], v[38:41]
	v_mfma_f32_16x16x32_bf16 v[34:37], v[158:161], v[220:223], v[34:37]
	v_mfma_f32_16x16x32_bf16 v[22:25], v[150:153], v[228:231], v[22:25]
	v_mfma_f32_16x16x32_bf16 v[18:21], v[158:161], v[228:231], v[18:21]
	v_mfma_f32_16x16x32_bf16 v[6:9], v[150:153], v[236:239], v[6:9]
	v_mfma_f32_16x16x32_bf16 v[2:5], v[158:161], v[236:239], v[2:5]
	s_setprio 0
	s_barrier

.LBB0_325:
	ds_read_b128 v[156:159], v151
	ds_read_b128 v[160:163], v151 offset:1024
	ds_read_b128 v[164:167], v151 offset:2048
	ds_read_b128 v[168:171], v151 offset:3072
	ds_read_b128 v[172:175], v152
	ds_read_b128 v[176:179], v152 offset:1024
	ds_read_b128 v[180:183], v152 offset:2048
	ds_read_b128 v[184:187], v152 offset:3072
	v_lshl_add_u64 v[220:221], s[44:45], 0, v[142:143]
	s_mov_b32 m0, s37
	v_lshl_add_u64 v[222:223], v[220:221], 0, s[6:7]
	ds_read_b128 v[188:191], v149
	ds_read_b128 v[192:195], v149 offset:1024
	ds_read_b128 v[196:199], v149 offset:2048
	ds_read_b128 v[200:203], v149 offset:3072
	ds_read_b128 v[204:207], v149 offset:4096
	ds_read_b128 v[208:211], v149 offset:5120
	ds_read_b128 v[212:215], v149 offset:6144
	ds_read_b128 v[216:219], v149 offset:7168
	global_load_lds_dwordx4 v[222:223], off
	v_lshl_add_u64 v[222:223], s[44:45], 0, v[140:141]
	v_lshl_add_u64 v[224:225], v[222:223], 0, s[6:7]
	s_mov_b32 m0, s36
	s_nop 0
	global_load_lds_dwordx4 v[224:225], off
	v_lshl_add_u64 v[224:225], v[220:221], 0, s[8:9]
	s_mov_b32 m0, s33
	s_nop 0
	global_load_lds_dwordx4 v[224:225], off
	v_lshl_add_u64 v[224:225], v[222:223], 0, s[8:9]
	s_mov_b32 m0, s29
	s_nop 0
	global_load_lds_dwordx4 v[224:225], off
	s_waitcnt vmcnt(8)
	s_waitcnt lgkmcnt(0)
	s_barrier
	s_setprio 1
	v_mfma_f32_16x16x32_bf16 v[126:129], v[156:159], v[188:191], v[126:129]
	v_mfma_f32_16x16x32_bf16 v[122:125], v[164:167], v[188:191], v[122:125]
	v_mfma_f32_16x16x32_bf16 v[118:121], v[156:159], v[196:199], v[118:121]
	v_mfma_f32_16x16x32_bf16 v[114:117], v[164:167], v[196:199], v[114:117]
	v_mfma_f32_16x16x32_bf16 v[110:113], v[156:159], v[204:207], v[110:113]
	v_mfma_f32_16x16x32_bf16 v[106:109], v[164:167], v[204:207], v[106:109]
	v_mfma_f32_16x16x32_bf16 v[102:105], v[156:159], v[212:215], v[102:105]
	v_mfma_f32_16x16x32_bf16 v[98:101], v[164:167], v[212:215], v[98:101]
	v_mfma_f32_16x16x32_bf16 v[126:129], v[160:163], v[192:195], v[126:129]
	v_mfma_f32_16x16x32_bf16 v[122:125], v[168:171], v[192:195], v[122:125]
	v_mfma_f32_16x16x32_bf16 v[118:121], v[160:163], v[200:203], v[118:121]
	v_mfma_f32_16x16x32_bf16 v[114:117], v[168:171], v[200:203], v[114:117]
	v_mfma_f32_16x16x32_bf16 v[110:113], v[160:163], v[208:211], v[110:113]
	v_mfma_f32_16x16x32_bf16 v[106:109], v[168:171], v[208:211], v[106:109]
	v_mfma_f32_16x16x32_bf16 v[102:105], v[160:163], v[216:219], v[102:105]
	v_mfma_f32_16x16x32_bf16 v[98:101], v[168:171], v[216:219], v[98:101]
	v_mfma_f32_16x16x32_bf16 v[94:97], v[172:175], v[188:191], v[94:97]
	v_mfma_f32_16x16x32_bf16 v[90:93], v[180:183], v[188:191], v[90:93]
	v_mfma_f32_16x16x32_bf16 v[86:89], v[172:175], v[196:199], v[86:89]
	v_mfma_f32_16x16x32_bf16 v[82:85], v[180:183], v[196:199], v[82:85]
	v_mfma_f32_16x16x32_bf16 v[78:81], v[172:175], v[204:207], v[78:81]
	v_mfma_f32_16x16x32_bf16 v[74:77], v[180:183], v[204:207], v[74:77]
	v_mfma_f32_16x16x32_bf16 v[70:73], v[172:175], v[212:215], v[70:73]
	v_mfma_f32_16x16x32_bf16 v[66:69], v[180:183], v[212:215], v[66:69]
	v_mfma_f32_16x16x32_bf16 v[94:97], v[176:179], v[192:195], v[94:97]
	v_mfma_f32_16x16x32_bf16 v[90:93], v[184:187], v[192:195], v[90:93]
	v_mfma_f32_16x16x32_bf16 v[86:89], v[176:179], v[200:203], v[86:89]
	v_mfma_f32_16x16x32_bf16 v[82:85], v[184:187], v[200:203], v[82:85]
	v_mfma_f32_16x16x32_bf16 v[78:81], v[176:179], v[208:211], v[78:81]
	v_mfma_f32_16x16x32_bf16 v[74:77], v[184:187], v[208:211], v[74:77]
	v_mfma_f32_16x16x32_bf16 v[70:73], v[176:179], v[216:219], v[70:73]
	v_mfma_f32_16x16x32_bf16 v[66:69], v[184:187], v[216:219], v[66:69]
	s_setprio 0
	s_barrier
	v_lshl_add_u64 v[224:225], s[44:45], 0, v[144:145]
	s_mov_b32 m0, s39
	v_lshl_add_u64 v[226:227], v[224:225], 0, s[10:11]
	ds_read_b128 v[188:191], v149 offset:16384
	ds_read_b128 v[192:195], v149 offset:17408
	ds_read_b128 v[196:199], v149 offset:18432
	ds_read_b128 v[200:203], v149 offset:19456
	ds_read_b128 v[204:207], v149 offset:20480
	ds_read_b128 v[208:211], v149 offset:21504
	ds_read_b128 v[212:215], v149 offset:22528
	ds_read_b128 v[216:219], v149 offset:23552
	global_load_lds_dwordx4 v[226:227], off
	v_lshl_add_u64 v[226:227], s[44:45], 0, v[146:147]
	v_lshl_add_u64 v[228:229], v[226:227], 0, s[10:11]
	s_mov_b32 m0, s46
	s_nop 0
	global_load_lds_dwordx4 v[228:229], off
	v_lshl_add_u64 v[228:229], v[224:225], 0, s[12:13]
	s_mov_b32 m0, s47
	s_nop 0
	global_load_lds_dwordx4 v[228:229], off
	v_lshl_add_u64 v[228:229], v[226:227], 0, s[12:13]
	s_mov_b32 m0, s48
	s_nop 0
	global_load_lds_dwordx4 v[228:229], off
	s_waitcnt vmcnt(4)
	s_waitcnt lgkmcnt(0)
	s_barrier
	s_setprio 1
	v_mfma_f32_16x16x32_bf16 v[62:65], v[156:159], v[188:191], v[62:65]
	v_mfma_f32_16x16x32_bf16 v[58:61], v[164:167], v[188:191], v[58:61]
	v_mfma_f32_16x16x32_bf16 v[54:57], v[156:159], v[196:199], v[54:57]
	v_mfma_f32_16x16x32_bf16 v[50:53], v[164:167], v[196:199], v[50:53]
	v_mfma_f32_16x16x32_bf16 v[46:49], v[156:159], v[204:207], v[46:49]
	v_mfma_f32_16x16x32_bf16 v[42:45], v[164:167], v[204:207], v[42:45]
	v_mfma_f32_16x16x32_bf16 v[38:41], v[156:159], v[212:215], v[38:41]
	v_mfma_f32_16x16x32_bf16 v[34:37], v[164:167], v[212:215], v[34:37]
	v_mfma_f32_16x16x32_bf16 v[62:65], v[160:163], v[192:195], v[62:65]
	v_mfma_f32_16x16x32_bf16 v[58:61], v[168:171], v[192:195], v[58:61]
	v_mfma_f32_16x16x32_bf16 v[54:57], v[160:163], v[200:203], v[54:57]
	v_mfma_f32_16x16x32_bf16 v[50:53], v[168:171], v[200:203], v[50:53]
	v_mfma_f32_16x16x32_bf16 v[46:49], v[160:163], v[208:211], v[46:49]
	v_mfma_f32_16x16x32_bf16 v[42:45], v[168:171], v[208:211], v[42:45]
	v_mfma_f32_16x16x32_bf16 v[38:41], v[160:163], v[216:219], v[38:41]
	v_mfma_f32_16x16x32_bf16 v[34:37], v[168:171], v[216:219], v[34:37]
	v_mfma_f32_16x16x32_bf16 v[30:33], v[172:175], v[188:191], v[30:33]
	v_mfma_f32_16x16x32_bf16 v[26:29], v[180:183], v[188:191], v[26:29]
	v_mfma_f32_16x16x32_bf16 v[22:25], v[172:175], v[196:199], v[22:25]
	v_mfma_f32_16x16x32_bf16 v[18:21], v[180:183], v[196:199], v[18:21]
	v_mfma_f32_16x16x32_bf16 v[14:17], v[172:175], v[204:207], v[14:17]
	v_mfma_f32_16x16x32_bf16 v[10:13], v[180:183], v[204:207], v[10:13]
	v_mfma_f32_16x16x32_bf16 v[6:9], v[172:175], v[212:215], v[6:9]
	v_mfma_f32_16x16x32_bf16 v[2:5], v[180:183], v[212:215], v[2:5]
	v_mfma_f32_16x16x32_bf16 v[30:33], v[176:179], v[192:195], v[30:33]
	v_mfma_f32_16x16x32_bf16 v[26:29], v[184:187], v[192:195], v[26:29]
	v_mfma_f32_16x16x32_bf16 v[22:25], v[176:179], v[200:203], v[22:25]
	v_mfma_f32_16x16x32_bf16 v[18:21], v[184:187], v[200:203], v[18:21]
	v_mfma_f32_16x16x32_bf16 v[14:17], v[176:179], v[208:211], v[14:17]
	v_mfma_f32_16x16x32_bf16 v[10:13], v[184:187], v[208:211], v[10:13]
	v_mfma_f32_16x16x32_bf16 v[6:9], v[176:179], v[216:219], v[6:9]
	v_mfma_f32_16x16x32_bf16 v[2:5], v[184:187], v[216:219], v[2:5]
	s_setprio 0
	s_barrier
	ds_read_b128 v[156:159], v153
	ds_read_b128 v[160:163], v153 offset:1024
	ds_read_b128 v[164:167], v153 offset:2048
	ds_read_b128 v[168:171], v153 offset:3072
	ds_read_b128 v[172:175], v154
	ds_read_b128 v[176:179], v154 offset:1024
	ds_read_b128 v[180:183], v154 offset:2048
	ds_read_b128 v[184:187], v154 offset:3072
	s_mov_b32 m0, s21
	v_lshl_add_u64 v[228:229], v[220:221], 0, s[30:31]
	ds_read_b128 v[188:191], v149 offset:32768
	ds_read_b128 v[192:195], v149 offset:33792
	ds_read_b128 v[196:199], v149 offset:34816
	ds_read_b128 v[200:203], v149 offset:35840
	ds_read_b128 v[204:207], v149 offset:36864
	ds_read_b128 v[208:211], v149 offset:37888
	ds_read_b128 v[212:215], v149 offset:38912
	ds_read_b128 v[216:219], v149 offset:39936
	global_load_lds_dwordx4 v[228:229], off
	v_lshl_add_u64 v[228:229], v[222:223], 0, s[30:31]
	s_mov_b32 m0, s22
	v_lshl_add_u64 v[220:221], v[220:221], 0, s[34:35]
	global_load_lds_dwordx4 v[228:229], off
	s_mov_b32 m0, s23
	s_nop 0
	global_load_lds_dwordx4 v[220:221], off
	v_lshl_add_u64 v[220:221], v[222:223], 0, s[34:35]
	s_mov_b32 m0, s28
	s_nop 0
	global_load_lds_dwordx4 v[220:221], off
	s_waitcnt vmcnt(8)
	s_waitcnt lgkmcnt(0)
	s_barrier
	s_setprio 1
	v_mfma_f32_16x16x32_bf16 v[126:129], v[156:159], v[188:191], v[126:129]
	v_mfma_f32_16x16x32_bf16 v[122:125], v[164:167], v[188:191], v[122:125]
	v_mfma_f32_16x16x32_bf16 v[118:121], v[156:159], v[196:199], v[118:121]
	v_mfma_f32_16x16x32_bf16 v[114:117], v[164:167], v[196:199], v[114:117]
	v_mfma_f32_16x16x32_bf16 v[110:113], v[156:159], v[204:207], v[110:113]
	v_mfma_f32_16x16x32_bf16 v[106:109], v[164:167], v[204:207], v[106:109]
	v_mfma_f32_16x16x32_bf16 v[102:105], v[156:159], v[212:215], v[102:105]
	v_mfma_f32_16x16x32_bf16 v[98:101], v[164:167], v[212:215], v[98:101]
	v_mfma_f32_16x16x32_bf16 v[126:129], v[160:163], v[192:195], v[126:129]
	v_mfma_f32_16x16x32_bf16 v[122:125], v[168:171], v[192:195], v[122:125]
	v_mfma_f32_16x16x32_bf16 v[118:121], v[160:163], v[200:203], v[118:121]
	v_mfma_f32_16x16x32_bf16 v[114:117], v[168:171], v[200:203], v[114:117]
	v_mfma_f32_16x16x32_bf16 v[110:113], v[160:163], v[208:211], v[110:113]
	v_mfma_f32_16x16x32_bf16 v[106:109], v[168:171], v[208:211], v[106:109]
	v_mfma_f32_16x16x32_bf16 v[102:105], v[160:163], v[216:219], v[102:105]
	v_mfma_f32_16x16x32_bf16 v[98:101], v[168:171], v[216:219], v[98:101]
	v_mfma_f32_16x16x32_bf16 v[94:97], v[172:175], v[188:191], v[94:97]
	v_mfma_f32_16x16x32_bf16 v[90:93], v[180:183], v[188:191], v[90:93]
	v_mfma_f32_16x16x32_bf16 v[86:89], v[172:175], v[196:199], v[86:89]
	v_mfma_f32_16x16x32_bf16 v[82:85], v[180:183], v[196:199], v[82:85]
	v_mfma_f32_16x16x32_bf16 v[78:81], v[172:175], v[204:207], v[78:81]
	v_mfma_f32_16x16x32_bf16 v[74:77], v[180:183], v[204:207], v[74:77]
	v_mfma_f32_16x16x32_bf16 v[70:73], v[172:175], v[212:215], v[70:73]
	v_mfma_f32_16x16x32_bf16 v[66:69], v[180:183], v[212:215], v[66:69]
	v_mfma_f32_16x16x32_bf16 v[94:97], v[176:179], v[192:195], v[94:97]
	v_mfma_f32_16x16x32_bf16 v[90:93], v[184:187], v[192:195], v[90:93]
	v_mfma_f32_16x16x32_bf16 v[86:89], v[176:179], v[200:203], v[86:89]
	v_mfma_f32_16x16x32_bf16 v[82:85], v[184:187], v[200:203], v[82:85]
	v_mfma_f32_16x16x32_bf16 v[78:81], v[176:179], v[208:211], v[78:81]
	v_mfma_f32_16x16x32_bf16 v[74:77], v[184:187], v[208:211], v[74:77]
	v_mfma_f32_16x16x32_bf16 v[70:73], v[176:179], v[216:219], v[70:73]
	v_mfma_f32_16x16x32_bf16 v[66:69], v[184:187], v[216:219], v[66:69]
	s_setprio 0
	s_barrier
	s_mov_b32 m0, s49
	v_lshl_add_u64 v[220:221], v[224:225], 0, s[40:41]
	ds_read_b128 v[188:191], v149 offset:49152
	ds_read_b128 v[192:195], v149 offset:50176
	ds_read_b128 v[196:199], v149 offset:51200
	ds_read_b128 v[200:203], v149 offset:52224
	ds_read_b128 v[204:207], v149 offset:53248
	ds_read_b128 v[208:211], v149 offset:54272
	ds_read_b128 v[212:215], v149 offset:55296
	ds_read_b128 v[216:219], v149 offset:56320
	global_load_lds_dwordx4 v[220:221], off
	v_lshl_add_u64 v[220:221], v[226:227], 0, s[40:41]
	s_mov_b32 m0, s50
	s_nop 0
	global_load_lds_dwordx4 v[220:221], off
	v_lshl_add_u64 v[220:221], v[224:225], 0, s[42:43]
	s_mov_b32 m0, s51
	s_nop 0
	global_load_lds_dwordx4 v[220:221], off
	v_lshl_add_u64 v[220:221], v[226:227], 0, s[42:43]
	s_mov_b32 m0, s56
	s_nop 0
	global_load_lds_dwordx4 v[220:221], off
	s_waitcnt vmcnt(4)
	s_waitcnt lgkmcnt(0)
	s_barrier
	s_setprio 1
	v_mfma_f32_16x16x32_bf16 v[62:65], v[156:159], v[188:191], v[62:65]
	v_mfma_f32_16x16x32_bf16 v[58:61], v[164:167], v[188:191], v[58:61]
	v_mfma_f32_16x16x32_bf16 v[54:57], v[156:159], v[196:199], v[54:57]
	v_mfma_f32_16x16x32_bf16 v[50:53], v[164:167], v[196:199], v[50:53]
	v_mfma_f32_16x16x32_bf16 v[46:49], v[156:159], v[204:207], v[46:49]
	v_mfma_f32_16x16x32_bf16 v[42:45], v[164:167], v[204:207], v[42:45]
	v_mfma_f32_16x16x32_bf16 v[38:41], v[156:159], v[212:215], v[38:41]
	v_mfma_f32_16x16x32_bf16 v[34:37], v[164:167], v[212:215], v[34:37]
	v_mfma_f32_16x16x32_bf16 v[62:65], v[160:163], v[192:195], v[62:65]
	v_mfma_f32_16x16x32_bf16 v[58:61], v[168:171], v[192:195], v[58:61]
	v_mfma_f32_16x16x32_bf16 v[54:57], v[160:163], v[200:203], v[54:57]
	v_mfma_f32_16x16x32_bf16 v[50:53], v[168:171], v[200:203], v[50:53]
	v_mfma_f32_16x16x32_bf16 v[46:49], v[160:163], v[208:211], v[46:49]
	v_mfma_f32_16x16x32_bf16 v[42:45], v[168:171], v[208:211], v[42:45]
	v_mfma_f32_16x16x32_bf16 v[38:41], v[160:163], v[216:219], v[38:41]
	v_mfma_f32_16x16x32_bf16 v[34:37], v[168:171], v[216:219], v[34:37]
	v_mfma_f32_16x16x32_bf16 v[30:33], v[172:175], v[188:191], v[30:33]
	v_mfma_f32_16x16x32_bf16 v[26:29], v[180:183], v[188:191], v[26:29]
	v_mfma_f32_16x16x32_bf16 v[22:25], v[172:175], v[196:199], v[22:25]
	v_mfma_f32_16x16x32_bf16 v[18:21], v[180:183], v[196:199], v[18:21]
	v_mfma_f32_16x16x32_bf16 v[14:17], v[172:175], v[204:207], v[14:17]
	v_mfma_f32_16x16x32_bf16 v[10:13], v[180:183], v[204:207], v[10:13]
	v_mfma_f32_16x16x32_bf16 v[6:9], v[172:175], v[212:215], v[6:9]
	v_mfma_f32_16x16x32_bf16 v[2:5], v[180:183], v[212:215], v[2:5]
	v_mfma_f32_16x16x32_bf16 v[30:33], v[176:179], v[192:195], v[30:33]
	v_mfma_f32_16x16x32_bf16 v[26:29], v[184:187], v[192:195], v[26:29]
	v_mfma_f32_16x16x32_bf16 v[22:25], v[176:179], v[200:203], v[22:25]
	v_mfma_f32_16x16x32_bf16 v[18:21], v[184:187], v[200:203], v[18:21]
	v_mfma_f32_16x16x32_bf16 v[14:17], v[176:179], v[208:211], v[14:17]
	v_mfma_f32_16x16x32_bf16 v[10:13], v[184:187], v[208:211], v[10:13]
	v_mfma_f32_16x16x32_bf16 v[6:9], v[176:179], v[216:219], v[6:9]
	v_mfma_f32_16x16x32_bf16 v[2:5], v[184:187], v[216:219], v[2:5]
	s_setprio 0
	s_barrier
	s_add_i32 s38, s38, 2
	s_add_u32 s44, s44, 0x100
	s_addc_u32 s45, s45, 0
	s_cmp_lt_u32 s38, 12
	s_cbranch_scc1 .LBB0_325
	v_add_u32_e32 v210, 0, v150
	v_add_u32_e32 v154, 0x10000, v210
	v_add_u32_e32 v170, 0x14000, v210
	ds_read_b128 v[140:143], v154
	ds_read_b128 v[144:147], v154 offset:1024
	ds_read_b128 v[150:153], v154 offset:2048
	ds_read_b128 v[154:157], v154 offset:3072
	ds_read_b128 v[158:161], v170
	ds_read_b128 v[162:165], v170 offset:1024
	ds_read_b128 v[166:169], v170 offset:2048
	ds_read_b128 v[170:173], v170 offset:3072
	s_add_u32 s4, s4, 0x40780
	s_addc_u32 s5, s5, 0
	s_cmpk_gt_u32 s20, 0xff
	s_mov_b64 s[6:7], 0x780
	s_mov_b32 m0, s37
	v_lshl_add_u64 v[138:139], v[138:139], 0, s[6:7]
	ds_read_b128 v[174:177], v149
	ds_read_b128 v[178:181], v149 offset:1024
	ds_read_b128 v[182:185], v149 offset:2048
	ds_read_b128 v[186:189], v149 offset:3072
	ds_read_b128 v[190:193], v149 offset:4096
	ds_read_b128 v[194:197], v149 offset:5120
	ds_read_b128 v[198:201], v149 offset:6144
	ds_read_b128 v[202:205], v149 offset:7168
	global_load_lds_dwordx4 v[138:139], off
	v_lshl_add_u64 v[136:137], v[136:137], 0, s[6:7]
	s_mov_b32 m0, s36
	v_lshl_add_u64 v[134:135], s[4:5], 0, v[134:135]
	global_load_lds_dwordx4 v[136:137], off
	s_mov_b32 m0, s33
	v_lshl_add_u64 v[132:133], s[4:5], 0, v[132:133]
	global_load_lds_dwordx4 v[134:135], off
	s_mov_b32 m0, s29
	s_nop 0
	global_load_lds_dwordx4 v[132:133], off
	s_waitcnt vmcnt(8)
	s_waitcnt lgkmcnt(0)
	s_barrier
	s_setprio 1
	v_mfma_f32_16x16x32_bf16 v[126:129], v[140:143], v[174:177], v[126:129]
	v_mfma_f32_16x16x32_bf16 v[122:125], v[150:153], v[174:177], v[122:125]
	v_mfma_f32_16x16x32_bf16 v[118:121], v[140:143], v[182:185], v[118:121]
	v_mfma_f32_16x16x32_bf16 v[114:117], v[150:153], v[182:185], v[114:117]
	v_mfma_f32_16x16x32_bf16 v[102:105], v[140:143], v[198:201], v[102:105]
	v_mfma_f32_16x16x32_bf16 v[98:101], v[150:153], v[198:201], v[98:101]
	v_mfma_f32_16x16x32_bf16 v[126:129], v[144:147], v[178:181], v[126:129]
	v_mfma_f32_16x16x32_bf16 v[122:125], v[154:157], v[178:181], v[122:125]
	v_mfma_f32_16x16x32_bf16 v[118:121], v[144:147], v[186:189], v[118:121]
	v_mfma_f32_16x16x32_bf16 v[114:117], v[154:157], v[186:189], v[114:117]
	v_mfma_f32_16x16x32_bf16 v[110:113], v[140:143], v[190:193], v[110:113]
	v_mfma_f32_16x16x32_bf16 v[106:109], v[150:153], v[190:193], v[106:109]
	v_mfma_f32_16x16x32_bf16 v[102:105], v[144:147], v[202:205], v[102:105]
	v_mfma_f32_16x16x32_bf16 v[98:101], v[154:157], v[202:205], v[98:101]
	v_mfma_f32_16x16x32_bf16 v[132:135], v[144:147], v[194:197], v[110:113]
	v_mfma_f32_16x16x32_bf16 v[136:139], v[154:157], v[194:197], v[106:109]
	v_mfma_f32_16x16x32_bf16 v[86:89], v[158:161], v[182:185], v[86:89]
	v_mfma_f32_16x16x32_bf16 v[82:85], v[166:169], v[182:185], v[82:85]
	v_mfma_f32_16x16x32_bf16 v[70:73], v[158:161], v[198:201], v[70:73]
	v_mfma_f32_16x16x32_bf16 v[66:69], v[166:169], v[198:201], v[66:69]
	v_mfma_f32_16x16x32_bf16 v[94:97], v[158:161], v[174:177], v[94:97]
	v_mfma_f32_16x16x32_bf16 v[90:93], v[166:169], v[174:177], v[90:93]
	v_mfma_f32_16x16x32_bf16 v[86:89], v[162:165], v[186:189], v[86:89]
	v_mfma_f32_16x16x32_bf16 v[82:85], v[170:173], v[186:189], v[82:85]
	v_mfma_f32_16x16x32_bf16 v[78:81], v[158:161], v[190:193], v[78:81]
	v_mfma_f32_16x16x32_bf16 v[74:77], v[166:169], v[190:193], v[74:77]
	v_mfma_f32_16x16x32_bf16 v[70:73], v[162:165], v[202:205], v[70:73]
	v_mfma_f32_16x16x32_bf16 v[66:69], v[170:173], v[202:205], v[66:69]
	v_mfma_f32_16x16x32_bf16 v[206:209], v[162:165], v[178:181], v[94:97]
	v_mfma_f32_16x16x32_bf16 v[174:177], v[170:173], v[178:181], v[90:93]
	v_mfma_f32_16x16x32_bf16 v[178:181], v[162:165], v[194:197], v[78:81]
	v_mfma_f32_16x16x32_bf16 v[182:185], v[170:173], v[194:197], v[74:77]
	s_setprio 0
	s_barrier
	s_nop 0
	ds_read_b128 v[74:77], v149 offset:16384
	ds_read_b128 v[78:81], v149 offset:17408
	ds_read_b128 v[90:93], v149 offset:18432
	ds_read_b128 v[94:97], v149 offset:19456
	ds_read_b128 v[106:109], v149 offset:20480
	ds_read_b128 v[110:113], v149 offset:21504
	ds_read_b128 v[186:189], v149 offset:22528
	ds_read_b128 v[190:193], v149 offset:23552
	s_waitcnt vmcnt(0)
	s_waitcnt lgkmcnt(0)
	s_barrier
	s_setprio 1
	v_mfma_f32_16x16x32_bf16 v[62:65], v[140:143], v[74:77], v[62:65]
	v_mfma_f32_16x16x32_bf16 v[58:61], v[150:153], v[74:77], v[58:61]
	v_mfma_f32_16x16x32_bf16 v[54:57], v[140:143], v[90:93], v[54:57]
	v_mfma_f32_16x16x32_bf16 v[50:53], v[150:153], v[90:93], v[50:53]
	v_mfma_f32_16x16x32_bf16 v[38:41], v[140:143], v[186:189], v[38:41]
	v_mfma_f32_16x16x32_bf16 v[34:37], v[150:153], v[186:189], v[34:37]
	v_mfma_f32_16x16x32_bf16 v[62:65], v[144:147], v[78:81], v[62:65]
	v_mfma_f32_16x16x32_bf16 v[58:61], v[154:157], v[78:81], v[58:61]
	v_mfma_f32_16x16x32_bf16 v[54:57], v[144:147], v[94:97], v[54:57]
	v_mfma_f32_16x16x32_bf16 v[50:53], v[154:157], v[94:97], v[50:53]
	v_mfma_f32_16x16x32_bf16 v[46:49], v[140:143], v[106:109], v[46:49]
	v_mfma_f32_16x16x32_bf16 v[42:45], v[150:153], v[106:109], v[42:45]
	v_mfma_f32_16x16x32_bf16 v[38:41], v[144:147], v[190:193], v[38:41]
	v_mfma_f32_16x16x32_bf16 v[34:37], v[154:157], v[190:193], v[34:37]
	v_mfma_f32_16x16x32_bf16 v[194:197], v[144:147], v[110:113], v[46:49]
	v_mfma_f32_16x16x32_bf16 v[198:201], v[154:157], v[110:113], v[42:45]
	v_mfma_f32_16x16x32_bf16 v[22:25], v[158:161], v[90:93], v[22:25]
	v_mfma_f32_16x16x32_bf16 v[18:21], v[166:169], v[90:93], v[18:21]
	v_mfma_f32_16x16x32_bf16 v[6:9], v[158:161], v[186:189], v[6:9]
	v_mfma_f32_16x16x32_bf16 v[2:5], v[166:169], v[186:189], v[2:5]
	v_mfma_f32_16x16x32_bf16 v[30:33], v[158:161], v[74:77], v[30:33]
	v_mfma_f32_16x16x32_bf16 v[26:29], v[166:169], v[74:77], v[26:29]
	v_mfma_f32_16x16x32_bf16 v[22:25], v[162:165], v[94:97], v[22:25]
	v_mfma_f32_16x16x32_bf16 v[18:21], v[170:173], v[94:97], v[18:21]
	v_mfma_f32_16x16x32_bf16 v[14:17], v[158:161], v[106:109], v[14:17]
	v_mfma_f32_16x16x32_bf16 v[10:13], v[166:169], v[106:109], v[10:13]
	v_mfma_f32_16x16x32_bf16 v[6:9], v[162:165], v[190:193], v[6:9]
	v_mfma_f32_16x16x32_bf16 v[2:5], v[170:173], v[190:193], v[2:5]
	v_mfma_f32_16x16x32_bf16 v[140:143], v[162:165], v[78:81], v[30:33]
	v_mfma_f32_16x16x32_bf16 v[144:147], v[170:173], v[78:81], v[26:29]
	v_mfma_f32_16x16x32_bf16 v[150:153], v[162:165], v[110:113], v[14:17]
	v_mfma_f32_16x16x32_bf16 v[154:157], v[170:173], v[110:113], v[10:13]
	s_setprio 0
	s_barrier
	v_add_u32_e32 v26, 0x18000, v210
	ds_read_b128 v[10:13], v26
	ds_read_b128 v[14:17], v26 offset:1024
	ds_read_b128 v[158:161], v26 offset:2048
	ds_read_b128 v[162:165], v26 offset:3072
	v_add_u32_e32 v26, 0x1c000, v210
	ds_read_b128 v[166:169], v26
	ds_read_b128 v[170:173], v26 offset:1024
	ds_read_b128 v[186:189], v26 offset:2048
	ds_read_b128 v[190:193], v26 offset:3072
	ds_read_b128 v[26:29], v149 offset:32768
	ds_read_b128 v[30:33], v149 offset:33792
	ds_read_b128 v[42:45], v149 offset:34816
	ds_read_b128 v[46:49], v149 offset:35840
	ds_read_b128 v[202:205], v149 offset:36864
	ds_read_b128 v[210:213], v149 offset:37888
	ds_read_b128 v[214:217], v149 offset:38912
	ds_read_b128 v[218:221], v149 offset:39936
	s_waitcnt lgkmcnt(0)
	s_barrier
	s_setprio 1
	v_mfma_f32_16x16x32_bf16 v[74:77], v[10:13], v[26:29], v[126:129]
	v_mfma_f32_16x16x32_bf16 v[126:129], v[14:17], v[30:33], v[74:77]
	v_mfma_f32_16x16x32_bf16 v[74:77], v[158:161], v[26:29], v[122:125]
	v_mfma_f32_16x16x32_bf16 v[122:125], v[162:165], v[30:33], v[74:77]
	v_mfma_f32_16x16x32_bf16 v[74:77], v[10:13], v[42:45], v[118:121]
	v_mfma_f32_16x16x32_bf16 v[110:113], v[14:17], v[46:49], v[74:77]
	v_mfma_f32_16x16x32_bf16 v[74:77], v[158:161], v[42:45], v[114:117]
	v_mfma_f32_16x16x32_bf16 v[106:109], v[162:165], v[46:49], v[74:77]
	v_mfma_f32_16x16x32_bf16 v[74:77], v[10:13], v[202:205], v[132:135]
	v_mfma_f32_16x16x32_bf16 v[94:97], v[14:17], v[210:213], v[74:77]
	v_mfma_f32_16x16x32_bf16 v[74:77], v[158:161], v[202:205], v[136:139]
	v_mfma_f32_16x16x32_bf16 v[90:93], v[162:165], v[210:213], v[74:77]
	v_mfma_f32_16x16x32_bf16 v[74:77], v[10:13], v[214:217], v[102:105]
	v_mfma_f32_16x16x32_bf16 v[78:81], v[14:17], v[218:221], v[74:77]
	v_mfma_f32_16x16x32_bf16 v[74:77], v[158:161], v[214:217], v[98:101]
	v_mfma_f32_16x16x32_bf16 v[74:77], v[162:165], v[218:221], v[74:77]
	v_mfma_f32_16x16x32_bf16 v[98:101], v[166:169], v[26:29], v[206:209]
	v_mfma_f32_16x16x32_bf16 v[26:29], v[186:189], v[26:29], v[174:177]
	v_mfma_f32_16x16x32_bf16 v[114:117], v[190:193], v[30:33], v[26:29]
	v_mfma_f32_16x16x32_bf16 v[26:29], v[166:169], v[42:45], v[86:89]
	v_mfma_f32_16x16x32_bf16 v[102:105], v[170:173], v[46:49], v[26:29]
	v_mfma_f32_16x16x32_bf16 v[26:29], v[186:189], v[42:45], v[82:85]
	v_mfma_f32_16x16x32_bf16 v[118:121], v[170:173], v[30:33], v[98:101]
	v_mfma_f32_16x16x32_bf16 v[98:101], v[190:193], v[46:49], v[26:29]
	v_mfma_f32_16x16x32_bf16 v[26:29], v[166:169], v[202:205], v[178:181]
	v_mfma_f32_16x16x32_bf16 v[86:89], v[170:173], v[210:213], v[26:29]
	v_mfma_f32_16x16x32_bf16 v[26:29], v[186:189], v[202:205], v[182:185]
	v_mfma_f32_16x16x32_bf16 v[82:85], v[190:193], v[210:213], v[26:29]
	v_mfma_f32_16x16x32_bf16 v[26:29], v[166:169], v[214:217], v[70:73]
	v_mfma_f32_16x16x32_bf16 v[70:73], v[170:173], v[218:221], v[26:29]
	v_mfma_f32_16x16x32_bf16 v[26:29], v[186:189], v[214:217], v[66:69]
	v_mfma_f32_16x16x32_bf16 v[66:69], v[190:193], v[218:221], v[26:29]
	s_setprio 0
	s_barrier
	ds_read_b128 v[132:135], v149 offset:49152
	ds_read_b128 v[136:139], v149 offset:50176
	ds_read_b128 v[174:177], v149 offset:51200
	ds_read_b128 v[178:181], v149 offset:52224
	ds_read_b128 v[182:185], v149 offset:53248
	ds_read_b128 v[202:205], v149 offset:54272
	ds_read_b128 v[206:209], v149 offset:55296
	ds_read_b128 v[210:213], v149 offset:56320
	s_waitcnt lgkmcnt(0)
	s_barrier
	s_setprio 1
	v_mfma_f32_16x16x32_bf16 v[26:29], v[10:13], v[132:135], v[62:65]
	v_mfma_f32_16x16x32_bf16 v[62:65], v[14:17], v[136:139], v[26:29]
	v_mfma_f32_16x16x32_bf16 v[26:29], v[158:161], v[132:135], v[58:61]
	v_mfma_f32_16x16x32_bf16 v[58:61], v[162:165], v[136:139], v[26:29]
	v_mfma_f32_16x16x32_bf16 v[26:29], v[10:13], v[174:177], v[54:57]
	v_mfma_f32_16x16x32_bf16 v[46:49], v[14:17], v[178:181], v[26:29]
	v_mfma_f32_16x16x32_bf16 v[26:29], v[158:161], v[174:177], v[50:53]
	v_mfma_f32_16x16x32_bf16 v[42:45], v[162:165], v[178:181], v[26:29]
	v_mfma_f32_16x16x32_bf16 v[26:29], v[10:13], v[182:185], v[194:197]
	v_mfma_f32_16x16x32_bf16 v[10:13], v[10:13], v[206:209], v[38:41]
	v_mfma_f32_16x16x32_bf16 v[30:33], v[14:17], v[202:205], v[26:29]
	v_mfma_f32_16x16x32_bf16 v[26:29], v[158:161], v[182:185], v[198:201]
	v_mfma_f32_16x16x32_bf16 v[14:17], v[14:17], v[210:213], v[10:13]
	v_mfma_f32_16x16x32_bf16 v[10:13], v[158:161], v[206:209], v[34:37]
	v_mfma_f32_16x16x32_bf16 v[26:29], v[162:165], v[202:205], v[26:29]
	v_mfma_f32_16x16x32_bf16 v[10:13], v[162:165], v[210:213], v[10:13]
	v_mfma_f32_16x16x32_bf16 v[34:37], v[166:169], v[132:135], v[140:143]
	v_mfma_f32_16x16x32_bf16 v[54:57], v[170:173], v[136:139], v[34:37]
	v_mfma_f32_16x16x32_bf16 v[34:37], v[186:189], v[132:135], v[144:147]
	v_mfma_f32_16x16x32_bf16 v[18:21], v[186:189], v[174:177], v[18:21]
	v_mfma_f32_16x16x32_bf16 v[50:53], v[190:193], v[136:139], v[34:37]
	v_mfma_f32_16x16x32_bf16 v[22:25], v[166:169], v[174:177], v[22:25]
	v_mfma_f32_16x16x32_bf16 v[34:37], v[190:193], v[178:181], v[18:21]
	v_mfma_f32_16x16x32_bf16 v[18:21], v[166:169], v[182:185], v[150:153]
	v_mfma_f32_16x16x32_bf16 v[38:41], v[170:173], v[178:181], v[22:25]
	v_mfma_f32_16x16x32_bf16 v[22:25], v[170:173], v[202:205], v[18:21]
	v_mfma_f32_16x16x32_bf16 v[18:21], v[186:189], v[182:185], v[154:157]
	v_mfma_f32_16x16x32_bf16 v[6:9], v[166:169], v[206:209], v[6:9]
	v_mfma_f32_16x16x32_bf16 v[2:5], v[186:189], v[206:209], v[2:5]
	v_mfma_f32_16x16x32_bf16 v[18:21], v[190:193], v[202:205], v[18:21]
	v_mfma_f32_16x16x32_bf16 v[6:9], v[170:173], v[210:213], v[6:9]
	v_mfma_f32_16x16x32_bf16 v[2:5], v[190:193], v[210:213], v[2:5]
	s_setprio 0
	s_barrier
	s_cbranch_scc1 .LBB0_328
	s_barrier

.LBB0_599:
	v_add_u32_e32 v150, s46, v219
	s_waitcnt lgkmcnt(0)
	v_add_u32_e32 v166, s47, v219
	ds_read_b128 v[138:141], v150
	ds_read_b128 v[142:145], v150 offset:1024
	ds_read_b128 v[146:149], v150 offset:2048
	ds_read_b128 v[150:153], v150 offset:3072
	ds_read_b128 v[154:157], v166
	ds_read_b128 v[158:161], v166 offset:1024
	ds_read_b128 v[162:165], v166 offset:2048
	ds_read_b128 v[166:169], v166 offset:3072
	v_lshl_add_u64 v[210:211], v[132:133], 0, s[4:5]
	s_mov_b32 m0, s44
	v_lshl_add_u64 v[212:213], v[210:211], 0, s[16:17]
	ds_read_b128 v[170:173], v217
	ds_read_b128 v[174:177], v217 offset:1024
	ds_read_b128 v[178:181], v217 offset:2048
	ds_read_b128 v[182:185], v217 offset:3072
	ds_read_b128 v[186:189], v217 offset:4096
	ds_read_b128 v[190:193], v217 offset:5120
	ds_read_b128 v[202:205], v217 offset:6144
	ds_read_b128 v[206:209], v217 offset:7168
	global_load_lds_dwordx4 v[212:213], off
	v_lshl_add_u64 v[212:213], v[130:131], 0, s[4:5]
	v_lshl_add_u64 v[214:215], v[212:213], 0, s[16:17]
	s_mov_b32 m0, s43
	s_nop 0
	global_load_lds_dwordx4 v[214:215], off
	v_lshl_add_u64 v[214:215], v[210:211], 0, s[18:19]
	s_mov_b32 m0, s42
	s_nop 0
	global_load_lds_dwordx4 v[214:215], off
	v_lshl_add_u64 v[214:215], v[212:213], 0, s[18:19]
	s_mov_b32 m0, s39
	s_nop 0
	global_load_lds_dwordx4 v[214:215], off
	s_waitcnt vmcnt(8)
	s_waitcnt lgkmcnt(0)
	s_barrier
	s_setprio 1
	v_mfma_f32_16x16x32_bf16 v[126:129], v[138:141], v[170:173], v[126:129]
	v_mfma_f32_16x16x32_bf16 v[122:125], v[146:149], v[170:173], v[122:125]
	v_mfma_f32_16x16x32_bf16 v[118:121], v[138:141], v[178:181], v[118:121]
	v_mfma_f32_16x16x32_bf16 v[114:117], v[146:149], v[178:181], v[114:117]
	v_mfma_f32_16x16x32_bf16 v[110:113], v[138:141], v[186:189], v[110:113]
	v_mfma_f32_16x16x32_bf16 v[106:109], v[146:149], v[186:189], v[106:109]
	v_mfma_f32_16x16x32_bf16 v[102:105], v[138:141], v[202:205], v[102:105]
	v_mfma_f32_16x16x32_bf16 v[98:101], v[146:149], v[202:205], v[98:101]
	v_mfma_f32_16x16x32_bf16 v[126:129], v[142:145], v[174:177], v[126:129]
	v_mfma_f32_16x16x32_bf16 v[122:125], v[150:153], v[174:177], v[122:125]
	v_mfma_f32_16x16x32_bf16 v[118:121], v[142:145], v[182:185], v[118:121]
	v_mfma_f32_16x16x32_bf16 v[114:117], v[150:153], v[182:185], v[114:117]
	v_mfma_f32_16x16x32_bf16 v[110:113], v[142:145], v[190:193], v[110:113]
	v_mfma_f32_16x16x32_bf16 v[106:109], v[150:153], v[190:193], v[106:109]
	v_mfma_f32_16x16x32_bf16 v[102:105], v[142:145], v[206:209], v[102:105]
	v_mfma_f32_16x16x32_bf16 v[98:101], v[150:153], v[206:209], v[98:101]
	v_mfma_f32_16x16x32_bf16 v[94:97], v[154:157], v[170:173], v[94:97]
	v_mfma_f32_16x16x32_bf16 v[90:93], v[162:165], v[170:173], v[90:93]
	v_mfma_f32_16x16x32_bf16 v[86:89], v[154:157], v[178:181], v[86:89]
	v_mfma_f32_16x16x32_bf16 v[82:85], v[162:165], v[178:181], v[82:85]
	v_mfma_f32_16x16x32_bf16 v[78:81], v[154:157], v[186:189], v[78:81]
	v_mfma_f32_16x16x32_bf16 v[74:77], v[162:165], v[186:189], v[74:77]
	v_mfma_f32_16x16x32_bf16 v[70:73], v[154:157], v[202:205], v[70:73]
	v_mfma_f32_16x16x32_bf16 v[66:69], v[162:165], v[202:205], v[66:69]
	v_mfma_f32_16x16x32_bf16 v[94:97], v[158:161], v[174:177], v[94:97]
	v_mfma_f32_16x16x32_bf16 v[90:93], v[166:169], v[174:177], v[90:93]
	v_mfma_f32_16x16x32_bf16 v[86:89], v[158:161], v[182:185], v[86:89]
	v_mfma_f32_16x16x32_bf16 v[82:85], v[166:169], v[182:185], v[82:85]
	v_mfma_f32_16x16x32_bf16 v[78:81], v[158:161], v[190:193], v[78:81]
	v_mfma_f32_16x16x32_bf16 v[74:77], v[166:169], v[190:193], v[74:77]
	v_mfma_f32_16x16x32_bf16 v[70:73], v[158:161], v[206:209], v[70:73]
	v_mfma_f32_16x16x32_bf16 v[66:69], v[166:169], v[206:209], v[66:69]
	s_setprio 0
	s_barrier
	v_lshl_add_u64 v[214:215], v[136:137], 0, s[4:5]
	s_mov_b32 m0, s48
	v_lshl_add_u64 v[220:221], v[214:215], 0, s[22:23]
	ds_read_b128 v[170:173], v217 offset:16384
	ds_read_b128 v[174:177], v217 offset:17408
	ds_read_b128 v[178:181], v217 offset:18432
	ds_read_b128 v[182:185], v217 offset:19456
	ds_read_b128 v[186:189], v217 offset:20480
	ds_read_b128 v[190:193], v217 offset:21504
	ds_read_b128 v[202:205], v217 offset:22528
	ds_read_b128 v[206:209], v217 offset:23552
	global_load_lds_dwordx4 v[220:221], off
	v_lshl_add_u64 v[220:221], v[134:135], 0, s[4:5]
	v_lshl_add_u64 v[222:223], v[220:221], 0, s[22:23]
	s_mov_b32 m0, s49
	s_nop 0
	global_load_lds_dwordx4 v[222:223], off
	v_lshl_add_u64 v[222:223], v[214:215], 0, s[30:31]
	s_mov_b32 m0, s50
	s_nop 0
	global_load_lds_dwordx4 v[222:223], off
	v_lshl_add_u64 v[222:223], v[220:221], 0, s[30:31]
	s_mov_b32 m0, s51
	s_nop 0
	global_load_lds_dwordx4 v[222:223], off
	s_waitcnt vmcnt(4)
	s_waitcnt lgkmcnt(0)
	s_barrier
	s_setprio 1
	v_mfma_f32_16x16x32_bf16 v[62:65], v[138:141], v[170:173], v[62:65]
	v_mfma_f32_16x16x32_bf16 v[58:61], v[146:149], v[170:173], v[58:61]
	v_mfma_f32_16x16x32_bf16 v[54:57], v[138:141], v[178:181], v[54:57]
	v_mfma_f32_16x16x32_bf16 v[50:53], v[146:149], v[178:181], v[50:53]
	v_mfma_f32_16x16x32_bf16 v[46:49], v[138:141], v[186:189], v[46:49]
	v_mfma_f32_16x16x32_bf16 v[42:45], v[146:149], v[186:189], v[42:45]
	v_mfma_f32_16x16x32_bf16 v[38:41], v[138:141], v[202:205], v[38:41]
	v_mfma_f32_16x16x32_bf16 v[34:37], v[146:149], v[202:205], v[34:37]
	v_mfma_f32_16x16x32_bf16 v[62:65], v[142:145], v[174:177], v[62:65]
	v_mfma_f32_16x16x32_bf16 v[58:61], v[150:153], v[174:177], v[58:61]
	v_mfma_f32_16x16x32_bf16 v[54:57], v[142:145], v[182:185], v[54:57]
	v_mfma_f32_16x16x32_bf16 v[50:53], v[150:153], v[182:185], v[50:53]
	v_mfma_f32_16x16x32_bf16 v[46:49], v[142:145], v[190:193], v[46:49]
	v_mfma_f32_16x16x32_bf16 v[42:45], v[150:153], v[190:193], v[42:45]
	v_mfma_f32_16x16x32_bf16 v[38:41], v[142:145], v[206:209], v[38:41]
	v_mfma_f32_16x16x32_bf16 v[34:37], v[150:153], v[206:209], v[34:37]
	v_mfma_f32_16x16x32_bf16 v[30:33], v[154:157], v[170:173], v[30:33]
	v_mfma_f32_16x16x32_bf16 v[26:29], v[162:165], v[170:173], v[26:29]
	v_mfma_f32_16x16x32_bf16 v[22:25], v[154:157], v[178:181], v[22:25]
	v_mfma_f32_16x16x32_bf16 v[18:21], v[162:165], v[178:181], v[18:21]
	v_mfma_f32_16x16x32_bf16 v[14:17], v[154:157], v[186:189], v[14:17]
	v_mfma_f32_16x16x32_bf16 v[10:13], v[162:165], v[186:189], v[10:13]
	v_mfma_f32_16x16x32_bf16 v[6:9], v[154:157], v[202:205], v[6:9]
	v_mfma_f32_16x16x32_bf16 v[2:5], v[162:165], v[202:205], v[2:5]
	v_mfma_f32_16x16x32_bf16 v[30:33], v[158:161], v[174:177], v[30:33]
	v_mfma_f32_16x16x32_bf16 v[26:29], v[166:169], v[174:177], v[26:29]
	v_mfma_f32_16x16x32_bf16 v[22:25], v[158:161], v[182:185], v[22:25]
	v_mfma_f32_16x16x32_bf16 v[18:21], v[166:169], v[182:185], v[18:21]
	v_mfma_f32_16x16x32_bf16 v[14:17], v[158:161], v[190:193], v[14:17]
	v_mfma_f32_16x16x32_bf16 v[10:13], v[166:169], v[190:193], v[10:13]
	v_mfma_f32_16x16x32_bf16 v[6:9], v[158:161], v[206:209], v[6:9]
	v_mfma_f32_16x16x32_bf16 v[2:5], v[166:169], v[206:209], v[2:5]
	s_setprio 0
	s_barrier
	v_add_u32_e32 v150, s56, v219
	v_add_u32_e32 v166, s57, v219
	ds_read_b128 v[138:141], v150
	ds_read_b128 v[142:145], v150 offset:1024
	ds_read_b128 v[146:149], v150 offset:2048
	ds_read_b128 v[150:153], v150 offset:3072
	ds_read_b128 v[154:157], v166
	ds_read_b128 v[158:161], v166 offset:1024
	ds_read_b128 v[162:165], v166 offset:2048
	ds_read_b128 v[166:169], v166 offset:3072
	s_mov_b32 m0, s29
	v_lshl_add_u64 v[222:223], v[210:211], 0, s[22:23]
	ds_read_b128 v[170:173], v217 offset:32768
	ds_read_b128 v[174:177], v217 offset:33792
	ds_read_b128 v[178:181], v217 offset:34816
	ds_read_b128 v[182:185], v217 offset:35840
	ds_read_b128 v[186:189], v217 offset:36864
	ds_read_b128 v[190:193], v217 offset:37888
	ds_read_b128 v[202:205], v217 offset:38912
	ds_read_b128 v[206:209], v217 offset:39936
	global_load_lds_dwordx4 v[222:223], off
	v_lshl_add_u64 v[222:223], v[212:213], 0, s[22:23]
	s_mov_b32 m0, s33
	v_lshl_add_u64 v[210:211], v[210:211], 0, s[30:31]
	global_load_lds_dwordx4 v[222:223], off
	s_mov_b32 m0, s36
	s_nop 0
	global_load_lds_dwordx4 v[210:211], off
	v_lshl_add_u64 v[210:211], v[212:213], 0, s[30:31]
	s_mov_b32 m0, s37
	s_nop 0
	global_load_lds_dwordx4 v[210:211], off
	s_waitcnt vmcnt(8)
	s_waitcnt lgkmcnt(0)
	s_barrier
	s_setprio 1
	v_mfma_f32_16x16x32_bf16 v[126:129], v[138:141], v[170:173], v[126:129]
	v_mfma_f32_16x16x32_bf16 v[122:125], v[146:149], v[170:173], v[122:125]
	v_mfma_f32_16x16x32_bf16 v[118:121], v[138:141], v[178:181], v[118:121]
	v_mfma_f32_16x16x32_bf16 v[114:117], v[146:149], v[178:181], v[114:117]
	v_mfma_f32_16x16x32_bf16 v[110:113], v[138:141], v[186:189], v[110:113]
	v_mfma_f32_16x16x32_bf16 v[106:109], v[146:149], v[186:189], v[106:109]
	v_mfma_f32_16x16x32_bf16 v[102:105], v[138:141], v[202:205], v[102:105]
	v_mfma_f32_16x16x32_bf16 v[98:101], v[146:149], v[202:205], v[98:101]
	v_mfma_f32_16x16x32_bf16 v[126:129], v[142:145], v[174:177], v[126:129]
	v_mfma_f32_16x16x32_bf16 v[122:125], v[150:153], v[174:177], v[122:125]
	v_mfma_f32_16x16x32_bf16 v[118:121], v[142:145], v[182:185], v[118:121]
	v_mfma_f32_16x16x32_bf16 v[114:117], v[150:153], v[182:185], v[114:117]
	v_mfma_f32_16x16x32_bf16 v[110:113], v[142:145], v[190:193], v[110:113]
	v_mfma_f32_16x16x32_bf16 v[106:109], v[150:153], v[190:193], v[106:109]
	v_mfma_f32_16x16x32_bf16 v[102:105], v[142:145], v[206:209], v[102:105]
	v_mfma_f32_16x16x32_bf16 v[98:101], v[150:153], v[206:209], v[98:101]
	v_mfma_f32_16x16x32_bf16 v[94:97], v[154:157], v[170:173], v[94:97]
	v_mfma_f32_16x16x32_bf16 v[90:93], v[162:165], v[170:173], v[90:93]
	v_mfma_f32_16x16x32_bf16 v[86:89], v[154:157], v[178:181], v[86:89]
	v_mfma_f32_16x16x32_bf16 v[82:85], v[162:165], v[178:181], v[82:85]
	v_mfma_f32_16x16x32_bf16 v[78:81], v[154:157], v[186:189], v[78:81]
	v_mfma_f32_16x16x32_bf16 v[74:77], v[162:165], v[186:189], v[74:77]
	v_mfma_f32_16x16x32_bf16 v[70:73], v[154:157], v[202:205], v[70:73]
	v_mfma_f32_16x16x32_bf16 v[66:69], v[162:165], v[202:205], v[66:69]
	v_mfma_f32_16x16x32_bf16 v[94:97], v[158:161], v[174:177], v[94:97]
	v_mfma_f32_16x16x32_bf16 v[90:93], v[166:169], v[174:177], v[90:93]
	v_mfma_f32_16x16x32_bf16 v[86:89], v[158:161], v[182:185], v[86:89]
	v_mfma_f32_16x16x32_bf16 v[82:85], v[166:169], v[182:185], v[82:85]
	v_mfma_f32_16x16x32_bf16 v[78:81], v[158:161], v[190:193], v[78:81]
	v_mfma_f32_16x16x32_bf16 v[74:77], v[166:169], v[190:193], v[74:77]
	v_mfma_f32_16x16x32_bf16 v[70:73], v[158:161], v[206:209], v[70:73]
	v_mfma_f32_16x16x32_bf16 v[66:69], v[166:169], v[206:209], v[66:69]
	s_setprio 0
	s_barrier
	s_mov_b32 m0, s58
	v_lshl_add_u64 v[210:211], v[214:215], 0, s[34:35]
	ds_read_b128 v[170:173], v217 offset:49152
	ds_read_b128 v[174:177], v217 offset:50176
	ds_read_b128 v[178:181], v217 offset:51200
	ds_read_b128 v[182:185], v217 offset:52224
	ds_read_b128 v[186:189], v217 offset:53248
	ds_read_b128 v[190:193], v217 offset:54272
	ds_read_b128 v[202:205], v217 offset:55296
	ds_read_b128 v[206:209], v217 offset:56320
	global_load_lds_dwordx4 v[210:211], off
	v_lshl_add_u64 v[210:211], v[220:221], 0, s[34:35]
	s_mov_b32 m0, s59
	s_nop 0
	global_load_lds_dwordx4 v[210:211], off
	v_lshl_add_u64 v[210:211], v[214:215], 0, s[40:41]
	s_mov_b32 m0, s38
	s_nop 0
	global_load_lds_dwordx4 v[210:211], off
	v_lshl_add_u64 v[210:211], v[220:221], 0, s[40:41]
	s_mov_b32 m0, s60
	s_nop 0
	global_load_lds_dwordx4 v[210:211], off
	s_waitcnt vmcnt(4)
	s_waitcnt lgkmcnt(0)
	s_barrier
	s_setprio 1
	v_mfma_f32_16x16x32_bf16 v[62:65], v[138:141], v[170:173], v[62:65]
	v_mfma_f32_16x16x32_bf16 v[58:61], v[146:149], v[170:173], v[58:61]
	v_mfma_f32_16x16x32_bf16 v[54:57], v[138:141], v[178:181], v[54:57]
	v_mfma_f32_16x16x32_bf16 v[50:53], v[146:149], v[178:181], v[50:53]
	v_mfma_f32_16x16x32_bf16 v[46:49], v[138:141], v[186:189], v[46:49]
	v_mfma_f32_16x16x32_bf16 v[42:45], v[146:149], v[186:189], v[42:45]
	v_mfma_f32_16x16x32_bf16 v[38:41], v[138:141], v[202:205], v[38:41]
	v_mfma_f32_16x16x32_bf16 v[34:37], v[146:149], v[202:205], v[34:37]
	v_mfma_f32_16x16x32_bf16 v[62:65], v[142:145], v[174:177], v[62:65]
	v_mfma_f32_16x16x32_bf16 v[58:61], v[150:153], v[174:177], v[58:61]
	v_mfma_f32_16x16x32_bf16 v[54:57], v[142:145], v[182:185], v[54:57]
	v_mfma_f32_16x16x32_bf16 v[50:53], v[150:153], v[182:185], v[50:53]
	v_mfma_f32_16x16x32_bf16 v[46:49], v[142:145], v[190:193], v[46:49]
	v_mfma_f32_16x16x32_bf16 v[42:45], v[150:153], v[190:193], v[42:45]
	v_mfma_f32_16x16x32_bf16 v[38:41], v[142:145], v[206:209], v[38:41]
	v_mfma_f32_16x16x32_bf16 v[34:37], v[150:153], v[206:209], v[34:37]
	v_mfma_f32_16x16x32_bf16 v[30:33], v[154:157], v[170:173], v[30:33]
	v_mfma_f32_16x16x32_bf16 v[26:29], v[162:165], v[170:173], v[26:29]
	v_mfma_f32_16x16x32_bf16 v[22:25], v[154:157], v[178:181], v[22:25]
	v_mfma_f32_16x16x32_bf16 v[18:21], v[162:165], v[178:181], v[18:21]
	v_mfma_f32_16x16x32_bf16 v[14:17], v[154:157], v[186:189], v[14:17]
	v_mfma_f32_16x16x32_bf16 v[10:13], v[162:165], v[186:189], v[10:13]
	v_mfma_f32_16x16x32_bf16 v[6:9], v[154:157], v[202:205], v[6:9]
	v_mfma_f32_16x16x32_bf16 v[2:5], v[162:165], v[202:205], v[2:5]
	v_mfma_f32_16x16x32_bf16 v[30:33], v[158:161], v[174:177], v[30:33]
	v_mfma_f32_16x16x32_bf16 v[26:29], v[166:169], v[174:177], v[26:29]
	v_mfma_f32_16x16x32_bf16 v[22:25], v[158:161], v[182:185], v[22:25]
	v_mfma_f32_16x16x32_bf16 v[18:21], v[166:169], v[182:185], v[18:21]
	v_mfma_f32_16x16x32_bf16 v[14:17], v[158:161], v[190:193], v[14:17]
	v_mfma_f32_16x16x32_bf16 v[10:13], v[166:169], v[190:193], v[10:13]
	v_mfma_f32_16x16x32_bf16 v[6:9], v[158:161], v[206:209], v[6:9]
	v_mfma_f32_16x16x32_bf16 v[2:5], v[166:169], v[206:209], v[2:5]
	s_setprio 0
	s_barrier
	s_add_i32 s45, s45, 2
	s_add_u32 s4, s4, 0x100
	s_addc_u32 s5, s5, 0
	s_cmp_gt_u32 s45, 27
	s_cbranch_scc0 .LBB0_599
	v_add_u32_e32 v142, 0x10000, v218
	v_add_u32_e32 v158, 0x14000, v218
	ds_read_b128 v[130:133], v142
	ds_read_b128 v[134:137], v142 offset:1024
	ds_read_b128 v[138:141], v142 offset:2048
	ds_read_b128 v[142:145], v142 offset:3072
	ds_read_b128 v[146:149], v158
	ds_read_b128 v[150:153], v158 offset:1024
	ds_read_b128 v[154:157], v158 offset:2048
	ds_read_b128 v[158:161], v158 offset:3072
	s_mov_b64 s[4:5], 0xf80
	s_mov_b32 m0, s44
	v_lshl_add_u64 v[200:201], v[200:201], 0, s[4:5]
	v_lshl_add_u64 v[198:199], v[198:199], 0, s[4:5]
	s_add_u32 s4, s14, 0x80f80
	ds_read_b128 v[162:165], v217
	ds_read_b128 v[166:169], v217 offset:1024
	ds_read_b128 v[170:173], v217 offset:2048
	ds_read_b128 v[174:177], v217 offset:3072
	ds_read_b128 v[178:181], v217 offset:4096
	ds_read_b128 v[182:185], v217 offset:5120
	ds_read_b128 v[186:189], v217 offset:6144
	ds_read_b128 v[190:193], v217 offset:7168
	global_load_lds_dwordx4 v[200:201], off
	s_mov_b32 m0, s43
	s_addc_u32 s5, s15, 0
	global_load_lds_dwordx4 v[198:199], off
	v_lshl_add_u64 v[194:195], s[4:5], 0, v[194:195]
	s_mov_b32 m0, s42
	s_nop 0
	global_load_lds_dwordx4 v[194:195], off
	v_lshl_add_u64 v[194:195], s[4:5], 0, v[196:197]
	s_mov_b32 m0, s39
	s_nop 0
	global_load_lds_dwordx4 v[194:195], off
	s_waitcnt vmcnt(8)
	s_waitcnt lgkmcnt(0)
	s_barrier
	s_setprio 1
	v_mfma_f32_16x16x32_bf16 v[126:129], v[130:133], v[162:165], v[126:129]
	v_mfma_f32_16x16x32_bf16 v[122:125], v[138:141], v[162:165], v[122:125]
	v_mfma_f32_16x16x32_bf16 v[118:121], v[130:133], v[170:173], v[118:121]
	v_mfma_f32_16x16x32_bf16 v[114:117], v[138:141], v[170:173], v[114:117]
	v_mfma_f32_16x16x32_bf16 v[102:105], v[130:133], v[186:189], v[102:105]
	v_mfma_f32_16x16x32_bf16 v[98:101], v[138:141], v[186:189], v[98:101]
	v_mfma_f32_16x16x32_bf16 v[126:129], v[134:137], v[166:169], v[126:129]
	v_mfma_f32_16x16x32_bf16 v[122:125], v[142:145], v[166:169], v[122:125]
	v_mfma_f32_16x16x32_bf16 v[118:121], v[134:137], v[174:177], v[118:121]
	v_mfma_f32_16x16x32_bf16 v[114:117], v[142:145], v[174:177], v[114:117]
	v_mfma_f32_16x16x32_bf16 v[110:113], v[130:133], v[178:181], v[110:113]
	v_mfma_f32_16x16x32_bf16 v[106:109], v[138:141], v[178:181], v[106:109]
	v_mfma_f32_16x16x32_bf16 v[102:105], v[134:137], v[190:193], v[102:105]
	v_mfma_f32_16x16x32_bf16 v[98:101], v[142:145], v[190:193], v[98:101]
	v_mfma_f32_16x16x32_bf16 v[194:197], v[134:137], v[182:185], v[110:113]
	v_mfma_f32_16x16x32_bf16 v[198:201], v[142:145], v[182:185], v[106:109]
	v_mfma_f32_16x16x32_bf16 v[86:89], v[146:149], v[170:173], v[86:89]
	v_mfma_f32_16x16x32_bf16 v[82:85], v[154:157], v[170:173], v[82:85]
	v_mfma_f32_16x16x32_bf16 v[70:73], v[146:149], v[186:189], v[70:73]
	v_mfma_f32_16x16x32_bf16 v[66:69], v[154:157], v[186:189], v[66:69]
	v_mfma_f32_16x16x32_bf16 v[94:97], v[146:149], v[162:165], v[94:97]
	v_mfma_f32_16x16x32_bf16 v[90:93], v[154:157], v[162:165], v[90:93]
	v_mfma_f32_16x16x32_bf16 v[86:89], v[150:153], v[174:177], v[86:89]
	v_mfma_f32_16x16x32_bf16 v[82:85], v[158:161], v[174:177], v[82:85]
	v_mfma_f32_16x16x32_bf16 v[78:81], v[146:149], v[178:181], v[78:81]
	v_mfma_f32_16x16x32_bf16 v[74:77], v[154:157], v[178:181], v[74:77]
	v_mfma_f32_16x16x32_bf16 v[70:73], v[150:153], v[190:193], v[70:73]
	v_mfma_f32_16x16x32_bf16 v[66:69], v[158:161], v[190:193], v[66:69]
	v_mfma_f32_16x16x32_bf16 v[202:205], v[150:153], v[166:169], v[94:97]
	v_mfma_f32_16x16x32_bf16 v[162:165], v[158:161], v[166:169], v[90:93]
	v_mfma_f32_16x16x32_bf16 v[166:169], v[150:153], v[182:185], v[78:81]
	v_mfma_f32_16x16x32_bf16 v[170:173], v[158:161], v[182:185], v[74:77]
	s_setprio 0
	s_barrier
	s_nop 0
	ds_read_b128 v[74:77], v217 offset:16384
	ds_read_b128 v[78:81], v217 offset:17408
	ds_read_b128 v[90:93], v217 offset:18432
	ds_read_b128 v[94:97], v217 offset:19456
	ds_read_b128 v[106:109], v217 offset:20480
	ds_read_b128 v[110:113], v217 offset:21504
	ds_read_b128 v[174:177], v217 offset:22528
	ds_read_b128 v[178:181], v217 offset:23552
	s_waitcnt vmcnt(0)
	s_waitcnt lgkmcnt(0)
	s_barrier
	s_setprio 1
	v_mfma_f32_16x16x32_bf16 v[62:65], v[130:133], v[74:77], v[62:65]
	v_mfma_f32_16x16x32_bf16 v[58:61], v[138:141], v[74:77], v[58:61]
	v_mfma_f32_16x16x32_bf16 v[54:57], v[130:133], v[90:93], v[54:57]
	v_mfma_f32_16x16x32_bf16 v[50:53], v[138:141], v[90:93], v[50:53]
	v_mfma_f32_16x16x32_bf16 v[38:41], v[130:133], v[174:177], v[38:41]
	v_mfma_f32_16x16x32_bf16 v[34:37], v[138:141], v[174:177], v[34:37]
	v_mfma_f32_16x16x32_bf16 v[62:65], v[134:137], v[78:81], v[62:65]
	v_mfma_f32_16x16x32_bf16 v[58:61], v[142:145], v[78:81], v[58:61]
	v_mfma_f32_16x16x32_bf16 v[54:57], v[134:137], v[94:97], v[54:57]
	v_mfma_f32_16x16x32_bf16 v[50:53], v[142:145], v[94:97], v[50:53]
	v_mfma_f32_16x16x32_bf16 v[46:49], v[130:133], v[106:109], v[46:49]
	v_mfma_f32_16x16x32_bf16 v[42:45], v[138:141], v[106:109], v[42:45]
	v_mfma_f32_16x16x32_bf16 v[38:41], v[134:137], v[178:181], v[38:41]
	v_mfma_f32_16x16x32_bf16 v[34:37], v[142:145], v[178:181], v[34:37]
	v_mfma_f32_16x16x32_bf16 v[182:185], v[134:137], v[110:113], v[46:49]
	v_mfma_f32_16x16x32_bf16 v[186:189], v[142:145], v[110:113], v[42:45]
	v_mfma_f32_16x16x32_bf16 v[22:25], v[146:149], v[90:93], v[22:25]
	v_mfma_f32_16x16x32_bf16 v[18:21], v[154:157], v[90:93], v[18:21]
	v_mfma_f32_16x16x32_bf16 v[6:9], v[146:149], v[174:177], v[6:9]
	v_mfma_f32_16x16x32_bf16 v[2:5], v[154:157], v[174:177], v[2:5]
	v_mfma_f32_16x16x32_bf16 v[30:33], v[146:149], v[74:77], v[30:33]
	v_mfma_f32_16x16x32_bf16 v[26:29], v[154:157], v[74:77], v[26:29]
	v_mfma_f32_16x16x32_bf16 v[22:25], v[150:153], v[94:97], v[22:25]
	v_mfma_f32_16x16x32_bf16 v[18:21], v[158:161], v[94:97], v[18:21]
	v_mfma_f32_16x16x32_bf16 v[14:17], v[146:149], v[106:109], v[14:17]
	v_mfma_f32_16x16x32_bf16 v[10:13], v[154:157], v[106:109], v[10:13]
	v_mfma_f32_16x16x32_bf16 v[6:9], v[150:153], v[178:181], v[6:9]
	v_mfma_f32_16x16x32_bf16 v[2:5], v[158:161], v[178:181], v[2:5]
	v_mfma_f32_16x16x32_bf16 v[130:133], v[150:153], v[78:81], v[30:33]
	v_mfma_f32_16x16x32_bf16 v[134:137], v[158:161], v[78:81], v[26:29]
	v_mfma_f32_16x16x32_bf16 v[138:141], v[150:153], v[110:113], v[14:17]
	v_mfma_f32_16x16x32_bf16 v[142:145], v[158:161], v[110:113], v[10:13]
	s_setprio 0
	s_barrier
	v_add_u32_e32 v26, 0x18000, v218
	ds_read_b128 v[10:13], v26
	ds_read_b128 v[14:17], v26 offset:1024
	ds_read_b128 v[146:149], v26 offset:2048
	ds_read_b128 v[150:153], v26 offset:3072
	v_add_u32_e32 v26, 0x1c000, v218
	ds_read_b128 v[154:157], v26
	ds_read_b128 v[158:161], v26 offset:1024
	ds_read_b128 v[174:177], v26 offset:2048
	ds_read_b128 v[178:181], v26 offset:3072
	ds_read_b128 v[26:29], v217 offset:32768
	ds_read_b128 v[30:33], v217 offset:33792
	ds_read_b128 v[42:45], v217 offset:34816
	ds_read_b128 v[46:49], v217 offset:35840
	ds_read_b128 v[190:193], v217 offset:36864
	ds_read_b128 v[206:209], v217 offset:37888
	ds_read_b128 v[210:213], v217 offset:38912
	ds_read_b128 v[218:221], v217 offset:39936
	s_waitcnt lgkmcnt(0)
	s_barrier
	s_setprio 1
	v_mfma_f32_16x16x32_bf16 v[74:77], v[10:13], v[26:29], v[126:129]
	v_mfma_f32_16x16x32_bf16 v[126:129], v[14:17], v[30:33], v[74:77]
	v_mfma_f32_16x16x32_bf16 v[74:77], v[146:149], v[26:29], v[122:125]
	v_mfma_f32_16x16x32_bf16 v[122:125], v[150:153], v[30:33], v[74:77]
	v_mfma_f32_16x16x32_bf16 v[74:77], v[10:13], v[42:45], v[118:121]
	v_mfma_f32_16x16x32_bf16 v[110:113], v[14:17], v[46:49], v[74:77]
	v_mfma_f32_16x16x32_bf16 v[74:77], v[146:149], v[42:45], v[114:117]
	v_mfma_f32_16x16x32_bf16 v[106:109], v[150:153], v[46:49], v[74:77]
	v_mfma_f32_16x16x32_bf16 v[74:77], v[10:13], v[190:193], v[194:197]
	v_mfma_f32_16x16x32_bf16 v[94:97], v[14:17], v[206:209], v[74:77]
	v_mfma_f32_16x16x32_bf16 v[74:77], v[146:149], v[190:193], v[198:201]
	v_mfma_f32_16x16x32_bf16 v[90:93], v[150:153], v[206:209], v[74:77]
	v_mfma_f32_16x16x32_bf16 v[74:77], v[10:13], v[210:213], v[102:105]
	v_mfma_f32_16x16x32_bf16 v[78:81], v[14:17], v[218:221], v[74:77]
	v_mfma_f32_16x16x32_bf16 v[74:77], v[146:149], v[210:213], v[98:101]
	v_mfma_f32_16x16x32_bf16 v[74:77], v[150:153], v[218:221], v[74:77]
	v_mfma_f32_16x16x32_bf16 v[98:101], v[154:157], v[26:29], v[202:205]
	v_mfma_f32_16x16x32_bf16 v[26:29], v[174:177], v[26:29], v[162:165]
	v_mfma_f32_16x16x32_bf16 v[114:117], v[178:181], v[30:33], v[26:29]
	v_mfma_f32_16x16x32_bf16 v[26:29], v[154:157], v[42:45], v[86:89]
	v_mfma_f32_16x16x32_bf16 v[102:105], v[158:161], v[46:49], v[26:29]
	v_mfma_f32_16x16x32_bf16 v[26:29], v[174:177], v[42:45], v[82:85]
	v_mfma_f32_16x16x32_bf16 v[118:121], v[158:161], v[30:33], v[98:101]
	v_mfma_f32_16x16x32_bf16 v[98:101], v[178:181], v[46:49], v[26:29]
	v_mfma_f32_16x16x32_bf16 v[26:29], v[154:157], v[190:193], v[166:169]
	v_mfma_f32_16x16x32_bf16 v[86:89], v[158:161], v[206:209], v[26:29]
	v_mfma_f32_16x16x32_bf16 v[26:29], v[174:177], v[190:193], v[170:173]
	v_mfma_f32_16x16x32_bf16 v[82:85], v[178:181], v[206:209], v[26:29]
	v_mfma_f32_16x16x32_bf16 v[26:29], v[154:157], v[210:213], v[70:73]
	v_mfma_f32_16x16x32_bf16 v[70:73], v[158:161], v[218:221], v[26:29]
	v_mfma_f32_16x16x32_bf16 v[26:29], v[174:177], v[210:213], v[66:69]
	v_mfma_f32_16x16x32_bf16 v[66:69], v[178:181], v[218:221], v[26:29]
	s_setprio 0
	s_barrier
	ds_read_b128 v[162:165], v217 offset:49152
	ds_read_b128 v[166:169], v217 offset:50176
	ds_read_b128 v[170:173], v217 offset:51200
	ds_read_b128 v[190:193], v217 offset:52224
	ds_read_b128 v[194:197], v217 offset:53248
	ds_read_b128 v[198:201], v217 offset:54272
	ds_read_b128 v[202:205], v217 offset:55296
	ds_read_b128 v[206:209], v217 offset:56320
	s_waitcnt lgkmcnt(0)
	s_barrier
	s_setprio 1
	v_mfma_f32_16x16x32_bf16 v[26:29], v[10:13], v[162:165], v[62:65]
	v_mfma_f32_16x16x32_bf16 v[62:65], v[14:17], v[166:169], v[26:29]
	v_mfma_f32_16x16x32_bf16 v[26:29], v[146:149], v[162:165], v[58:61]
	v_mfma_f32_16x16x32_bf16 v[58:61], v[150:153], v[166:169], v[26:29]
	v_mfma_f32_16x16x32_bf16 v[26:29], v[10:13], v[170:173], v[54:57]
	v_mfma_f32_16x16x32_bf16 v[46:49], v[14:17], v[190:193], v[26:29]
	v_mfma_f32_16x16x32_bf16 v[26:29], v[146:149], v[170:173], v[50:53]
	v_mfma_f32_16x16x32_bf16 v[42:45], v[150:153], v[190:193], v[26:29]
	v_mfma_f32_16x16x32_bf16 v[26:29], v[10:13], v[194:197], v[182:185]
	v_mfma_f32_16x16x32_bf16 v[10:13], v[10:13], v[202:205], v[38:41]
	v_mfma_f32_16x16x32_bf16 v[30:33], v[14:17], v[198:201], v[26:29]
	v_mfma_f32_16x16x32_bf16 v[26:29], v[146:149], v[194:197], v[186:189]
	v_mfma_f32_16x16x32_bf16 v[14:17], v[14:17], v[206:209], v[10:13]
	v_mfma_f32_16x16x32_bf16 v[10:13], v[146:149], v[202:205], v[34:37]
	v_mfma_f32_16x16x32_bf16 v[26:29], v[150:153], v[198:201], v[26:29]
	v_mfma_f32_16x16x32_bf16 v[10:13], v[150:153], v[206:209], v[10:13]
	v_mfma_f32_16x16x32_bf16 v[34:37], v[154:157], v[162:165], v[130:133]
	v_mfma_f32_16x16x32_bf16 v[54:57], v[158:161], v[166:169], v[34:37]
	v_mfma_f32_16x16x32_bf16 v[34:37], v[174:177], v[162:165], v[134:137]
	v_mfma_f32_16x16x32_bf16 v[18:21], v[174:177], v[170:173], v[18:21]
	v_mfma_f32_16x16x32_bf16 v[50:53], v[178:181], v[166:169], v[34:37]
	v_mfma_f32_16x16x32_bf16 v[22:25], v[154:157], v[170:173], v[22:25]
	v_mfma_f32_16x16x32_bf16 v[34:37], v[178:181], v[190:193], v[18:21]
	v_mfma_f32_16x16x32_bf16 v[18:21], v[154:157], v[194:197], v[138:141]
	v_mfma_f32_16x16x32_bf16 v[38:41], v[158:161], v[190:193], v[22:25]
	v_mfma_f32_16x16x32_bf16 v[22:25], v[158:161], v[198:201], v[18:21]
	v_mfma_f32_16x16x32_bf16 v[18:21], v[174:177], v[194:197], v[142:145]
	v_mfma_f32_16x16x32_bf16 v[6:9], v[154:157], v[202:205], v[6:9]
	v_mfma_f32_16x16x32_bf16 v[2:5], v[174:177], v[202:205], v[2:5]
	v_mfma_f32_16x16x32_bf16 v[18:21], v[178:181], v[198:201], v[18:21]
	v_mfma_f32_16x16x32_bf16 v[6:9], v[158:161], v[206:209], v[6:9]
	v_mfma_f32_16x16x32_bf16 v[2:5], v[178:181], v[206:209], v[2:5]
	s_setprio 0
	s_barrier

.LBB0_641:
	ds_read_b128 v[150:153], v145
	ds_read_b128 v[154:157], v145 offset:1024
	ds_read_b128 v[158:161], v145 offset:2048
	s_waitcnt lgkmcnt(0)
	ds_read_b128 v[162:165], v145 offset:3072
	ds_read_b128 v[166:169], v146
	ds_read_b128 v[170:173], v146 offset:1024
	ds_read_b128 v[174:177], v146 offset:2048
	ds_read_b128 v[178:181], v146 offset:3072
	v_lshl_add_u64 v[214:215], v[136:137], 0, s[4:5]
	s_mov_b32 m0, s40
	v_lshl_add_u64 v[216:217], v[214:215], 0, s[6:7]
	ds_read_b128 v[182:185], v143
	ds_read_b128 v[186:189], v143 offset:1024
	ds_read_b128 v[190:193], v143 offset:2048
	ds_read_b128 v[194:197], v143 offset:3072
	ds_read_b128 v[198:201], v143 offset:4096
	ds_read_b128 v[202:205], v143 offset:5120
	ds_read_b128 v[206:209], v143 offset:6144
	ds_read_b128 v[210:213], v143 offset:7168
	global_load_lds_dwordx4 v[216:217], off
	v_lshl_add_u64 v[216:217], v[134:135], 0, s[4:5]
	v_lshl_add_u64 v[218:219], v[216:217], 0, s[6:7]
	s_mov_b32 m0, s39
	s_nop 0
	global_load_lds_dwordx4 v[218:219], off
	v_lshl_add_u64 v[218:219], v[214:215], 0, s[12:13]
	s_mov_b32 m0, s38
	s_nop 0
	global_load_lds_dwordx4 v[218:219], off
	v_lshl_add_u64 v[218:219], v[216:217], 0, s[12:13]
	s_mov_b32 m0, s37
	s_nop 0
	global_load_lds_dwordx4 v[218:219], off
	s_waitcnt vmcnt(8)
	s_waitcnt lgkmcnt(0)
	s_barrier
	s_setprio 1
	v_mfma_f32_16x16x32_bf16 v[126:129], v[150:153], v[182:185], v[126:129]
	v_mfma_f32_16x16x32_bf16 v[122:125], v[158:161], v[182:185], v[122:125]
	v_mfma_f32_16x16x32_bf16 v[118:121], v[150:153], v[190:193], v[118:121]
	v_mfma_f32_16x16x32_bf16 v[114:117], v[158:161], v[190:193], v[114:117]
	v_mfma_f32_16x16x32_bf16 v[110:113], v[150:153], v[198:201], v[110:113]
	v_mfma_f32_16x16x32_bf16 v[106:109], v[158:161], v[198:201], v[106:109]
	v_mfma_f32_16x16x32_bf16 v[102:105], v[150:153], v[206:209], v[102:105]
	v_mfma_f32_16x16x32_bf16 v[98:101], v[158:161], v[206:209], v[98:101]
	v_mfma_f32_16x16x32_bf16 v[126:129], v[154:157], v[186:189], v[126:129]
	v_mfma_f32_16x16x32_bf16 v[122:125], v[162:165], v[186:189], v[122:125]
	v_mfma_f32_16x16x32_bf16 v[118:121], v[154:157], v[194:197], v[118:121]
	v_mfma_f32_16x16x32_bf16 v[114:117], v[162:165], v[194:197], v[114:117]
	v_mfma_f32_16x16x32_bf16 v[110:113], v[154:157], v[202:205], v[110:113]
	v_mfma_f32_16x16x32_bf16 v[106:109], v[162:165], v[202:205], v[106:109]
	v_mfma_f32_16x16x32_bf16 v[102:105], v[154:157], v[210:213], v[102:105]
	v_mfma_f32_16x16x32_bf16 v[98:101], v[162:165], v[210:213], v[98:101]
	v_mfma_f32_16x16x32_bf16 v[94:97], v[166:169], v[182:185], v[94:97]
	v_mfma_f32_16x16x32_bf16 v[90:93], v[174:177], v[182:185], v[90:93]
	v_mfma_f32_16x16x32_bf16 v[86:89], v[166:169], v[190:193], v[86:89]
	v_mfma_f32_16x16x32_bf16 v[82:85], v[174:177], v[190:193], v[82:85]
	v_mfma_f32_16x16x32_bf16 v[78:81], v[166:169], v[198:201], v[78:81]
	v_mfma_f32_16x16x32_bf16 v[74:77], v[174:177], v[198:201], v[74:77]
	v_mfma_f32_16x16x32_bf16 v[70:73], v[166:169], v[206:209], v[70:73]
	v_mfma_f32_16x16x32_bf16 v[66:69], v[174:177], v[206:209], v[66:69]
	v_mfma_f32_16x16x32_bf16 v[94:97], v[170:173], v[186:189], v[94:97]
	v_mfma_f32_16x16x32_bf16 v[90:93], v[178:181], v[186:189], v[90:93]
	v_mfma_f32_16x16x32_bf16 v[86:89], v[170:173], v[194:197], v[86:89]
	v_mfma_f32_16x16x32_bf16 v[82:85], v[178:181], v[194:197], v[82:85]
	v_mfma_f32_16x16x32_bf16 v[78:81], v[170:173], v[202:205], v[78:81]
	v_mfma_f32_16x16x32_bf16 v[74:77], v[178:181], v[202:205], v[74:77]
	v_mfma_f32_16x16x32_bf16 v[70:73], v[170:173], v[210:213], v[70:73]
	v_mfma_f32_16x16x32_bf16 v[66:69], v[178:181], v[210:213], v[66:69]
	s_setprio 0
	s_barrier
	v_lshl_add_u64 v[218:219], v[140:141], 0, s[4:5]
	s_mov_b32 m0, s42
	v_lshl_add_u64 v[220:221], v[218:219], 0, s[14:15]
	ds_read_b128 v[182:185], v143 offset:16384
	ds_read_b128 v[186:189], v143 offset:17408
	ds_read_b128 v[190:193], v143 offset:18432
	ds_read_b128 v[194:197], v143 offset:19456
	ds_read_b128 v[198:201], v143 offset:20480
	ds_read_b128 v[202:205], v143 offset:21504
	ds_read_b128 v[206:209], v143 offset:22528
	ds_read_b128 v[210:213], v143 offset:23552
	global_load_lds_dwordx4 v[220:221], off
	v_lshl_add_u64 v[220:221], v[138:139], 0, s[4:5]
	v_lshl_add_u64 v[222:223], v[220:221], 0, s[14:15]
	s_mov_b32 m0, s43
	s_nop 0
	global_load_lds_dwordx4 v[222:223], off
	v_lshl_add_u64 v[222:223], v[218:219], 0, s[16:17]
	s_mov_b32 m0, s44
	s_nop 0
	global_load_lds_dwordx4 v[222:223], off
	v_lshl_add_u64 v[222:223], v[220:221], 0, s[16:17]
	s_mov_b32 m0, s45
	s_nop 0
	global_load_lds_dwordx4 v[222:223], off
	s_waitcnt vmcnt(4)
	s_waitcnt lgkmcnt(0)
	s_barrier
	s_setprio 1
	v_mfma_f32_16x16x32_bf16 v[62:65], v[150:153], v[182:185], v[62:65]
	v_mfma_f32_16x16x32_bf16 v[58:61], v[158:161], v[182:185], v[58:61]
	v_mfma_f32_16x16x32_bf16 v[54:57], v[150:153], v[190:193], v[54:57]
	v_mfma_f32_16x16x32_bf16 v[50:53], v[158:161], v[190:193], v[50:53]
	v_mfma_f32_16x16x32_bf16 v[46:49], v[150:153], v[198:201], v[46:49]
	v_mfma_f32_16x16x32_bf16 v[42:45], v[158:161], v[198:201], v[42:45]
	v_mfma_f32_16x16x32_bf16 v[38:41], v[150:153], v[206:209], v[38:41]
	v_mfma_f32_16x16x32_bf16 v[34:37], v[158:161], v[206:209], v[34:37]
	v_mfma_f32_16x16x32_bf16 v[62:65], v[154:157], v[186:189], v[62:65]
	v_mfma_f32_16x16x32_bf16 v[58:61], v[162:165], v[186:189], v[58:61]
	v_mfma_f32_16x16x32_bf16 v[54:57], v[154:157], v[194:197], v[54:57]
	v_mfma_f32_16x16x32_bf16 v[50:53], v[162:165], v[194:197], v[50:53]
	v_mfma_f32_16x16x32_bf16 v[46:49], v[154:157], v[202:205], v[46:49]
	v_mfma_f32_16x16x32_bf16 v[42:45], v[162:165], v[202:205], v[42:45]
	v_mfma_f32_16x16x32_bf16 v[38:41], v[154:157], v[210:213], v[38:41]
	v_mfma_f32_16x16x32_bf16 v[34:37], v[162:165], v[210:213], v[34:37]
	v_mfma_f32_16x16x32_bf16 v[30:33], v[166:169], v[182:185], v[30:33]
	v_mfma_f32_16x16x32_bf16 v[26:29], v[174:177], v[182:185], v[26:29]
	v_mfma_f32_16x16x32_bf16 v[22:25], v[166:169], v[190:193], v[22:25]
	v_mfma_f32_16x16x32_bf16 v[18:21], v[174:177], v[190:193], v[18:21]
	v_mfma_f32_16x16x32_bf16 v[14:17], v[166:169], v[198:201], v[14:17]
	v_mfma_f32_16x16x32_bf16 v[10:13], v[174:177], v[198:201], v[10:13]
	v_mfma_f32_16x16x32_bf16 v[6:9], v[166:169], v[206:209], v[6:9]
	v_mfma_f32_16x16x32_bf16 v[2:5], v[174:177], v[206:209], v[2:5]
	v_mfma_f32_16x16x32_bf16 v[30:33], v[170:173], v[186:189], v[30:33]
	v_mfma_f32_16x16x32_bf16 v[26:29], v[178:181], v[186:189], v[26:29]
	v_mfma_f32_16x16x32_bf16 v[22:25], v[170:173], v[194:197], v[22:25]
	v_mfma_f32_16x16x32_bf16 v[18:21], v[178:181], v[194:197], v[18:21]
	v_mfma_f32_16x16x32_bf16 v[14:17], v[170:173], v[202:205], v[14:17]
	v_mfma_f32_16x16x32_bf16 v[10:13], v[178:181], v[202:205], v[10:13]
	v_mfma_f32_16x16x32_bf16 v[6:9], v[170:173], v[210:213], v[6:9]
	v_mfma_f32_16x16x32_bf16 v[2:5], v[178:181], v[210:213], v[2:5]
	s_setprio 0
	s_barrier
	ds_read_b128 v[150:153], v147
	ds_read_b128 v[154:157], v147 offset:1024
	ds_read_b128 v[158:161], v147 offset:2048
	ds_read_b128 v[162:165], v147 offset:3072
	ds_read_b128 v[166:169], v148
	ds_read_b128 v[170:173], v148 offset:1024
	ds_read_b128 v[174:177], v148 offset:2048
	ds_read_b128 v[178:181], v148 offset:3072
	s_mov_b32 m0, s28
	v_lshl_add_u64 v[222:223], v[214:215], 0, s[18:19]
	ds_read_b128 v[182:185], v143 offset:32768
	ds_read_b128 v[186:189], v143 offset:33792
	ds_read_b128 v[190:193], v143 offset:34816
	ds_read_b128 v[194:197], v143 offset:35840
	ds_read_b128 v[198:201], v143 offset:36864
	ds_read_b128 v[202:205], v143 offset:37888
	ds_read_b128 v[206:209], v143 offset:38912
	ds_read_b128 v[210:213], v143 offset:39936
	global_load_lds_dwordx4 v[222:223], off
	v_lshl_add_u64 v[222:223], v[216:217], 0, s[18:19]
	s_mov_b32 m0, s29
	v_lshl_add_u64 v[214:215], v[214:215], 0, s[22:23]
	global_load_lds_dwordx4 v[222:223], off
	s_mov_b32 m0, s33
	s_nop 0
	global_load_lds_dwordx4 v[214:215], off
	v_lshl_add_u64 v[214:215], v[216:217], 0, s[22:23]
	s_mov_b32 m0, s36
	s_nop 0
	global_load_lds_dwordx4 v[214:215], off
	s_waitcnt vmcnt(8)
	s_waitcnt lgkmcnt(0)
	s_barrier
	s_setprio 1
	v_mfma_f32_16x16x32_bf16 v[126:129], v[150:153], v[182:185], v[126:129]
	v_mfma_f32_16x16x32_bf16 v[122:125], v[158:161], v[182:185], v[122:125]
	v_mfma_f32_16x16x32_bf16 v[118:121], v[150:153], v[190:193], v[118:121]
	v_mfma_f32_16x16x32_bf16 v[114:117], v[158:161], v[190:193], v[114:117]
	v_mfma_f32_16x16x32_bf16 v[110:113], v[150:153], v[198:201], v[110:113]
	v_mfma_f32_16x16x32_bf16 v[106:109], v[158:161], v[198:201], v[106:109]
	v_mfma_f32_16x16x32_bf16 v[102:105], v[150:153], v[206:209], v[102:105]
	v_mfma_f32_16x16x32_bf16 v[98:101], v[158:161], v[206:209], v[98:101]
	v_mfma_f32_16x16x32_bf16 v[126:129], v[154:157], v[186:189], v[126:129]
	v_mfma_f32_16x16x32_bf16 v[122:125], v[162:165], v[186:189], v[122:125]
	v_mfma_f32_16x16x32_bf16 v[118:121], v[154:157], v[194:197], v[118:121]
	v_mfma_f32_16x16x32_bf16 v[114:117], v[162:165], v[194:197], v[114:117]
	v_mfma_f32_16x16x32_bf16 v[110:113], v[154:157], v[202:205], v[110:113]
	v_mfma_f32_16x16x32_bf16 v[106:109], v[162:165], v[202:205], v[106:109]
	v_mfma_f32_16x16x32_bf16 v[102:105], v[154:157], v[210:213], v[102:105]
	v_mfma_f32_16x16x32_bf16 v[98:101], v[162:165], v[210:213], v[98:101]
	v_mfma_f32_16x16x32_bf16 v[94:97], v[166:169], v[182:185], v[94:97]
	v_mfma_f32_16x16x32_bf16 v[90:93], v[174:177], v[182:185], v[90:93]
	v_mfma_f32_16x16x32_bf16 v[86:89], v[166:169], v[190:193], v[86:89]
	v_mfma_f32_16x16x32_bf16 v[82:85], v[174:177], v[190:193], v[82:85]
	v_mfma_f32_16x16x32_bf16 v[78:81], v[166:169], v[198:201], v[78:81]
	v_mfma_f32_16x16x32_bf16 v[74:77], v[174:177], v[198:201], v[74:77]
	v_mfma_f32_16x16x32_bf16 v[70:73], v[166:169], v[206:209], v[70:73]
	v_mfma_f32_16x16x32_bf16 v[66:69], v[174:177], v[206:209], v[66:69]
	v_mfma_f32_16x16x32_bf16 v[94:97], v[170:173], v[186:189], v[94:97]
	v_mfma_f32_16x16x32_bf16 v[90:93], v[178:181], v[186:189], v[90:93]
	v_mfma_f32_16x16x32_bf16 v[86:89], v[170:173], v[194:197], v[86:89]
	v_mfma_f32_16x16x32_bf16 v[82:85], v[178:181], v[194:197], v[82:85]
	v_mfma_f32_16x16x32_bf16 v[78:81], v[170:173], v[202:205], v[78:81]
	v_mfma_f32_16x16x32_bf16 v[74:77], v[178:181], v[202:205], v[74:77]
	v_mfma_f32_16x16x32_bf16 v[70:73], v[170:173], v[210:213], v[70:73]
	v_mfma_f32_16x16x32_bf16 v[66:69], v[178:181], v[210:213], v[66:69]
	s_setprio 0
	s_barrier
	s_mov_b32 m0, s46
	v_lshl_add_u64 v[214:215], v[218:219], 0, s[30:31]
	ds_read_b128 v[182:185], v143 offset:49152
	ds_read_b128 v[186:189], v143 offset:50176
	ds_read_b128 v[190:193], v143 offset:51200
	ds_read_b128 v[194:197], v143 offset:52224
	ds_read_b128 v[198:201], v143 offset:53248
	ds_read_b128 v[202:205], v143 offset:54272
	ds_read_b128 v[206:209], v143 offset:55296
	ds_read_b128 v[210:213], v143 offset:56320
	global_load_lds_dwordx4 v[214:215], off
	v_lshl_add_u64 v[214:215], v[220:221], 0, s[30:31]
	s_mov_b32 m0, s47
	s_nop 0
	global_load_lds_dwordx4 v[214:215], off
	v_lshl_add_u64 v[214:215], v[218:219], 0, s[34:35]
	s_mov_b32 m0, s48
	s_nop 0
	global_load_lds_dwordx4 v[214:215], off
	v_lshl_add_u64 v[214:215], v[220:221], 0, s[34:35]
	s_mov_b32 m0, s49
	s_nop 0
	global_load_lds_dwordx4 v[214:215], off
	s_waitcnt vmcnt(4)
	s_waitcnt lgkmcnt(0)
	s_barrier
	s_setprio 1
	v_mfma_f32_16x16x32_bf16 v[62:65], v[150:153], v[182:185], v[62:65]
	v_mfma_f32_16x16x32_bf16 v[58:61], v[158:161], v[182:185], v[58:61]
	v_mfma_f32_16x16x32_bf16 v[54:57], v[150:153], v[190:193], v[54:57]
	v_mfma_f32_16x16x32_bf16 v[50:53], v[158:161], v[190:193], v[50:53]
	v_mfma_f32_16x16x32_bf16 v[46:49], v[150:153], v[198:201], v[46:49]
	v_mfma_f32_16x16x32_bf16 v[42:45], v[158:161], v[198:201], v[42:45]
	v_mfma_f32_16x16x32_bf16 v[38:41], v[150:153], v[206:209], v[38:41]
	v_mfma_f32_16x16x32_bf16 v[34:37], v[158:161], v[206:209], v[34:37]
	v_mfma_f32_16x16x32_bf16 v[62:65], v[154:157], v[186:189], v[62:65]
	v_mfma_f32_16x16x32_bf16 v[58:61], v[162:165], v[186:189], v[58:61]
	v_mfma_f32_16x16x32_bf16 v[54:57], v[154:157], v[194:197], v[54:57]
	v_mfma_f32_16x16x32_bf16 v[50:53], v[162:165], v[194:197], v[50:53]
	v_mfma_f32_16x16x32_bf16 v[46:49], v[154:157], v[202:205], v[46:49]
	v_mfma_f32_16x16x32_bf16 v[42:45], v[162:165], v[202:205], v[42:45]
	v_mfma_f32_16x16x32_bf16 v[38:41], v[154:157], v[210:213], v[38:41]
	v_mfma_f32_16x16x32_bf16 v[34:37], v[162:165], v[210:213], v[34:37]
	v_mfma_f32_16x16x32_bf16 v[30:33], v[166:169], v[182:185], v[30:33]
	v_mfma_f32_16x16x32_bf16 v[26:29], v[174:177], v[182:185], v[26:29]
	v_mfma_f32_16x16x32_bf16 v[22:25], v[166:169], v[190:193], v[22:25]
	v_mfma_f32_16x16x32_bf16 v[18:21], v[174:177], v[190:193], v[18:21]
	v_mfma_f32_16x16x32_bf16 v[14:17], v[166:169], v[198:201], v[14:17]
	v_mfma_f32_16x16x32_bf16 v[10:13], v[174:177], v[198:201], v[10:13]
	v_mfma_f32_16x16x32_bf16 v[6:9], v[166:169], v[206:209], v[6:9]
	v_mfma_f32_16x16x32_bf16 v[2:5], v[174:177], v[206:209], v[2:5]
	v_mfma_f32_16x16x32_bf16 v[30:33], v[170:173], v[186:189], v[30:33]
	v_mfma_f32_16x16x32_bf16 v[26:29], v[178:181], v[186:189], v[26:29]
	v_mfma_f32_16x16x32_bf16 v[22:25], v[170:173], v[194:197], v[22:25]
	v_mfma_f32_16x16x32_bf16 v[18:21], v[178:181], v[194:197], v[18:21]
	v_mfma_f32_16x16x32_bf16 v[14:17], v[170:173], v[202:205], v[14:17]
	v_mfma_f32_16x16x32_bf16 v[10:13], v[178:181], v[202:205], v[10:13]
	v_mfma_f32_16x16x32_bf16 v[6:9], v[170:173], v[210:213], v[6:9]
	v_mfma_f32_16x16x32_bf16 v[2:5], v[178:181], v[210:213], v[2:5]
	s_setprio 0
	s_barrier
	s_add_i32 s41, s41, 2
	s_add_u32 s4, s4, 0x100
	s_addc_u32 s5, s5, 0
	s_cmp_gt_u32 s41, 3
	s_cbranch_scc0 .LBB0_641
	v_add_u32_e32 v212, 0, v144
	v_add_u32_e32 v148, 0x10000, v212
	v_add_u32_e32 v164, 0x14000, v212
	ds_read_b128 v[134:137], v148
	ds_read_b128 v[138:141], v148 offset:1024
	ds_read_b128 v[144:147], v148 offset:2048
	ds_read_b128 v[148:151], v148 offset:3072
	ds_read_b128 v[152:155], v164
	ds_read_b128 v[156:159], v164 offset:1024
	ds_read_b128 v[160:163], v164 offset:2048
	ds_read_b128 v[164:167], v164 offset:3072
	s_add_u32 s4, s8, 0x3200380
	s_addc_u32 s5, s9, 0
	s_add_u32 s6, s8, 0x3220380
	s_addc_u32 s7, s9, 0
	s_cmpk_lt_u32 s21, 0x100
	s_mov_b32 m0, s40
	v_lshl_add_u64 v[200:201], s[4:5], 0, v[130:131]
	ds_read_b128 v[168:171], v143
	ds_read_b128 v[172:175], v143 offset:1024
	ds_read_b128 v[176:179], v143 offset:2048
	ds_read_b128 v[180:183], v143 offset:3072
	ds_read_b128 v[184:187], v143 offset:4096
	ds_read_b128 v[188:191], v143 offset:5120
	ds_read_b128 v[192:195], v143 offset:6144
	ds_read_b128 v[196:199], v143 offset:7168
	global_load_lds_dwordx4 v[200:201], off
	v_lshl_add_u64 v[200:201], s[4:5], 0, v[132:133]
	s_mov_b32 m0, s39
	v_lshl_add_u64 v[130:131], s[6:7], 0, v[130:131]
	global_load_lds_dwordx4 v[200:201], off
	s_mov_b32 m0, s38
	s_nop 0
	global_load_lds_dwordx4 v[130:131], off
	v_lshl_add_u64 v[130:131], s[6:7], 0, v[132:133]
	s_mov_b32 m0, s37
	s_nop 0
	global_load_lds_dwordx4 v[130:131], off
	s_waitcnt vmcnt(8)
	s_waitcnt lgkmcnt(0)
	s_barrier
	s_setprio 1
	v_mfma_f32_16x16x32_bf16 v[126:129], v[134:137], v[168:171], v[126:129]
	v_mfma_f32_16x16x32_bf16 v[118:121], v[134:137], v[176:179], v[118:121]
	v_mfma_f32_16x16x32_bf16 v[110:113], v[134:137], v[184:187], v[110:113]
	v_mfma_f32_16x16x32_bf16 v[102:105], v[134:137], v[192:195], v[102:105]
	v_mfma_f32_16x16x32_bf16 v[126:129], v[138:141], v[172:175], v[126:129]
	v_mfma_f32_16x16x32_bf16 v[122:125], v[144:147], v[168:171], v[122:125]
	v_mfma_f32_16x16x32_bf16 v[118:121], v[138:141], v[180:183], v[118:121]
	v_mfma_f32_16x16x32_bf16 v[114:117], v[144:147], v[176:179], v[114:117]
	v_mfma_f32_16x16x32_bf16 v[110:113], v[138:141], v[188:191], v[110:113]
	v_mfma_f32_16x16x32_bf16 v[106:109], v[144:147], v[184:187], v[106:109]
	v_mfma_f32_16x16x32_bf16 v[102:105], v[138:141], v[196:199], v[102:105]
	v_mfma_f32_16x16x32_bf16 v[98:101], v[144:147], v[192:195], v[98:101]
	v_mfma_f32_16x16x32_bf16 v[130:133], v[148:151], v[172:175], v[122:125]
	v_mfma_f32_16x16x32_bf16 v[200:203], v[148:151], v[180:183], v[114:117]
	v_mfma_f32_16x16x32_bf16 v[204:207], v[148:151], v[188:191], v[106:109]
	v_mfma_f32_16x16x32_bf16 v[208:211], v[148:151], v[196:199], v[98:101]
	v_mfma_f32_16x16x32_bf16 v[94:97], v[152:155], v[168:171], v[94:97]
	v_mfma_f32_16x16x32_bf16 v[86:89], v[152:155], v[176:179], v[86:89]
	v_mfma_f32_16x16x32_bf16 v[78:81], v[152:155], v[184:187], v[78:81]
	v_mfma_f32_16x16x32_bf16 v[70:73], v[152:155], v[192:195], v[70:73]
	v_mfma_f32_16x16x32_bf16 v[66:69], v[160:163], v[192:195], v[66:69]
	v_mfma_f32_16x16x32_bf16 v[94:97], v[156:159], v[172:175], v[94:97]
	v_mfma_f32_16x16x32_bf16 v[90:93], v[160:163], v[168:171], v[90:93]
	v_mfma_f32_16x16x32_bf16 v[86:89], v[156:159], v[180:183], v[86:89]
	v_mfma_f32_16x16x32_bf16 v[82:85], v[160:163], v[176:179], v[82:85]
	v_mfma_f32_16x16x32_bf16 v[78:81], v[156:159], v[188:191], v[78:81]
	v_mfma_f32_16x16x32_bf16 v[74:77], v[160:163], v[184:187], v[74:77]
	v_mfma_f32_16x16x32_bf16 v[70:73], v[156:159], v[196:199], v[70:73]
	v_mfma_f32_16x16x32_bf16 v[66:69], v[164:167], v[196:199], v[66:69]
	v_mfma_f32_16x16x32_bf16 v[168:171], v[164:167], v[172:175], v[90:93]
	v_mfma_f32_16x16x32_bf16 v[172:175], v[164:167], v[180:183], v[82:85]
	v_mfma_f32_16x16x32_bf16 v[176:179], v[164:167], v[188:191], v[74:77]
	s_setprio 0
	s_barrier
	s_nop 0
	ds_read_b128 v[74:77], v143 offset:16384
	ds_read_b128 v[82:85], v143 offset:17408
	ds_read_b128 v[90:93], v143 offset:18432
	ds_read_b128 v[98:101], v143 offset:19456
	ds_read_b128 v[106:109], v143 offset:20480
	ds_read_b128 v[114:117], v143 offset:21504
	ds_read_b128 v[122:125], v143 offset:22528
	ds_read_b128 v[180:183], v143 offset:23552
	s_waitcnt vmcnt(0)
	s_waitcnt lgkmcnt(0)
	s_barrier
	s_setprio 1
	v_mfma_f32_16x16x32_bf16 v[54:57], v[134:137], v[90:93], v[54:57]
	v_mfma_f32_16x16x32_bf16 v[46:49], v[134:137], v[106:109], v[46:49]
	v_mfma_f32_16x16x32_bf16 v[38:41], v[134:137], v[122:125], v[38:41]
	v_mfma_f32_16x16x32_bf16 v[62:65], v[134:137], v[74:77], v[62:65]
	v_mfma_f32_16x16x32_bf16 v[58:61], v[144:147], v[74:77], v[58:61]
	v_mfma_f32_16x16x32_bf16 v[54:57], v[138:141], v[98:101], v[54:57]
	v_mfma_f32_16x16x32_bf16 v[50:53], v[144:147], v[90:93], v[50:53]
	v_mfma_f32_16x16x32_bf16 v[46:49], v[138:141], v[114:117], v[46:49]
	v_mfma_f32_16x16x32_bf16 v[42:45], v[144:147], v[106:109], v[42:45]
	v_mfma_f32_16x16x32_bf16 v[38:41], v[138:141], v[180:183], v[38:41]
	v_mfma_f32_16x16x32_bf16 v[34:37], v[144:147], v[122:125], v[34:37]
	v_mfma_f32_16x16x32_bf16 v[184:187], v[138:141], v[82:85], v[62:65]
	v_mfma_f32_16x16x32_bf16 v[188:191], v[148:151], v[82:85], v[58:61]
	v_mfma_f32_16x16x32_bf16 v[192:195], v[148:151], v[98:101], v[50:53]
	v_mfma_f32_16x16x32_bf16 v[196:199], v[148:151], v[114:117], v[42:45]
	v_mfma_f32_16x16x32_bf16 v[134:137], v[148:151], v[180:183], v[34:37]
	v_mfma_f32_16x16x32_bf16 v[30:33], v[152:155], v[74:77], v[30:33]
	v_mfma_f32_16x16x32_bf16 v[22:25], v[152:155], v[90:93], v[22:25]
	v_mfma_f32_16x16x32_bf16 v[14:17], v[152:155], v[106:109], v[14:17]
	v_mfma_f32_16x16x32_bf16 v[6:9], v[152:155], v[122:125], v[6:9]
	v_mfma_f32_16x16x32_bf16 v[30:33], v[156:159], v[82:85], v[30:33]
	v_mfma_f32_16x16x32_bf16 v[26:29], v[160:163], v[74:77], v[26:29]
	v_mfma_f32_16x16x32_bf16 v[22:25], v[156:159], v[98:101], v[22:25]
	v_mfma_f32_16x16x32_bf16 v[18:21], v[160:163], v[90:93], v[18:21]
	v_mfma_f32_16x16x32_bf16 v[14:17], v[156:159], v[114:117], v[14:17]
	v_mfma_f32_16x16x32_bf16 v[10:13], v[160:163], v[106:109], v[10:13]
	v_mfma_f32_16x16x32_bf16 v[6:9], v[156:159], v[180:183], v[6:9]
	v_mfma_f32_16x16x32_bf16 v[2:5], v[160:163], v[122:125], v[2:5]
	v_mfma_f32_16x16x32_bf16 v[138:141], v[164:167], v[82:85], v[26:29]
	v_mfma_f32_16x16x32_bf16 v[144:147], v[164:167], v[98:101], v[18:21]
	v_mfma_f32_16x16x32_bf16 v[148:151], v[164:167], v[114:117], v[10:13]
	v_mfma_f32_16x16x32_bf16 v[152:155], v[164:167], v[180:183], v[2:5]
	s_setprio 0
	s_barrier
	v_add_u32_e32 v18, 0x18000, v212
	s_nop 0
	ds_read_b128 v[2:5], v18
	ds_read_b128 v[10:13], v18 offset:1024
	ds_read_b128 v[156:159], v18 offset:2048
	ds_read_b128 v[160:163], v18 offset:3072
	v_add_u32_e32 v18, 0x1c000, v212
	ds_read_b128 v[164:167], v18
	ds_read_b128 v[180:183], v18 offset:1024
	ds_read_b128 v[212:215], v18 offset:2048
	ds_read_b128 v[216:219], v18 offset:3072
	ds_read_b128 v[18:21], v143 offset:32768
	ds_read_b128 v[26:29], v143 offset:33792
	ds_read_b128 v[34:37], v143 offset:34816
	ds_read_b128 v[42:45], v143 offset:35840
	ds_read_b128 v[50:53], v143 offset:36864
	ds_read_b128 v[62:65], v143 offset:37888
	ds_read_b128 v[220:223], v143 offset:38912
	ds_read_b128 v[224:227], v143 offset:39936
	s_waitcnt lgkmcnt(0)
	s_barrier
	s_setprio 1
	v_mfma_f32_16x16x32_bf16 v[58:61], v[2:5], v[18:21], v[126:129]
	v_mfma_f32_16x16x32_bf16 v[122:125], v[10:13], v[26:29], v[58:61]
	v_mfma_f32_16x16x32_bf16 v[58:61], v[156:159], v[18:21], v[130:133]
	v_mfma_f32_16x16x32_bf16 v[114:117], v[160:163], v[26:29], v[58:61]
	v_mfma_f32_16x16x32_bf16 v[58:61], v[2:5], v[34:37], v[118:121]
	v_mfma_f32_16x16x32_bf16 v[106:109], v[10:13], v[42:45], v[58:61]
	v_mfma_f32_16x16x32_bf16 v[58:61], v[156:159], v[34:37], v[200:203]
	v_mfma_f32_16x16x32_bf16 v[98:101], v[160:163], v[42:45], v[58:61]
	v_mfma_f32_16x16x32_bf16 v[58:61], v[2:5], v[50:53], v[110:113]
	v_mfma_f32_16x16x32_bf16 v[90:93], v[10:13], v[62:65], v[58:61]
	v_mfma_f32_16x16x32_bf16 v[58:61], v[156:159], v[50:53], v[204:207]
	v_mfma_f32_16x16x32_bf16 v[82:85], v[160:163], v[62:65], v[58:61]
	v_mfma_f32_16x16x32_bf16 v[58:61], v[2:5], v[220:223], v[102:105]
	v_mfma_f32_16x16x32_bf16 v[74:77], v[10:13], v[224:227], v[58:61]
	v_mfma_f32_16x16x32_bf16 v[58:61], v[156:159], v[220:223], v[208:211]
	v_mfma_f32_16x16x32_bf16 v[58:61], v[160:163], v[224:227], v[58:61]
	v_mfma_f32_16x16x32_bf16 v[94:97], v[164:167], v[18:21], v[94:97]
	v_mfma_f32_16x16x32_bf16 v[18:21], v[212:215], v[18:21], v[168:171]
	v_mfma_f32_16x16x32_bf16 v[118:121], v[216:219], v[26:29], v[18:21]
	v_mfma_f32_16x16x32_bf16 v[18:21], v[164:167], v[34:37], v[86:89]
	v_mfma_f32_16x16x32_bf16 v[110:113], v[180:183], v[42:45], v[18:21]
	v_mfma_f32_16x16x32_bf16 v[18:21], v[212:215], v[34:37], v[172:175]
	v_mfma_f32_16x16x32_bf16 v[102:105], v[216:219], v[42:45], v[18:21]
	v_mfma_f32_16x16x32_bf16 v[18:21], v[164:167], v[50:53], v[78:81]
	v_mfma_f32_16x16x32_bf16 v[126:129], v[180:183], v[26:29], v[94:97]
	v_mfma_f32_16x16x32_bf16 v[94:97], v[180:183], v[62:65], v[18:21]
	v_mfma_f32_16x16x32_bf16 v[18:21], v[212:215], v[50:53], v[176:179]
	v_mfma_f32_16x16x32_bf16 v[86:89], v[216:219], v[62:65], v[18:21]
	v_mfma_f32_16x16x32_bf16 v[18:21], v[164:167], v[220:223], v[70:73]
	v_mfma_f32_16x16x32_bf16 v[78:81], v[180:183], v[224:227], v[18:21]
	v_mfma_f32_16x16x32_bf16 v[18:21], v[212:215], v[220:223], v[66:69]
	v_mfma_f32_16x16x32_bf16 v[62:65], v[216:219], v[224:227], v[18:21]
	s_setprio 0
	s_barrier
	ds_read_b128 v[130:133], v143 offset:49152
	ds_read_b128 v[168:171], v143 offset:50176
	ds_read_b128 v[172:175], v143 offset:51200
	ds_read_b128 v[176:179], v143 offset:52224
	ds_read_b128 v[200:203], v143 offset:53248
	ds_read_b128 v[204:207], v143 offset:54272
	ds_read_b128 v[208:211], v143 offset:55296
	ds_read_b128 v[220:223], v143 offset:56320
	s_waitcnt lgkmcnt(0)
	s_barrier
	s_setprio 1
	v_mfma_f32_16x16x32_bf16 v[18:21], v[2:5], v[130:133], v[184:187]
	v_mfma_f32_16x16x32_bf16 v[66:69], v[10:13], v[168:171], v[18:21]
	v_mfma_f32_16x16x32_bf16 v[18:21], v[156:159], v[130:133], v[188:191]
	v_mfma_f32_16x16x32_bf16 v[50:53], v[160:163], v[168:171], v[18:21]
	v_mfma_f32_16x16x32_bf16 v[18:21], v[2:5], v[172:175], v[54:57]
	v_mfma_f32_16x16x32_bf16 v[42:45], v[10:13], v[176:179], v[18:21]
	v_mfma_f32_16x16x32_bf16 v[18:21], v[156:159], v[172:175], v[192:195]
	v_mfma_f32_16x16x32_bf16 v[34:37], v[160:163], v[176:179], v[18:21]
	v_mfma_f32_16x16x32_bf16 v[18:21], v[2:5], v[200:203], v[46:49]
	v_mfma_f32_16x16x32_bf16 v[2:5], v[2:5], v[208:211], v[38:41]
	v_mfma_f32_16x16x32_bf16 v[26:29], v[10:13], v[204:207], v[18:21]
	v_mfma_f32_16x16x32_bf16 v[18:21], v[156:159], v[200:203], v[196:199]
	v_mfma_f32_16x16x32_bf16 v[10:13], v[10:13], v[220:223], v[2:5]
	v_mfma_f32_16x16x32_bf16 v[2:5], v[156:159], v[208:211], v[134:137]
	v_mfma_f32_16x16x32_bf16 v[18:21], v[160:163], v[204:207], v[18:21]
	v_mfma_f32_16x16x32_bf16 v[2:5], v[160:163], v[220:223], v[2:5]
	v_mfma_f32_16x16x32_bf16 v[30:33], v[164:167], v[130:133], v[30:33]
	v_mfma_f32_16x16x32_bf16 v[70:73], v[180:183], v[168:171], v[30:33]
	v_mfma_f32_16x16x32_bf16 v[30:33], v[212:215], v[130:133], v[138:141]
	v_mfma_f32_16x16x32_bf16 v[22:25], v[164:167], v[172:175], v[22:25]
	v_mfma_f32_16x16x32_bf16 v[14:17], v[164:167], v[200:203], v[14:17]
	v_mfma_f32_16x16x32_bf16 v[54:57], v[216:219], v[168:171], v[30:33]
	v_mfma_f32_16x16x32_bf16 v[46:49], v[180:183], v[176:179], v[22:25]
	v_mfma_f32_16x16x32_bf16 v[22:25], v[212:215], v[172:175], v[144:147]
	v_mfma_f32_16x16x32_bf16 v[30:33], v[180:183], v[204:207], v[14:17]
	v_mfma_f32_16x16x32_bf16 v[14:17], v[212:215], v[200:203], v[148:151]
	v_mfma_f32_16x16x32_bf16 v[6:9], v[164:167], v[208:211], v[6:9]
	v_mfma_f32_16x16x32_bf16 v[38:41], v[216:219], v[176:179], v[22:25]
	v_mfma_f32_16x16x32_bf16 v[22:25], v[216:219], v[204:207], v[14:17]
	v_mfma_f32_16x16x32_bf16 v[14:17], v[180:183], v[220:223], v[6:9]
	v_mfma_f32_16x16x32_bf16 v[6:9], v[212:215], v[208:211], v[152:155]
	v_mfma_f32_16x16x32_bf16 v[6:9], v[216:219], v[220:223], v[6:9]
	s_setprio 0
	s_barrier
	s_cbranch_scc0 .LBB0_644
	s_barrier

.LBB0_707:
	v_add_u32_e32 v11, s38, v152
	s_add_i32 s24, s24, 2
	ds_read_b128 v[156:159], v11
	ds_read_b128 v[160:163], v11 offset:1024
	ds_read_b128 v[164:167], v11 offset:2048
	ds_read_b128 v[172:175], v11 offset:3072
	v_add_u32_e32 v11, s39, v152
	s_add_u32 s25, s14, s60
	ds_read_b128 v[176:179], v11
	ds_read_b128 v[180:183], v11 offset:1024
	ds_read_b128 v[184:187], v11 offset:2048
	ds_read_b128 v[188:191], v11 offset:3072
	s_addc_u32 s26, s15, s61
	s_add_u32 s25, s25, 0x100
	s_addc_u32 s26, s26, 0
	s_add_u32 s27, s45, s60
	s_addc_u32 s49, s47, s61
	s_cmpk_eq_i32 s60, 0x700
	s_cselect_b32 s63, s59, s49
	s_cselect_b32 s62, s58, s27
	s_cselect_b32 s65, s57, s26
	s_cselect_b32 s64, s56, s25
	v_lshl_add_u64 v[168:169], v[150:151], 0, s[60:61]
	s_add_i32 s49, s29, 0x8000
	v_lshl_add_u64 v[224:225], v[168:169], 0, s[22:23]
	s_mov_b32 m0, s49
	ds_read_b128 v[192:195], v155
	ds_read_b128 v[196:199], v155 offset:1024
	ds_read_b128 v[200:203], v155 offset:2048
	ds_read_b128 v[204:207], v155 offset:3072
	ds_read_b128 v[208:211], v155 offset:4096
	ds_read_b128 v[212:215], v155 offset:5120
	ds_read_b128 v[216:219], v155 offset:6144
	ds_read_b128 v[220:223], v155 offset:7168
	global_load_lds_dwordx4 v[224:225], off
	v_lshl_add_u64 v[224:225], v[12:13], 0, s[60:61]
	s_add_i32 s27, s29, 0xa000
	v_lshl_add_u64 v[226:227], v[224:225], 0, s[22:23]
	s_mov_b32 m0, s27
	s_add_i32 s25, s29, 0xc000
	global_load_lds_dwordx4 v[226:227], off
	v_lshl_add_u64 v[168:169], v[168:169], 0, s[30:31]
	s_mov_b32 m0, s25
	s_add_i32 s26, s29, 0xe000
	global_load_lds_dwordx4 v[168:169], off
	v_lshl_add_u64 v[168:169], v[224:225], 0, s[30:31]
	s_mov_b32 m0, s26
	s_nop 0
	global_load_lds_dwordx4 v[168:169], off
	s_waitcnt vmcnt(8)
	s_waitcnt lgkmcnt(0)
	s_barrier
	s_setprio 1
	v_mfma_f32_16x16x32_bf16 v[126:129], v[156:159], v[192:195], v[126:129]
	v_mfma_f32_16x16x32_bf16 v[122:125], v[164:167], v[192:195], v[122:125]
	v_mfma_f32_16x16x32_bf16 v[110:113], v[156:159], v[200:203], v[110:113]
	v_mfma_f32_16x16x32_bf16 v[106:109], v[164:167], v[200:203], v[106:109]
	v_mfma_f32_16x16x32_bf16 v[94:97], v[156:159], v[208:211], v[94:97]
	v_mfma_f32_16x16x32_bf16 v[90:93], v[164:167], v[208:211], v[90:93]
	v_mfma_f32_16x16x32_bf16 v[78:81], v[156:159], v[216:219], v[78:81]
	v_mfma_f32_16x16x32_bf16 v[74:77], v[164:167], v[216:219], v[74:77]
	v_mfma_f32_16x16x32_bf16 v[126:129], v[160:163], v[196:199], v[126:129]
	v_mfma_f32_16x16x32_bf16 v[122:125], v[172:175], v[196:199], v[122:125]
	v_mfma_f32_16x16x32_bf16 v[110:113], v[160:163], v[204:207], v[110:113]
	v_mfma_f32_16x16x32_bf16 v[106:109], v[172:175], v[204:207], v[106:109]
	v_mfma_f32_16x16x32_bf16 v[94:97], v[160:163], v[212:215], v[94:97]
	v_mfma_f32_16x16x32_bf16 v[90:93], v[172:175], v[212:215], v[90:93]
	v_mfma_f32_16x16x32_bf16 v[78:81], v[160:163], v[220:223], v[78:81]
	v_mfma_f32_16x16x32_bf16 v[74:77], v[172:175], v[220:223], v[74:77]
	v_mfma_f32_16x16x32_bf16 v[62:65], v[176:179], v[192:195], v[62:65]
	v_mfma_f32_16x16x32_bf16 v[58:61], v[184:187], v[192:195], v[58:61]
	v_mfma_f32_16x16x32_bf16 v[46:49], v[176:179], v[200:203], v[46:49]
	v_mfma_f32_16x16x32_bf16 v[42:45], v[184:187], v[200:203], v[42:45]
	v_mfma_f32_16x16x32_bf16 v[30:33], v[176:179], v[208:211], v[30:33]
	v_mfma_f32_16x16x32_bf16 v[26:29], v[184:187], v[208:211], v[26:29]
	v_mfma_f32_16x16x32_bf16 v[14:17], v[176:179], v[216:219], v[14:17]
	v_mfma_f32_16x16x32_bf16 v[130:133], v[184:187], v[216:219], v[130:133]
	v_mfma_f32_16x16x32_bf16 v[62:65], v[180:183], v[196:199], v[62:65]
	v_mfma_f32_16x16x32_bf16 v[58:61], v[188:191], v[196:199], v[58:61]
	v_mfma_f32_16x16x32_bf16 v[46:49], v[180:183], v[204:207], v[46:49]
	v_mfma_f32_16x16x32_bf16 v[42:45], v[188:191], v[204:207], v[42:45]
	v_mfma_f32_16x16x32_bf16 v[30:33], v[180:183], v[212:215], v[30:33]
	v_mfma_f32_16x16x32_bf16 v[26:29], v[188:191], v[212:215], v[26:29]
	v_mfma_f32_16x16x32_bf16 v[14:17], v[180:183], v[220:223], v[14:17]
	v_mfma_f32_16x16x32_bf16 v[130:133], v[188:191], v[220:223], v[130:133]
	s_setprio 0
	s_barrier
	s_add_i32 s51, s38, s11
	v_lshl_add_u64 v[168:169], s[62:63], 0, v[136:137]
	s_mov_b32 m0, s51
	ds_read_b128 v[192:195], v155 offset:16384
	ds_read_b128 v[196:199], v155 offset:17408
	ds_read_b128 v[200:203], v155 offset:18432
	ds_read_b128 v[204:207], v155 offset:19456
	ds_read_b128 v[208:211], v155 offset:20480
	ds_read_b128 v[212:215], v155 offset:21504
	ds_read_b128 v[216:219], v155 offset:22528
	ds_read_b128 v[220:223], v155 offset:23552
	global_load_lds_dwordx4 v[168:169], off
	s_add_i32 m0, s51, 0x2000
	s_add_u32 s66, s62, 0x40000
	v_lshl_add_u64 v[224:225], s[62:63], 0, v[140:141]
	s_addc_u32 s67, s63, 0
	s_add_i32 s51, s39, s11
	global_load_lds_dwordx4 v[224:225], off
	v_lshl_add_u64 v[226:227], s[66:67], 0, v[136:137]
	s_mov_b32 m0, s51
	s_nop 0
	global_load_lds_dwordx4 v[226:227], off
	v_lshl_add_u64 v[226:227], s[66:67], 0, v[140:141]
	s_add_i32 m0, s51, 0x2000
	s_nop 0
	global_load_lds_dwordx4 v[226:227], off
	s_waitcnt vmcnt(4)
	s_waitcnt lgkmcnt(0)
	s_barrier
	s_setprio 1
	v_mfma_f32_16x16x32_bf16 v[118:121], v[156:159], v[192:195], v[118:121]
	v_mfma_f32_16x16x32_bf16 v[114:117], v[164:167], v[192:195], v[114:117]
	v_mfma_f32_16x16x32_bf16 v[102:105], v[156:159], v[200:203], v[102:105]
	v_mfma_f32_16x16x32_bf16 v[98:101], v[164:167], v[200:203], v[98:101]
	v_mfma_f32_16x16x32_bf16 v[86:89], v[156:159], v[208:211], v[86:89]
	v_mfma_f32_16x16x32_bf16 v[82:85], v[164:167], v[208:211], v[82:85]
	v_mfma_f32_16x16x32_bf16 v[70:73], v[156:159], v[216:219], v[70:73]
	v_mfma_f32_16x16x32_bf16 v[66:69], v[164:167], v[216:219], v[66:69]
	v_mfma_f32_16x16x32_bf16 v[118:121], v[160:163], v[196:199], v[118:121]
	v_mfma_f32_16x16x32_bf16 v[114:117], v[172:175], v[196:199], v[114:117]
	v_mfma_f32_16x16x32_bf16 v[102:105], v[160:163], v[204:207], v[102:105]
	v_mfma_f32_16x16x32_bf16 v[98:101], v[172:175], v[204:207], v[98:101]
	v_mfma_f32_16x16x32_bf16 v[86:89], v[160:163], v[212:215], v[86:89]
	v_mfma_f32_16x16x32_bf16 v[82:85], v[172:175], v[212:215], v[82:85]
	v_mfma_f32_16x16x32_bf16 v[70:73], v[160:163], v[220:223], v[70:73]
	v_mfma_f32_16x16x32_bf16 v[66:69], v[172:175], v[220:223], v[66:69]
	v_mfma_f32_16x16x32_bf16 v[54:57], v[176:179], v[192:195], v[54:57]
	v_mfma_f32_16x16x32_bf16 v[50:53], v[184:187], v[192:195], v[50:53]
	v_mfma_f32_16x16x32_bf16 v[38:41], v[176:179], v[200:203], v[38:41]
	v_mfma_f32_16x16x32_bf16 v[34:37], v[184:187], v[200:203], v[34:37]
	v_mfma_f32_16x16x32_bf16 v[22:25], v[176:179], v[208:211], v[22:25]
	v_mfma_f32_16x16x32_bf16 v[18:21], v[184:187], v[208:211], v[18:21]
	v_mfma_f32_16x16x32_bf16 v[6:9], v[176:179], v[216:219], v[6:9]
	v_mfma_f32_16x16x32_bf16 v[2:5], v[184:187], v[216:219], v[2:5]
	v_mfma_f32_16x16x32_bf16 v[54:57], v[180:183], v[196:199], v[54:57]
	v_mfma_f32_16x16x32_bf16 v[50:53], v[188:191], v[196:199], v[50:53]
	v_mfma_f32_16x16x32_bf16 v[38:41], v[180:183], v[204:207], v[38:41]
	v_mfma_f32_16x16x32_bf16 v[34:37], v[188:191], v[204:207], v[34:37]
	v_mfma_f32_16x16x32_bf16 v[22:25], v[180:183], v[212:215], v[22:25]
	v_mfma_f32_16x16x32_bf16 v[18:21], v[188:191], v[212:215], v[18:21]
	v_mfma_f32_16x16x32_bf16 v[6:9], v[180:183], v[220:223], v[6:9]
	v_mfma_f32_16x16x32_bf16 v[2:5], v[188:191], v[220:223], v[2:5]
	s_setprio 0
	s_barrier
	s_add_i32 s51, 0, 0x18000
	v_add_u32_e32 v11, s51, v152
	s_add_i32 s66, 0, 0x1c000
	ds_read_b128 v[156:159], v11
	ds_read_b128 v[160:163], v11 offset:1024
	ds_read_b128 v[164:167], v11 offset:2048
	ds_read_b128 v[172:175], v11 offset:3072
	v_add_u32_e32 v11, s66, v152
	ds_read_b128 v[176:179], v11
	ds_read_b128 v[180:183], v11 offset:1024
	ds_read_b128 v[184:187], v11 offset:2048
	ds_read_b128 v[188:191], v11 offset:3072
	s_mov_b32 m0, s29
	v_lshl_add_u64 v[226:227], s[64:65], 0, v[134:135]
	ds_read_b128 v[192:195], v155 offset:32768
	ds_read_b128 v[196:199], v155 offset:33792
	ds_read_b128 v[200:203], v155 offset:34816
	ds_read_b128 v[204:207], v155 offset:35840
	ds_read_b128 v[208:211], v155 offset:36864
	ds_read_b128 v[212:215], v155 offset:37888
	ds_read_b128 v[216:219], v155 offset:38912
	ds_read_b128 v[220:223], v155 offset:39936
	global_load_lds_dwordx4 v[226:227], off
	v_lshl_add_u64 v[226:227], s[64:65], 0, v[138:139]
	s_add_u32 s64, s64, 0x40000
	s_mov_b32 m0, s33
	s_addc_u32 s65, s65, 0
	global_load_lds_dwordx4 v[226:227], off
	v_lshl_add_u64 v[226:227], s[64:65], 0, v[134:135]
	s_mov_b32 m0, s36
	s_nop 0
	global_load_lds_dwordx4 v[226:227], off
	v_lshl_add_u64 v[226:227], s[64:65], 0, v[138:139]
	s_mov_b32 m0, s37
	s_nop 0
	global_load_lds_dwordx4 v[226:227], off
	s_waitcnt vmcnt(8)
	s_waitcnt lgkmcnt(0)
	s_barrier
	s_setprio 1
	v_mfma_f32_16x16x32_bf16 v[126:129], v[156:159], v[192:195], v[126:129]
	v_mfma_f32_16x16x32_bf16 v[122:125], v[164:167], v[192:195], v[122:125]
	v_mfma_f32_16x16x32_bf16 v[110:113], v[156:159], v[200:203], v[110:113]
	v_mfma_f32_16x16x32_bf16 v[106:109], v[164:167], v[200:203], v[106:109]
	v_mfma_f32_16x16x32_bf16 v[94:97], v[156:159], v[208:211], v[94:97]
	v_mfma_f32_16x16x32_bf16 v[90:93], v[164:167], v[208:211], v[90:93]
	v_mfma_f32_16x16x32_bf16 v[78:81], v[156:159], v[216:219], v[78:81]
	v_mfma_f32_16x16x32_bf16 v[74:77], v[164:167], v[216:219], v[74:77]
	v_mfma_f32_16x16x32_bf16 v[126:129], v[160:163], v[196:199], v[126:129]
	v_mfma_f32_16x16x32_bf16 v[122:125], v[172:175], v[196:199], v[122:125]
	v_mfma_f32_16x16x32_bf16 v[110:113], v[160:163], v[204:207], v[110:113]
	v_mfma_f32_16x16x32_bf16 v[106:109], v[172:175], v[204:207], v[106:109]
	v_mfma_f32_16x16x32_bf16 v[94:97], v[160:163], v[212:215], v[94:97]
	v_mfma_f32_16x16x32_bf16 v[90:93], v[172:175], v[212:215], v[90:93]
	v_mfma_f32_16x16x32_bf16 v[78:81], v[160:163], v[220:223], v[78:81]
	v_mfma_f32_16x16x32_bf16 v[74:77], v[172:175], v[220:223], v[74:77]
	v_mfma_f32_16x16x32_bf16 v[62:65], v[176:179], v[192:195], v[62:65]
	v_mfma_f32_16x16x32_bf16 v[58:61], v[184:187], v[192:195], v[58:61]
	v_mfma_f32_16x16x32_bf16 v[46:49], v[176:179], v[200:203], v[46:49]
	v_mfma_f32_16x16x32_bf16 v[42:45], v[184:187], v[200:203], v[42:45]
	v_mfma_f32_16x16x32_bf16 v[30:33], v[176:179], v[208:211], v[30:33]
	v_mfma_f32_16x16x32_bf16 v[26:29], v[184:187], v[208:211], v[26:29]
	v_mfma_f32_16x16x32_bf16 v[14:17], v[176:179], v[216:219], v[14:17]
	v_mfma_f32_16x16x32_bf16 v[130:133], v[184:187], v[216:219], v[130:133]
	v_mfma_f32_16x16x32_bf16 v[62:65], v[180:183], v[196:199], v[62:65]
	v_mfma_f32_16x16x32_bf16 v[58:61], v[188:191], v[196:199], v[58:61]
	v_mfma_f32_16x16x32_bf16 v[46:49], v[180:183], v[204:207], v[46:49]
	v_mfma_f32_16x16x32_bf16 v[42:45], v[188:191], v[204:207], v[42:45]
	v_mfma_f32_16x16x32_bf16 v[30:33], v[180:183], v[212:215], v[30:33]
	v_mfma_f32_16x16x32_bf16 v[26:29], v[188:191], v[212:215], v[26:29]
	v_mfma_f32_16x16x32_bf16 v[14:17], v[180:183], v[220:223], v[14:17]
	v_mfma_f32_16x16x32_bf16 v[130:133], v[188:191], v[220:223], v[130:133]
	s_setprio 0
	s_barrier
	s_add_i32 s51, s51, s11
	v_lshl_add_u64 v[168:169], v[168:169], 0, s[22:23]
	s_mov_b32 m0, s51
	ds_read_b128 v[192:195], v155 offset:49152
	ds_read_b128 v[196:199], v155 offset:50176
	ds_read_b128 v[200:203], v155 offset:51200
	ds_read_b128 v[204:207], v155 offset:52224
	ds_read_b128 v[208:211], v155 offset:53248
	ds_read_b128 v[212:215], v155 offset:54272
	ds_read_b128 v[216:219], v155 offset:55296
	ds_read_b128 v[220:223], v155 offset:56320
	global_load_lds_dwordx4 v[168:169], off
	s_add_i32 m0, s51, 0x2000
	s_add_u32 s62, s62, 0x40080
	v_lshl_add_u64 v[168:169], v[224:225], 0, s[22:23]
	s_addc_u32 s63, s63, 0
	s_add_i32 s51, s66, s11
	global_load_lds_dwordx4 v[168:169], off
	v_lshl_add_u64 v[168:169], s[62:63], 0, v[136:137]
	s_mov_b32 m0, s51
	s_nop 0
	global_load_lds_dwordx4 v[168:169], off
	v_lshl_add_u64 v[168:169], s[62:63], 0, v[140:141]
	s_add_i32 m0, s51, 0x2000
	s_nop 0
	global_load_lds_dwordx4 v[168:169], off
	s_waitcnt vmcnt(4)
	s_waitcnt lgkmcnt(0)
	s_barrier
	s_setprio 1
	v_mfma_f32_16x16x32_bf16 v[118:121], v[156:159], v[192:195], v[118:121]
	v_mfma_f32_16x16x32_bf16 v[114:117], v[164:167], v[192:195], v[114:117]
	v_mfma_f32_16x16x32_bf16 v[102:105], v[156:159], v[200:203], v[102:105]
	v_mfma_f32_16x16x32_bf16 v[98:101], v[164:167], v[200:203], v[98:101]
	v_mfma_f32_16x16x32_bf16 v[86:89], v[156:159], v[208:211], v[86:89]
	v_mfma_f32_16x16x32_bf16 v[82:85], v[164:167], v[208:211], v[82:85]
	v_mfma_f32_16x16x32_bf16 v[70:73], v[156:159], v[216:219], v[70:73]
	v_mfma_f32_16x16x32_bf16 v[66:69], v[164:167], v[216:219], v[66:69]
	v_mfma_f32_16x16x32_bf16 v[118:121], v[160:163], v[196:199], v[118:121]
	v_mfma_f32_16x16x32_bf16 v[114:117], v[172:175], v[196:199], v[114:117]
	v_mfma_f32_16x16x32_bf16 v[102:105], v[160:163], v[204:207], v[102:105]
	v_mfma_f32_16x16x32_bf16 v[98:101], v[172:175], v[204:207], v[98:101]
	v_mfma_f32_16x16x32_bf16 v[86:89], v[160:163], v[212:215], v[86:89]
	v_mfma_f32_16x16x32_bf16 v[82:85], v[172:175], v[212:215], v[82:85]
	v_mfma_f32_16x16x32_bf16 v[70:73], v[160:163], v[220:223], v[70:73]
	v_mfma_f32_16x16x32_bf16 v[66:69], v[172:175], v[220:223], v[66:69]
	v_mfma_f32_16x16x32_bf16 v[54:57], v[176:179], v[192:195], v[54:57]
	v_mfma_f32_16x16x32_bf16 v[50:53], v[184:187], v[192:195], v[50:53]
	v_mfma_f32_16x16x32_bf16 v[38:41], v[176:179], v[200:203], v[38:41]
	v_mfma_f32_16x16x32_bf16 v[34:37], v[184:187], v[200:203], v[34:37]
	v_mfma_f32_16x16x32_bf16 v[22:25], v[176:179], v[208:211], v[22:25]
	v_mfma_f32_16x16x32_bf16 v[18:21], v[184:187], v[208:211], v[18:21]
	v_mfma_f32_16x16x32_bf16 v[6:9], v[176:179], v[216:219], v[6:9]
	v_mfma_f32_16x16x32_bf16 v[2:5], v[184:187], v[216:219], v[2:5]
	v_mfma_f32_16x16x32_bf16 v[54:57], v[180:183], v[196:199], v[54:57]
	v_mfma_f32_16x16x32_bf16 v[50:53], v[188:191], v[196:199], v[50:53]
	v_mfma_f32_16x16x32_bf16 v[38:41], v[180:183], v[204:207], v[38:41]
	v_mfma_f32_16x16x32_bf16 v[34:37], v[188:191], v[204:207], v[34:37]
	v_mfma_f32_16x16x32_bf16 v[22:25], v[180:183], v[212:215], v[22:25]
	v_mfma_f32_16x16x32_bf16 v[18:21], v[188:191], v[212:215], v[18:21]
	v_mfma_f32_16x16x32_bf16 v[6:9], v[180:183], v[220:223], v[6:9]
	v_mfma_f32_16x16x32_bf16 v[2:5], v[188:191], v[220:223], v[2:5]
	s_setprio 0
	s_barrier
	s_add_u32 s60, s60, 0x100
	s_addc_u32 s61, s61, 0
	s_cmp_ge_u32 s24, s3
	s_cbranch_scc0 .LBB0_707
	s_and_b64 vcc, exec, s[4:5]
	s_cbranch_vccz .LBB0_711
	v_add_u32_e32 v11, 0, v152
	v_add_u32_e32 v12, 0x10000, v11
	ds_read_b128 v[156:159], v12
	ds_read_b128 v[160:163], v12 offset:1024
	ds_read_b128 v[164:167], v12 offset:2048
	ds_read_b128 v[172:175], v12 offset:3072
	v_add_u32_e32 v12, 0x14000, v11
	ds_read_b128 v[176:179], v12
	ds_read_b128 v[180:183], v12 offset:1024
	ds_read_b128 v[184:187], v12 offset:2048
	ds_read_b128 v[188:191], v12 offset:3072
	v_lshl_add_u64 v[12:13], s[14:15], 0, v[134:135]
	s_mov_b32 m0, s49
	v_lshl_add_u64 v[12:13], v[12:13], 0, s[42:43]
	ds_read_b128 v[192:195], v155
	ds_read_b128 v[196:199], v155 offset:1024
	ds_read_b128 v[200:203], v155 offset:2048
	ds_read_b128 v[204:207], v155 offset:3072
	ds_read_b128 v[208:211], v155 offset:4096
	ds_read_b128 v[212:215], v155 offset:5120
	ds_read_b128 v[216:219], v155 offset:6144
	ds_read_b128 v[220:223], v155 offset:7168
	global_load_lds_dwordx4 v[12:13], off
	v_lshl_add_u64 v[12:13], s[14:15], 0, v[138:139]
	s_add_u32 s60, s14, 0x40780
	v_lshl_add_u64 v[12:13], v[12:13], 0, s[42:43]
	s_mov_b32 m0, s27
	s_addc_u32 s61, s15, 0
	global_load_lds_dwordx4 v[12:13], off
	v_lshl_add_u64 v[12:13], s[60:61], 0, v[134:135]
	s_mov_b32 m0, s25
	s_nop 0
	global_load_lds_dwordx4 v[12:13], off
	v_lshl_add_u64 v[12:13], s[60:61], 0, v[138:139]
	s_mov_b32 m0, s26
	s_nop 0
	global_load_lds_dwordx4 v[12:13], off
	s_waitcnt vmcnt(8)
	s_waitcnt lgkmcnt(0)
	s_barrier
	s_setprio 1
	v_mfma_f32_16x16x32_bf16 v[126:129], v[156:159], v[192:195], v[126:129]
	v_mfma_f32_16x16x32_bf16 v[122:125], v[164:167], v[192:195], v[122:125]
	v_mfma_f32_16x16x32_bf16 v[110:113], v[156:159], v[200:203], v[110:113]
	v_mfma_f32_16x16x32_bf16 v[106:109], v[164:167], v[200:203], v[106:109]
	v_mfma_f32_16x16x32_bf16 v[94:97], v[156:159], v[208:211], v[94:97]
	v_mfma_f32_16x16x32_bf16 v[90:93], v[164:167], v[208:211], v[90:93]
	v_mfma_f32_16x16x32_bf16 v[78:81], v[156:159], v[216:219], v[78:81]
	v_mfma_f32_16x16x32_bf16 v[74:77], v[164:167], v[216:219], v[74:77]
	v_mfma_f32_16x16x32_bf16 v[126:129], v[160:163], v[196:199], v[126:129]
	v_mfma_f32_16x16x32_bf16 v[122:125], v[172:175], v[196:199], v[122:125]
	v_mfma_f32_16x16x32_bf16 v[110:113], v[160:163], v[204:207], v[110:113]
	v_mfma_f32_16x16x32_bf16 v[106:109], v[172:175], v[204:207], v[106:109]
	v_mfma_f32_16x16x32_bf16 v[94:97], v[160:163], v[212:215], v[94:97]
	v_mfma_f32_16x16x32_bf16 v[90:93], v[172:175], v[212:215], v[90:93]
	v_mfma_f32_16x16x32_bf16 v[78:81], v[160:163], v[220:223], v[78:81]
	v_mfma_f32_16x16x32_bf16 v[74:77], v[172:175], v[220:223], v[74:77]
	v_mfma_f32_16x16x32_bf16 v[62:65], v[176:179], v[192:195], v[62:65]
	v_mfma_f32_16x16x32_bf16 v[58:61], v[184:187], v[192:195], v[58:61]
	v_mfma_f32_16x16x32_bf16 v[46:49], v[176:179], v[200:203], v[46:49]
	v_mfma_f32_16x16x32_bf16 v[42:45], v[184:187], v[200:203], v[42:45]
	v_mfma_f32_16x16x32_bf16 v[30:33], v[176:179], v[208:211], v[30:33]
	v_mfma_f32_16x16x32_bf16 v[26:29], v[184:187], v[208:211], v[26:29]
	v_mfma_f32_16x16x32_bf16 v[12:15], v[176:179], v[216:219], v[14:17]
	v_mfma_f32_16x16x32_bf16 v[130:133], v[184:187], v[216:219], v[130:133]
	v_mfma_f32_16x16x32_bf16 v[62:65], v[180:183], v[196:199], v[62:65]
	v_mfma_f32_16x16x32_bf16 v[58:61], v[188:191], v[196:199], v[58:61]
	v_mfma_f32_16x16x32_bf16 v[46:49], v[180:183], v[204:207], v[46:49]
	v_mfma_f32_16x16x32_bf16 v[42:45], v[188:191], v[204:207], v[42:45]
	v_mfma_f32_16x16x32_bf16 v[30:33], v[180:183], v[212:215], v[30:33]
	v_mfma_f32_16x16x32_bf16 v[26:29], v[188:191], v[212:215], v[26:29]
	v_mfma_f32_16x16x32_bf16 v[12:15], v[180:183], v[220:223], v[12:15]
	v_mfma_f32_16x16x32_bf16 v[130:133], v[188:191], v[220:223], v[130:133]
	s_setprio 0
	s_barrier
	ds_read_b128 v[192:195], v155 offset:16384
	ds_read_b128 v[196:199], v155 offset:17408
	ds_read_b128 v[200:203], v155 offset:18432
	ds_read_b128 v[204:207], v155 offset:19456
	ds_read_b128 v[208:211], v155 offset:20480
	ds_read_b128 v[212:215], v155 offset:21504
	ds_read_b128 v[216:219], v155 offset:22528
	ds_read_b128 v[220:223], v155 offset:23552
	s_waitcnt vmcnt(0)
	s_waitcnt lgkmcnt(0)
	s_barrier
	s_setprio 1
	v_mfma_f32_16x16x32_bf16 v[118:121], v[156:159], v[192:195], v[118:121]
	v_mfma_f32_16x16x32_bf16 v[114:117], v[164:167], v[192:195], v[114:117]
	v_mfma_f32_16x16x32_bf16 v[102:105], v[156:159], v[200:203], v[102:105]
	v_mfma_f32_16x16x32_bf16 v[98:101], v[164:167], v[200:203], v[98:101]
	v_mfma_f32_16x16x32_bf16 v[86:89], v[156:159], v[208:211], v[86:89]
	v_mfma_f32_16x16x32_bf16 v[82:85], v[164:167], v[208:211], v[82:85]
	v_mfma_f32_16x16x32_bf16 v[70:73], v[156:159], v[216:219], v[70:73]
	v_mfma_f32_16x16x32_bf16 v[66:69], v[164:167], v[216:219], v[66:69]
	v_mfma_f32_16x16x32_bf16 v[118:121], v[160:163], v[196:199], v[118:121]
	v_mfma_f32_16x16x32_bf16 v[114:117], v[172:175], v[196:199], v[114:117]
	v_mfma_f32_16x16x32_bf16 v[102:105], v[160:163], v[204:207], v[102:105]
	v_mfma_f32_16x16x32_bf16 v[98:101], v[172:175], v[204:207], v[98:101]
	v_mfma_f32_16x16x32_bf16 v[86:89], v[160:163], v[212:215], v[86:89]
	v_mfma_f32_16x16x32_bf16 v[82:85], v[172:175], v[212:215], v[82:85]
	v_mfma_f32_16x16x32_bf16 v[70:73], v[160:163], v[220:223], v[70:73]
	v_mfma_f32_16x16x32_bf16 v[66:69], v[172:175], v[220:223], v[66:69]
	v_mfma_f32_16x16x32_bf16 v[54:57], v[176:179], v[192:195], v[54:57]
	v_mfma_f32_16x16x32_bf16 v[50:53], v[184:187], v[192:195], v[50:53]
	v_mfma_f32_16x16x32_bf16 v[38:41], v[176:179], v[200:203], v[38:41]
	v_mfma_f32_16x16x32_bf16 v[34:37], v[184:187], v[200:203], v[34:37]
	v_mfma_f32_16x16x32_bf16 v[22:25], v[176:179], v[208:211], v[22:25]
	v_mfma_f32_16x16x32_bf16 v[16:19], v[184:187], v[208:211], v[18:21]
	v_mfma_f32_16x16x32_bf16 v[6:9], v[176:179], v[216:219], v[6:9]
	v_mfma_f32_16x16x32_bf16 v[2:5], v[184:187], v[216:219], v[2:5]
	v_mfma_f32_16x16x32_bf16 v[54:57], v[180:183], v[196:199], v[54:57]
	v_mfma_f32_16x16x32_bf16 v[50:53], v[188:191], v[196:199], v[50:53]
	v_mfma_f32_16x16x32_bf16 v[38:41], v[180:183], v[204:207], v[38:41]
	v_mfma_f32_16x16x32_bf16 v[34:37], v[188:191], v[204:207], v[34:37]
	v_mfma_f32_16x16x32_bf16 v[22:25], v[180:183], v[212:215], v[22:25]
	v_mfma_f32_16x16x32_bf16 v[18:21], v[188:191], v[212:215], v[16:19]
	v_mfma_f32_16x16x32_bf16 v[6:9], v[180:183], v[220:223], v[6:9]
	v_mfma_f32_16x16x32_bf16 v[2:5], v[188:191], v[220:223], v[2:5]
	s_setprio 0
	s_barrier
	v_add_u32_e32 v16, 0x18000, v11
	v_add_u32_e32 v11, 0x1c000, v11
	ds_read_b128 v[156:159], v16
	ds_read_b128 v[160:163], v16 offset:1024
	ds_read_b128 v[164:167], v16 offset:2048
	ds_read_b128 v[172:175], v16 offset:3072
	ds_read_b128 v[176:179], v11
	ds_read_b128 v[180:183], v11 offset:1024
	ds_read_b128 v[184:187], v11 offset:2048
	ds_read_b128 v[188:191], v11 offset:3072
	ds_read_b128 v[192:195], v155 offset:32768
	ds_read_b128 v[196:199], v155 offset:33792
	ds_read_b128 v[200:203], v155 offset:34816
	ds_read_b128 v[204:207], v155 offset:35840
	ds_read_b128 v[208:211], v155 offset:36864
	ds_read_b128 v[212:215], v155 offset:37888
	ds_read_b128 v[216:219], v155 offset:38912
	ds_read_b128 v[220:223], v155 offset:39936
	s_waitcnt lgkmcnt(0)
	s_barrier
	s_setprio 1
	v_mfma_f32_16x16x32_bf16 v[126:129], v[156:159], v[192:195], v[126:129]
	v_mfma_f32_16x16x32_bf16 v[122:125], v[164:167], v[192:195], v[122:125]
	v_mfma_f32_16x16x32_bf16 v[110:113], v[156:159], v[200:203], v[110:113]
	v_mfma_f32_16x16x32_bf16 v[106:109], v[164:167], v[200:203], v[106:109]
	v_mfma_f32_16x16x32_bf16 v[94:97], v[156:159], v[208:211], v[94:97]
	v_mfma_f32_16x16x32_bf16 v[90:93], v[164:167], v[208:211], v[90:93]
	v_mfma_f32_16x16x32_bf16 v[78:81], v[156:159], v[216:219], v[78:81]
	v_mfma_f32_16x16x32_bf16 v[74:77], v[164:167], v[216:219], v[74:77]
	v_mfma_f32_16x16x32_bf16 v[126:129], v[160:163], v[196:199], v[126:129]
	v_mfma_f32_16x16x32_bf16 v[122:125], v[172:175], v[196:199], v[122:125]
	v_mfma_f32_16x16x32_bf16 v[110:113], v[160:163], v[204:207], v[110:113]
	v_mfma_f32_16x16x32_bf16 v[106:109], v[172:175], v[204:207], v[106:109]
	v_mfma_f32_16x16x32_bf16 v[94:97], v[160:163], v[212:215], v[94:97]
	v_mfma_f32_16x16x32_bf16 v[90:93], v[172:175], v[212:215], v[90:93]
	v_mfma_f32_16x16x32_bf16 v[78:81], v[160:163], v[220:223], v[78:81]
	v_mfma_f32_16x16x32_bf16 v[74:77], v[172:175], v[220:223], v[74:77]
	v_mfma_f32_16x16x32_bf16 v[62:65], v[176:179], v[192:195], v[62:65]
	v_mfma_f32_16x16x32_bf16 v[58:61], v[184:187], v[192:195], v[58:61]
	v_mfma_f32_16x16x32_bf16 v[46:49], v[176:179], v[200:203], v[46:49]
	v_mfma_f32_16x16x32_bf16 v[42:45], v[184:187], v[200:203], v[42:45]
	v_mfma_f32_16x16x32_bf16 v[30:33], v[176:179], v[208:211], v[30:33]
	v_mfma_f32_16x16x32_bf16 v[26:29], v[184:187], v[208:211], v[26:29]
	v_mfma_f32_16x16x32_bf16 v[12:15], v[176:179], v[216:219], v[12:15]
	v_mfma_f32_16x16x32_bf16 v[130:133], v[184:187], v[216:219], v[130:133]
	v_mfma_f32_16x16x32_bf16 v[62:65], v[180:183], v[196:199], v[62:65]
	v_mfma_f32_16x16x32_bf16 v[58:61], v[188:191], v[196:199], v[58:61]
	v_mfma_f32_16x16x32_bf16 v[46:49], v[180:183], v[204:207], v[46:49]
	v_mfma_f32_16x16x32_bf16 v[42:45], v[188:191], v[204:207], v[42:45]
	v_mfma_f32_16x16x32_bf16 v[30:33], v[180:183], v[212:215], v[30:33]
	v_mfma_f32_16x16x32_bf16 v[26:29], v[188:191], v[212:215], v[26:29]
	v_mfma_f32_16x16x32_bf16 v[14:17], v[180:183], v[220:223], v[12:15]
	v_mfma_f32_16x16x32_bf16 v[130:133], v[188:191], v[220:223], v[130:133]
	s_setprio 0
	s_barrier
	ds_read_b128 v[192:195], v155 offset:49152
	ds_read_b128 v[196:199], v155 offset:50176
	ds_read_b128 v[200:203], v155 offset:51200
	ds_read_b128 v[204:207], v155 offset:52224
	ds_read_b128 v[208:211], v155 offset:53248
	ds_read_b128 v[212:215], v155 offset:54272
	ds_read_b128 v[216:219], v155 offset:55296
	ds_read_b128 v[220:223], v155 offset:56320
	s_waitcnt lgkmcnt(0)
	s_barrier
	s_setprio 1
	v_mfma_f32_16x16x32_bf16 v[118:121], v[156:159], v[192:195], v[118:121]
	v_mfma_f32_16x16x32_bf16 v[114:117], v[164:167], v[192:195], v[114:117]
	v_mfma_f32_16x16x32_bf16 v[102:105], v[156:159], v[200:203], v[102:105]
	v_mfma_f32_16x16x32_bf16 v[98:101], v[164:167], v[200:203], v[98:101]
	v_mfma_f32_16x16x32_bf16 v[86:89], v[156:159], v[208:211], v[86:89]
	v_mfma_f32_16x16x32_bf16 v[82:85], v[164:167], v[208:211], v[82:85]
	v_mfma_f32_16x16x32_bf16 v[70:73], v[156:159], v[216:219], v[70:73]
	v_mfma_f32_16x16x32_bf16 v[66:69], v[164:167], v[216:219], v[66:69]
	v_mfma_f32_16x16x32_bf16 v[118:121], v[160:163], v[196:199], v[118:121]
	v_mfma_f32_16x16x32_bf16 v[114:117], v[172:175], v[196:199], v[114:117]
	v_mfma_f32_16x16x32_bf16 v[102:105], v[160:163], v[204:207], v[102:105]
	v_mfma_f32_16x16x32_bf16 v[98:101], v[172:175], v[204:207], v[98:101]
	v_mfma_f32_16x16x32_bf16 v[86:89], v[160:163], v[212:215], v[86:89]
	v_mfma_f32_16x16x32_bf16 v[82:85], v[172:175], v[212:215], v[82:85]
	v_mfma_f32_16x16x32_bf16 v[70:73], v[160:163], v[220:223], v[70:73]
	v_mfma_f32_16x16x32_bf16 v[66:69], v[172:175], v[220:223], v[66:69]
	v_mfma_f32_16x16x32_bf16 v[54:57], v[176:179], v[192:195], v[54:57]
	v_mfma_f32_16x16x32_bf16 v[50:53], v[184:187], v[192:195], v[50:53]
	v_mfma_f32_16x16x32_bf16 v[38:41], v[176:179], v[200:203], v[38:41]
	v_mfma_f32_16x16x32_bf16 v[34:37], v[184:187], v[200:203], v[34:37]
	v_mfma_f32_16x16x32_bf16 v[22:25], v[176:179], v[208:211], v[22:25]
	v_mfma_f32_16x16x32_bf16 v[18:21], v[184:187], v[208:211], v[18:21]
	v_mfma_f32_16x16x32_bf16 v[6:9], v[176:179], v[216:219], v[6:9]
	v_mfma_f32_16x16x32_bf16 v[2:5], v[184:187], v[216:219], v[2:5]
	v_mfma_f32_16x16x32_bf16 v[54:57], v[180:183], v[196:199], v[54:57]
	v_mfma_f32_16x16x32_bf16 v[50:53], v[188:191], v[196:199], v[50:53]
	v_mfma_f32_16x16x32_bf16 v[38:41], v[180:183], v[204:207], v[38:41]
	v_mfma_f32_16x16x32_bf16 v[34:37], v[188:191], v[204:207], v[34:37]
	v_mfma_f32_16x16x32_bf16 v[22:25], v[180:183], v[212:215], v[22:25]
	v_mfma_f32_16x16x32_bf16 v[18:21], v[188:191], v[212:215], v[18:21]
	v_mfma_f32_16x16x32_bf16 v[6:9], v[180:183], v[220:223], v[6:9]
	v_mfma_f32_16x16x32_bf16 v[2:5], v[188:191], v[220:223], v[2:5]
	s_setprio 0
	s_barrier
	s_andn2_b64 vcc, exec, s[40:41]
	s_cbranch_vccz .LBB0_712

.LBB0_853:
	s_add_i32 s78, s78, 2
	s_add_u32 s0, s70, s8
	s_addc_u32 s1, s71, s9
	s_add_u32 s0, s0, 0x100
	s_addc_u32 s1, s1, 0
	s_add_u32 s3, s50, s8
	s_addc_u32 s10, s65, s9
	s_add_i32 s24, 0, 0x10000
	v_add_u32_e32 v2, s24, v226
	s_add_i32 s26, 0, 0x14000
	s_waitcnt lgkmcnt(0)
	ds_read_b128 v[134:137], v2
	ds_read_b128 v[138:141], v2 offset:1024
	ds_read_b128 v[142:145], v2 offset:2048
	ds_read_b128 v[146:149], v2 offset:3072
	v_add_u32_e32 v2, s26, v226
	ds_read_b128 v[150:153], v2
	ds_read_b128 v[154:157], v2 offset:1024
	ds_read_b128 v[158:161], v2 offset:2048
	ds_read_b128 v[162:165], v2 offset:3072
	s_cmpk_eq_i32 s8, 0x700
	s_cselect_b32 s11, s69, s10
	s_cselect_b32 s10, s68, s3
	s_cselect_b32 s77, s67, s1
	s_cselect_b32 s76, s66, s0
	v_lshl_add_u64 v[4:5], v[222:223], 0, s[8:9]
	s_add_i32 s0, s88, 0x8000
	v_lshl_add_u64 v[224:225], v[4:5], 0, s[44:45]
	s_mov_b32 m0, s0
	s_waitcnt lgkmcnt(0)
	ds_read_b128 v[166:169], v227
	ds_read_b128 v[170:173], v227 offset:1024
	ds_read_b128 v[174:177], v227 offset:2048
	ds_read_b128 v[178:181], v227 offset:3072
	ds_read_b128 v[182:185], v227 offset:4096
	ds_read_b128 v[186:189], v227 offset:5120
	ds_read_b128 v[190:193], v227 offset:6144
	ds_read_b128 v[194:197], v227 offset:7168
	global_load_lds_dwordx4 v[224:225], off
	v_lshl_add_u64 v[224:225], v[220:221], 0, s[8:9]
	s_add_i32 s79, s88, 0xa000
	v_lshl_add_u64 v[246:247], v[224:225], 0, s[44:45]
	s_mov_b32 m0, s79
	s_add_i32 s22, s88, 0xc000
	global_load_lds_dwordx4 v[246:247], off
	v_lshl_add_u64 v[4:5], v[4:5], 0, s[46:47]
	s_mov_b32 m0, s22
	s_add_i32 s23, s88, 0xe000
	global_load_lds_dwordx4 v[4:5], off
	v_lshl_add_u64 v[4:5], v[224:225], 0, s[46:47]
	s_mov_b32 m0, s23
	s_nop 0
	global_load_lds_dwordx4 v[4:5], off
	s_waitcnt vmcnt(8)
	s_waitcnt lgkmcnt(0)
	s_barrier
	s_setprio 1
	v_mfma_f32_16x16x32_bf16 v[82:85], v[134:137], v[166:169], v[82:85]
	v_mfma_f32_16x16x32_bf16 v[10:13], v[142:145], v[166:169], v[10:13]
	v_mfma_f32_16x16x32_bf16 v[130:133], v[134:137], v[174:177], v[130:133]
	v_mfma_f32_16x16x32_bf16 v[66:69], v[142:145], v[174:177], v[66:69]
	v_mfma_f32_16x16x32_bf16 v[126:129], v[134:137], v[182:185], v[126:129]
	v_mfma_f32_16x16x32_bf16 v[62:65], v[142:145], v[182:185], v[62:65]
	v_mfma_f32_16x16x32_bf16 v[122:125], v[134:137], v[190:193], v[122:125]
	v_mfma_f32_16x16x32_bf16 v[58:61], v[142:145], v[190:193], v[58:61]
	v_mfma_f32_16x16x32_bf16 v[82:85], v[138:141], v[170:173], v[82:85]
	v_mfma_f32_16x16x32_bf16 v[10:13], v[146:149], v[170:173], v[10:13]
	v_mfma_f32_16x16x32_bf16 v[130:133], v[138:141], v[178:181], v[130:133]
	v_mfma_f32_16x16x32_bf16 v[66:69], v[146:149], v[178:181], v[66:69]
	v_mfma_f32_16x16x32_bf16 v[126:129], v[138:141], v[186:189], v[126:129]
	v_mfma_f32_16x16x32_bf16 v[62:65], v[146:149], v[186:189], v[62:65]
	v_mfma_f32_16x16x32_bf16 v[122:125], v[138:141], v[194:197], v[122:125]
	v_mfma_f32_16x16x32_bf16 v[58:61], v[146:149], v[194:197], v[58:61]
	v_mfma_f32_16x16x32_bf16 v[70:73], v[150:153], v[166:169], v[70:73]
	v_mfma_f32_16x16x32_bf16 v[4:7], v[158:161], v[166:169], v[6:9]
	v_mfma_f32_16x16x32_bf16 v[118:121], v[150:153], v[174:177], v[118:121]
	v_mfma_f32_16x16x32_bf16 v[54:57], v[158:161], v[174:177], v[54:57]
	v_mfma_f32_16x16x32_bf16 v[114:117], v[150:153], v[182:185], v[114:117]
	v_mfma_f32_16x16x32_bf16 v[50:53], v[158:161], v[182:185], v[50:53]
	v_mfma_f32_16x16x32_bf16 v[110:113], v[150:153], v[190:193], v[110:113]
	v_mfma_f32_16x16x32_bf16 v[46:49], v[158:161], v[190:193], v[46:49]
	v_mfma_f32_16x16x32_bf16 v[70:73], v[154:157], v[170:173], v[70:73]
	v_mfma_f32_16x16x32_bf16 v[4:7], v[162:165], v[170:173], v[4:7]
	v_mfma_f32_16x16x32_bf16 v[118:121], v[154:157], v[178:181], v[118:121]
	v_mfma_f32_16x16x32_bf16 v[54:57], v[162:165], v[178:181], v[54:57]
	v_mfma_f32_16x16x32_bf16 v[114:117], v[154:157], v[186:189], v[114:117]
	v_mfma_f32_16x16x32_bf16 v[50:53], v[162:165], v[186:189], v[50:53]
	v_mfma_f32_16x16x32_bf16 v[110:113], v[154:157], v[194:197], v[110:113]
	v_mfma_f32_16x16x32_bf16 v[46:49], v[162:165], v[194:197], v[46:49]
	s_setprio 0
	s_barrier
	s_add_i32 s1, s24, s87
	v_lshl_add_u64 v[224:225], s[10:11], 0, v[200:201]
	s_mov_b32 m0, s1
	ds_read_b128 v[166:169], v227 offset:16384
	ds_read_b128 v[170:173], v227 offset:17408
	ds_read_b128 v[174:177], v227 offset:18432
	ds_read_b128 v[178:181], v227 offset:19456
	ds_read_b128 v[182:185], v227 offset:20480
	ds_read_b128 v[186:189], v227 offset:21504
	ds_read_b128 v[190:193], v227 offset:22528
	ds_read_b128 v[194:197], v227 offset:23552
	global_load_lds_dwordx4 v[224:225], off
	s_add_i32 m0, s1, 0x2000
	s_add_u32 s24, s10, 0x40000
	v_lshl_add_u64 v[246:247], s[10:11], 0, v[204:205]
	s_addc_u32 s25, s11, 0
	s_add_i32 s1, s26, s87
	global_load_lds_dwordx4 v[246:247], off
	v_lshl_add_u64 v[8:9], s[24:25], 0, v[200:201]
	s_mov_b32 m0, s1
	s_nop 0
	global_load_lds_dwordx4 v[8:9], off
	v_lshl_add_u64 v[8:9], s[24:25], 0, v[204:205]
	s_add_i32 m0, s1, 0x2000
	s_nop 0
	global_load_lds_dwordx4 v[8:9], off
	s_waitcnt vmcnt(4)
	s_waitcnt lgkmcnt(0)
	s_barrier
	s_setprio 1
	v_mfma_f32_16x16x32_bf16 v[102:105], v[134:137], v[166:169], v[102:105]
	v_mfma_f32_16x16x32_bf16 v[30:33], v[142:145], v[166:169], v[30:33]
	v_mfma_f32_16x16x32_bf16 v[106:109], v[134:137], v[174:177], v[106:109]
	v_mfma_f32_16x16x32_bf16 v[42:45], v[142:145], v[174:177], v[42:45]
	v_mfma_f32_16x16x32_bf16 v[98:101], v[134:137], v[182:185], v[98:101]
	v_mfma_f32_16x16x32_bf16 v[38:41], v[142:145], v[182:185], v[38:41]
	v_mfma_f32_16x16x32_bf16 v[94:97], v[134:137], v[190:193], v[94:97]
	v_mfma_f32_16x16x32_bf16 v[34:37], v[142:145], v[190:193], v[34:37]
	v_mfma_f32_16x16x32_bf16 v[102:105], v[138:141], v[170:173], v[102:105]
	v_mfma_f32_16x16x32_bf16 v[30:33], v[146:149], v[170:173], v[30:33]
	v_mfma_f32_16x16x32_bf16 v[106:109], v[138:141], v[178:181], v[106:109]
	v_mfma_f32_16x16x32_bf16 v[42:45], v[146:149], v[178:181], v[42:45]
	v_mfma_f32_16x16x32_bf16 v[98:101], v[138:141], v[186:189], v[98:101]
	v_mfma_f32_16x16x32_bf16 v[38:41], v[146:149], v[186:189], v[38:41]
	v_mfma_f32_16x16x32_bf16 v[94:97], v[138:141], v[194:197], v[94:97]
	v_mfma_f32_16x16x32_bf16 v[34:37], v[146:149], v[194:197], v[34:37]
	v_mfma_f32_16x16x32_bf16 v[74:77], v[150:153], v[166:169], v[74:77]
	v_mfma_f32_16x16x32_bf16 v[14:17], v[158:161], v[166:169], v[14:17]
	v_mfma_f32_16x16x32_bf16 v[90:93], v[150:153], v[174:177], v[90:93]
	v_mfma_f32_16x16x32_bf16 v[26:29], v[158:161], v[174:177], v[26:29]
	v_mfma_f32_16x16x32_bf16 v[86:89], v[150:153], v[182:185], v[86:89]
	v_mfma_f32_16x16x32_bf16 v[22:25], v[158:161], v[182:185], v[22:25]
	v_mfma_f32_16x16x32_bf16 v[78:81], v[150:153], v[190:193], v[78:81]
	v_mfma_f32_16x16x32_bf16 v[18:21], v[158:161], v[190:193], v[18:21]
	v_mfma_f32_16x16x32_bf16 v[74:77], v[154:157], v[170:173], v[74:77]
	v_mfma_f32_16x16x32_bf16 v[14:17], v[162:165], v[170:173], v[14:17]
	v_mfma_f32_16x16x32_bf16 v[90:93], v[154:157], v[178:181], v[90:93]
	v_mfma_f32_16x16x32_bf16 v[26:29], v[162:165], v[178:181], v[26:29]
	v_mfma_f32_16x16x32_bf16 v[86:89], v[154:157], v[186:189], v[86:89]
	v_mfma_f32_16x16x32_bf16 v[22:25], v[162:165], v[186:189], v[22:25]
	v_mfma_f32_16x16x32_bf16 v[78:81], v[154:157], v[194:197], v[78:81]
	v_mfma_f32_16x16x32_bf16 v[18:21], v[162:165], v[194:197], v[18:21]
	s_setprio 0
	s_barrier
	s_add_i32 s1, 0, 0x18000
	v_add_u32_e32 v2, s1, v226
	s_add_i32 s3, 0, 0x1c000
	ds_read_b128 v[134:137], v2
	ds_read_b128 v[138:141], v2 offset:1024
	ds_read_b128 v[142:145], v2 offset:2048
	ds_read_b128 v[146:149], v2 offset:3072
	v_add_u32_e32 v2, s3, v226
	ds_read_b128 v[150:153], v2
	ds_read_b128 v[154:157], v2 offset:1024
	ds_read_b128 v[158:161], v2 offset:2048
	ds_read_b128 v[162:165], v2 offset:3072
	s_mov_b32 m0, s88
	v_lshl_add_u64 v[8:9], s[76:77], 0, v[198:199]
	s_add_u32 s24, s76, 0x40000
	ds_read_b128 v[166:169], v227 offset:32768
	ds_read_b128 v[170:173], v227 offset:33792
	ds_read_b128 v[174:177], v227 offset:34816
	ds_read_b128 v[178:181], v227 offset:35840
	ds_read_b128 v[182:185], v227 offset:36864
	ds_read_b128 v[186:189], v227 offset:37888
	ds_read_b128 v[190:193], v227 offset:38912
	ds_read_b128 v[194:197], v227 offset:39936
	global_load_lds_dwordx4 v[8:9], off
	v_lshl_add_u64 v[8:9], s[76:77], 0, v[202:203]
	s_mov_b32 m0, s28
	s_addc_u32 s25, s77, 0
	global_load_lds_dwordx4 v[8:9], off
	v_lshl_add_u64 v[8:9], s[24:25], 0, v[198:199]
	s_mov_b32 m0, s29
	s_nop 0
	global_load_lds_dwordx4 v[8:9], off
	v_lshl_add_u64 v[8:9], s[24:25], 0, v[202:203]
	s_mov_b32 m0, s18
	s_nop 0
	global_load_lds_dwordx4 v[8:9], off
	s_waitcnt vmcnt(8)
	s_waitcnt lgkmcnt(0)
	s_barrier
	s_setprio 1
	v_mfma_f32_16x16x32_bf16 v[82:85], v[134:137], v[166:169], v[82:85]
	v_mfma_f32_16x16x32_bf16 v[8:11], v[142:145], v[166:169], v[10:13]
	v_mfma_f32_16x16x32_bf16 v[130:133], v[134:137], v[174:177], v[130:133]
	v_mfma_f32_16x16x32_bf16 v[66:69], v[142:145], v[174:177], v[66:69]
	v_mfma_f32_16x16x32_bf16 v[126:129], v[134:137], v[182:185], v[126:129]
	v_mfma_f32_16x16x32_bf16 v[62:65], v[142:145], v[182:185], v[62:65]
	v_mfma_f32_16x16x32_bf16 v[122:125], v[134:137], v[190:193], v[122:125]
	v_mfma_f32_16x16x32_bf16 v[58:61], v[142:145], v[190:193], v[58:61]
	v_mfma_f32_16x16x32_bf16 v[82:85], v[138:141], v[170:173], v[82:85]
	v_mfma_f32_16x16x32_bf16 v[10:13], v[146:149], v[170:173], v[8:11]
	v_mfma_f32_16x16x32_bf16 v[130:133], v[138:141], v[178:181], v[130:133]
	v_mfma_f32_16x16x32_bf16 v[66:69], v[146:149], v[178:181], v[66:69]
	v_mfma_f32_16x16x32_bf16 v[126:129], v[138:141], v[186:189], v[126:129]
	v_mfma_f32_16x16x32_bf16 v[62:65], v[146:149], v[186:189], v[62:65]
	v_mfma_f32_16x16x32_bf16 v[122:125], v[138:141], v[194:197], v[122:125]
	v_mfma_f32_16x16x32_bf16 v[58:61], v[146:149], v[194:197], v[58:61]
	v_mfma_f32_16x16x32_bf16 v[70:73], v[150:153], v[166:169], v[70:73]
	v_mfma_f32_16x16x32_bf16 v[4:7], v[158:161], v[166:169], v[4:7]
	v_mfma_f32_16x16x32_bf16 v[118:121], v[150:153], v[174:177], v[118:121]
	v_mfma_f32_16x16x32_bf16 v[54:57], v[158:161], v[174:177], v[54:57]
	v_mfma_f32_16x16x32_bf16 v[114:117], v[150:153], v[182:185], v[114:117]
	v_mfma_f32_16x16x32_bf16 v[50:53], v[158:161], v[182:185], v[50:53]
	v_mfma_f32_16x16x32_bf16 v[110:113], v[150:153], v[190:193], v[110:113]
	v_mfma_f32_16x16x32_bf16 v[46:49], v[158:161], v[190:193], v[46:49]
	v_mfma_f32_16x16x32_bf16 v[70:73], v[154:157], v[170:173], v[70:73]
	v_mfma_f32_16x16x32_bf16 v[6:9], v[162:165], v[170:173], v[4:7]
	v_mfma_f32_16x16x32_bf16 v[118:121], v[154:157], v[178:181], v[118:121]
	v_mfma_f32_16x16x32_bf16 v[54:57], v[162:165], v[178:181], v[54:57]
	v_mfma_f32_16x16x32_bf16 v[114:117], v[154:157], v[186:189], v[114:117]
	v_mfma_f32_16x16x32_bf16 v[50:53], v[162:165], v[186:189], v[50:53]
	v_mfma_f32_16x16x32_bf16 v[110:113], v[154:157], v[194:197], v[110:113]
	v_mfma_f32_16x16x32_bf16 v[46:49], v[162:165], v[194:197], v[46:49]
	s_setprio 0
	s_barrier
	s_add_i32 s1, s1, s87
	v_lshl_add_u64 v[4:5], v[224:225], 0, s[44:45]
	s_mov_b32 m0, s1
	ds_read_b128 v[166:169], v227 offset:49152
	ds_read_b128 v[170:173], v227 offset:50176
	ds_read_b128 v[174:177], v227 offset:51200
	ds_read_b128 v[178:181], v227 offset:52224
	ds_read_b128 v[182:185], v227 offset:53248
	ds_read_b128 v[186:189], v227 offset:54272
	ds_read_b128 v[190:193], v227 offset:55296
	ds_read_b128 v[194:197], v227 offset:56320
	global_load_lds_dwordx4 v[4:5], off
	s_add_i32 m0, s1, 0x2000
	s_add_u32 s10, s10, 0x40080
	v_lshl_add_u64 v[4:5], v[246:247], 0, s[44:45]
	s_addc_u32 s11, s11, 0
	s_add_i32 s1, s3, s87
	global_load_lds_dwordx4 v[4:5], off
	v_lshl_add_u64 v[4:5], s[10:11], 0, v[200:201]
	s_mov_b32 m0, s1
	s_nop 0
	global_load_lds_dwordx4 v[4:5], off
	v_lshl_add_u64 v[4:5], s[10:11], 0, v[204:205]
	s_add_i32 m0, s1, 0x2000
	s_nop 0
	global_load_lds_dwordx4 v[4:5], off
	s_waitcnt vmcnt(4)
	s_waitcnt lgkmcnt(0)
	s_barrier
	s_setprio 1
	v_mfma_f32_16x16x32_bf16 v[102:105], v[134:137], v[166:169], v[102:105]
	v_mfma_f32_16x16x32_bf16 v[30:33], v[142:145], v[166:169], v[30:33]
	v_mfma_f32_16x16x32_bf16 v[106:109], v[134:137], v[174:177], v[106:109]
	v_mfma_f32_16x16x32_bf16 v[42:45], v[142:145], v[174:177], v[42:45]
	v_mfma_f32_16x16x32_bf16 v[98:101], v[134:137], v[182:185], v[98:101]
	v_mfma_f32_16x16x32_bf16 v[38:41], v[142:145], v[182:185], v[38:41]
	v_mfma_f32_16x16x32_bf16 v[94:97], v[134:137], v[190:193], v[94:97]
	v_mfma_f32_16x16x32_bf16 v[34:37], v[142:145], v[190:193], v[34:37]
	v_mfma_f32_16x16x32_bf16 v[102:105], v[138:141], v[170:173], v[102:105]
	v_mfma_f32_16x16x32_bf16 v[30:33], v[146:149], v[170:173], v[30:33]
	v_mfma_f32_16x16x32_bf16 v[106:109], v[138:141], v[178:181], v[106:109]
	v_mfma_f32_16x16x32_bf16 v[42:45], v[146:149], v[178:181], v[42:45]
	v_mfma_f32_16x16x32_bf16 v[98:101], v[138:141], v[186:189], v[98:101]
	v_mfma_f32_16x16x32_bf16 v[38:41], v[146:149], v[186:189], v[38:41]
	v_mfma_f32_16x16x32_bf16 v[94:97], v[138:141], v[194:197], v[94:97]
	v_mfma_f32_16x16x32_bf16 v[34:37], v[146:149], v[194:197], v[34:37]
	v_mfma_f32_16x16x32_bf16 v[74:77], v[150:153], v[166:169], v[74:77]
	v_mfma_f32_16x16x32_bf16 v[14:17], v[158:161], v[166:169], v[14:17]
	v_mfma_f32_16x16x32_bf16 v[90:93], v[150:153], v[174:177], v[90:93]
	v_mfma_f32_16x16x32_bf16 v[26:29], v[158:161], v[174:177], v[26:29]
	v_mfma_f32_16x16x32_bf16 v[86:89], v[150:153], v[182:185], v[86:89]
	v_mfma_f32_16x16x32_bf16 v[22:25], v[158:161], v[182:185], v[22:25]
	v_mfma_f32_16x16x32_bf16 v[78:81], v[150:153], v[190:193], v[78:81]
	v_mfma_f32_16x16x32_bf16 v[18:21], v[158:161], v[190:193], v[18:21]
	v_mfma_f32_16x16x32_bf16 v[74:77], v[154:157], v[170:173], v[74:77]
	v_mfma_f32_16x16x32_bf16 v[14:17], v[162:165], v[170:173], v[14:17]
	v_mfma_f32_16x16x32_bf16 v[90:93], v[154:157], v[178:181], v[90:93]
	v_mfma_f32_16x16x32_bf16 v[26:29], v[162:165], v[178:181], v[26:29]
	v_mfma_f32_16x16x32_bf16 v[86:89], v[154:157], v[186:189], v[86:89]
	v_mfma_f32_16x16x32_bf16 v[22:25], v[162:165], v[186:189], v[22:25]
	v_mfma_f32_16x16x32_bf16 v[78:81], v[154:157], v[194:197], v[78:81]
	v_mfma_f32_16x16x32_bf16 v[18:21], v[162:165], v[194:197], v[18:21]
	s_setprio 0
	s_barrier
	s_add_u32 s8, s8, 0x100
	s_addc_u32 s9, s9, 0
	s_cmp_ge_u32 s78, s17
	s_cbranch_scc0 .LBB0_853
	s_and_b64 vcc, exec, s[72:73]
	s_cbranch_vccz .LBB0_856
	v_add_u32_e32 v2, 0, v226
	v_add_u32_e32 v4, 0x10000, v2
	ds_read_b128 v[134:137], v4
	ds_read_b128 v[138:141], v4 offset:1024
	ds_read_b128 v[142:145], v4 offset:2048
	ds_read_b128 v[146:149], v4 offset:3072
	v_add_u32_e32 v4, 0x14000, v2
	ds_read_b128 v[150:153], v4
	ds_read_b128 v[154:157], v4 offset:1024
	ds_read_b128 v[158:161], v4 offset:2048
	ds_read_b128 v[162:165], v4 offset:3072
	s_mov_b32 m0, s0
	v_lshl_add_u64 v[4:5], s[70:71], 0, v[198:199]
	s_mov_b64 s[0:1], 0x780
	v_lshl_add_u64 v[4:5], v[4:5], 0, s[0:1]
	ds_read_b128 v[166:169], v227
	ds_read_b128 v[170:173], v227 offset:1024
	ds_read_b128 v[174:177], v227 offset:2048
	ds_read_b128 v[178:181], v227 offset:3072
	ds_read_b128 v[182:185], v227 offset:4096
	ds_read_b128 v[186:189], v227 offset:5120
	ds_read_b128 v[190:193], v227 offset:6144
	ds_read_b128 v[194:197], v227 offset:7168
	global_load_lds_dwordx4 v[4:5], off
	v_lshl_add_u64 v[4:5], s[70:71], 0, v[202:203]
	v_lshl_add_u64 v[4:5], v[4:5], 0, s[0:1]
	s_add_u32 s0, s70, 0x40780
	s_mov_b32 m0, s79
	s_addc_u32 s1, s71, 0
	global_load_lds_dwordx4 v[4:5], off
	v_lshl_add_u64 v[4:5], s[0:1], 0, v[198:199]
	s_mov_b32 m0, s22
	s_nop 0
	global_load_lds_dwordx4 v[4:5], off
	v_lshl_add_u64 v[4:5], s[0:1], 0, v[202:203]
	s_mov_b32 m0, s23
	s_nop 0
	global_load_lds_dwordx4 v[4:5], off
	s_waitcnt vmcnt(8)
	s_waitcnt lgkmcnt(0)
	s_barrier
	s_setprio 1
	v_mfma_f32_16x16x32_bf16 v[82:85], v[134:137], v[166:169], v[82:85]
	v_mfma_f32_16x16x32_bf16 v[10:13], v[142:145], v[166:169], v[10:13]
	v_mfma_f32_16x16x32_bf16 v[130:133], v[134:137], v[174:177], v[130:133]
	v_mfma_f32_16x16x32_bf16 v[66:69], v[142:145], v[174:177], v[66:69]
	v_mfma_f32_16x16x32_bf16 v[126:129], v[134:137], v[182:185], v[126:129]
	v_mfma_f32_16x16x32_bf16 v[62:65], v[142:145], v[182:185], v[62:65]
	v_mfma_f32_16x16x32_bf16 v[122:125], v[134:137], v[190:193], v[122:125]
	v_mfma_f32_16x16x32_bf16 v[58:61], v[142:145], v[190:193], v[58:61]
	v_mfma_f32_16x16x32_bf16 v[82:85], v[138:141], v[170:173], v[82:85]
	v_mfma_f32_16x16x32_bf16 v[10:13], v[146:149], v[170:173], v[10:13]
	v_mfma_f32_16x16x32_bf16 v[130:133], v[138:141], v[178:181], v[130:133]
	v_mfma_f32_16x16x32_bf16 v[66:69], v[146:149], v[178:181], v[66:69]
	v_mfma_f32_16x16x32_bf16 v[126:129], v[138:141], v[186:189], v[126:129]
	v_mfma_f32_16x16x32_bf16 v[62:65], v[146:149], v[186:189], v[62:65]
	v_mfma_f32_16x16x32_bf16 v[122:125], v[138:141], v[194:197], v[122:125]
	v_mfma_f32_16x16x32_bf16 v[58:61], v[146:149], v[194:197], v[58:61]
	v_mfma_f32_16x16x32_bf16 v[70:73], v[150:153], v[166:169], v[70:73]
	v_mfma_f32_16x16x32_bf16 v[4:7], v[158:161], v[166:169], v[6:9]
	v_mfma_f32_16x16x32_bf16 v[118:121], v[150:153], v[174:177], v[118:121]
	v_mfma_f32_16x16x32_bf16 v[54:57], v[158:161], v[174:177], v[54:57]
	v_mfma_f32_16x16x32_bf16 v[114:117], v[150:153], v[182:185], v[114:117]
	v_mfma_f32_16x16x32_bf16 v[50:53], v[158:161], v[182:185], v[50:53]
	v_mfma_f32_16x16x32_bf16 v[110:113], v[150:153], v[190:193], v[110:113]
	v_mfma_f32_16x16x32_bf16 v[46:49], v[158:161], v[190:193], v[46:49]
	v_mfma_f32_16x16x32_bf16 v[70:73], v[154:157], v[170:173], v[70:73]
	v_mfma_f32_16x16x32_bf16 v[4:7], v[162:165], v[170:173], v[4:7]
	v_mfma_f32_16x16x32_bf16 v[118:121], v[154:157], v[178:181], v[118:121]
	v_mfma_f32_16x16x32_bf16 v[54:57], v[162:165], v[178:181], v[54:57]
	v_mfma_f32_16x16x32_bf16 v[114:117], v[154:157], v[186:189], v[114:117]
	v_mfma_f32_16x16x32_bf16 v[50:53], v[162:165], v[186:189], v[50:53]
	v_mfma_f32_16x16x32_bf16 v[110:113], v[154:157], v[194:197], v[110:113]
	v_mfma_f32_16x16x32_bf16 v[46:49], v[162:165], v[194:197], v[46:49]
	s_setprio 0
	s_barrier
	ds_read_b128 v[166:169], v227 offset:16384
	ds_read_b128 v[170:173], v227 offset:17408
	ds_read_b128 v[174:177], v227 offset:18432
	ds_read_b128 v[178:181], v227 offset:19456
	ds_read_b128 v[182:185], v227 offset:20480
	ds_read_b128 v[186:189], v227 offset:21504
	ds_read_b128 v[190:193], v227 offset:22528
	ds_read_b128 v[194:197], v227 offset:23552
	s_waitcnt vmcnt(0)
	s_waitcnt lgkmcnt(0)
	s_barrier
	s_setprio 1
	v_mfma_f32_16x16x32_bf16 v[102:105], v[134:137], v[166:169], v[102:105]
	v_mfma_f32_16x16x32_bf16 v[30:33], v[142:145], v[166:169], v[30:33]
	v_mfma_f32_16x16x32_bf16 v[106:109], v[134:137], v[174:177], v[106:109]
	v_mfma_f32_16x16x32_bf16 v[42:45], v[142:145], v[174:177], v[42:45]
	v_mfma_f32_16x16x32_bf16 v[98:101], v[134:137], v[182:185], v[98:101]
	v_mfma_f32_16x16x32_bf16 v[38:41], v[142:145], v[182:185], v[38:41]
	v_mfma_f32_16x16x32_bf16 v[94:97], v[134:137], v[190:193], v[94:97]
	v_mfma_f32_16x16x32_bf16 v[34:37], v[142:145], v[190:193], v[34:37]
	v_mfma_f32_16x16x32_bf16 v[102:105], v[138:141], v[170:173], v[102:105]
	v_mfma_f32_16x16x32_bf16 v[30:33], v[146:149], v[170:173], v[30:33]
	v_mfma_f32_16x16x32_bf16 v[106:109], v[138:141], v[178:181], v[106:109]
	v_mfma_f32_16x16x32_bf16 v[42:45], v[146:149], v[178:181], v[42:45]
	v_mfma_f32_16x16x32_bf16 v[98:101], v[138:141], v[186:189], v[98:101]
	v_mfma_f32_16x16x32_bf16 v[38:41], v[146:149], v[186:189], v[38:41]
	v_mfma_f32_16x16x32_bf16 v[94:97], v[138:141], v[194:197], v[94:97]
	v_mfma_f32_16x16x32_bf16 v[34:37], v[146:149], v[194:197], v[34:37]
	v_mfma_f32_16x16x32_bf16 v[74:77], v[150:153], v[166:169], v[74:77]
	v_mfma_f32_16x16x32_bf16 v[14:17], v[158:161], v[166:169], v[14:17]
	v_mfma_f32_16x16x32_bf16 v[90:93], v[150:153], v[174:177], v[90:93]
	v_mfma_f32_16x16x32_bf16 v[26:29], v[158:161], v[174:177], v[26:29]
	v_mfma_f32_16x16x32_bf16 v[86:89], v[150:153], v[182:185], v[86:89]
	v_mfma_f32_16x16x32_bf16 v[22:25], v[158:161], v[182:185], v[22:25]
	v_mfma_f32_16x16x32_bf16 v[78:81], v[150:153], v[190:193], v[78:81]
	v_mfma_f32_16x16x32_bf16 v[18:21], v[158:161], v[190:193], v[18:21]
	v_mfma_f32_16x16x32_bf16 v[74:77], v[154:157], v[170:173], v[74:77]
	v_mfma_f32_16x16x32_bf16 v[14:17], v[162:165], v[170:173], v[14:17]
	v_mfma_f32_16x16x32_bf16 v[90:93], v[154:157], v[178:181], v[90:93]
	v_mfma_f32_16x16x32_bf16 v[26:29], v[162:165], v[178:181], v[26:29]
	v_mfma_f32_16x16x32_bf16 v[86:89], v[154:157], v[186:189], v[86:89]
	v_mfma_f32_16x16x32_bf16 v[22:25], v[162:165], v[186:189], v[22:25]
	v_mfma_f32_16x16x32_bf16 v[78:81], v[154:157], v[194:197], v[78:81]
	v_mfma_f32_16x16x32_bf16 v[18:21], v[162:165], v[194:197], v[18:21]
	s_setprio 0
	s_barrier
	v_add_u32_e32 v8, 0x18000, v2
	v_add_u32_e32 v2, 0x1c000, v2
	ds_read_b128 v[134:137], v8
	ds_read_b128 v[138:141], v8 offset:1024
	ds_read_b128 v[142:145], v8 offset:2048
	ds_read_b128 v[146:149], v8 offset:3072
	ds_read_b128 v[150:153], v2
	ds_read_b128 v[154:157], v2 offset:1024
	ds_read_b128 v[158:161], v2 offset:2048
	ds_read_b128 v[162:165], v2 offset:3072
	ds_read_b128 v[166:169], v227 offset:32768
	ds_read_b128 v[170:173], v227 offset:33792
	ds_read_b128 v[174:177], v227 offset:34816
	ds_read_b128 v[178:181], v227 offset:35840
	ds_read_b128 v[182:185], v227 offset:36864
	ds_read_b128 v[186:189], v227 offset:37888
	ds_read_b128 v[190:193], v227 offset:38912
	ds_read_b128 v[194:197], v227 offset:39936
	s_waitcnt lgkmcnt(0)
	s_barrier
	s_setprio 1
	v_mfma_f32_16x16x32_bf16 v[82:85], v[134:137], v[166:169], v[82:85]
	v_mfma_f32_16x16x32_bf16 v[8:11], v[142:145], v[166:169], v[10:13]
	v_mfma_f32_16x16x32_bf16 v[130:133], v[134:137], v[174:177], v[130:133]
	v_mfma_f32_16x16x32_bf16 v[66:69], v[142:145], v[174:177], v[66:69]
	v_mfma_f32_16x16x32_bf16 v[126:129], v[134:137], v[182:185], v[126:129]
	v_mfma_f32_16x16x32_bf16 v[62:65], v[142:145], v[182:185], v[62:65]
	v_mfma_f32_16x16x32_bf16 v[122:125], v[134:137], v[190:193], v[122:125]
	v_mfma_f32_16x16x32_bf16 v[58:61], v[142:145], v[190:193], v[58:61]
	v_mfma_f32_16x16x32_bf16 v[82:85], v[138:141], v[170:173], v[82:85]
	v_mfma_f32_16x16x32_bf16 v[10:13], v[146:149], v[170:173], v[8:11]
	v_mfma_f32_16x16x32_bf16 v[130:133], v[138:141], v[178:181], v[130:133]
	v_mfma_f32_16x16x32_bf16 v[66:69], v[146:149], v[178:181], v[66:69]
	v_mfma_f32_16x16x32_bf16 v[126:129], v[138:141], v[186:189], v[126:129]
	v_mfma_f32_16x16x32_bf16 v[62:65], v[146:149], v[186:189], v[62:65]
	v_mfma_f32_16x16x32_bf16 v[122:125], v[138:141], v[194:197], v[122:125]
	v_mfma_f32_16x16x32_bf16 v[58:61], v[146:149], v[194:197], v[58:61]
	v_mfma_f32_16x16x32_bf16 v[70:73], v[150:153], v[166:169], v[70:73]
	v_mfma_f32_16x16x32_bf16 v[4:7], v[158:161], v[166:169], v[4:7]
	v_mfma_f32_16x16x32_bf16 v[118:121], v[150:153], v[174:177], v[118:121]
	v_mfma_f32_16x16x32_bf16 v[54:57], v[158:161], v[174:177], v[54:57]
	v_mfma_f32_16x16x32_bf16 v[114:117], v[150:153], v[182:185], v[114:117]
	v_mfma_f32_16x16x32_bf16 v[50:53], v[158:161], v[182:185], v[50:53]
	v_mfma_f32_16x16x32_bf16 v[110:113], v[150:153], v[190:193], v[110:113]
	v_mfma_f32_16x16x32_bf16 v[46:49], v[158:161], v[190:193], v[46:49]
	v_mfma_f32_16x16x32_bf16 v[70:73], v[154:157], v[170:173], v[70:73]
	v_mfma_f32_16x16x32_bf16 v[6:9], v[162:165], v[170:173], v[4:7]
	v_mfma_f32_16x16x32_bf16 v[118:121], v[154:157], v[178:181], v[118:121]
	v_mfma_f32_16x16x32_bf16 v[54:57], v[162:165], v[178:181], v[54:57]
	v_mfma_f32_16x16x32_bf16 v[114:117], v[154:157], v[186:189], v[114:117]
	v_mfma_f32_16x16x32_bf16 v[50:53], v[162:165], v[186:189], v[50:53]
	v_mfma_f32_16x16x32_bf16 v[110:113], v[154:157], v[194:197], v[110:113]
	v_mfma_f32_16x16x32_bf16 v[46:49], v[162:165], v[194:197], v[46:49]
	s_setprio 0
	s_barrier
	ds_read_b128 v[166:169], v227 offset:49152
	ds_read_b128 v[170:173], v227 offset:50176
	ds_read_b128 v[174:177], v227 offset:51200
	ds_read_b128 v[178:181], v227 offset:52224
	ds_read_b128 v[182:185], v227 offset:53248
	ds_read_b128 v[186:189], v227 offset:54272
	ds_read_b128 v[190:193], v227 offset:55296
	ds_read_b128 v[194:197], v227 offset:56320
	s_waitcnt lgkmcnt(0)
	s_barrier
	s_setprio 1
	v_mfma_f32_16x16x32_bf16 v[102:105], v[134:137], v[166:169], v[102:105]
	v_mfma_f32_16x16x32_bf16 v[30:33], v[142:145], v[166:169], v[30:33]
	v_mfma_f32_16x16x32_bf16 v[106:109], v[134:137], v[174:177], v[106:109]
	v_mfma_f32_16x16x32_bf16 v[42:45], v[142:145], v[174:177], v[42:45]
	v_mfma_f32_16x16x32_bf16 v[98:101], v[134:137], v[182:185], v[98:101]
	v_mfma_f32_16x16x32_bf16 v[38:41], v[142:145], v[182:185], v[38:41]
	v_mfma_f32_16x16x32_bf16 v[94:97], v[134:137], v[190:193], v[94:97]
	v_mfma_f32_16x16x32_bf16 v[34:37], v[142:145], v[190:193], v[34:37]
	v_mfma_f32_16x16x32_bf16 v[102:105], v[138:141], v[170:173], v[102:105]
	v_mfma_f32_16x16x32_bf16 v[30:33], v[146:149], v[170:173], v[30:33]
	v_mfma_f32_16x16x32_bf16 v[106:109], v[138:141], v[178:181], v[106:109]
	v_mfma_f32_16x16x32_bf16 v[42:45], v[146:149], v[178:181], v[42:45]
	v_mfma_f32_16x16x32_bf16 v[98:101], v[138:141], v[186:189], v[98:101]
	v_mfma_f32_16x16x32_bf16 v[38:41], v[146:149], v[186:189], v[38:41]
	v_mfma_f32_16x16x32_bf16 v[94:97], v[138:141], v[194:197], v[94:97]
	v_mfma_f32_16x16x32_bf16 v[34:37], v[146:149], v[194:197], v[34:37]
	v_mfma_f32_16x16x32_bf16 v[74:77], v[150:153], v[166:169], v[74:77]
	v_mfma_f32_16x16x32_bf16 v[14:17], v[158:161], v[166:169], v[14:17]
	v_mfma_f32_16x16x32_bf16 v[90:93], v[150:153], v[174:177], v[90:93]
	v_mfma_f32_16x16x32_bf16 v[26:29], v[158:161], v[174:177], v[26:29]
	v_mfma_f32_16x16x32_bf16 v[86:89], v[150:153], v[182:185], v[86:89]
	v_mfma_f32_16x16x32_bf16 v[22:25], v[158:161], v[182:185], v[22:25]
	v_mfma_f32_16x16x32_bf16 v[78:81], v[150:153], v[190:193], v[78:81]
	v_mfma_f32_16x16x32_bf16 v[18:21], v[158:161], v[190:193], v[18:21]
	v_mfma_f32_16x16x32_bf16 v[74:77], v[154:157], v[170:173], v[74:77]
	v_mfma_f32_16x16x32_bf16 v[14:17], v[162:165], v[170:173], v[14:17]
	v_mfma_f32_16x16x32_bf16 v[90:93], v[154:157], v[178:181], v[90:93]
	v_mfma_f32_16x16x32_bf16 v[26:29], v[162:165], v[178:181], v[26:29]
	v_mfma_f32_16x16x32_bf16 v[86:89], v[154:157], v[186:189], v[86:89]
	v_mfma_f32_16x16x32_bf16 v[22:25], v[162:165], v[186:189], v[22:25]
	v_mfma_f32_16x16x32_bf16 v[78:81], v[154:157], v[194:197], v[78:81]
	v_mfma_f32_16x16x32_bf16 v[18:21], v[162:165], v[194:197], v[18:21]
	s_setprio 0
	s_barrier

.LBB0_1036:
	v_add_u32_e32 v11, s38, v152
	s_add_i32 s1, s1, 2
	ds_read_b128 v[156:159], v11
	ds_read_b128 v[160:163], v11 offset:1024
	ds_read_b128 v[164:167], v11 offset:2048
	ds_read_b128 v[168:171], v11 offset:3072
	v_add_u32_e32 v11, s39, v152
	s_add_u32 s3, s14, s58
	ds_read_b128 v[172:175], v11
	ds_read_b128 v[176:179], v11 offset:1024
	ds_read_b128 v[184:187], v11 offset:2048
	ds_read_b128 v[188:191], v11 offset:3072
	s_addc_u32 s22, s15, s59
	s_add_u32 s3, s3, 0x100
	s_addc_u32 s22, s22, 0
	s_add_u32 s23, s53, s58
	s_addc_u32 s24, s64, s59
	s_cmpk_eq_i32 s58, 0x1500
	s_cselect_b32 s61, s57, s24
	s_cselect_b32 s60, s56, s23
	s_cselect_b32 s63, s55, s22
	s_cselect_b32 s62, s54, s3
	v_lshl_add_u64 v[180:181], v[150:151], 0, s[58:59]
	s_add_i32 s24, s31, 0x8000
	v_lshl_add_u64 v[216:217], v[180:181], 0, s[42:43]
	s_mov_b32 m0, s24
	ds_read_b128 v[192:195], v154
	ds_read_b128 v[196:199], v154 offset:1024
	ds_read_b128 v[200:203], v154 offset:2048
	ds_read_b128 v[204:207], v154 offset:3072
	ds_read_b128 v[208:211], v154 offset:4096
	ds_read_b128 v[212:215], v154 offset:5120
	ds_read_b128 v[220:223], v154 offset:6144
	ds_read_b128 v[224:227], v154 offset:7168
	global_load_lds_dwordx4 v[216:217], off
	v_lshl_add_u64 v[216:217], v[12:13], 0, s[58:59]
	s_add_i32 s23, s31, 0xa000
	v_lshl_add_u64 v[228:229], v[216:217], 0, s[42:43]
	s_mov_b32 m0, s23
	s_add_i32 s3, s31, 0xc000
	global_load_lds_dwordx4 v[228:229], off
	v_lshl_add_u64 v[180:181], v[180:181], 0, s[44:45]
	s_mov_b32 m0, s3
	s_add_i32 s22, s31, 0xe000
	global_load_lds_dwordx4 v[180:181], off
	v_lshl_add_u64 v[180:181], v[216:217], 0, s[44:45]
	s_mov_b32 m0, s22
	s_nop 0
	global_load_lds_dwordx4 v[180:181], off
	s_waitcnt vmcnt(8)
	s_waitcnt lgkmcnt(0)
	s_barrier
	s_setprio 1
	v_mfma_f32_16x16x32_bf16 v[126:129], v[156:159], v[192:195], v[126:129]
	v_mfma_f32_16x16x32_bf16 v[122:125], v[164:167], v[192:195], v[122:125]
	v_mfma_f32_16x16x32_bf16 v[106:109], v[156:159], v[200:203], v[106:109]
	v_mfma_f32_16x16x32_bf16 v[110:113], v[164:167], v[200:203], v[110:113]
	v_mfma_f32_16x16x32_bf16 v[90:93], v[156:159], v[208:211], v[90:93]
	v_mfma_f32_16x16x32_bf16 v[94:97], v[164:167], v[208:211], v[94:97]
	v_mfma_f32_16x16x32_bf16 v[74:77], v[156:159], v[220:223], v[74:77]
	v_mfma_f32_16x16x32_bf16 v[78:81], v[164:167], v[220:223], v[78:81]
	v_mfma_f32_16x16x32_bf16 v[126:129], v[160:163], v[196:199], v[126:129]
	v_mfma_f32_16x16x32_bf16 v[122:125], v[168:171], v[196:199], v[122:125]
	v_mfma_f32_16x16x32_bf16 v[106:109], v[160:163], v[204:207], v[106:109]
	v_mfma_f32_16x16x32_bf16 v[110:113], v[168:171], v[204:207], v[110:113]
	v_mfma_f32_16x16x32_bf16 v[90:93], v[160:163], v[212:215], v[90:93]
	v_mfma_f32_16x16x32_bf16 v[94:97], v[168:171], v[212:215], v[94:97]
	v_mfma_f32_16x16x32_bf16 v[74:77], v[160:163], v[224:227], v[74:77]
	v_mfma_f32_16x16x32_bf16 v[78:81], v[168:171], v[224:227], v[78:81]
	v_mfma_f32_16x16x32_bf16 v[58:61], v[172:175], v[192:195], v[58:61]
	v_mfma_f32_16x16x32_bf16 v[62:65], v[184:187], v[192:195], v[62:65]
	v_mfma_f32_16x16x32_bf16 v[42:45], v[172:175], v[200:203], v[42:45]
	v_mfma_f32_16x16x32_bf16 v[46:49], v[184:187], v[200:203], v[46:49]
	v_mfma_f32_16x16x32_bf16 v[26:29], v[172:175], v[208:211], v[26:29]
	v_mfma_f32_16x16x32_bf16 v[30:33], v[184:187], v[208:211], v[30:33]
	v_mfma_f32_16x16x32_bf16 v[130:133], v[172:175], v[220:223], v[130:133]
	v_mfma_f32_16x16x32_bf16 v[14:17], v[184:187], v[220:223], v[14:17]
	v_mfma_f32_16x16x32_bf16 v[58:61], v[176:179], v[196:199], v[58:61]
	v_mfma_f32_16x16x32_bf16 v[62:65], v[188:191], v[196:199], v[62:65]
	v_mfma_f32_16x16x32_bf16 v[42:45], v[176:179], v[204:207], v[42:45]
	v_mfma_f32_16x16x32_bf16 v[46:49], v[188:191], v[204:207], v[46:49]
	v_mfma_f32_16x16x32_bf16 v[26:29], v[176:179], v[212:215], v[26:29]
	v_mfma_f32_16x16x32_bf16 v[30:33], v[188:191], v[212:215], v[30:33]
	v_mfma_f32_16x16x32_bf16 v[130:133], v[176:179], v[224:227], v[130:133]
	v_mfma_f32_16x16x32_bf16 v[14:17], v[188:191], v[224:227], v[14:17]
	s_setprio 0
	s_barrier
	s_add_i32 s25, s38, s30
	v_lshl_add_u64 v[180:181], s[60:61], 0, v[136:137]
	s_mov_b32 m0, s25
	ds_read_b128 v[192:195], v154 offset:16384
	ds_read_b128 v[196:199], v154 offset:17408
	ds_read_b128 v[200:203], v154 offset:18432
	ds_read_b128 v[204:207], v154 offset:19456
	ds_read_b128 v[208:211], v154 offset:20480
	ds_read_b128 v[212:215], v154 offset:21504
	ds_read_b128 v[220:223], v154 offset:22528
	ds_read_b128 v[224:227], v154 offset:23552
	global_load_lds_dwordx4 v[180:181], off
	s_add_i32 m0, s25, 0x2000
	s_add_u32 s26, s60, 0xb0000
	v_lshl_add_u64 v[216:217], s[60:61], 0, v[140:141]
	s_addc_u32 s27, s61, 0
	s_add_i32 s25, s39, s30
	global_load_lds_dwordx4 v[216:217], off
	v_lshl_add_u64 v[228:229], s[26:27], 0, v[136:137]
	s_mov_b32 m0, s25
	s_nop 0
	global_load_lds_dwordx4 v[228:229], off
	v_lshl_add_u64 v[228:229], s[26:27], 0, v[140:141]
	s_add_i32 m0, s25, 0x2000
	s_nop 0
	global_load_lds_dwordx4 v[228:229], off
	s_waitcnt vmcnt(4)
	s_waitcnt lgkmcnt(0)
	s_barrier
	s_setprio 1
	v_mfma_f32_16x16x32_bf16 v[114:117], v[156:159], v[192:195], v[114:117]
	v_mfma_f32_16x16x32_bf16 v[118:121], v[164:167], v[192:195], v[118:121]
	v_mfma_f32_16x16x32_bf16 v[98:101], v[156:159], v[200:203], v[98:101]
	v_mfma_f32_16x16x32_bf16 v[102:105], v[164:167], v[200:203], v[102:105]
	v_mfma_f32_16x16x32_bf16 v[82:85], v[156:159], v[208:211], v[82:85]
	v_mfma_f32_16x16x32_bf16 v[86:89], v[164:167], v[208:211], v[86:89]
	v_mfma_f32_16x16x32_bf16 v[66:69], v[156:159], v[220:223], v[66:69]
	v_mfma_f32_16x16x32_bf16 v[70:73], v[164:167], v[220:223], v[70:73]
	v_mfma_f32_16x16x32_bf16 v[114:117], v[160:163], v[196:199], v[114:117]
	v_mfma_f32_16x16x32_bf16 v[118:121], v[168:171], v[196:199], v[118:121]
	v_mfma_f32_16x16x32_bf16 v[98:101], v[160:163], v[204:207], v[98:101]
	v_mfma_f32_16x16x32_bf16 v[102:105], v[168:171], v[204:207], v[102:105]
	v_mfma_f32_16x16x32_bf16 v[82:85], v[160:163], v[212:215], v[82:85]
	v_mfma_f32_16x16x32_bf16 v[86:89], v[168:171], v[212:215], v[86:89]
	v_mfma_f32_16x16x32_bf16 v[66:69], v[160:163], v[224:227], v[66:69]
	v_mfma_f32_16x16x32_bf16 v[70:73], v[168:171], v[224:227], v[70:73]
	v_mfma_f32_16x16x32_bf16 v[50:53], v[172:175], v[192:195], v[50:53]
	v_mfma_f32_16x16x32_bf16 v[54:57], v[184:187], v[192:195], v[54:57]
	v_mfma_f32_16x16x32_bf16 v[34:37], v[172:175], v[200:203], v[34:37]
	v_mfma_f32_16x16x32_bf16 v[38:41], v[184:187], v[200:203], v[38:41]
	v_mfma_f32_16x16x32_bf16 v[18:21], v[172:175], v[208:211], v[18:21]
	v_mfma_f32_16x16x32_bf16 v[22:25], v[184:187], v[208:211], v[22:25]
	v_mfma_f32_16x16x32_bf16 v[6:9], v[172:175], v[220:223], v[6:9]
	v_mfma_f32_16x16x32_bf16 v[2:5], v[184:187], v[220:223], v[2:5]
	v_mfma_f32_16x16x32_bf16 v[50:53], v[176:179], v[196:199], v[50:53]
	v_mfma_f32_16x16x32_bf16 v[54:57], v[188:191], v[196:199], v[54:57]
	v_mfma_f32_16x16x32_bf16 v[34:37], v[176:179], v[204:207], v[34:37]
	v_mfma_f32_16x16x32_bf16 v[38:41], v[188:191], v[204:207], v[38:41]
	v_mfma_f32_16x16x32_bf16 v[18:21], v[176:179], v[212:215], v[18:21]
	v_mfma_f32_16x16x32_bf16 v[22:25], v[188:191], v[212:215], v[22:25]
	v_mfma_f32_16x16x32_bf16 v[6:9], v[176:179], v[224:227], v[6:9]
	v_mfma_f32_16x16x32_bf16 v[2:5], v[188:191], v[224:227], v[2:5]
	s_setprio 0
	s_barrier
	s_add_i32 s25, 0, 0x18000
	v_add_u32_e32 v11, s25, v152
	s_add_i32 s65, 0, 0x1c000
	ds_read_b128 v[156:159], v11
	ds_read_b128 v[160:163], v11 offset:1024
	ds_read_b128 v[164:167], v11 offset:2048
	ds_read_b128 v[168:171], v11 offset:3072
	v_add_u32_e32 v11, s65, v152
	ds_read_b128 v[172:175], v11
	ds_read_b128 v[176:179], v11 offset:1024
	ds_read_b128 v[184:187], v11 offset:2048
	ds_read_b128 v[188:191], v11 offset:3072
	s_mov_b32 m0, s31
	v_lshl_add_u64 v[228:229], s[62:63], 0, v[134:135]
	s_add_u32 s26, s62, 0xb0000
	ds_read_b128 v[192:195], v154 offset:32768
	ds_read_b128 v[196:199], v154 offset:33792
	ds_read_b128 v[200:203], v154 offset:34816
	ds_read_b128 v[204:207], v154 offset:35840
	ds_read_b128 v[208:211], v154 offset:36864
	ds_read_b128 v[212:215], v154 offset:37888
	ds_read_b128 v[220:223], v154 offset:38912
	ds_read_b128 v[224:227], v154 offset:39936
	global_load_lds_dwordx4 v[228:229], off
	v_lshl_add_u64 v[228:229], s[62:63], 0, v[138:139]
	s_mov_b32 m0, s33
	s_addc_u32 s27, s63, 0
	global_load_lds_dwordx4 v[228:229], off
	v_lshl_add_u64 v[228:229], s[26:27], 0, v[134:135]
	s_mov_b32 m0, s36
	s_nop 0
	global_load_lds_dwordx4 v[228:229], off
	v_lshl_add_u64 v[228:229], s[26:27], 0, v[138:139]
	s_mov_b32 m0, s37
	s_nop 0
	global_load_lds_dwordx4 v[228:229], off
	s_waitcnt vmcnt(8)
	s_waitcnt lgkmcnt(0)
	s_barrier
	s_setprio 1
	v_mfma_f32_16x16x32_bf16 v[126:129], v[156:159], v[192:195], v[126:129]
	v_mfma_f32_16x16x32_bf16 v[122:125], v[164:167], v[192:195], v[122:125]
	v_mfma_f32_16x16x32_bf16 v[106:109], v[156:159], v[200:203], v[106:109]
	v_mfma_f32_16x16x32_bf16 v[110:113], v[164:167], v[200:203], v[110:113]
	v_mfma_f32_16x16x32_bf16 v[90:93], v[156:159], v[208:211], v[90:93]
	v_mfma_f32_16x16x32_bf16 v[94:97], v[164:167], v[208:211], v[94:97]
	v_mfma_f32_16x16x32_bf16 v[74:77], v[156:159], v[220:223], v[74:77]
	v_mfma_f32_16x16x32_bf16 v[78:81], v[164:167], v[220:223], v[78:81]
	v_mfma_f32_16x16x32_bf16 v[126:129], v[160:163], v[196:199], v[126:129]
	v_mfma_f32_16x16x32_bf16 v[122:125], v[168:171], v[196:199], v[122:125]
	v_mfma_f32_16x16x32_bf16 v[106:109], v[160:163], v[204:207], v[106:109]
	v_mfma_f32_16x16x32_bf16 v[110:113], v[168:171], v[204:207], v[110:113]
	v_mfma_f32_16x16x32_bf16 v[90:93], v[160:163], v[212:215], v[90:93]
	v_mfma_f32_16x16x32_bf16 v[94:97], v[168:171], v[212:215], v[94:97]
	v_mfma_f32_16x16x32_bf16 v[74:77], v[160:163], v[224:227], v[74:77]
	v_mfma_f32_16x16x32_bf16 v[78:81], v[168:171], v[224:227], v[78:81]
	v_mfma_f32_16x16x32_bf16 v[58:61], v[172:175], v[192:195], v[58:61]
	v_mfma_f32_16x16x32_bf16 v[62:65], v[184:187], v[192:195], v[62:65]
	v_mfma_f32_16x16x32_bf16 v[42:45], v[172:175], v[200:203], v[42:45]
	v_mfma_f32_16x16x32_bf16 v[46:49], v[184:187], v[200:203], v[46:49]
	v_mfma_f32_16x16x32_bf16 v[26:29], v[172:175], v[208:211], v[26:29]
	v_mfma_f32_16x16x32_bf16 v[30:33], v[184:187], v[208:211], v[30:33]
	v_mfma_f32_16x16x32_bf16 v[130:133], v[172:175], v[220:223], v[130:133]
	v_mfma_f32_16x16x32_bf16 v[14:17], v[184:187], v[220:223], v[14:17]
	v_mfma_f32_16x16x32_bf16 v[58:61], v[176:179], v[196:199], v[58:61]
	v_mfma_f32_16x16x32_bf16 v[62:65], v[188:191], v[196:199], v[62:65]
	v_mfma_f32_16x16x32_bf16 v[42:45], v[176:179], v[204:207], v[42:45]
	v_mfma_f32_16x16x32_bf16 v[46:49], v[188:191], v[204:207], v[46:49]
	v_mfma_f32_16x16x32_bf16 v[26:29], v[176:179], v[212:215], v[26:29]
	v_mfma_f32_16x16x32_bf16 v[30:33], v[188:191], v[212:215], v[30:33]
	v_mfma_f32_16x16x32_bf16 v[130:133], v[176:179], v[224:227], v[130:133]
	v_mfma_f32_16x16x32_bf16 v[14:17], v[188:191], v[224:227], v[14:17]
	s_setprio 0
	s_barrier
	s_add_i32 s25, s25, s30
	v_lshl_add_u64 v[180:181], v[180:181], 0, s[42:43]
	s_mov_b32 m0, s25
	ds_read_b128 v[192:195], v154 offset:49152
	ds_read_b128 v[196:199], v154 offset:50176
	ds_read_b128 v[200:203], v154 offset:51200
	ds_read_b128 v[204:207], v154 offset:52224
	ds_read_b128 v[208:211], v154 offset:53248
	ds_read_b128 v[212:215], v154 offset:54272
	ds_read_b128 v[220:223], v154 offset:55296
	ds_read_b128 v[224:227], v154 offset:56320
	global_load_lds_dwordx4 v[180:181], off
	s_add_i32 m0, s25, 0x2000
	s_add_u32 s26, s60, 0xb0080
	v_lshl_add_u64 v[180:181], v[216:217], 0, s[42:43]
	s_addc_u32 s27, s61, 0
	s_add_i32 s25, s65, s30
	global_load_lds_dwordx4 v[180:181], off
	v_lshl_add_u64 v[180:181], s[26:27], 0, v[136:137]
	s_mov_b32 m0, s25
	s_nop 0
	global_load_lds_dwordx4 v[180:181], off
	v_lshl_add_u64 v[180:181], s[26:27], 0, v[140:141]
	s_add_i32 m0, s25, 0x2000
	s_nop 0
	global_load_lds_dwordx4 v[180:181], off
	s_waitcnt vmcnt(4)
	s_waitcnt lgkmcnt(0)
	s_barrier
	s_setprio 1
	v_mfma_f32_16x16x32_bf16 v[114:117], v[156:159], v[192:195], v[114:117]
	v_mfma_f32_16x16x32_bf16 v[118:121], v[164:167], v[192:195], v[118:121]
	v_mfma_f32_16x16x32_bf16 v[98:101], v[156:159], v[200:203], v[98:101]
	v_mfma_f32_16x16x32_bf16 v[102:105], v[164:167], v[200:203], v[102:105]
	v_mfma_f32_16x16x32_bf16 v[82:85], v[156:159], v[208:211], v[82:85]
	v_mfma_f32_16x16x32_bf16 v[86:89], v[164:167], v[208:211], v[86:89]
	v_mfma_f32_16x16x32_bf16 v[66:69], v[156:159], v[220:223], v[66:69]
	v_mfma_f32_16x16x32_bf16 v[70:73], v[164:167], v[220:223], v[70:73]
	v_mfma_f32_16x16x32_bf16 v[114:117], v[160:163], v[196:199], v[114:117]
	v_mfma_f32_16x16x32_bf16 v[118:121], v[168:171], v[196:199], v[118:121]
	v_mfma_f32_16x16x32_bf16 v[98:101], v[160:163], v[204:207], v[98:101]
	v_mfma_f32_16x16x32_bf16 v[102:105], v[168:171], v[204:207], v[102:105]
	v_mfma_f32_16x16x32_bf16 v[82:85], v[160:163], v[212:215], v[82:85]
	v_mfma_f32_16x16x32_bf16 v[86:89], v[168:171], v[212:215], v[86:89]
	v_mfma_f32_16x16x32_bf16 v[66:69], v[160:163], v[224:227], v[66:69]
	v_mfma_f32_16x16x32_bf16 v[70:73], v[168:171], v[224:227], v[70:73]
	v_mfma_f32_16x16x32_bf16 v[50:53], v[172:175], v[192:195], v[50:53]
	v_mfma_f32_16x16x32_bf16 v[54:57], v[184:187], v[192:195], v[54:57]
	v_mfma_f32_16x16x32_bf16 v[34:37], v[172:175], v[200:203], v[34:37]
	v_mfma_f32_16x16x32_bf16 v[38:41], v[184:187], v[200:203], v[38:41]
	v_mfma_f32_16x16x32_bf16 v[18:21], v[172:175], v[208:211], v[18:21]
	v_mfma_f32_16x16x32_bf16 v[22:25], v[184:187], v[208:211], v[22:25]
	v_mfma_f32_16x16x32_bf16 v[6:9], v[172:175], v[220:223], v[6:9]
	v_mfma_f32_16x16x32_bf16 v[2:5], v[184:187], v[220:223], v[2:5]
	v_mfma_f32_16x16x32_bf16 v[50:53], v[176:179], v[196:199], v[50:53]
	v_mfma_f32_16x16x32_bf16 v[54:57], v[188:191], v[196:199], v[54:57]
	v_mfma_f32_16x16x32_bf16 v[34:37], v[176:179], v[204:207], v[34:37]
	v_mfma_f32_16x16x32_bf16 v[38:41], v[188:191], v[204:207], v[38:41]
	v_mfma_f32_16x16x32_bf16 v[18:21], v[176:179], v[212:215], v[18:21]
	v_mfma_f32_16x16x32_bf16 v[22:25], v[188:191], v[212:215], v[22:25]
	v_mfma_f32_16x16x32_bf16 v[6:9], v[176:179], v[224:227], v[6:9]
	v_mfma_f32_16x16x32_bf16 v[2:5], v[188:191], v[224:227], v[2:5]
	s_setprio 0
	s_barrier
	s_add_u32 s58, s58, 0x100
	s_addc_u32 s59, s59, 0
	s_cmp_ge_u32 s1, s0
	s_cbranch_scc0 .LBB0_1036
	s_and_b64 vcc, exec, s[4:5]
	s_cbranch_vccz .LBB0_1040
	v_add_u32_e32 v11, 0, v152
	v_add_u32_e32 v12, 0x10000, v11
	ds_read_b128 v[156:159], v12
	ds_read_b128 v[160:163], v12 offset:1024
	ds_read_b128 v[164:167], v12 offset:2048
	ds_read_b128 v[168:171], v12 offset:3072
	v_add_u32_e32 v12, 0x14000, v11
	ds_read_b128 v[172:175], v12
	ds_read_b128 v[176:179], v12 offset:1024
	ds_read_b128 v[184:187], v12 offset:2048
	ds_read_b128 v[188:191], v12 offset:3072
	s_add_u32 s0, s14, 0x1580
	s_addc_u32 s1, s15, 0
	s_mov_b32 m0, s24
	v_lshl_add_u64 v[12:13], s[0:1], 0, v[134:135]
	ds_read_b128 v[192:195], v154
	ds_read_b128 v[196:199], v154 offset:1024
	ds_read_b128 v[200:203], v154 offset:2048
	ds_read_b128 v[204:207], v154 offset:3072
	ds_read_b128 v[208:211], v154 offset:4096
	ds_read_b128 v[212:215], v154 offset:5120
	ds_read_b128 v[220:223], v154 offset:6144
	ds_read_b128 v[224:227], v154 offset:7168
	global_load_lds_dwordx4 v[12:13], off
	v_lshl_add_u64 v[12:13], s[0:1], 0, v[138:139]
	s_add_u32 s0, s14, 0xb1580
	s_mov_b32 m0, s23
	s_addc_u32 s1, s15, 0
	global_load_lds_dwordx4 v[12:13], off
	v_lshl_add_u64 v[12:13], s[0:1], 0, v[134:135]
	s_mov_b32 m0, s3
	s_nop 0
	global_load_lds_dwordx4 v[12:13], off
	v_lshl_add_u64 v[12:13], s[0:1], 0, v[138:139]
	s_mov_b32 m0, s22
	s_nop 0
	global_load_lds_dwordx4 v[12:13], off
	s_waitcnt vmcnt(8)
	s_waitcnt lgkmcnt(0)
	s_barrier
	s_setprio 1
	v_mfma_f32_16x16x32_bf16 v[126:129], v[156:159], v[192:195], v[126:129]
	v_mfma_f32_16x16x32_bf16 v[122:125], v[164:167], v[192:195], v[122:125]
	v_mfma_f32_16x16x32_bf16 v[106:109], v[156:159], v[200:203], v[106:109]
	v_mfma_f32_16x16x32_bf16 v[110:113], v[164:167], v[200:203], v[110:113]
	v_mfma_f32_16x16x32_bf16 v[90:93], v[156:159], v[208:211], v[90:93]
	v_mfma_f32_16x16x32_bf16 v[94:97], v[164:167], v[208:211], v[94:97]
	v_mfma_f32_16x16x32_bf16 v[74:77], v[156:159], v[220:223], v[74:77]
	v_mfma_f32_16x16x32_bf16 v[78:81], v[164:167], v[220:223], v[78:81]
	v_mfma_f32_16x16x32_bf16 v[126:129], v[160:163], v[196:199], v[126:129]
	v_mfma_f32_16x16x32_bf16 v[122:125], v[168:171], v[196:199], v[122:125]
	v_mfma_f32_16x16x32_bf16 v[106:109], v[160:163], v[204:207], v[106:109]
	v_mfma_f32_16x16x32_bf16 v[110:113], v[168:171], v[204:207], v[110:113]
	v_mfma_f32_16x16x32_bf16 v[90:93], v[160:163], v[212:215], v[90:93]
	v_mfma_f32_16x16x32_bf16 v[94:97], v[168:171], v[212:215], v[94:97]
	v_mfma_f32_16x16x32_bf16 v[74:77], v[160:163], v[224:227], v[74:77]
	v_mfma_f32_16x16x32_bf16 v[78:81], v[168:171], v[224:227], v[78:81]
	v_mfma_f32_16x16x32_bf16 v[58:61], v[172:175], v[192:195], v[58:61]
	v_mfma_f32_16x16x32_bf16 v[62:65], v[184:187], v[192:195], v[62:65]
	v_mfma_f32_16x16x32_bf16 v[42:45], v[172:175], v[200:203], v[42:45]
	v_mfma_f32_16x16x32_bf16 v[46:49], v[184:187], v[200:203], v[46:49]
	v_mfma_f32_16x16x32_bf16 v[26:29], v[172:175], v[208:211], v[26:29]
	v_mfma_f32_16x16x32_bf16 v[30:33], v[184:187], v[208:211], v[30:33]
	v_mfma_f32_16x16x32_bf16 v[130:133], v[172:175], v[220:223], v[130:133]
	v_mfma_f32_16x16x32_bf16 v[12:15], v[184:187], v[220:223], v[14:17]
	v_mfma_f32_16x16x32_bf16 v[58:61], v[176:179], v[196:199], v[58:61]
	v_mfma_f32_16x16x32_bf16 v[62:65], v[188:191], v[196:199], v[62:65]
	v_mfma_f32_16x16x32_bf16 v[42:45], v[176:179], v[204:207], v[42:45]
	v_mfma_f32_16x16x32_bf16 v[46:49], v[188:191], v[204:207], v[46:49]
	v_mfma_f32_16x16x32_bf16 v[26:29], v[176:179], v[212:215], v[26:29]
	v_mfma_f32_16x16x32_bf16 v[30:33], v[188:191], v[212:215], v[30:33]
	v_mfma_f32_16x16x32_bf16 v[130:133], v[176:179], v[224:227], v[130:133]
	v_mfma_f32_16x16x32_bf16 v[12:15], v[188:191], v[224:227], v[12:15]
	s_setprio 0
	s_barrier
	ds_read_b128 v[192:195], v154 offset:16384
	ds_read_b128 v[196:199], v154 offset:17408
	ds_read_b128 v[200:203], v154 offset:18432
	ds_read_b128 v[204:207], v154 offset:19456
	ds_read_b128 v[208:211], v154 offset:20480
	ds_read_b128 v[212:215], v154 offset:21504
	ds_read_b128 v[220:223], v154 offset:22528
	ds_read_b128 v[224:227], v154 offset:23552
	s_waitcnt vmcnt(0)
	s_waitcnt lgkmcnt(0)
	s_barrier
	s_setprio 1
	v_mfma_f32_16x16x32_bf16 v[114:117], v[156:159], v[192:195], v[114:117]
	v_mfma_f32_16x16x32_bf16 v[118:121], v[164:167], v[192:195], v[118:121]
	v_mfma_f32_16x16x32_bf16 v[98:101], v[156:159], v[200:203], v[98:101]
	v_mfma_f32_16x16x32_bf16 v[102:105], v[164:167], v[200:203], v[102:105]
	v_mfma_f32_16x16x32_bf16 v[82:85], v[156:159], v[208:211], v[82:85]
	v_mfma_f32_16x16x32_bf16 v[86:89], v[164:167], v[208:211], v[86:89]
	v_mfma_f32_16x16x32_bf16 v[66:69], v[156:159], v[220:223], v[66:69]
	v_mfma_f32_16x16x32_bf16 v[70:73], v[164:167], v[220:223], v[70:73]
	v_mfma_f32_16x16x32_bf16 v[114:117], v[160:163], v[196:199], v[114:117]
	v_mfma_f32_16x16x32_bf16 v[118:121], v[168:171], v[196:199], v[118:121]
	v_mfma_f32_16x16x32_bf16 v[98:101], v[160:163], v[204:207], v[98:101]
	v_mfma_f32_16x16x32_bf16 v[102:105], v[168:171], v[204:207], v[102:105]
	v_mfma_f32_16x16x32_bf16 v[82:85], v[160:163], v[212:215], v[82:85]
	v_mfma_f32_16x16x32_bf16 v[86:89], v[168:171], v[212:215], v[86:89]
	v_mfma_f32_16x16x32_bf16 v[66:69], v[160:163], v[224:227], v[66:69]
	v_mfma_f32_16x16x32_bf16 v[70:73], v[168:171], v[224:227], v[70:73]
	v_mfma_f32_16x16x32_bf16 v[50:53], v[172:175], v[192:195], v[50:53]
	v_mfma_f32_16x16x32_bf16 v[54:57], v[184:187], v[192:195], v[54:57]
	v_mfma_f32_16x16x32_bf16 v[34:37], v[172:175], v[200:203], v[34:37]
	v_mfma_f32_16x16x32_bf16 v[38:41], v[184:187], v[200:203], v[38:41]
	v_mfma_f32_16x16x32_bf16 v[16:19], v[172:175], v[208:211], v[18:21]
	v_mfma_f32_16x16x32_bf16 v[22:25], v[184:187], v[208:211], v[22:25]
	v_mfma_f32_16x16x32_bf16 v[6:9], v[172:175], v[220:223], v[6:9]
	v_mfma_f32_16x16x32_bf16 v[2:5], v[184:187], v[220:223], v[2:5]
	v_mfma_f32_16x16x32_bf16 v[50:53], v[176:179], v[196:199], v[50:53]
	v_mfma_f32_16x16x32_bf16 v[54:57], v[188:191], v[196:199], v[54:57]
	v_mfma_f32_16x16x32_bf16 v[34:37], v[176:179], v[204:207], v[34:37]
	v_mfma_f32_16x16x32_bf16 v[38:41], v[188:191], v[204:207], v[38:41]
	v_mfma_f32_16x16x32_bf16 v[18:21], v[176:179], v[212:215], v[16:19]
	v_mfma_f32_16x16x32_bf16 v[22:25], v[188:191], v[212:215], v[22:25]
	v_mfma_f32_16x16x32_bf16 v[6:9], v[176:179], v[224:227], v[6:9]
	v_mfma_f32_16x16x32_bf16 v[2:5], v[188:191], v[224:227], v[2:5]
	s_setprio 0
	s_barrier
	v_add_u32_e32 v16, 0x18000, v11
	v_add_u32_e32 v11, 0x1c000, v11
	ds_read_b128 v[156:159], v16
	ds_read_b128 v[160:163], v16 offset:1024
	ds_read_b128 v[164:167], v16 offset:2048
	ds_read_b128 v[168:171], v16 offset:3072
	ds_read_b128 v[172:175], v11
	ds_read_b128 v[176:179], v11 offset:1024
	ds_read_b128 v[184:187], v11 offset:2048
	ds_read_b128 v[188:191], v11 offset:3072
	ds_read_b128 v[192:195], v154 offset:32768
	ds_read_b128 v[196:199], v154 offset:33792
	ds_read_b128 v[200:203], v154 offset:34816
	ds_read_b128 v[204:207], v154 offset:35840
	ds_read_b128 v[208:211], v154 offset:36864
	ds_read_b128 v[212:215], v154 offset:37888
	ds_read_b128 v[220:223], v154 offset:38912
	ds_read_b128 v[224:227], v154 offset:39936
	s_waitcnt lgkmcnt(0)
	s_barrier
	s_setprio 1
	v_mfma_f32_16x16x32_bf16 v[126:129], v[156:159], v[192:195], v[126:129]
	v_mfma_f32_16x16x32_bf16 v[122:125], v[164:167], v[192:195], v[122:125]
	v_mfma_f32_16x16x32_bf16 v[106:109], v[156:159], v[200:203], v[106:109]
	v_mfma_f32_16x16x32_bf16 v[110:113], v[164:167], v[200:203], v[110:113]
	v_mfma_f32_16x16x32_bf16 v[90:93], v[156:159], v[208:211], v[90:93]
	v_mfma_f32_16x16x32_bf16 v[94:97], v[164:167], v[208:211], v[94:97]
	v_mfma_f32_16x16x32_bf16 v[74:77], v[156:159], v[220:223], v[74:77]
	v_mfma_f32_16x16x32_bf16 v[78:81], v[164:167], v[220:223], v[78:81]
	v_mfma_f32_16x16x32_bf16 v[126:129], v[160:163], v[196:199], v[126:129]
	v_mfma_f32_16x16x32_bf16 v[122:125], v[168:171], v[196:199], v[122:125]
	v_mfma_f32_16x16x32_bf16 v[106:109], v[160:163], v[204:207], v[106:109]
	v_mfma_f32_16x16x32_bf16 v[110:113], v[168:171], v[204:207], v[110:113]
	v_mfma_f32_16x16x32_bf16 v[90:93], v[160:163], v[212:215], v[90:93]
	v_mfma_f32_16x16x32_bf16 v[94:97], v[168:171], v[212:215], v[94:97]
	v_mfma_f32_16x16x32_bf16 v[74:77], v[160:163], v[224:227], v[74:77]
	v_mfma_f32_16x16x32_bf16 v[78:81], v[168:171], v[224:227], v[78:81]
	v_mfma_f32_16x16x32_bf16 v[58:61], v[172:175], v[192:195], v[58:61]
	v_mfma_f32_16x16x32_bf16 v[62:65], v[184:187], v[192:195], v[62:65]
	v_mfma_f32_16x16x32_bf16 v[42:45], v[172:175], v[200:203], v[42:45]
	v_mfma_f32_16x16x32_bf16 v[46:49], v[184:187], v[200:203], v[46:49]
	v_mfma_f32_16x16x32_bf16 v[26:29], v[172:175], v[208:211], v[26:29]
	v_mfma_f32_16x16x32_bf16 v[30:33], v[184:187], v[208:211], v[30:33]
	v_mfma_f32_16x16x32_bf16 v[130:133], v[172:175], v[220:223], v[130:133]
	v_mfma_f32_16x16x32_bf16 v[12:15], v[184:187], v[220:223], v[12:15]
	v_mfma_f32_16x16x32_bf16 v[58:61], v[176:179], v[196:199], v[58:61]
	v_mfma_f32_16x16x32_bf16 v[62:65], v[188:191], v[196:199], v[62:65]
	v_mfma_f32_16x16x32_bf16 v[42:45], v[176:179], v[204:207], v[42:45]
	v_mfma_f32_16x16x32_bf16 v[46:49], v[188:191], v[204:207], v[46:49]
	v_mfma_f32_16x16x32_bf16 v[26:29], v[176:179], v[212:215], v[26:29]
	v_mfma_f32_16x16x32_bf16 v[30:33], v[188:191], v[212:215], v[30:33]
	v_mfma_f32_16x16x32_bf16 v[130:133], v[176:179], v[224:227], v[130:133]
	v_mfma_f32_16x16x32_bf16 v[14:17], v[188:191], v[224:227], v[12:15]
	s_setprio 0
	s_barrier
	ds_read_b128 v[192:195], v154 offset:49152
	ds_read_b128 v[196:199], v154 offset:50176
	ds_read_b128 v[200:203], v154 offset:51200
	ds_read_b128 v[204:207], v154 offset:52224
	ds_read_b128 v[208:211], v154 offset:53248
	ds_read_b128 v[212:215], v154 offset:54272
	ds_read_b128 v[220:223], v154 offset:55296
	ds_read_b128 v[224:227], v154 offset:56320
	s_waitcnt lgkmcnt(0)
	s_barrier
	s_setprio 1
	v_mfma_f32_16x16x32_bf16 v[114:117], v[156:159], v[192:195], v[114:117]
	v_mfma_f32_16x16x32_bf16 v[118:121], v[164:167], v[192:195], v[118:121]
	v_mfma_f32_16x16x32_bf16 v[98:101], v[156:159], v[200:203], v[98:101]
	v_mfma_f32_16x16x32_bf16 v[102:105], v[164:167], v[200:203], v[102:105]
	v_mfma_f32_16x16x32_bf16 v[82:85], v[156:159], v[208:211], v[82:85]
	v_mfma_f32_16x16x32_bf16 v[86:89], v[164:167], v[208:211], v[86:89]
	v_mfma_f32_16x16x32_bf16 v[66:69], v[156:159], v[220:223], v[66:69]
	v_mfma_f32_16x16x32_bf16 v[70:73], v[164:167], v[220:223], v[70:73]
	v_mfma_f32_16x16x32_bf16 v[114:117], v[160:163], v[196:199], v[114:117]
	v_mfma_f32_16x16x32_bf16 v[118:121], v[168:171], v[196:199], v[118:121]
	v_mfma_f32_16x16x32_bf16 v[98:101], v[160:163], v[204:207], v[98:101]
	v_mfma_f32_16x16x32_bf16 v[102:105], v[168:171], v[204:207], v[102:105]
	v_mfma_f32_16x16x32_bf16 v[82:85], v[160:163], v[212:215], v[82:85]
	v_mfma_f32_16x16x32_bf16 v[86:89], v[168:171], v[212:215], v[86:89]
	v_mfma_f32_16x16x32_bf16 v[66:69], v[160:163], v[224:227], v[66:69]
	v_mfma_f32_16x16x32_bf16 v[70:73], v[168:171], v[224:227], v[70:73]
	v_mfma_f32_16x16x32_bf16 v[50:53], v[172:175], v[192:195], v[50:53]
	v_mfma_f32_16x16x32_bf16 v[54:57], v[184:187], v[192:195], v[54:57]
	v_mfma_f32_16x16x32_bf16 v[34:37], v[172:175], v[200:203], v[34:37]
	v_mfma_f32_16x16x32_bf16 v[38:41], v[184:187], v[200:203], v[38:41]
	v_mfma_f32_16x16x32_bf16 v[18:21], v[172:175], v[208:211], v[18:21]
	v_mfma_f32_16x16x32_bf16 v[22:25], v[184:187], v[208:211], v[22:25]
	v_mfma_f32_16x16x32_bf16 v[6:9], v[172:175], v[220:223], v[6:9]
	v_mfma_f32_16x16x32_bf16 v[2:5], v[184:187], v[220:223], v[2:5]
	v_mfma_f32_16x16x32_bf16 v[50:53], v[176:179], v[196:199], v[50:53]
	v_mfma_f32_16x16x32_bf16 v[54:57], v[188:191], v[196:199], v[54:57]
	v_mfma_f32_16x16x32_bf16 v[34:37], v[176:179], v[204:207], v[34:37]
	v_mfma_f32_16x16x32_bf16 v[38:41], v[188:191], v[204:207], v[38:41]
	v_mfma_f32_16x16x32_bf16 v[18:21], v[176:179], v[212:215], v[18:21]
	v_mfma_f32_16x16x32_bf16 v[22:25], v[188:191], v[212:215], v[22:25]
	v_mfma_f32_16x16x32_bf16 v[6:9], v[176:179], v[224:227], v[6:9]
	v_mfma_f32_16x16x32_bf16 v[2:5], v[188:191], v[224:227], v[2:5]
	s_setprio 0
	s_barrier
	s_andn2_b64 vcc, exec, s[48:49]
	s_cbranch_vccz .LBB0_1041

.LBB0_1134:
	s_add_i32 s51, s51, 2
	s_add_u32 s0, s10, s86
	ds_read_b128 v[134:137], v243
	ds_read_b128 v[138:141], v243 offset:1024
	ds_read_b128 v[142:145], v243 offset:2048
	ds_read_b128 v[146:149], v243 offset:3072
	ds_read_b128 v[150:153], v244
	ds_read_b128 v[154:157], v244 offset:1024
	ds_read_b128 v[158:161], v244 offset:2048
	ds_read_b128 v[162:165], v244 offset:3072
	s_addc_u32 s1, s11, s87
	s_add_u32 s0, s0, 0x100
	s_addc_u32 s1, s1, 0
	s_add_u32 s3, s14, s86
	s_addc_u32 s22, s50, s87
	s_cmpk_eq_i32 s86, 0x700
	s_cselect_b32 s89, s83, s22
	s_cselect_b32 s88, s82, s3
	s_cselect_b32 s91, s85, s1
	s_cselect_b32 s90, s84, s0
	v_lshl_add_u64 v[214:215], v[132:133], 0, s[86:87]
	s_add_i32 s0, s21, 0x8000
	v_lshl_add_u64 v[216:217], v[214:215], 0, s[44:45]
	s_mov_b32 m0, s0
	ds_read_b128 v[166:169], v245
	ds_read_b128 v[170:173], v245 offset:1024
	ds_read_b128 v[174:177], v245 offset:2048
	ds_read_b128 v[178:181], v245 offset:3072
	ds_read_b128 v[182:185], v245 offset:4096
	ds_read_b128 v[186:189], v245 offset:5120
	ds_read_b128 v[190:193], v245 offset:6144
	ds_read_b128 v[210:213], v245 offset:7168
	global_load_lds_dwordx4 v[216:217], off
	v_lshl_add_u64 v[216:217], v[130:131], 0, s[86:87]
	s_add_i32 s67, s21, 0xa000
	v_lshl_add_u64 v[218:219], v[216:217], 0, s[44:45]
	s_mov_b32 m0, s67
	s_add_i32 s22, s21, 0xc000
	global_load_lds_dwordx4 v[218:219], off
	v_lshl_add_u64 v[214:215], v[214:215], 0, s[46:47]
	s_mov_b32 m0, s22
	s_add_i32 s23, s21, 0xe000
	global_load_lds_dwordx4 v[214:215], off
	v_lshl_add_u64 v[214:215], v[216:217], 0, s[46:47]
	s_mov_b32 m0, s23
	s_nop 0
	global_load_lds_dwordx4 v[214:215], off
	s_waitcnt vmcnt(8)
	s_waitcnt lgkmcnt(0)
	s_barrier
	s_setprio 1
	v_mfma_f32_16x16x32_bf16 v[118:121], v[134:137], v[166:169], v[118:121]
	v_mfma_f32_16x16x32_bf16 v[114:117], v[142:145], v[166:169], v[114:117]
	v_mfma_f32_16x16x32_bf16 v[62:65], v[134:137], v[174:177], v[62:65]
	v_mfma_f32_16x16x32_bf16 v[58:61], v[142:145], v[174:177], v[58:61]
	v_mfma_f32_16x16x32_bf16 v[54:57], v[134:137], v[182:185], v[54:57]
	v_mfma_f32_16x16x32_bf16 v[50:53], v[142:145], v[182:185], v[50:53]
	v_mfma_f32_16x16x32_bf16 v[126:129], v[134:137], v[190:193], v[126:129]
	v_mfma_f32_16x16x32_bf16 v[102:105], v[142:145], v[190:193], v[102:105]
	v_mfma_f32_16x16x32_bf16 v[118:121], v[138:141], v[170:173], v[118:121]
	v_mfma_f32_16x16x32_bf16 v[114:117], v[146:149], v[170:173], v[114:117]
	v_mfma_f32_16x16x32_bf16 v[62:65], v[138:141], v[178:181], v[62:65]
	v_mfma_f32_16x16x32_bf16 v[58:61], v[146:149], v[178:181], v[58:61]
	v_mfma_f32_16x16x32_bf16 v[54:57], v[138:141], v[186:189], v[54:57]
	v_mfma_f32_16x16x32_bf16 v[50:53], v[146:149], v[186:189], v[50:53]
	v_mfma_f32_16x16x32_bf16 v[126:129], v[138:141], v[210:213], v[126:129]
	v_mfma_f32_16x16x32_bf16 v[102:105], v[146:149], v[210:213], v[102:105]
	v_mfma_f32_16x16x32_bf16 v[110:113], v[150:153], v[166:169], v[110:113]
	v_mfma_f32_16x16x32_bf16 v[106:109], v[158:161], v[166:169], v[106:109]
	v_mfma_f32_16x16x32_bf16 v[46:49], v[150:153], v[174:177], v[46:49]
	v_mfma_f32_16x16x32_bf16 v[42:45], v[158:161], v[174:177], v[42:45]
	v_mfma_f32_16x16x32_bf16 v[38:41], v[150:153], v[182:185], v[38:41]
	v_mfma_f32_16x16x32_bf16 v[34:37], v[158:161], v[182:185], v[34:37]
	v_mfma_f32_16x16x32_bf16 v[122:125], v[150:153], v[190:193], v[122:125]
	v_mfma_f32_16x16x32_bf16 v[98:101], v[158:161], v[190:193], v[98:101]
	v_mfma_f32_16x16x32_bf16 v[110:113], v[154:157], v[170:173], v[110:113]
	v_mfma_f32_16x16x32_bf16 v[106:109], v[162:165], v[170:173], v[106:109]
	v_mfma_f32_16x16x32_bf16 v[46:49], v[154:157], v[178:181], v[46:49]
	v_mfma_f32_16x16x32_bf16 v[42:45], v[162:165], v[178:181], v[42:45]
	v_mfma_f32_16x16x32_bf16 v[38:41], v[154:157], v[186:189], v[38:41]
	v_mfma_f32_16x16x32_bf16 v[34:37], v[162:165], v[186:189], v[34:37]
	v_mfma_f32_16x16x32_bf16 v[122:125], v[154:157], v[210:213], v[122:125]
	v_mfma_f32_16x16x32_bf16 v[98:101], v[162:165], v[210:213], v[98:101]
	s_setprio 0
	s_barrier
	s_add_i32 s1, s36, s20
	v_lshl_add_u64 v[214:215], s[88:89], 0, v[196:197]
	s_mov_b32 m0, s1
	ds_read_b128 v[166:169], v245 offset:16384
	ds_read_b128 v[170:173], v245 offset:17408
	ds_read_b128 v[174:177], v245 offset:18432
	ds_read_b128 v[178:181], v245 offset:19456
	ds_read_b128 v[182:185], v245 offset:20480
	ds_read_b128 v[186:189], v245 offset:21504
	ds_read_b128 v[190:193], v245 offset:22528
	ds_read_b128 v[210:213], v245 offset:23552
	global_load_lds_dwordx4 v[214:215], off
	s_add_i32 m0, s1, 0x2000
	s_add_u32 s24, s88, 0x40000
	v_lshl_add_u64 v[216:217], s[88:89], 0, v[200:201]
	s_addc_u32 s25, s89, 0
	s_add_i32 s1, s37, s20
	global_load_lds_dwordx4 v[216:217], off
	v_lshl_add_u64 v[218:219], s[24:25], 0, v[196:197]
	s_mov_b32 m0, s1
	s_nop 0
	global_load_lds_dwordx4 v[218:219], off
	v_lshl_add_u64 v[218:219], s[24:25], 0, v[200:201]
	s_add_i32 m0, s1, 0x2000
	s_nop 0
	global_load_lds_dwordx4 v[218:219], off
	s_waitcnt vmcnt(4)
	s_waitcnt lgkmcnt(0)
	s_barrier
	s_setprio 1
	v_mfma_f32_16x16x32_bf16 v[94:97], v[134:137], v[166:169], v[94:97]
	v_mfma_f32_16x16x32_bf16 v[90:93], v[142:145], v[166:169], v[90:93]
	v_mfma_f32_16x16x32_bf16 v[30:33], v[134:137], v[174:177], v[30:33]
	v_mfma_f32_16x16x32_bf16 v[26:29], v[142:145], v[174:177], v[26:29]
	v_mfma_f32_16x16x32_bf16 v[22:25], v[134:137], v[182:185], v[22:25]
	v_mfma_f32_16x16x32_bf16 v[18:21], v[142:145], v[182:185], v[18:21]
	v_mfma_f32_16x16x32_bf16 v[82:85], v[134:137], v[190:193], v[82:85]
	v_mfma_f32_16x16x32_bf16 v[74:77], v[142:145], v[190:193], v[74:77]
	v_mfma_f32_16x16x32_bf16 v[94:97], v[138:141], v[170:173], v[94:97]
	v_mfma_f32_16x16x32_bf16 v[90:93], v[146:149], v[170:173], v[90:93]
	v_mfma_f32_16x16x32_bf16 v[30:33], v[138:141], v[178:181], v[30:33]
	v_mfma_f32_16x16x32_bf16 v[26:29], v[146:149], v[178:181], v[26:29]
	v_mfma_f32_16x16x32_bf16 v[22:25], v[138:141], v[186:189], v[22:25]
	v_mfma_f32_16x16x32_bf16 v[18:21], v[146:149], v[186:189], v[18:21]
	v_mfma_f32_16x16x32_bf16 v[82:85], v[138:141], v[210:213], v[82:85]
	v_mfma_f32_16x16x32_bf16 v[74:77], v[146:149], v[210:213], v[74:77]
	v_mfma_f32_16x16x32_bf16 v[86:89], v[150:153], v[166:169], v[86:89]
	v_mfma_f32_16x16x32_bf16 v[78:81], v[158:161], v[166:169], v[78:81]
	v_mfma_f32_16x16x32_bf16 v[14:17], v[150:153], v[174:177], v[14:17]
	v_mfma_f32_16x16x32_bf16 v[10:13], v[158:161], v[174:177], v[10:13]
	v_mfma_f32_16x16x32_bf16 v[6:9], v[150:153], v[182:185], v[6:9]
	v_mfma_f32_16x16x32_bf16 v[2:5], v[158:161], v[182:185], v[2:5]
	v_mfma_f32_16x16x32_bf16 v[70:73], v[150:153], v[190:193], v[70:73]
	v_mfma_f32_16x16x32_bf16 v[66:69], v[158:161], v[190:193], v[66:69]
	v_mfma_f32_16x16x32_bf16 v[86:89], v[154:157], v[170:173], v[86:89]
	v_mfma_f32_16x16x32_bf16 v[78:81], v[162:165], v[170:173], v[78:81]
	v_mfma_f32_16x16x32_bf16 v[14:17], v[154:157], v[178:181], v[14:17]
	v_mfma_f32_16x16x32_bf16 v[10:13], v[162:165], v[178:181], v[10:13]
	v_mfma_f32_16x16x32_bf16 v[6:9], v[154:157], v[186:189], v[6:9]
	v_mfma_f32_16x16x32_bf16 v[2:5], v[162:165], v[186:189], v[2:5]
	v_mfma_f32_16x16x32_bf16 v[70:73], v[154:157], v[210:213], v[70:73]
	v_mfma_f32_16x16x32_bf16 v[66:69], v[162:165], v[210:213], v[66:69]
	s_setprio 0
	s_barrier
	s_add_i32 s1, 0, 0x18000
	s_add_i32 s3, 0, 0x1c000
	v_add_u32_e32 v146, s1, v233
	v_add_u32_e32 v162, s3, v233
	ds_read_b128 v[134:137], v146
	ds_read_b128 v[138:141], v146 offset:1024
	ds_read_b128 v[142:145], v146 offset:2048
	ds_read_b128 v[146:149], v146 offset:3072
	ds_read_b128 v[150:153], v162
	ds_read_b128 v[154:157], v162 offset:1024
	ds_read_b128 v[158:161], v162 offset:2048
	ds_read_b128 v[162:165], v162 offset:3072
	s_mov_b32 m0, s21
	v_lshl_add_u64 v[218:219], s[90:91], 0, v[194:195]
	s_add_u32 s24, s90, 0x40000
	ds_read_b128 v[166:169], v245 offset:32768
	ds_read_b128 v[170:173], v245 offset:33792
	ds_read_b128 v[174:177], v245 offset:34816
	ds_read_b128 v[178:181], v245 offset:35840
	ds_read_b128 v[182:185], v245 offset:36864
	ds_read_b128 v[186:189], v245 offset:37888
	ds_read_b128 v[190:193], v245 offset:38912
	ds_read_b128 v[210:213], v245 offset:39936
	global_load_lds_dwordx4 v[218:219], off
	v_lshl_add_u64 v[218:219], s[90:91], 0, v[198:199]
	s_mov_b32 m0, s28
	s_addc_u32 s25, s91, 0
	global_load_lds_dwordx4 v[218:219], off
	v_lshl_add_u64 v[218:219], s[24:25], 0, v[194:195]
	s_mov_b32 m0, s29
	s_nop 0
	global_load_lds_dwordx4 v[218:219], off
	v_lshl_add_u64 v[218:219], s[24:25], 0, v[198:199]
	s_mov_b32 m0, s30
	s_nop 0
	global_load_lds_dwordx4 v[218:219], off
	s_waitcnt vmcnt(8)
	s_waitcnt lgkmcnt(0)
	s_barrier
	s_setprio 1
	v_mfma_f32_16x16x32_bf16 v[118:121], v[134:137], v[166:169], v[118:121]
	v_mfma_f32_16x16x32_bf16 v[114:117], v[142:145], v[166:169], v[114:117]
	v_mfma_f32_16x16x32_bf16 v[62:65], v[134:137], v[174:177], v[62:65]
	v_mfma_f32_16x16x32_bf16 v[58:61], v[142:145], v[174:177], v[58:61]
	v_mfma_f32_16x16x32_bf16 v[54:57], v[134:137], v[182:185], v[54:57]
	v_mfma_f32_16x16x32_bf16 v[50:53], v[142:145], v[182:185], v[50:53]
	v_mfma_f32_16x16x32_bf16 v[126:129], v[134:137], v[190:193], v[126:129]
	v_mfma_f32_16x16x32_bf16 v[102:105], v[142:145], v[190:193], v[102:105]
	v_mfma_f32_16x16x32_bf16 v[118:121], v[138:141], v[170:173], v[118:121]
	v_mfma_f32_16x16x32_bf16 v[114:117], v[146:149], v[170:173], v[114:117]
	v_mfma_f32_16x16x32_bf16 v[62:65], v[138:141], v[178:181], v[62:65]
	v_mfma_f32_16x16x32_bf16 v[58:61], v[146:149], v[178:181], v[58:61]
	v_mfma_f32_16x16x32_bf16 v[54:57], v[138:141], v[186:189], v[54:57]
	v_mfma_f32_16x16x32_bf16 v[50:53], v[146:149], v[186:189], v[50:53]
	v_mfma_f32_16x16x32_bf16 v[126:129], v[138:141], v[210:213], v[126:129]
	v_mfma_f32_16x16x32_bf16 v[102:105], v[146:149], v[210:213], v[102:105]
	v_mfma_f32_16x16x32_bf16 v[110:113], v[150:153], v[166:169], v[110:113]
	v_mfma_f32_16x16x32_bf16 v[106:109], v[158:161], v[166:169], v[106:109]
	v_mfma_f32_16x16x32_bf16 v[46:49], v[150:153], v[174:177], v[46:49]
	v_mfma_f32_16x16x32_bf16 v[42:45], v[158:161], v[174:177], v[42:45]
	v_mfma_f32_16x16x32_bf16 v[38:41], v[150:153], v[182:185], v[38:41]
	v_mfma_f32_16x16x32_bf16 v[34:37], v[158:161], v[182:185], v[34:37]
	v_mfma_f32_16x16x32_bf16 v[122:125], v[150:153], v[190:193], v[122:125]
	v_mfma_f32_16x16x32_bf16 v[98:101], v[158:161], v[190:193], v[98:101]
	v_mfma_f32_16x16x32_bf16 v[110:113], v[154:157], v[170:173], v[110:113]
	v_mfma_f32_16x16x32_bf16 v[106:109], v[162:165], v[170:173], v[106:109]
	v_mfma_f32_16x16x32_bf16 v[46:49], v[154:157], v[178:181], v[46:49]
	v_mfma_f32_16x16x32_bf16 v[42:45], v[162:165], v[178:181], v[42:45]
	v_mfma_f32_16x16x32_bf16 v[38:41], v[154:157], v[186:189], v[38:41]
	v_mfma_f32_16x16x32_bf16 v[34:37], v[162:165], v[186:189], v[34:37]
	v_mfma_f32_16x16x32_bf16 v[122:125], v[154:157], v[210:213], v[122:125]
	v_mfma_f32_16x16x32_bf16 v[98:101], v[162:165], v[210:213], v[98:101]
	s_setprio 0
	s_barrier
	s_add_i32 s1, s1, s20
	v_lshl_add_u64 v[214:215], v[214:215], 0, s[44:45]
	s_mov_b32 m0, s1
	ds_read_b128 v[166:169], v245 offset:49152
	ds_read_b128 v[170:173], v245 offset:50176
	ds_read_b128 v[174:177], v245 offset:51200
	ds_read_b128 v[178:181], v245 offset:52224
	ds_read_b128 v[182:185], v245 offset:53248
	ds_read_b128 v[186:189], v245 offset:54272
	ds_read_b128 v[190:193], v245 offset:55296
	ds_read_b128 v[210:213], v245 offset:56320
	global_load_lds_dwordx4 v[214:215], off
	s_add_i32 m0, s1, 0x2000
	s_add_u32 s24, s88, 0x40080
	v_lshl_add_u64 v[214:215], v[216:217], 0, s[44:45]
	s_addc_u32 s25, s89, 0
	s_add_i32 s1, s3, s20
	global_load_lds_dwordx4 v[214:215], off
	v_lshl_add_u64 v[214:215], s[24:25], 0, v[196:197]
	s_mov_b32 m0, s1
	s_nop 0
	global_load_lds_dwordx4 v[214:215], off
	v_lshl_add_u64 v[214:215], s[24:25], 0, v[200:201]
	s_add_i32 m0, s1, 0x2000
	s_nop 0
	global_load_lds_dwordx4 v[214:215], off
	s_waitcnt vmcnt(4)
	s_waitcnt lgkmcnt(0)
	s_barrier
	s_setprio 1
	v_mfma_f32_16x16x32_bf16 v[94:97], v[134:137], v[166:169], v[94:97]
	v_mfma_f32_16x16x32_bf16 v[90:93], v[142:145], v[166:169], v[90:93]
	v_mfma_f32_16x16x32_bf16 v[30:33], v[134:137], v[174:177], v[30:33]
	v_mfma_f32_16x16x32_bf16 v[26:29], v[142:145], v[174:177], v[26:29]
	v_mfma_f32_16x16x32_bf16 v[22:25], v[134:137], v[182:185], v[22:25]
	v_mfma_f32_16x16x32_bf16 v[18:21], v[142:145], v[182:185], v[18:21]
	v_mfma_f32_16x16x32_bf16 v[82:85], v[134:137], v[190:193], v[82:85]
	v_mfma_f32_16x16x32_bf16 v[74:77], v[142:145], v[190:193], v[74:77]
	v_mfma_f32_16x16x32_bf16 v[94:97], v[138:141], v[170:173], v[94:97]
	v_mfma_f32_16x16x32_bf16 v[90:93], v[146:149], v[170:173], v[90:93]
	v_mfma_f32_16x16x32_bf16 v[30:33], v[138:141], v[178:181], v[30:33]
	v_mfma_f32_16x16x32_bf16 v[26:29], v[146:149], v[178:181], v[26:29]
	v_mfma_f32_16x16x32_bf16 v[22:25], v[138:141], v[186:189], v[22:25]
	v_mfma_f32_16x16x32_bf16 v[18:21], v[146:149], v[186:189], v[18:21]
	v_mfma_f32_16x16x32_bf16 v[82:85], v[138:141], v[210:213], v[82:85]
	v_mfma_f32_16x16x32_bf16 v[74:77], v[146:149], v[210:213], v[74:77]
	v_mfma_f32_16x16x32_bf16 v[86:89], v[150:153], v[166:169], v[86:89]
	v_mfma_f32_16x16x32_bf16 v[78:81], v[158:161], v[166:169], v[78:81]
	v_mfma_f32_16x16x32_bf16 v[14:17], v[150:153], v[174:177], v[14:17]
	v_mfma_f32_16x16x32_bf16 v[10:13], v[158:161], v[174:177], v[10:13]
	v_mfma_f32_16x16x32_bf16 v[6:9], v[150:153], v[182:185], v[6:9]
	v_mfma_f32_16x16x32_bf16 v[2:5], v[158:161], v[182:185], v[2:5]
	v_mfma_f32_16x16x32_bf16 v[70:73], v[150:153], v[190:193], v[70:73]
	v_mfma_f32_16x16x32_bf16 v[66:69], v[158:161], v[190:193], v[66:69]
	v_mfma_f32_16x16x32_bf16 v[86:89], v[154:157], v[170:173], v[86:89]
	v_mfma_f32_16x16x32_bf16 v[78:81], v[162:165], v[170:173], v[78:81]
	v_mfma_f32_16x16x32_bf16 v[14:17], v[154:157], v[178:181], v[14:17]
	v_mfma_f32_16x16x32_bf16 v[10:13], v[162:165], v[178:181], v[10:13]
	v_mfma_f32_16x16x32_bf16 v[6:9], v[154:157], v[186:189], v[6:9]
	v_mfma_f32_16x16x32_bf16 v[2:5], v[162:165], v[186:189], v[2:5]
	v_mfma_f32_16x16x32_bf16 v[70:73], v[154:157], v[210:213], v[70:73]
	v_mfma_f32_16x16x32_bf16 v[66:69], v[162:165], v[210:213], v[66:69]
	s_setprio 0
	s_barrier
	s_add_u32 s86, s86, 0x100
	s_addc_u32 s87, s87, 0
	s_cmp_ge_u32 s51, s13
	s_cbranch_scc0 .LBB0_1134
	s_and_b64 vcc, exec, s[80:81]
	s_cbranch_vccz .LBB0_1137
	v_add_u32_e32 v202, 0, v233
	v_add_u32_e32 v142, 0x10000, v202
	v_add_u32_e32 v158, 0x14000, v202
	ds_read_b128 v[130:133], v142
	ds_read_b128 v[134:137], v142 offset:1024
	ds_read_b128 v[138:141], v142 offset:2048
	ds_read_b128 v[142:145], v142 offset:3072
	ds_read_b128 v[146:149], v158
	ds_read_b128 v[150:153], v158 offset:1024
	ds_read_b128 v[154:157], v158 offset:2048
	ds_read_b128 v[158:161], v158 offset:3072
	v_lshl_add_u64 v[210:211], s[10:11], 0, v[194:195]
	s_mov_b32 m0, s0
	v_lshl_add_u64 v[210:211], v[210:211], 0, s[26:27]
	ds_read_b128 v[162:165], v245
	ds_read_b128 v[166:169], v245 offset:1024
	ds_read_b128 v[170:173], v245 offset:2048
	ds_read_b128 v[174:177], v245 offset:3072
	ds_read_b128 v[178:181], v245 offset:4096
	ds_read_b128 v[182:185], v245 offset:5120
	ds_read_b128 v[186:189], v245 offset:6144
	ds_read_b128 v[190:193], v245 offset:7168
	global_load_lds_dwordx4 v[210:211], off
	v_lshl_add_u64 v[210:211], s[10:11], 0, v[198:199]
	s_add_u32 s0, s10, 0x40780
	v_lshl_add_u64 v[210:211], v[210:211], 0, s[26:27]
	s_mov_b32 m0, s67
	s_addc_u32 s1, s11, 0
	global_load_lds_dwordx4 v[210:211], off
	v_lshl_add_u64 v[210:211], s[0:1], 0, v[194:195]
	s_mov_b32 m0, s22
	s_nop 0
	global_load_lds_dwordx4 v[210:211], off
	v_lshl_add_u64 v[210:211], s[0:1], 0, v[198:199]
	s_mov_b32 m0, s23
	s_nop 0
	global_load_lds_dwordx4 v[210:211], off
	s_waitcnt vmcnt(8)
	s_waitcnt lgkmcnt(0)
	s_barrier
	s_setprio 1
	v_mfma_f32_16x16x32_bf16 v[118:121], v[130:133], v[162:165], v[118:121]
	v_mfma_f32_16x16x32_bf16 v[114:117], v[138:141], v[162:165], v[114:117]
	v_mfma_f32_16x16x32_bf16 v[62:65], v[130:133], v[170:173], v[62:65]
	v_mfma_f32_16x16x32_bf16 v[58:61], v[138:141], v[170:173], v[58:61]
	v_mfma_f32_16x16x32_bf16 v[54:57], v[130:133], v[178:181], v[54:57]
	v_mfma_f32_16x16x32_bf16 v[50:53], v[138:141], v[178:181], v[50:53]
	v_mfma_f32_16x16x32_bf16 v[126:129], v[130:133], v[186:189], v[126:129]
	v_mfma_f32_16x16x32_bf16 v[102:105], v[138:141], v[186:189], v[102:105]
	v_mfma_f32_16x16x32_bf16 v[118:121], v[134:137], v[166:169], v[118:121]
	v_mfma_f32_16x16x32_bf16 v[114:117], v[142:145], v[166:169], v[114:117]
	v_mfma_f32_16x16x32_bf16 v[62:65], v[134:137], v[174:177], v[62:65]
	v_mfma_f32_16x16x32_bf16 v[58:61], v[142:145], v[174:177], v[58:61]
	v_mfma_f32_16x16x32_bf16 v[54:57], v[134:137], v[182:185], v[54:57]
	v_mfma_f32_16x16x32_bf16 v[50:53], v[142:145], v[182:185], v[50:53]
	v_mfma_f32_16x16x32_bf16 v[126:129], v[134:137], v[190:193], v[126:129]
	v_mfma_f32_16x16x32_bf16 v[102:105], v[142:145], v[190:193], v[102:105]
	v_mfma_f32_16x16x32_bf16 v[110:113], v[146:149], v[162:165], v[110:113]
	v_mfma_f32_16x16x32_bf16 v[106:109], v[154:157], v[162:165], v[106:109]
	v_mfma_f32_16x16x32_bf16 v[46:49], v[146:149], v[170:173], v[46:49]
	v_mfma_f32_16x16x32_bf16 v[42:45], v[154:157], v[170:173], v[42:45]
	v_mfma_f32_16x16x32_bf16 v[38:41], v[146:149], v[178:181], v[38:41]
	v_mfma_f32_16x16x32_bf16 v[34:37], v[154:157], v[178:181], v[34:37]
	v_mfma_f32_16x16x32_bf16 v[122:125], v[146:149], v[186:189], v[122:125]
	v_mfma_f32_16x16x32_bf16 v[98:101], v[154:157], v[186:189], v[98:101]
	v_mfma_f32_16x16x32_bf16 v[110:113], v[150:153], v[166:169], v[110:113]
	v_mfma_f32_16x16x32_bf16 v[106:109], v[158:161], v[166:169], v[106:109]
	v_mfma_f32_16x16x32_bf16 v[46:49], v[150:153], v[174:177], v[46:49]
	v_mfma_f32_16x16x32_bf16 v[42:45], v[158:161], v[174:177], v[42:45]
	v_mfma_f32_16x16x32_bf16 v[38:41], v[150:153], v[182:185], v[38:41]
	v_mfma_f32_16x16x32_bf16 v[34:37], v[158:161], v[182:185], v[34:37]
	v_mfma_f32_16x16x32_bf16 v[122:125], v[150:153], v[190:193], v[122:125]
	v_mfma_f32_16x16x32_bf16 v[98:101], v[158:161], v[190:193], v[98:101]
	s_setprio 0
	s_barrier
	ds_read_b128 v[162:165], v245 offset:16384
	ds_read_b128 v[166:169], v245 offset:17408
	ds_read_b128 v[170:173], v245 offset:18432
	ds_read_b128 v[174:177], v245 offset:19456
	ds_read_b128 v[178:181], v245 offset:20480
	ds_read_b128 v[182:185], v245 offset:21504
	ds_read_b128 v[186:189], v245 offset:22528
	ds_read_b128 v[190:193], v245 offset:23552
	s_waitcnt vmcnt(0)
	s_waitcnt lgkmcnt(0)
	s_barrier
	s_setprio 1
	v_mfma_f32_16x16x32_bf16 v[94:97], v[130:133], v[162:165], v[94:97]
	v_mfma_f32_16x16x32_bf16 v[90:93], v[138:141], v[162:165], v[90:93]
	v_mfma_f32_16x16x32_bf16 v[30:33], v[130:133], v[170:173], v[30:33]
	v_mfma_f32_16x16x32_bf16 v[26:29], v[138:141], v[170:173], v[26:29]
	v_mfma_f32_16x16x32_bf16 v[22:25], v[130:133], v[178:181], v[22:25]
	v_mfma_f32_16x16x32_bf16 v[18:21], v[138:141], v[178:181], v[18:21]
	v_mfma_f32_16x16x32_bf16 v[82:85], v[130:133], v[186:189], v[82:85]
	v_mfma_f32_16x16x32_bf16 v[74:77], v[138:141], v[186:189], v[74:77]
	v_mfma_f32_16x16x32_bf16 v[94:97], v[134:137], v[166:169], v[94:97]
	v_mfma_f32_16x16x32_bf16 v[90:93], v[142:145], v[166:169], v[90:93]
	v_mfma_f32_16x16x32_bf16 v[30:33], v[134:137], v[174:177], v[30:33]
	v_mfma_f32_16x16x32_bf16 v[26:29], v[142:145], v[174:177], v[26:29]
	v_mfma_f32_16x16x32_bf16 v[22:25], v[134:137], v[182:185], v[22:25]
	v_mfma_f32_16x16x32_bf16 v[18:21], v[142:145], v[182:185], v[18:21]
	v_mfma_f32_16x16x32_bf16 v[82:85], v[134:137], v[190:193], v[82:85]
	v_mfma_f32_16x16x32_bf16 v[74:77], v[142:145], v[190:193], v[74:77]
	v_mfma_f32_16x16x32_bf16 v[86:89], v[146:149], v[162:165], v[86:89]
	v_mfma_f32_16x16x32_bf16 v[78:81], v[154:157], v[162:165], v[78:81]
	v_mfma_f32_16x16x32_bf16 v[14:17], v[146:149], v[170:173], v[14:17]
	v_mfma_f32_16x16x32_bf16 v[10:13], v[154:157], v[170:173], v[10:13]
	v_mfma_f32_16x16x32_bf16 v[6:9], v[146:149], v[178:181], v[6:9]
	v_mfma_f32_16x16x32_bf16 v[2:5], v[154:157], v[178:181], v[2:5]
	v_mfma_f32_16x16x32_bf16 v[70:73], v[146:149], v[186:189], v[70:73]
	v_mfma_f32_16x16x32_bf16 v[66:69], v[154:157], v[186:189], v[66:69]
	v_mfma_f32_16x16x32_bf16 v[86:89], v[150:153], v[166:169], v[86:89]
	v_mfma_f32_16x16x32_bf16 v[78:81], v[158:161], v[166:169], v[78:81]
	v_mfma_f32_16x16x32_bf16 v[14:17], v[150:153], v[174:177], v[14:17]
	v_mfma_f32_16x16x32_bf16 v[10:13], v[158:161], v[174:177], v[10:13]
	v_mfma_f32_16x16x32_bf16 v[6:9], v[150:153], v[182:185], v[6:9]
	v_mfma_f32_16x16x32_bf16 v[2:5], v[158:161], v[182:185], v[2:5]
	v_mfma_f32_16x16x32_bf16 v[70:73], v[150:153], v[190:193], v[70:73]
	v_mfma_f32_16x16x32_bf16 v[66:69], v[158:161], v[190:193], v[66:69]
	s_setprio 0
	s_barrier
	v_add_u32_e32 v142, 0x18000, v202
	v_add_u32_e32 v158, 0x1c000, v202
	ds_read_b128 v[130:133], v142
	ds_read_b128 v[134:137], v142 offset:1024
	ds_read_b128 v[138:141], v142 offset:2048
	ds_read_b128 v[142:145], v142 offset:3072
	ds_read_b128 v[146:149], v158
	ds_read_b128 v[150:153], v158 offset:1024
	ds_read_b128 v[154:157], v158 offset:2048
	ds_read_b128 v[158:161], v158 offset:3072
	ds_read_b128 v[162:165], v245 offset:32768
	ds_read_b128 v[166:169], v245 offset:33792
	ds_read_b128 v[170:173], v245 offset:34816
	ds_read_b128 v[174:177], v245 offset:35840
	ds_read_b128 v[178:181], v245 offset:36864
	ds_read_b128 v[182:185], v245 offset:37888
	ds_read_b128 v[186:189], v245 offset:38912
	ds_read_b128 v[190:193], v245 offset:39936
	s_waitcnt lgkmcnt(0)
	s_barrier
	s_setprio 1
	v_mfma_f32_16x16x32_bf16 v[118:121], v[130:133], v[162:165], v[118:121]
	v_mfma_f32_16x16x32_bf16 v[114:117], v[138:141], v[162:165], v[114:117]
	v_mfma_f32_16x16x32_bf16 v[62:65], v[130:133], v[170:173], v[62:65]
	v_mfma_f32_16x16x32_bf16 v[58:61], v[138:141], v[170:173], v[58:61]
	v_mfma_f32_16x16x32_bf16 v[54:57], v[130:133], v[178:181], v[54:57]
	v_mfma_f32_16x16x32_bf16 v[50:53], v[138:141], v[178:181], v[50:53]
	v_mfma_f32_16x16x32_bf16 v[126:129], v[130:133], v[186:189], v[126:129]
	v_mfma_f32_16x16x32_bf16 v[102:105], v[138:141], v[186:189], v[102:105]
	v_mfma_f32_16x16x32_bf16 v[118:121], v[134:137], v[166:169], v[118:121]
	v_mfma_f32_16x16x32_bf16 v[114:117], v[142:145], v[166:169], v[114:117]
	v_mfma_f32_16x16x32_bf16 v[62:65], v[134:137], v[174:177], v[62:65]
	v_mfma_f32_16x16x32_bf16 v[58:61], v[142:145], v[174:177], v[58:61]
	v_mfma_f32_16x16x32_bf16 v[54:57], v[134:137], v[182:185], v[54:57]
	v_mfma_f32_16x16x32_bf16 v[50:53], v[142:145], v[182:185], v[50:53]
	v_mfma_f32_16x16x32_bf16 v[126:129], v[134:137], v[190:193], v[126:129]
	v_mfma_f32_16x16x32_bf16 v[102:105], v[142:145], v[190:193], v[102:105]
	v_mfma_f32_16x16x32_bf16 v[110:113], v[146:149], v[162:165], v[110:113]
	v_mfma_f32_16x16x32_bf16 v[106:109], v[154:157], v[162:165], v[106:109]
	v_mfma_f32_16x16x32_bf16 v[46:49], v[146:149], v[170:173], v[46:49]
	v_mfma_f32_16x16x32_bf16 v[42:45], v[154:157], v[170:173], v[42:45]
	v_mfma_f32_16x16x32_bf16 v[38:41], v[146:149], v[178:181], v[38:41]
	v_mfma_f32_16x16x32_bf16 v[34:37], v[154:157], v[178:181], v[34:37]
	v_mfma_f32_16x16x32_bf16 v[122:125], v[146:149], v[186:189], v[122:125]
	v_mfma_f32_16x16x32_bf16 v[98:101], v[154:157], v[186:189], v[98:101]
	v_mfma_f32_16x16x32_bf16 v[110:113], v[150:153], v[166:169], v[110:113]
	v_mfma_f32_16x16x32_bf16 v[106:109], v[158:161], v[166:169], v[106:109]
	v_mfma_f32_16x16x32_bf16 v[46:49], v[150:153], v[174:177], v[46:49]
	v_mfma_f32_16x16x32_bf16 v[42:45], v[158:161], v[174:177], v[42:45]
	v_mfma_f32_16x16x32_bf16 v[38:41], v[150:153], v[182:185], v[38:41]
	v_mfma_f32_16x16x32_bf16 v[34:37], v[158:161], v[182:185], v[34:37]
	v_mfma_f32_16x16x32_bf16 v[122:125], v[150:153], v[190:193], v[122:125]
	v_mfma_f32_16x16x32_bf16 v[98:101], v[158:161], v[190:193], v[98:101]
	s_setprio 0
	s_barrier
	ds_read_b128 v[162:165], v245 offset:49152
	ds_read_b128 v[166:169], v245 offset:50176
	ds_read_b128 v[170:173], v245 offset:51200
	ds_read_b128 v[174:177], v245 offset:52224
	ds_read_b128 v[178:181], v245 offset:53248
	ds_read_b128 v[182:185], v245 offset:54272
	ds_read_b128 v[186:189], v245 offset:55296
	ds_read_b128 v[190:193], v245 offset:56320
	s_waitcnt lgkmcnt(0)
	s_barrier
	s_setprio 1
	v_mfma_f32_16x16x32_bf16 v[94:97], v[130:133], v[162:165], v[94:97]
	v_mfma_f32_16x16x32_bf16 v[90:93], v[138:141], v[162:165], v[90:93]
	v_mfma_f32_16x16x32_bf16 v[30:33], v[130:133], v[170:173], v[30:33]
	v_mfma_f32_16x16x32_bf16 v[26:29], v[138:141], v[170:173], v[26:29]
	v_mfma_f32_16x16x32_bf16 v[22:25], v[130:133], v[178:181], v[22:25]
	v_mfma_f32_16x16x32_bf16 v[18:21], v[138:141], v[178:181], v[18:21]
	v_mfma_f32_16x16x32_bf16 v[82:85], v[130:133], v[186:189], v[82:85]
	v_mfma_f32_16x16x32_bf16 v[74:77], v[138:141], v[186:189], v[74:77]
	v_mfma_f32_16x16x32_bf16 v[94:97], v[134:137], v[166:169], v[94:97]
	v_mfma_f32_16x16x32_bf16 v[90:93], v[142:145], v[166:169], v[90:93]
	v_mfma_f32_16x16x32_bf16 v[30:33], v[134:137], v[174:177], v[30:33]
	v_mfma_f32_16x16x32_bf16 v[26:29], v[142:145], v[174:177], v[26:29]
	v_mfma_f32_16x16x32_bf16 v[22:25], v[134:137], v[182:185], v[22:25]
	v_mfma_f32_16x16x32_bf16 v[18:21], v[142:145], v[182:185], v[18:21]
	v_mfma_f32_16x16x32_bf16 v[82:85], v[134:137], v[190:193], v[82:85]
	v_mfma_f32_16x16x32_bf16 v[74:77], v[142:145], v[190:193], v[74:77]
	v_mfma_f32_16x16x32_bf16 v[86:89], v[146:149], v[162:165], v[86:89]
	v_mfma_f32_16x16x32_bf16 v[78:81], v[154:157], v[162:165], v[78:81]
	v_mfma_f32_16x16x32_bf16 v[14:17], v[146:149], v[170:173], v[14:17]
	v_mfma_f32_16x16x32_bf16 v[10:13], v[154:157], v[170:173], v[10:13]
	v_mfma_f32_16x16x32_bf16 v[6:9], v[146:149], v[178:181], v[6:9]
	v_mfma_f32_16x16x32_bf16 v[2:5], v[154:157], v[178:181], v[2:5]
	v_mfma_f32_16x16x32_bf16 v[70:73], v[146:149], v[186:189], v[70:73]
	v_mfma_f32_16x16x32_bf16 v[66:69], v[154:157], v[186:189], v[66:69]
	v_mfma_f32_16x16x32_bf16 v[86:89], v[150:153], v[166:169], v[86:89]
	v_mfma_f32_16x16x32_bf16 v[78:81], v[158:161], v[166:169], v[78:81]
	v_mfma_f32_16x16x32_bf16 v[14:17], v[150:153], v[174:177], v[14:17]
	v_mfma_f32_16x16x32_bf16 v[10:13], v[158:161], v[174:177], v[10:13]
	v_mfma_f32_16x16x32_bf16 v[6:9], v[150:153], v[182:185], v[6:9]
	v_mfma_f32_16x16x32_bf16 v[2:5], v[158:161], v[182:185], v[2:5]
	v_mfma_f32_16x16x32_bf16 v[70:73], v[150:153], v[190:193], v[70:73]
	v_mfma_f32_16x16x32_bf16 v[66:69], v[158:161], v[190:193], v[66:69]
	s_setprio 0
	s_barrier

.LBB0_1261:
	v_add_u32_e32 v11, s38, v152
	s_add_i32 s1, s1, 2
	ds_read_b128 v[156:159], v11
	ds_read_b128 v[160:163], v11 offset:1024
	ds_read_b128 v[164:167], v11 offset:2048
	ds_read_b128 v[168:171], v11 offset:3072
	v_add_u32_e32 v11, s39, v152
	s_add_u32 s3, s14, s62
	ds_read_b128 v[172:175], v11
	ds_read_b128 v[176:179], v11 offset:1024
	ds_read_b128 v[184:187], v11 offset:2048
	ds_read_b128 v[188:191], v11 offset:3072
	s_addc_u32 s22, s15, s63
	s_add_u32 s3, s3, 0x100
	s_addc_u32 s22, s22, 0
	s_add_u32 s23, s53, s62
	s_addc_u32 s24, s55, s63
	s_cmpk_eq_i32 s62, 0x700
	s_cselect_b32 s65, s61, s24
	s_cselect_b32 s64, s60, s23
	s_cselect_b32 s67, s59, s22
	s_cselect_b32 s66, s58, s3
	v_lshl_add_u64 v[180:181], v[150:151], 0, s[62:63]
	s_add_i32 s24, s31, 0x8000
	v_lshl_add_u64 v[216:217], v[180:181], 0, s[42:43]
	s_mov_b32 m0, s24
	ds_read_b128 v[192:195], v154
	ds_read_b128 v[196:199], v154 offset:1024
	ds_read_b128 v[200:203], v154 offset:2048
	ds_read_b128 v[204:207], v154 offset:3072
	ds_read_b128 v[208:211], v154 offset:4096
	ds_read_b128 v[212:215], v154 offset:5120
	ds_read_b128 v[220:223], v154 offset:6144
	ds_read_b128 v[224:227], v154 offset:7168
	global_load_lds_dwordx4 v[216:217], off
	v_lshl_add_u64 v[216:217], v[12:13], 0, s[62:63]
	s_add_i32 s23, s31, 0xa000
	v_lshl_add_u64 v[228:229], v[216:217], 0, s[42:43]
	s_mov_b32 m0, s23
	s_add_i32 s3, s31, 0xc000
	global_load_lds_dwordx4 v[228:229], off
	v_lshl_add_u64 v[180:181], v[180:181], 0, s[44:45]
	s_mov_b32 m0, s3
	s_add_i32 s22, s31, 0xe000
	global_load_lds_dwordx4 v[180:181], off
	v_lshl_add_u64 v[180:181], v[216:217], 0, s[44:45]
	s_mov_b32 m0, s22
	s_nop 0
	global_load_lds_dwordx4 v[180:181], off
	s_waitcnt vmcnt(8)
	s_waitcnt lgkmcnt(0)
	s_barrier
	s_setprio 1
	v_mfma_f32_16x16x32_bf16 v[126:129], v[156:159], v[192:195], v[126:129]
	v_mfma_f32_16x16x32_bf16 v[122:125], v[164:167], v[192:195], v[122:125]
	v_mfma_f32_16x16x32_bf16 v[106:109], v[156:159], v[200:203], v[106:109]
	v_mfma_f32_16x16x32_bf16 v[110:113], v[164:167], v[200:203], v[110:113]
	v_mfma_f32_16x16x32_bf16 v[90:93], v[156:159], v[208:211], v[90:93]
	v_mfma_f32_16x16x32_bf16 v[94:97], v[164:167], v[208:211], v[94:97]
	v_mfma_f32_16x16x32_bf16 v[74:77], v[156:159], v[220:223], v[74:77]
	v_mfma_f32_16x16x32_bf16 v[78:81], v[164:167], v[220:223], v[78:81]
	v_mfma_f32_16x16x32_bf16 v[126:129], v[160:163], v[196:199], v[126:129]
	v_mfma_f32_16x16x32_bf16 v[122:125], v[168:171], v[196:199], v[122:125]
	v_mfma_f32_16x16x32_bf16 v[106:109], v[160:163], v[204:207], v[106:109]
	v_mfma_f32_16x16x32_bf16 v[110:113], v[168:171], v[204:207], v[110:113]
	v_mfma_f32_16x16x32_bf16 v[90:93], v[160:163], v[212:215], v[90:93]
	v_mfma_f32_16x16x32_bf16 v[94:97], v[168:171], v[212:215], v[94:97]
	v_mfma_f32_16x16x32_bf16 v[74:77], v[160:163], v[224:227], v[74:77]
	v_mfma_f32_16x16x32_bf16 v[78:81], v[168:171], v[224:227], v[78:81]
	v_mfma_f32_16x16x32_bf16 v[58:61], v[172:175], v[192:195], v[58:61]
	v_mfma_f32_16x16x32_bf16 v[62:65], v[184:187], v[192:195], v[62:65]
	v_mfma_f32_16x16x32_bf16 v[42:45], v[172:175], v[200:203], v[42:45]
	v_mfma_f32_16x16x32_bf16 v[46:49], v[184:187], v[200:203], v[46:49]
	v_mfma_f32_16x16x32_bf16 v[26:29], v[172:175], v[208:211], v[26:29]
	v_mfma_f32_16x16x32_bf16 v[30:33], v[184:187], v[208:211], v[30:33]
	v_mfma_f32_16x16x32_bf16 v[130:133], v[172:175], v[220:223], v[130:133]
	v_mfma_f32_16x16x32_bf16 v[14:17], v[184:187], v[220:223], v[14:17]
	v_mfma_f32_16x16x32_bf16 v[58:61], v[176:179], v[196:199], v[58:61]
	v_mfma_f32_16x16x32_bf16 v[62:65], v[188:191], v[196:199], v[62:65]
	v_mfma_f32_16x16x32_bf16 v[42:45], v[176:179], v[204:207], v[42:45]
	v_mfma_f32_16x16x32_bf16 v[46:49], v[188:191], v[204:207], v[46:49]
	v_mfma_f32_16x16x32_bf16 v[26:29], v[176:179], v[212:215], v[26:29]
	v_mfma_f32_16x16x32_bf16 v[30:33], v[188:191], v[212:215], v[30:33]
	v_mfma_f32_16x16x32_bf16 v[130:133], v[176:179], v[224:227], v[130:133]
	v_mfma_f32_16x16x32_bf16 v[14:17], v[188:191], v[224:227], v[14:17]
	s_setprio 0
	s_barrier
	s_add_i32 s25, s38, s11
	v_lshl_add_u64 v[180:181], s[64:65], 0, v[136:137]
	s_mov_b32 m0, s25
	ds_read_b128 v[192:195], v154 offset:16384
	ds_read_b128 v[196:199], v154 offset:17408
	ds_read_b128 v[200:203], v154 offset:18432
	ds_read_b128 v[204:207], v154 offset:19456
	ds_read_b128 v[208:211], v154 offset:20480
	ds_read_b128 v[212:215], v154 offset:21504
	ds_read_b128 v[220:223], v154 offset:22528
	ds_read_b128 v[224:227], v154 offset:23552
	global_load_lds_dwordx4 v[180:181], off
	s_add_i32 m0, s25, 0x2000
	s_add_u32 s26, s64, 0x40000
	v_lshl_add_u64 v[216:217], s[64:65], 0, v[140:141]
	s_addc_u32 s27, s65, 0
	s_add_i32 s25, s39, s11
	global_load_lds_dwordx4 v[216:217], off
	v_lshl_add_u64 v[228:229], s[26:27], 0, v[136:137]
	s_mov_b32 m0, s25
	s_nop 0
	global_load_lds_dwordx4 v[228:229], off
	v_lshl_add_u64 v[228:229], s[26:27], 0, v[140:141]
	s_add_i32 m0, s25, 0x2000
	s_nop 0
	global_load_lds_dwordx4 v[228:229], off
	s_waitcnt vmcnt(4)
	s_waitcnt lgkmcnt(0)
	s_barrier
	s_setprio 1
	v_mfma_f32_16x16x32_bf16 v[114:117], v[156:159], v[192:195], v[114:117]
	v_mfma_f32_16x16x32_bf16 v[118:121], v[164:167], v[192:195], v[118:121]
	v_mfma_f32_16x16x32_bf16 v[98:101], v[156:159], v[200:203], v[98:101]
	v_mfma_f32_16x16x32_bf16 v[102:105], v[164:167], v[200:203], v[102:105]
	v_mfma_f32_16x16x32_bf16 v[82:85], v[156:159], v[208:211], v[82:85]
	v_mfma_f32_16x16x32_bf16 v[86:89], v[164:167], v[208:211], v[86:89]
	v_mfma_f32_16x16x32_bf16 v[66:69], v[156:159], v[220:223], v[66:69]
	v_mfma_f32_16x16x32_bf16 v[70:73], v[164:167], v[220:223], v[70:73]
	v_mfma_f32_16x16x32_bf16 v[114:117], v[160:163], v[196:199], v[114:117]
	v_mfma_f32_16x16x32_bf16 v[118:121], v[168:171], v[196:199], v[118:121]
	v_mfma_f32_16x16x32_bf16 v[98:101], v[160:163], v[204:207], v[98:101]
	v_mfma_f32_16x16x32_bf16 v[102:105], v[168:171], v[204:207], v[102:105]
	v_mfma_f32_16x16x32_bf16 v[82:85], v[160:163], v[212:215], v[82:85]
	v_mfma_f32_16x16x32_bf16 v[86:89], v[168:171], v[212:215], v[86:89]
	v_mfma_f32_16x16x32_bf16 v[66:69], v[160:163], v[224:227], v[66:69]
	v_mfma_f32_16x16x32_bf16 v[70:73], v[168:171], v[224:227], v[70:73]
	v_mfma_f32_16x16x32_bf16 v[50:53], v[172:175], v[192:195], v[50:53]
	v_mfma_f32_16x16x32_bf16 v[54:57], v[184:187], v[192:195], v[54:57]
	v_mfma_f32_16x16x32_bf16 v[34:37], v[172:175], v[200:203], v[34:37]
	v_mfma_f32_16x16x32_bf16 v[38:41], v[184:187], v[200:203], v[38:41]
	v_mfma_f32_16x16x32_bf16 v[18:21], v[172:175], v[208:211], v[18:21]
	v_mfma_f32_16x16x32_bf16 v[22:25], v[184:187], v[208:211], v[22:25]
	v_mfma_f32_16x16x32_bf16 v[6:9], v[172:175], v[220:223], v[6:9]
	v_mfma_f32_16x16x32_bf16 v[2:5], v[184:187], v[220:223], v[2:5]
	v_mfma_f32_16x16x32_bf16 v[50:53], v[176:179], v[196:199], v[50:53]
	v_mfma_f32_16x16x32_bf16 v[54:57], v[188:191], v[196:199], v[54:57]
	v_mfma_f32_16x16x32_bf16 v[34:37], v[176:179], v[204:207], v[34:37]
	v_mfma_f32_16x16x32_bf16 v[38:41], v[188:191], v[204:207], v[38:41]
	v_mfma_f32_16x16x32_bf16 v[18:21], v[176:179], v[212:215], v[18:21]
	v_mfma_f32_16x16x32_bf16 v[22:25], v[188:191], v[212:215], v[22:25]
	v_mfma_f32_16x16x32_bf16 v[6:9], v[176:179], v[224:227], v[6:9]
	v_mfma_f32_16x16x32_bf16 v[2:5], v[188:191], v[224:227], v[2:5]
	s_setprio 0
	s_barrier
	s_add_i32 s25, 0, 0x18000
	v_add_u32_e32 v11, s25, v152
	s_add_i32 s57, 0, 0x1c000
	ds_read_b128 v[156:159], v11
	ds_read_b128 v[160:163], v11 offset:1024
	ds_read_b128 v[164:167], v11 offset:2048
	ds_read_b128 v[168:171], v11 offset:3072
	v_add_u32_e32 v11, s57, v152
	ds_read_b128 v[172:175], v11
	ds_read_b128 v[176:179], v11 offset:1024
	ds_read_b128 v[184:187], v11 offset:2048
	ds_read_b128 v[188:191], v11 offset:3072
	s_mov_b32 m0, s31
	v_lshl_add_u64 v[228:229], s[66:67], 0, v[134:135]
	s_add_u32 s26, s66, 0x40000
	ds_read_b128 v[192:195], v154 offset:32768
	ds_read_b128 v[196:199], v154 offset:33792
	ds_read_b128 v[200:203], v154 offset:34816
	ds_read_b128 v[204:207], v154 offset:35840
	ds_read_b128 v[208:211], v154 offset:36864
	ds_read_b128 v[212:215], v154 offset:37888
	ds_read_b128 v[220:223], v154 offset:38912
	ds_read_b128 v[224:227], v154 offset:39936
	global_load_lds_dwordx4 v[228:229], off
	v_lshl_add_u64 v[228:229], s[66:67], 0, v[138:139]
	s_mov_b32 m0, s33
	s_addc_u32 s27, s67, 0
	global_load_lds_dwordx4 v[228:229], off
	v_lshl_add_u64 v[228:229], s[26:27], 0, v[134:135]
	s_mov_b32 m0, s36
	s_nop 0
	global_load_lds_dwordx4 v[228:229], off
	v_lshl_add_u64 v[228:229], s[26:27], 0, v[138:139]
	s_mov_b32 m0, s37
	s_nop 0
	global_load_lds_dwordx4 v[228:229], off
	s_waitcnt vmcnt(8)
	s_waitcnt lgkmcnt(0)
	s_barrier
	s_setprio 1
	v_mfma_f32_16x16x32_bf16 v[126:129], v[156:159], v[192:195], v[126:129]
	v_mfma_f32_16x16x32_bf16 v[122:125], v[164:167], v[192:195], v[122:125]
	v_mfma_f32_16x16x32_bf16 v[106:109], v[156:159], v[200:203], v[106:109]
	v_mfma_f32_16x16x32_bf16 v[110:113], v[164:167], v[200:203], v[110:113]
	v_mfma_f32_16x16x32_bf16 v[90:93], v[156:159], v[208:211], v[90:93]
	v_mfma_f32_16x16x32_bf16 v[94:97], v[164:167], v[208:211], v[94:97]
	v_mfma_f32_16x16x32_bf16 v[74:77], v[156:159], v[220:223], v[74:77]
	v_mfma_f32_16x16x32_bf16 v[78:81], v[164:167], v[220:223], v[78:81]
	v_mfma_f32_16x16x32_bf16 v[126:129], v[160:163], v[196:199], v[126:129]
	v_mfma_f32_16x16x32_bf16 v[122:125], v[168:171], v[196:199], v[122:125]
	v_mfma_f32_16x16x32_bf16 v[106:109], v[160:163], v[204:207], v[106:109]
	v_mfma_f32_16x16x32_bf16 v[110:113], v[168:171], v[204:207], v[110:113]
	v_mfma_f32_16x16x32_bf16 v[90:93], v[160:163], v[212:215], v[90:93]
	v_mfma_f32_16x16x32_bf16 v[94:97], v[168:171], v[212:215], v[94:97]
	v_mfma_f32_16x16x32_bf16 v[74:77], v[160:163], v[224:227], v[74:77]
	v_mfma_f32_16x16x32_bf16 v[78:81], v[168:171], v[224:227], v[78:81]
	v_mfma_f32_16x16x32_bf16 v[58:61], v[172:175], v[192:195], v[58:61]
	v_mfma_f32_16x16x32_bf16 v[62:65], v[184:187], v[192:195], v[62:65]
	v_mfma_f32_16x16x32_bf16 v[42:45], v[172:175], v[200:203], v[42:45]
	v_mfma_f32_16x16x32_bf16 v[46:49], v[184:187], v[200:203], v[46:49]
	v_mfma_f32_16x16x32_bf16 v[26:29], v[172:175], v[208:211], v[26:29]
	v_mfma_f32_16x16x32_bf16 v[30:33], v[184:187], v[208:211], v[30:33]
	v_mfma_f32_16x16x32_bf16 v[130:133], v[172:175], v[220:223], v[130:133]
	v_mfma_f32_16x16x32_bf16 v[14:17], v[184:187], v[220:223], v[14:17]
	v_mfma_f32_16x16x32_bf16 v[58:61], v[176:179], v[196:199], v[58:61]
	v_mfma_f32_16x16x32_bf16 v[62:65], v[188:191], v[196:199], v[62:65]
	v_mfma_f32_16x16x32_bf16 v[42:45], v[176:179], v[204:207], v[42:45]
	v_mfma_f32_16x16x32_bf16 v[46:49], v[188:191], v[204:207], v[46:49]
	v_mfma_f32_16x16x32_bf16 v[26:29], v[176:179], v[212:215], v[26:29]
	v_mfma_f32_16x16x32_bf16 v[30:33], v[188:191], v[212:215], v[30:33]
	v_mfma_f32_16x16x32_bf16 v[130:133], v[176:179], v[224:227], v[130:133]
	v_mfma_f32_16x16x32_bf16 v[14:17], v[188:191], v[224:227], v[14:17]
	s_setprio 0
	s_barrier
	s_add_i32 s25, s25, s11
	v_lshl_add_u64 v[180:181], v[180:181], 0, s[42:43]
	s_mov_b32 m0, s25
	ds_read_b128 v[192:195], v154 offset:49152
	ds_read_b128 v[196:199], v154 offset:50176
	ds_read_b128 v[200:203], v154 offset:51200
	ds_read_b128 v[204:207], v154 offset:52224
	ds_read_b128 v[208:211], v154 offset:53248
	ds_read_b128 v[212:215], v154 offset:54272
	ds_read_b128 v[220:223], v154 offset:55296
	ds_read_b128 v[224:227], v154 offset:56320
	global_load_lds_dwordx4 v[180:181], off
	s_add_i32 m0, s25, 0x2000
	s_add_u32 s26, s64, 0x40080
	v_lshl_add_u64 v[180:181], v[216:217], 0, s[42:43]
	s_addc_u32 s27, s65, 0
	s_add_i32 s25, s57, s11
	global_load_lds_dwordx4 v[180:181], off
	v_lshl_add_u64 v[180:181], s[26:27], 0, v[136:137]
	s_mov_b32 m0, s25
	s_nop 0
	global_load_lds_dwordx4 v[180:181], off
	v_lshl_add_u64 v[180:181], s[26:27], 0, v[140:141]
	s_add_i32 m0, s25, 0x2000
	s_nop 0
	global_load_lds_dwordx4 v[180:181], off
	s_waitcnt vmcnt(4)
	s_waitcnt lgkmcnt(0)
	s_barrier
	s_setprio 1
	v_mfma_f32_16x16x32_bf16 v[114:117], v[156:159], v[192:195], v[114:117]
	v_mfma_f32_16x16x32_bf16 v[118:121], v[164:167], v[192:195], v[118:121]
	v_mfma_f32_16x16x32_bf16 v[98:101], v[156:159], v[200:203], v[98:101]
	v_mfma_f32_16x16x32_bf16 v[102:105], v[164:167], v[200:203], v[102:105]
	v_mfma_f32_16x16x32_bf16 v[82:85], v[156:159], v[208:211], v[82:85]
	v_mfma_f32_16x16x32_bf16 v[86:89], v[164:167], v[208:211], v[86:89]
	v_mfma_f32_16x16x32_bf16 v[66:69], v[156:159], v[220:223], v[66:69]
	v_mfma_f32_16x16x32_bf16 v[70:73], v[164:167], v[220:223], v[70:73]
	v_mfma_f32_16x16x32_bf16 v[114:117], v[160:163], v[196:199], v[114:117]
	v_mfma_f32_16x16x32_bf16 v[118:121], v[168:171], v[196:199], v[118:121]
	v_mfma_f32_16x16x32_bf16 v[98:101], v[160:163], v[204:207], v[98:101]
	v_mfma_f32_16x16x32_bf16 v[102:105], v[168:171], v[204:207], v[102:105]
	v_mfma_f32_16x16x32_bf16 v[82:85], v[160:163], v[212:215], v[82:85]
	v_mfma_f32_16x16x32_bf16 v[86:89], v[168:171], v[212:215], v[86:89]
	v_mfma_f32_16x16x32_bf16 v[66:69], v[160:163], v[224:227], v[66:69]
	v_mfma_f32_16x16x32_bf16 v[70:73], v[168:171], v[224:227], v[70:73]
	v_mfma_f32_16x16x32_bf16 v[50:53], v[172:175], v[192:195], v[50:53]
	v_mfma_f32_16x16x32_bf16 v[54:57], v[184:187], v[192:195], v[54:57]
	v_mfma_f32_16x16x32_bf16 v[34:37], v[172:175], v[200:203], v[34:37]
	v_mfma_f32_16x16x32_bf16 v[38:41], v[184:187], v[200:203], v[38:41]
	v_mfma_f32_16x16x32_bf16 v[18:21], v[172:175], v[208:211], v[18:21]
	v_mfma_f32_16x16x32_bf16 v[22:25], v[184:187], v[208:211], v[22:25]
	v_mfma_f32_16x16x32_bf16 v[6:9], v[172:175], v[220:223], v[6:9]
	v_mfma_f32_16x16x32_bf16 v[2:5], v[184:187], v[220:223], v[2:5]
	v_mfma_f32_16x16x32_bf16 v[50:53], v[176:179], v[196:199], v[50:53]
	v_mfma_f32_16x16x32_bf16 v[54:57], v[188:191], v[196:199], v[54:57]
	v_mfma_f32_16x16x32_bf16 v[34:37], v[176:179], v[204:207], v[34:37]
	v_mfma_f32_16x16x32_bf16 v[38:41], v[188:191], v[204:207], v[38:41]
	v_mfma_f32_16x16x32_bf16 v[18:21], v[176:179], v[212:215], v[18:21]
	v_mfma_f32_16x16x32_bf16 v[22:25], v[188:191], v[212:215], v[22:25]
	v_mfma_f32_16x16x32_bf16 v[6:9], v[176:179], v[224:227], v[6:9]
	v_mfma_f32_16x16x32_bf16 v[2:5], v[188:191], v[224:227], v[2:5]
	s_setprio 0
	s_barrier
	s_add_u32 s62, s62, 0x100
	s_addc_u32 s63, s63, 0
	s_cmp_ge_u32 s1, s0
	s_cbranch_scc0 .LBB0_1261
	s_and_b64 vcc, exec, s[4:5]
	s_cbranch_vccz .LBB0_1265
	v_add_u32_e32 v11, 0, v152
	v_add_u32_e32 v12, 0x10000, v11
	ds_read_b128 v[156:159], v12
	ds_read_b128 v[160:163], v12 offset:1024
	ds_read_b128 v[164:167], v12 offset:2048
	ds_read_b128 v[168:171], v12 offset:3072
	v_add_u32_e32 v12, 0x14000, v11
	ds_read_b128 v[172:175], v12
	ds_read_b128 v[176:179], v12 offset:1024
	ds_read_b128 v[184:187], v12 offset:2048
	ds_read_b128 v[188:191], v12 offset:3072
	v_lshl_add_u64 v[12:13], s[14:15], 0, v[134:135]
	s_mov_b32 m0, s24
	v_lshl_add_u64 v[12:13], v[12:13], 0, s[50:51]
	ds_read_b128 v[192:195], v154
	ds_read_b128 v[196:199], v154 offset:1024
	ds_read_b128 v[200:203], v154 offset:2048
	ds_read_b128 v[204:207], v154 offset:3072
	ds_read_b128 v[208:211], v154 offset:4096
	ds_read_b128 v[212:215], v154 offset:5120
	ds_read_b128 v[220:223], v154 offset:6144
	ds_read_b128 v[224:227], v154 offset:7168
	global_load_lds_dwordx4 v[12:13], off
	v_lshl_add_u64 v[12:13], s[14:15], 0, v[138:139]
	s_add_u32 s0, s14, 0x40780
	v_lshl_add_u64 v[12:13], v[12:13], 0, s[50:51]
	s_mov_b32 m0, s23
	s_addc_u32 s1, s15, 0
	global_load_lds_dwordx4 v[12:13], off
	v_lshl_add_u64 v[12:13], s[0:1], 0, v[134:135]
	s_mov_b32 m0, s3
	s_nop 0
	global_load_lds_dwordx4 v[12:13], off
	v_lshl_add_u64 v[12:13], s[0:1], 0, v[138:139]
	s_mov_b32 m0, s22
	s_nop 0
	global_load_lds_dwordx4 v[12:13], off
	s_waitcnt vmcnt(8)
	s_waitcnt lgkmcnt(0)
	s_barrier
	s_setprio 1
	v_mfma_f32_16x16x32_bf16 v[126:129], v[156:159], v[192:195], v[126:129]
	v_mfma_f32_16x16x32_bf16 v[122:125], v[164:167], v[192:195], v[122:125]
	v_mfma_f32_16x16x32_bf16 v[106:109], v[156:159], v[200:203], v[106:109]
	v_mfma_f32_16x16x32_bf16 v[110:113], v[164:167], v[200:203], v[110:113]
	v_mfma_f32_16x16x32_bf16 v[90:93], v[156:159], v[208:211], v[90:93]
	v_mfma_f32_16x16x32_bf16 v[94:97], v[164:167], v[208:211], v[94:97]
	v_mfma_f32_16x16x32_bf16 v[74:77], v[156:159], v[220:223], v[74:77]
	v_mfma_f32_16x16x32_bf16 v[78:81], v[164:167], v[220:223], v[78:81]
	v_mfma_f32_16x16x32_bf16 v[126:129], v[160:163], v[196:199], v[126:129]
	v_mfma_f32_16x16x32_bf16 v[122:125], v[168:171], v[196:199], v[122:125]
	v_mfma_f32_16x16x32_bf16 v[106:109], v[160:163], v[204:207], v[106:109]
	v_mfma_f32_16x16x32_bf16 v[110:113], v[168:171], v[204:207], v[110:113]
	v_mfma_f32_16x16x32_bf16 v[90:93], v[160:163], v[212:215], v[90:93]
	v_mfma_f32_16x16x32_bf16 v[94:97], v[168:171], v[212:215], v[94:97]
	v_mfma_f32_16x16x32_bf16 v[74:77], v[160:163], v[224:227], v[74:77]
	v_mfma_f32_16x16x32_bf16 v[78:81], v[168:171], v[224:227], v[78:81]
	v_mfma_f32_16x16x32_bf16 v[58:61], v[172:175], v[192:195], v[58:61]
	v_mfma_f32_16x16x32_bf16 v[62:65], v[184:187], v[192:195], v[62:65]
	v_mfma_f32_16x16x32_bf16 v[42:45], v[172:175], v[200:203], v[42:45]
	v_mfma_f32_16x16x32_bf16 v[46:49], v[184:187], v[200:203], v[46:49]
	v_mfma_f32_16x16x32_bf16 v[26:29], v[172:175], v[208:211], v[26:29]
	v_mfma_f32_16x16x32_bf16 v[30:33], v[184:187], v[208:211], v[30:33]
	v_mfma_f32_16x16x32_bf16 v[130:133], v[172:175], v[220:223], v[130:133]
	v_mfma_f32_16x16x32_bf16 v[12:15], v[184:187], v[220:223], v[14:17]
	v_mfma_f32_16x16x32_bf16 v[58:61], v[176:179], v[196:199], v[58:61]
	v_mfma_f32_16x16x32_bf16 v[62:65], v[188:191], v[196:199], v[62:65]
	v_mfma_f32_16x16x32_bf16 v[42:45], v[176:179], v[204:207], v[42:45]
	v_mfma_f32_16x16x32_bf16 v[46:49], v[188:191], v[204:207], v[46:49]
	v_mfma_f32_16x16x32_bf16 v[26:29], v[176:179], v[212:215], v[26:29]
	v_mfma_f32_16x16x32_bf16 v[30:33], v[188:191], v[212:215], v[30:33]
	v_mfma_f32_16x16x32_bf16 v[130:133], v[176:179], v[224:227], v[130:133]
	v_mfma_f32_16x16x32_bf16 v[12:15], v[188:191], v[224:227], v[12:15]
	s_setprio 0
	s_barrier
	ds_read_b128 v[192:195], v154 offset:16384
	ds_read_b128 v[196:199], v154 offset:17408
	ds_read_b128 v[200:203], v154 offset:18432
	ds_read_b128 v[204:207], v154 offset:19456
	ds_read_b128 v[208:211], v154 offset:20480
	ds_read_b128 v[212:215], v154 offset:21504
	ds_read_b128 v[220:223], v154 offset:22528
	ds_read_b128 v[224:227], v154 offset:23552
	s_waitcnt vmcnt(0)
	s_waitcnt lgkmcnt(0)
	s_barrier
	s_setprio 1
	v_mfma_f32_16x16x32_bf16 v[114:117], v[156:159], v[192:195], v[114:117]
	v_mfma_f32_16x16x32_bf16 v[118:121], v[164:167], v[192:195], v[118:121]
	v_mfma_f32_16x16x32_bf16 v[98:101], v[156:159], v[200:203], v[98:101]
	v_mfma_f32_16x16x32_bf16 v[102:105], v[164:167], v[200:203], v[102:105]
	v_mfma_f32_16x16x32_bf16 v[82:85], v[156:159], v[208:211], v[82:85]
	v_mfma_f32_16x16x32_bf16 v[86:89], v[164:167], v[208:211], v[86:89]
	v_mfma_f32_16x16x32_bf16 v[66:69], v[156:159], v[220:223], v[66:69]
	v_mfma_f32_16x16x32_bf16 v[70:73], v[164:167], v[220:223], v[70:73]
	v_mfma_f32_16x16x32_bf16 v[114:117], v[160:163], v[196:199], v[114:117]
	v_mfma_f32_16x16x32_bf16 v[118:121], v[168:171], v[196:199], v[118:121]
	v_mfma_f32_16x16x32_bf16 v[98:101], v[160:163], v[204:207], v[98:101]
	v_mfma_f32_16x16x32_bf16 v[102:105], v[168:171], v[204:207], v[102:105]
	v_mfma_f32_16x16x32_bf16 v[82:85], v[160:163], v[212:215], v[82:85]
	v_mfma_f32_16x16x32_bf16 v[86:89], v[168:171], v[212:215], v[86:89]
	v_mfma_f32_16x16x32_bf16 v[66:69], v[160:163], v[224:227], v[66:69]
	v_mfma_f32_16x16x32_bf16 v[70:73], v[168:171], v[224:227], v[70:73]
	v_mfma_f32_16x16x32_bf16 v[50:53], v[172:175], v[192:195], v[50:53]
	v_mfma_f32_16x16x32_bf16 v[54:57], v[184:187], v[192:195], v[54:57]
	v_mfma_f32_16x16x32_bf16 v[34:37], v[172:175], v[200:203], v[34:37]
	v_mfma_f32_16x16x32_bf16 v[38:41], v[184:187], v[200:203], v[38:41]
	v_mfma_f32_16x16x32_bf16 v[16:19], v[172:175], v[208:211], v[18:21]
	v_mfma_f32_16x16x32_bf16 v[22:25], v[184:187], v[208:211], v[22:25]
	v_mfma_f32_16x16x32_bf16 v[6:9], v[172:175], v[220:223], v[6:9]
	v_mfma_f32_16x16x32_bf16 v[2:5], v[184:187], v[220:223], v[2:5]
	v_mfma_f32_16x16x32_bf16 v[50:53], v[176:179], v[196:199], v[50:53]
	v_mfma_f32_16x16x32_bf16 v[54:57], v[188:191], v[196:199], v[54:57]
	v_mfma_f32_16x16x32_bf16 v[34:37], v[176:179], v[204:207], v[34:37]
	v_mfma_f32_16x16x32_bf16 v[38:41], v[188:191], v[204:207], v[38:41]
	v_mfma_f32_16x16x32_bf16 v[18:21], v[176:179], v[212:215], v[16:19]
	v_mfma_f32_16x16x32_bf16 v[22:25], v[188:191], v[212:215], v[22:25]
	v_mfma_f32_16x16x32_bf16 v[6:9], v[176:179], v[224:227], v[6:9]
	v_mfma_f32_16x16x32_bf16 v[2:5], v[188:191], v[224:227], v[2:5]
	s_setprio 0
	s_barrier
	v_add_u32_e32 v16, 0x18000, v11
	v_add_u32_e32 v11, 0x1c000, v11
	ds_read_b128 v[156:159], v16
	ds_read_b128 v[160:163], v16 offset:1024
	ds_read_b128 v[164:167], v16 offset:2048
	ds_read_b128 v[168:171], v16 offset:3072
	ds_read_b128 v[172:175], v11
	ds_read_b128 v[176:179], v11 offset:1024
	ds_read_b128 v[184:187], v11 offset:2048
	ds_read_b128 v[188:191], v11 offset:3072
	ds_read_b128 v[192:195], v154 offset:32768
	ds_read_b128 v[196:199], v154 offset:33792
	ds_read_b128 v[200:203], v154 offset:34816
	ds_read_b128 v[204:207], v154 offset:35840
	ds_read_b128 v[208:211], v154 offset:36864
	ds_read_b128 v[212:215], v154 offset:37888
	ds_read_b128 v[220:223], v154 offset:38912
	ds_read_b128 v[224:227], v154 offset:39936
	s_waitcnt lgkmcnt(0)
	s_barrier
	s_setprio 1
	v_mfma_f32_16x16x32_bf16 v[126:129], v[156:159], v[192:195], v[126:129]
	v_mfma_f32_16x16x32_bf16 v[122:125], v[164:167], v[192:195], v[122:125]
	v_mfma_f32_16x16x32_bf16 v[106:109], v[156:159], v[200:203], v[106:109]
	v_mfma_f32_16x16x32_bf16 v[110:113], v[164:167], v[200:203], v[110:113]
	v_mfma_f32_16x16x32_bf16 v[90:93], v[156:159], v[208:211], v[90:93]
	v_mfma_f32_16x16x32_bf16 v[94:97], v[164:167], v[208:211], v[94:97]
	v_mfma_f32_16x16x32_bf16 v[74:77], v[156:159], v[220:223], v[74:77]
	v_mfma_f32_16x16x32_bf16 v[78:81], v[164:167], v[220:223], v[78:81]
	v_mfma_f32_16x16x32_bf16 v[126:129], v[160:163], v[196:199], v[126:129]
	v_mfma_f32_16x16x32_bf16 v[122:125], v[168:171], v[196:199], v[122:125]
	v_mfma_f32_16x16x32_bf16 v[106:109], v[160:163], v[204:207], v[106:109]
	v_mfma_f32_16x16x32_bf16 v[110:113], v[168:171], v[204:207], v[110:113]
	v_mfma_f32_16x16x32_bf16 v[90:93], v[160:163], v[212:215], v[90:93]
	v_mfma_f32_16x16x32_bf16 v[94:97], v[168:171], v[212:215], v[94:97]
	v_mfma_f32_16x16x32_bf16 v[74:77], v[160:163], v[224:227], v[74:77]
	v_mfma_f32_16x16x32_bf16 v[78:81], v[168:171], v[224:227], v[78:81]
	v_mfma_f32_16x16x32_bf16 v[58:61], v[172:175], v[192:195], v[58:61]
	v_mfma_f32_16x16x32_bf16 v[62:65], v[184:187], v[192:195], v[62:65]
	v_mfma_f32_16x16x32_bf16 v[42:45], v[172:175], v[200:203], v[42:45]
	v_mfma_f32_16x16x32_bf16 v[46:49], v[184:187], v[200:203], v[46:49]
	v_mfma_f32_16x16x32_bf16 v[26:29], v[172:175], v[208:211], v[26:29]
	v_mfma_f32_16x16x32_bf16 v[30:33], v[184:187], v[208:211], v[30:33]
	v_mfma_f32_16x16x32_bf16 v[130:133], v[172:175], v[220:223], v[130:133]
	v_mfma_f32_16x16x32_bf16 v[12:15], v[184:187], v[220:223], v[12:15]
	v_mfma_f32_16x16x32_bf16 v[58:61], v[176:179], v[196:199], v[58:61]
	v_mfma_f32_16x16x32_bf16 v[62:65], v[188:191], v[196:199], v[62:65]
	v_mfma_f32_16x16x32_bf16 v[42:45], v[176:179], v[204:207], v[42:45]
	v_mfma_f32_16x16x32_bf16 v[46:49], v[188:191], v[204:207], v[46:49]
	v_mfma_f32_16x16x32_bf16 v[26:29], v[176:179], v[212:215], v[26:29]
	v_mfma_f32_16x16x32_bf16 v[30:33], v[188:191], v[212:215], v[30:33]
	v_mfma_f32_16x16x32_bf16 v[130:133], v[176:179], v[224:227], v[130:133]
	v_mfma_f32_16x16x32_bf16 v[14:17], v[188:191], v[224:227], v[12:15]
	s_setprio 0
	s_barrier
	ds_read_b128 v[192:195], v154 offset:49152
	ds_read_b128 v[196:199], v154 offset:50176
	ds_read_b128 v[200:203], v154 offset:51200
	ds_read_b128 v[204:207], v154 offset:52224
	ds_read_b128 v[208:211], v154 offset:53248
	ds_read_b128 v[212:215], v154 offset:54272
	ds_read_b128 v[220:223], v154 offset:55296
	ds_read_b128 v[224:227], v154 offset:56320
	s_waitcnt lgkmcnt(0)
	s_barrier
	s_setprio 1
	v_mfma_f32_16x16x32_bf16 v[114:117], v[156:159], v[192:195], v[114:117]
	v_mfma_f32_16x16x32_bf16 v[118:121], v[164:167], v[192:195], v[118:121]
	v_mfma_f32_16x16x32_bf16 v[98:101], v[156:159], v[200:203], v[98:101]
	v_mfma_f32_16x16x32_bf16 v[102:105], v[164:167], v[200:203], v[102:105]
	v_mfma_f32_16x16x32_bf16 v[82:85], v[156:159], v[208:211], v[82:85]
	v_mfma_f32_16x16x32_bf16 v[86:89], v[164:167], v[208:211], v[86:89]
	v_mfma_f32_16x16x32_bf16 v[66:69], v[156:159], v[220:223], v[66:69]
	v_mfma_f32_16x16x32_bf16 v[70:73], v[164:167], v[220:223], v[70:73]
	v_mfma_f32_16x16x32_bf16 v[114:117], v[160:163], v[196:199], v[114:117]
	v_mfma_f32_16x16x32_bf16 v[118:121], v[168:171], v[196:199], v[118:121]
	v_mfma_f32_16x16x32_bf16 v[98:101], v[160:163], v[204:207], v[98:101]
	v_mfma_f32_16x16x32_bf16 v[102:105], v[168:171], v[204:207], v[102:105]
	v_mfma_f32_16x16x32_bf16 v[82:85], v[160:163], v[212:215], v[82:85]
	v_mfma_f32_16x16x32_bf16 v[86:89], v[168:171], v[212:215], v[86:89]
	v_mfma_f32_16x16x32_bf16 v[66:69], v[160:163], v[224:227], v[66:69]
	v_mfma_f32_16x16x32_bf16 v[70:73], v[168:171], v[224:227], v[70:73]
	v_mfma_f32_16x16x32_bf16 v[50:53], v[172:175], v[192:195], v[50:53]
	v_mfma_f32_16x16x32_bf16 v[54:57], v[184:187], v[192:195], v[54:57]
	v_mfma_f32_16x16x32_bf16 v[34:37], v[172:175], v[200:203], v[34:37]
	v_mfma_f32_16x16x32_bf16 v[38:41], v[184:187], v[200:203], v[38:41]
	v_mfma_f32_16x16x32_bf16 v[18:21], v[172:175], v[208:211], v[18:21]
	v_mfma_f32_16x16x32_bf16 v[22:25], v[184:187], v[208:211], v[22:25]
	v_mfma_f32_16x16x32_bf16 v[6:9], v[172:175], v[220:223], v[6:9]
	v_mfma_f32_16x16x32_bf16 v[2:5], v[184:187], v[220:223], v[2:5]
	v_mfma_f32_16x16x32_bf16 v[50:53], v[176:179], v[196:199], v[50:53]
	v_mfma_f32_16x16x32_bf16 v[54:57], v[188:191], v[196:199], v[54:57]
	v_mfma_f32_16x16x32_bf16 v[34:37], v[176:179], v[204:207], v[34:37]
	v_mfma_f32_16x16x32_bf16 v[38:41], v[188:191], v[204:207], v[38:41]
	v_mfma_f32_16x16x32_bf16 v[18:21], v[176:179], v[212:215], v[18:21]
	v_mfma_f32_16x16x32_bf16 v[22:25], v[188:191], v[212:215], v[22:25]
	v_mfma_f32_16x16x32_bf16 v[6:9], v[176:179], v[224:227], v[6:9]
	v_mfma_f32_16x16x32_bf16 v[2:5], v[188:191], v[224:227], v[2:5]
	s_setprio 0
	s_barrier
	s_andn2_b64 vcc, exec, s[48:49]
	s_cbranch_vccz .LBB0_1266

.LBB0_1400:
	s_add_i32 s74, s74, 2
	s_add_u32 s0, s16, s8
	s_addc_u32 s1, s17, s9
	s_add_u32 s0, s0, 0x100
	s_addc_u32 s1, s1, 0
	s_add_u32 s3, s72, s8
	s_addc_u32 s10, s73, s9
	s_add_i32 s25, 0, 0x10000
	v_add_u32_e32 v2, s25, v226
	s_add_i32 s75, 0, 0x14000
	s_waitcnt lgkmcnt(0)
	ds_read_b128 v[134:137], v2
	ds_read_b128 v[138:141], v2 offset:1024
	ds_read_b128 v[142:145], v2 offset:2048
	ds_read_b128 v[146:149], v2 offset:3072
	v_add_u32_e32 v2, s75, v226
	ds_read_b128 v[150:153], v2
	ds_read_b128 v[154:157], v2 offset:1024
	ds_read_b128 v[158:161], v2 offset:2048
	ds_read_b128 v[162:165], v2 offset:3072
	s_cmpk_eq_i32 s8, 0x700
	s_cselect_b32 s11, s65, s10
	s_cselect_b32 s10, s64, s3
	s_cselect_b32 s71, s63, s1
	s_cselect_b32 s70, s62, s0
	v_lshl_add_u64 v[4:5], v[222:223], 0, s[8:9]
	s_add_i32 s0, s24, 0x8000
	v_lshl_add_u64 v[224:225], v[4:5], 0, s[30:31]
	s_mov_b32 m0, s0
	s_waitcnt lgkmcnt(0)
	ds_read_b128 v[166:169], v227
	ds_read_b128 v[170:173], v227 offset:1024
	ds_read_b128 v[174:177], v227 offset:2048
	ds_read_b128 v[178:181], v227 offset:3072
	ds_read_b128 v[182:185], v227 offset:4096
	ds_read_b128 v[186:189], v227 offset:5120
	ds_read_b128 v[190:193], v227 offset:6144
	ds_read_b128 v[194:197], v227 offset:7168
	global_load_lds_dwordx4 v[224:225], off
	v_lshl_add_u64 v[224:225], v[220:221], 0, s[8:9]
	s_add_i32 s33, s24, 0xa000
	v_lshl_add_u64 v[246:247], v[224:225], 0, s[30:31]
	s_mov_b32 m0, s33
	s_add_i32 s22, s24, 0xc000
	global_load_lds_dwordx4 v[246:247], off
	v_lshl_add_u64 v[4:5], v[4:5], 0, s[44:45]
	s_mov_b32 m0, s22
	s_add_i32 s23, s24, 0xe000
	global_load_lds_dwordx4 v[4:5], off
	v_lshl_add_u64 v[4:5], v[224:225], 0, s[44:45]
	s_mov_b32 m0, s23
	s_nop 0
	global_load_lds_dwordx4 v[4:5], off
	s_waitcnt vmcnt(8)
	s_waitcnt lgkmcnt(0)
	s_barrier
	s_setprio 1
	v_mfma_f32_16x16x32_bf16 v[82:85], v[134:137], v[166:169], v[82:85]
	v_mfma_f32_16x16x32_bf16 v[10:13], v[142:145], v[166:169], v[10:13]
	v_mfma_f32_16x16x32_bf16 v[130:133], v[134:137], v[174:177], v[130:133]
	v_mfma_f32_16x16x32_bf16 v[66:69], v[142:145], v[174:177], v[66:69]
	v_mfma_f32_16x16x32_bf16 v[126:129], v[134:137], v[182:185], v[126:129]
	v_mfma_f32_16x16x32_bf16 v[62:65], v[142:145], v[182:185], v[62:65]
	v_mfma_f32_16x16x32_bf16 v[122:125], v[134:137], v[190:193], v[122:125]
	v_mfma_f32_16x16x32_bf16 v[58:61], v[142:145], v[190:193], v[58:61]
	v_mfma_f32_16x16x32_bf16 v[82:85], v[138:141], v[170:173], v[82:85]
	v_mfma_f32_16x16x32_bf16 v[10:13], v[146:149], v[170:173], v[10:13]
	v_mfma_f32_16x16x32_bf16 v[130:133], v[138:141], v[178:181], v[130:133]
	v_mfma_f32_16x16x32_bf16 v[66:69], v[146:149], v[178:181], v[66:69]
	v_mfma_f32_16x16x32_bf16 v[126:129], v[138:141], v[186:189], v[126:129]
	v_mfma_f32_16x16x32_bf16 v[62:65], v[146:149], v[186:189], v[62:65]
	v_mfma_f32_16x16x32_bf16 v[122:125], v[138:141], v[194:197], v[122:125]
	v_mfma_f32_16x16x32_bf16 v[58:61], v[146:149], v[194:197], v[58:61]
	v_mfma_f32_16x16x32_bf16 v[70:73], v[150:153], v[166:169], v[70:73]
	v_mfma_f32_16x16x32_bf16 v[4:7], v[158:161], v[166:169], v[6:9]
	v_mfma_f32_16x16x32_bf16 v[118:121], v[150:153], v[174:177], v[118:121]
	v_mfma_f32_16x16x32_bf16 v[54:57], v[158:161], v[174:177], v[54:57]
	v_mfma_f32_16x16x32_bf16 v[114:117], v[150:153], v[182:185], v[114:117]
	v_mfma_f32_16x16x32_bf16 v[50:53], v[158:161], v[182:185], v[50:53]
	v_mfma_f32_16x16x32_bf16 v[110:113], v[150:153], v[190:193], v[110:113]
	v_mfma_f32_16x16x32_bf16 v[46:49], v[158:161], v[190:193], v[46:49]
	v_mfma_f32_16x16x32_bf16 v[70:73], v[154:157], v[170:173], v[70:73]
	v_mfma_f32_16x16x32_bf16 v[4:7], v[162:165], v[170:173], v[4:7]
	v_mfma_f32_16x16x32_bf16 v[118:121], v[154:157], v[178:181], v[118:121]
	v_mfma_f32_16x16x32_bf16 v[54:57], v[162:165], v[178:181], v[54:57]
	v_mfma_f32_16x16x32_bf16 v[114:117], v[154:157], v[186:189], v[114:117]
	v_mfma_f32_16x16x32_bf16 v[50:53], v[162:165], v[186:189], v[50:53]
	v_mfma_f32_16x16x32_bf16 v[110:113], v[154:157], v[194:197], v[110:113]
	v_mfma_f32_16x16x32_bf16 v[46:49], v[162:165], v[194:197], v[46:49]
	s_setprio 0
	s_barrier
	s_add_i32 s1, s25, s78
	v_lshl_add_u64 v[224:225], s[10:11], 0, v[200:201]
	s_mov_b32 m0, s1
	ds_read_b128 v[166:169], v227 offset:16384
	ds_read_b128 v[170:173], v227 offset:17408
	ds_read_b128 v[174:177], v227 offset:18432
	ds_read_b128 v[178:181], v227 offset:19456
	ds_read_b128 v[182:185], v227 offset:20480
	ds_read_b128 v[186:189], v227 offset:21504
	ds_read_b128 v[190:193], v227 offset:22528
	ds_read_b128 v[194:197], v227 offset:23552
	global_load_lds_dwordx4 v[224:225], off
	s_add_i32 m0, s1, 0x2000
	s_add_u32 s26, s10, 0x40000
	v_lshl_add_u64 v[246:247], s[10:11], 0, v[204:205]
	s_addc_u32 s27, s11, 0
	s_add_i32 s1, s75, s78
	global_load_lds_dwordx4 v[246:247], off
	v_lshl_add_u64 v[8:9], s[26:27], 0, v[200:201]
	s_mov_b32 m0, s1
	s_nop 0
	global_load_lds_dwordx4 v[8:9], off
	v_lshl_add_u64 v[8:9], s[26:27], 0, v[204:205]
	s_add_i32 m0, s1, 0x2000
	s_nop 0
	global_load_lds_dwordx4 v[8:9], off
	s_waitcnt vmcnt(4)
	s_waitcnt lgkmcnt(0)
	s_barrier
	s_setprio 1
	v_mfma_f32_16x16x32_bf16 v[102:105], v[134:137], v[166:169], v[102:105]
	v_mfma_f32_16x16x32_bf16 v[30:33], v[142:145], v[166:169], v[30:33]
	v_mfma_f32_16x16x32_bf16 v[106:109], v[134:137], v[174:177], v[106:109]
	v_mfma_f32_16x16x32_bf16 v[42:45], v[142:145], v[174:177], v[42:45]
	v_mfma_f32_16x16x32_bf16 v[98:101], v[134:137], v[182:185], v[98:101]
	v_mfma_f32_16x16x32_bf16 v[38:41], v[142:145], v[182:185], v[38:41]
	v_mfma_f32_16x16x32_bf16 v[94:97], v[134:137], v[190:193], v[94:97]
	v_mfma_f32_16x16x32_bf16 v[34:37], v[142:145], v[190:193], v[34:37]
	v_mfma_f32_16x16x32_bf16 v[102:105], v[138:141], v[170:173], v[102:105]
	v_mfma_f32_16x16x32_bf16 v[30:33], v[146:149], v[170:173], v[30:33]
	v_mfma_f32_16x16x32_bf16 v[106:109], v[138:141], v[178:181], v[106:109]
	v_mfma_f32_16x16x32_bf16 v[42:45], v[146:149], v[178:181], v[42:45]
	v_mfma_f32_16x16x32_bf16 v[98:101], v[138:141], v[186:189], v[98:101]
	v_mfma_f32_16x16x32_bf16 v[38:41], v[146:149], v[186:189], v[38:41]
	v_mfma_f32_16x16x32_bf16 v[94:97], v[138:141], v[194:197], v[94:97]
	v_mfma_f32_16x16x32_bf16 v[34:37], v[146:149], v[194:197], v[34:37]
	v_mfma_f32_16x16x32_bf16 v[74:77], v[150:153], v[166:169], v[74:77]
	v_mfma_f32_16x16x32_bf16 v[14:17], v[158:161], v[166:169], v[14:17]
	v_mfma_f32_16x16x32_bf16 v[90:93], v[150:153], v[174:177], v[90:93]
	v_mfma_f32_16x16x32_bf16 v[26:29], v[158:161], v[174:177], v[26:29]
	v_mfma_f32_16x16x32_bf16 v[86:89], v[150:153], v[182:185], v[86:89]
	v_mfma_f32_16x16x32_bf16 v[22:25], v[158:161], v[182:185], v[22:25]
	v_mfma_f32_16x16x32_bf16 v[78:81], v[150:153], v[190:193], v[78:81]
	v_mfma_f32_16x16x32_bf16 v[18:21], v[158:161], v[190:193], v[18:21]
	v_mfma_f32_16x16x32_bf16 v[74:77], v[154:157], v[170:173], v[74:77]
	v_mfma_f32_16x16x32_bf16 v[14:17], v[162:165], v[170:173], v[14:17]
	v_mfma_f32_16x16x32_bf16 v[90:93], v[154:157], v[178:181], v[90:93]
	v_mfma_f32_16x16x32_bf16 v[26:29], v[162:165], v[178:181], v[26:29]
	v_mfma_f32_16x16x32_bf16 v[86:89], v[154:157], v[186:189], v[86:89]
	v_mfma_f32_16x16x32_bf16 v[22:25], v[162:165], v[186:189], v[22:25]
	v_mfma_f32_16x16x32_bf16 v[78:81], v[154:157], v[194:197], v[78:81]
	v_mfma_f32_16x16x32_bf16 v[18:21], v[162:165], v[194:197], v[18:21]
	s_setprio 0
	s_barrier
	s_add_i32 s1, 0, 0x18000
	v_add_u32_e32 v2, s1, v226
	s_add_i32 s3, 0, 0x1c000
	ds_read_b128 v[134:137], v2
	ds_read_b128 v[138:141], v2 offset:1024
	ds_read_b128 v[142:145], v2 offset:2048
	ds_read_b128 v[146:149], v2 offset:3072
	v_add_u32_e32 v2, s3, v226
	ds_read_b128 v[150:153], v2
	ds_read_b128 v[154:157], v2 offset:1024
	ds_read_b128 v[158:161], v2 offset:2048
	ds_read_b128 v[162:165], v2 offset:3072
	s_mov_b32 m0, s24
	v_lshl_add_u64 v[8:9], s[70:71], 0, v[198:199]
	s_add_u32 s26, s70, 0x40000
	ds_read_b128 v[166:169], v227 offset:32768
	ds_read_b128 v[170:173], v227 offset:33792
	ds_read_b128 v[174:177], v227 offset:34816
	ds_read_b128 v[178:181], v227 offset:35840
	ds_read_b128 v[182:185], v227 offset:36864
	ds_read_b128 v[186:189], v227 offset:37888
	ds_read_b128 v[190:193], v227 offset:38912
	ds_read_b128 v[194:197], v227 offset:39936
	global_load_lds_dwordx4 v[8:9], off
	v_lshl_add_u64 v[8:9], s[70:71], 0, v[202:203]
	s_mov_b32 m0, s83
	s_addc_u32 s27, s71, 0
	global_load_lds_dwordx4 v[8:9], off
	v_lshl_add_u64 v[8:9], s[26:27], 0, v[198:199]
	s_mov_b32 m0, s84
	s_nop 0
	global_load_lds_dwordx4 v[8:9], off
	v_lshl_add_u64 v[8:9], s[26:27], 0, v[202:203]
	s_mov_b32 m0, s85
	s_nop 0
	global_load_lds_dwordx4 v[8:9], off
	s_waitcnt vmcnt(8)
	s_waitcnt lgkmcnt(0)
	s_barrier
	s_setprio 1
	v_mfma_f32_16x16x32_bf16 v[82:85], v[134:137], v[166:169], v[82:85]
	v_mfma_f32_16x16x32_bf16 v[8:11], v[142:145], v[166:169], v[10:13]
	v_mfma_f32_16x16x32_bf16 v[130:133], v[134:137], v[174:177], v[130:133]
	v_mfma_f32_16x16x32_bf16 v[66:69], v[142:145], v[174:177], v[66:69]
	v_mfma_f32_16x16x32_bf16 v[126:129], v[134:137], v[182:185], v[126:129]
	v_mfma_f32_16x16x32_bf16 v[62:65], v[142:145], v[182:185], v[62:65]
	v_mfma_f32_16x16x32_bf16 v[122:125], v[134:137], v[190:193], v[122:125]
	v_mfma_f32_16x16x32_bf16 v[58:61], v[142:145], v[190:193], v[58:61]
	v_mfma_f32_16x16x32_bf16 v[82:85], v[138:141], v[170:173], v[82:85]
	v_mfma_f32_16x16x32_bf16 v[10:13], v[146:149], v[170:173], v[8:11]
	v_mfma_f32_16x16x32_bf16 v[130:133], v[138:141], v[178:181], v[130:133]
	v_mfma_f32_16x16x32_bf16 v[66:69], v[146:149], v[178:181], v[66:69]
	v_mfma_f32_16x16x32_bf16 v[126:129], v[138:141], v[186:189], v[126:129]
	v_mfma_f32_16x16x32_bf16 v[62:65], v[146:149], v[186:189], v[62:65]
	v_mfma_f32_16x16x32_bf16 v[122:125], v[138:141], v[194:197], v[122:125]
	v_mfma_f32_16x16x32_bf16 v[58:61], v[146:149], v[194:197], v[58:61]
	v_mfma_f32_16x16x32_bf16 v[70:73], v[150:153], v[166:169], v[70:73]
	v_mfma_f32_16x16x32_bf16 v[4:7], v[158:161], v[166:169], v[4:7]
	v_mfma_f32_16x16x32_bf16 v[118:121], v[150:153], v[174:177], v[118:121]
	v_mfma_f32_16x16x32_bf16 v[54:57], v[158:161], v[174:177], v[54:57]
	v_mfma_f32_16x16x32_bf16 v[114:117], v[150:153], v[182:185], v[114:117]
	v_mfma_f32_16x16x32_bf16 v[50:53], v[158:161], v[182:185], v[50:53]
	v_mfma_f32_16x16x32_bf16 v[110:113], v[150:153], v[190:193], v[110:113]
	v_mfma_f32_16x16x32_bf16 v[46:49], v[158:161], v[190:193], v[46:49]
	v_mfma_f32_16x16x32_bf16 v[70:73], v[154:157], v[170:173], v[70:73]
	v_mfma_f32_16x16x32_bf16 v[6:9], v[162:165], v[170:173], v[4:7]
	v_mfma_f32_16x16x32_bf16 v[118:121], v[154:157], v[178:181], v[118:121]
	v_mfma_f32_16x16x32_bf16 v[54:57], v[162:165], v[178:181], v[54:57]
	v_mfma_f32_16x16x32_bf16 v[114:117], v[154:157], v[186:189], v[114:117]
	v_mfma_f32_16x16x32_bf16 v[50:53], v[162:165], v[186:189], v[50:53]
	v_mfma_f32_16x16x32_bf16 v[110:113], v[154:157], v[194:197], v[110:113]
	v_mfma_f32_16x16x32_bf16 v[46:49], v[162:165], v[194:197], v[46:49]
	s_setprio 0
	s_barrier
	s_add_i32 s1, s1, s78
	v_lshl_add_u64 v[4:5], v[224:225], 0, s[30:31]
	s_mov_b32 m0, s1
	ds_read_b128 v[166:169], v227 offset:49152
	ds_read_b128 v[170:173], v227 offset:50176
	ds_read_b128 v[174:177], v227 offset:51200
	ds_read_b128 v[178:181], v227 offset:52224
	ds_read_b128 v[182:185], v227 offset:53248
	ds_read_b128 v[186:189], v227 offset:54272
	ds_read_b128 v[190:193], v227 offset:55296
	ds_read_b128 v[194:197], v227 offset:56320
	global_load_lds_dwordx4 v[4:5], off
	s_add_i32 m0, s1, 0x2000
	s_add_u32 s10, s10, 0x40080
	v_lshl_add_u64 v[4:5], v[246:247], 0, s[30:31]
	s_addc_u32 s11, s11, 0
	s_add_i32 s1, s3, s78
	global_load_lds_dwordx4 v[4:5], off
	v_lshl_add_u64 v[4:5], s[10:11], 0, v[200:201]
	s_mov_b32 m0, s1
	s_nop 0
	global_load_lds_dwordx4 v[4:5], off
	v_lshl_add_u64 v[4:5], s[10:11], 0, v[204:205]
	s_add_i32 m0, s1, 0x2000
	s_nop 0
	global_load_lds_dwordx4 v[4:5], off
	s_waitcnt vmcnt(4)
	s_waitcnt lgkmcnt(0)
	s_barrier
	s_setprio 1
	v_mfma_f32_16x16x32_bf16 v[102:105], v[134:137], v[166:169], v[102:105]
	v_mfma_f32_16x16x32_bf16 v[30:33], v[142:145], v[166:169], v[30:33]
	v_mfma_f32_16x16x32_bf16 v[106:109], v[134:137], v[174:177], v[106:109]
	v_mfma_f32_16x16x32_bf16 v[42:45], v[142:145], v[174:177], v[42:45]
	v_mfma_f32_16x16x32_bf16 v[98:101], v[134:137], v[182:185], v[98:101]
	v_mfma_f32_16x16x32_bf16 v[38:41], v[142:145], v[182:185], v[38:41]
	v_mfma_f32_16x16x32_bf16 v[94:97], v[134:137], v[190:193], v[94:97]
	v_mfma_f32_16x16x32_bf16 v[34:37], v[142:145], v[190:193], v[34:37]
	v_mfma_f32_16x16x32_bf16 v[102:105], v[138:141], v[170:173], v[102:105]
	v_mfma_f32_16x16x32_bf16 v[30:33], v[146:149], v[170:173], v[30:33]
	v_mfma_f32_16x16x32_bf16 v[106:109], v[138:141], v[178:181], v[106:109]
	v_mfma_f32_16x16x32_bf16 v[42:45], v[146:149], v[178:181], v[42:45]
	v_mfma_f32_16x16x32_bf16 v[98:101], v[138:141], v[186:189], v[98:101]
	v_mfma_f32_16x16x32_bf16 v[38:41], v[146:149], v[186:189], v[38:41]
	v_mfma_f32_16x16x32_bf16 v[94:97], v[138:141], v[194:197], v[94:97]
	v_mfma_f32_16x16x32_bf16 v[34:37], v[146:149], v[194:197], v[34:37]
	v_mfma_f32_16x16x32_bf16 v[74:77], v[150:153], v[166:169], v[74:77]
	v_mfma_f32_16x16x32_bf16 v[14:17], v[158:161], v[166:169], v[14:17]
	v_mfma_f32_16x16x32_bf16 v[90:93], v[150:153], v[174:177], v[90:93]
	v_mfma_f32_16x16x32_bf16 v[26:29], v[158:161], v[174:177], v[26:29]
	v_mfma_f32_16x16x32_bf16 v[86:89], v[150:153], v[182:185], v[86:89]
	v_mfma_f32_16x16x32_bf16 v[22:25], v[158:161], v[182:185], v[22:25]
	v_mfma_f32_16x16x32_bf16 v[78:81], v[150:153], v[190:193], v[78:81]
	v_mfma_f32_16x16x32_bf16 v[18:21], v[158:161], v[190:193], v[18:21]
	v_mfma_f32_16x16x32_bf16 v[74:77], v[154:157], v[170:173], v[74:77]
	v_mfma_f32_16x16x32_bf16 v[14:17], v[162:165], v[170:173], v[14:17]
	v_mfma_f32_16x16x32_bf16 v[90:93], v[154:157], v[178:181], v[90:93]
	v_mfma_f32_16x16x32_bf16 v[26:29], v[162:165], v[178:181], v[26:29]
	v_mfma_f32_16x16x32_bf16 v[86:89], v[154:157], v[186:189], v[86:89]
	v_mfma_f32_16x16x32_bf16 v[22:25], v[162:165], v[186:189], v[22:25]
	v_mfma_f32_16x16x32_bf16 v[78:81], v[154:157], v[194:197], v[78:81]
	v_mfma_f32_16x16x32_bf16 v[18:21], v[162:165], v[194:197], v[18:21]
	s_setprio 0
	s_barrier
	s_add_u32 s8, s8, 0x100
	s_addc_u32 s9, s9, 0
	s_cmp_ge_u32 s74, s96
	s_cbranch_scc0 .LBB0_1400
	s_and_b64 vcc, exec, s[66:67]
	s_cbranch_vccz .LBB0_1403
	v_add_u32_e32 v2, 0, v226
	v_add_u32_e32 v4, 0x10000, v2
	ds_read_b128 v[134:137], v4
	ds_read_b128 v[138:141], v4 offset:1024
	ds_read_b128 v[142:145], v4 offset:2048
	ds_read_b128 v[146:149], v4 offset:3072
	v_add_u32_e32 v4, 0x14000, v2
	ds_read_b128 v[150:153], v4
	ds_read_b128 v[154:157], v4 offset:1024
	ds_read_b128 v[158:161], v4 offset:2048
	ds_read_b128 v[162:165], v4 offset:3072
	v_lshl_add_u64 v[4:5], s[16:17], 0, v[198:199]
	s_mov_b32 m0, s0
	v_lshl_add_u64 v[4:5], v[4:5], 0, s[58:59]
	ds_read_b128 v[166:169], v227
	ds_read_b128 v[170:173], v227 offset:1024
	ds_read_b128 v[174:177], v227 offset:2048
	ds_read_b128 v[178:181], v227 offset:3072
	ds_read_b128 v[182:185], v227 offset:4096
	ds_read_b128 v[186:189], v227 offset:5120
	ds_read_b128 v[190:193], v227 offset:6144
	ds_read_b128 v[194:197], v227 offset:7168
	global_load_lds_dwordx4 v[4:5], off
	v_lshl_add_u64 v[4:5], s[16:17], 0, v[202:203]
	s_add_u32 s0, s16, 0x40780
	v_lshl_add_u64 v[4:5], v[4:5], 0, s[58:59]
	s_mov_b32 m0, s33
	s_addc_u32 s1, s17, 0
	global_load_lds_dwordx4 v[4:5], off
	v_lshl_add_u64 v[4:5], s[0:1], 0, v[198:199]
	s_mov_b32 m0, s22
	s_nop 0
	global_load_lds_dwordx4 v[4:5], off
	v_lshl_add_u64 v[4:5], s[0:1], 0, v[202:203]
	s_mov_b32 m0, s23
	s_nop 0
	global_load_lds_dwordx4 v[4:5], off
	s_waitcnt vmcnt(8)
	s_waitcnt lgkmcnt(0)
	s_barrier
	s_setprio 1
	v_mfma_f32_16x16x32_bf16 v[82:85], v[134:137], v[166:169], v[82:85]
	v_mfma_f32_16x16x32_bf16 v[10:13], v[142:145], v[166:169], v[10:13]
	v_mfma_f32_16x16x32_bf16 v[130:133], v[134:137], v[174:177], v[130:133]
	v_mfma_f32_16x16x32_bf16 v[66:69], v[142:145], v[174:177], v[66:69]
	v_mfma_f32_16x16x32_bf16 v[126:129], v[134:137], v[182:185], v[126:129]
	v_mfma_f32_16x16x32_bf16 v[62:65], v[142:145], v[182:185], v[62:65]
	v_mfma_f32_16x16x32_bf16 v[122:125], v[134:137], v[190:193], v[122:125]
	v_mfma_f32_16x16x32_bf16 v[58:61], v[142:145], v[190:193], v[58:61]
	v_mfma_f32_16x16x32_bf16 v[82:85], v[138:141], v[170:173], v[82:85]
	v_mfma_f32_16x16x32_bf16 v[10:13], v[146:149], v[170:173], v[10:13]
	v_mfma_f32_16x16x32_bf16 v[130:133], v[138:141], v[178:181], v[130:133]
	v_mfma_f32_16x16x32_bf16 v[66:69], v[146:149], v[178:181], v[66:69]
	v_mfma_f32_16x16x32_bf16 v[126:129], v[138:141], v[186:189], v[126:129]
	v_mfma_f32_16x16x32_bf16 v[62:65], v[146:149], v[186:189], v[62:65]
	v_mfma_f32_16x16x32_bf16 v[122:125], v[138:141], v[194:197], v[122:125]
	v_mfma_f32_16x16x32_bf16 v[58:61], v[146:149], v[194:197], v[58:61]
	v_mfma_f32_16x16x32_bf16 v[70:73], v[150:153], v[166:169], v[70:73]
	v_mfma_f32_16x16x32_bf16 v[4:7], v[158:161], v[166:169], v[6:9]
	v_mfma_f32_16x16x32_bf16 v[118:121], v[150:153], v[174:177], v[118:121]
	v_mfma_f32_16x16x32_bf16 v[54:57], v[158:161], v[174:177], v[54:57]
	v_mfma_f32_16x16x32_bf16 v[114:117], v[150:153], v[182:185], v[114:117]
	v_mfma_f32_16x16x32_bf16 v[50:53], v[158:161], v[182:185], v[50:53]
	v_mfma_f32_16x16x32_bf16 v[110:113], v[150:153], v[190:193], v[110:113]
	v_mfma_f32_16x16x32_bf16 v[46:49], v[158:161], v[190:193], v[46:49]
	v_mfma_f32_16x16x32_bf16 v[70:73], v[154:157], v[170:173], v[70:73]
	v_mfma_f32_16x16x32_bf16 v[4:7], v[162:165], v[170:173], v[4:7]
	v_mfma_f32_16x16x32_bf16 v[118:121], v[154:157], v[178:181], v[118:121]
	v_mfma_f32_16x16x32_bf16 v[54:57], v[162:165], v[178:181], v[54:57]
	v_mfma_f32_16x16x32_bf16 v[114:117], v[154:157], v[186:189], v[114:117]
	v_mfma_f32_16x16x32_bf16 v[50:53], v[162:165], v[186:189], v[50:53]
	v_mfma_f32_16x16x32_bf16 v[110:113], v[154:157], v[194:197], v[110:113]
	v_mfma_f32_16x16x32_bf16 v[46:49], v[162:165], v[194:197], v[46:49]
	s_setprio 0
	s_barrier
	ds_read_b128 v[166:169], v227 offset:16384
	ds_read_b128 v[170:173], v227 offset:17408
	ds_read_b128 v[174:177], v227 offset:18432
	ds_read_b128 v[178:181], v227 offset:19456
	ds_read_b128 v[182:185], v227 offset:20480
	ds_read_b128 v[186:189], v227 offset:21504
	ds_read_b128 v[190:193], v227 offset:22528
	ds_read_b128 v[194:197], v227 offset:23552
	s_waitcnt vmcnt(0)
	s_waitcnt lgkmcnt(0)
	s_barrier
	s_setprio 1
	v_mfma_f32_16x16x32_bf16 v[102:105], v[134:137], v[166:169], v[102:105]
	v_mfma_f32_16x16x32_bf16 v[30:33], v[142:145], v[166:169], v[30:33]
	v_mfma_f32_16x16x32_bf16 v[106:109], v[134:137], v[174:177], v[106:109]
	v_mfma_f32_16x16x32_bf16 v[42:45], v[142:145], v[174:177], v[42:45]
	v_mfma_f32_16x16x32_bf16 v[98:101], v[134:137], v[182:185], v[98:101]
	v_mfma_f32_16x16x32_bf16 v[38:41], v[142:145], v[182:185], v[38:41]
	v_mfma_f32_16x16x32_bf16 v[94:97], v[134:137], v[190:193], v[94:97]
	v_mfma_f32_16x16x32_bf16 v[34:37], v[142:145], v[190:193], v[34:37]
	v_mfma_f32_16x16x32_bf16 v[102:105], v[138:141], v[170:173], v[102:105]
	v_mfma_f32_16x16x32_bf16 v[30:33], v[146:149], v[170:173], v[30:33]
	v_mfma_f32_16x16x32_bf16 v[106:109], v[138:141], v[178:181], v[106:109]
	v_mfma_f32_16x16x32_bf16 v[42:45], v[146:149], v[178:181], v[42:45]
	v_mfma_f32_16x16x32_bf16 v[98:101], v[138:141], v[186:189], v[98:101]
	v_mfma_f32_16x16x32_bf16 v[38:41], v[146:149], v[186:189], v[38:41]
	v_mfma_f32_16x16x32_bf16 v[94:97], v[138:141], v[194:197], v[94:97]
	v_mfma_f32_16x16x32_bf16 v[34:37], v[146:149], v[194:197], v[34:37]
	v_mfma_f32_16x16x32_bf16 v[74:77], v[150:153], v[166:169], v[74:77]
	v_mfma_f32_16x16x32_bf16 v[14:17], v[158:161], v[166:169], v[14:17]
	v_mfma_f32_16x16x32_bf16 v[90:93], v[150:153], v[174:177], v[90:93]
	v_mfma_f32_16x16x32_bf16 v[26:29], v[158:161], v[174:177], v[26:29]
	v_mfma_f32_16x16x32_bf16 v[86:89], v[150:153], v[182:185], v[86:89]
	v_mfma_f32_16x16x32_bf16 v[22:25], v[158:161], v[182:185], v[22:25]
	v_mfma_f32_16x16x32_bf16 v[78:81], v[150:153], v[190:193], v[78:81]
	v_mfma_f32_16x16x32_bf16 v[18:21], v[158:161], v[190:193], v[18:21]
	v_mfma_f32_16x16x32_bf16 v[74:77], v[154:157], v[170:173], v[74:77]
	v_mfma_f32_16x16x32_bf16 v[14:17], v[162:165], v[170:173], v[14:17]
	v_mfma_f32_16x16x32_bf16 v[90:93], v[154:157], v[178:181], v[90:93]
	v_mfma_f32_16x16x32_bf16 v[26:29], v[162:165], v[178:181], v[26:29]
	v_mfma_f32_16x16x32_bf16 v[86:89], v[154:157], v[186:189], v[86:89]
	v_mfma_f32_16x16x32_bf16 v[22:25], v[162:165], v[186:189], v[22:25]
	v_mfma_f32_16x16x32_bf16 v[78:81], v[154:157], v[194:197], v[78:81]
	v_mfma_f32_16x16x32_bf16 v[18:21], v[162:165], v[194:197], v[18:21]
	s_setprio 0
	s_barrier
	v_add_u32_e32 v8, 0x18000, v2
	v_add_u32_e32 v2, 0x1c000, v2
	ds_read_b128 v[134:137], v8
	ds_read_b128 v[138:141], v8 offset:1024
	ds_read_b128 v[142:145], v8 offset:2048
	ds_read_b128 v[146:149], v8 offset:3072
	ds_read_b128 v[150:153], v2
	ds_read_b128 v[154:157], v2 offset:1024
	ds_read_b128 v[158:161], v2 offset:2048
	ds_read_b128 v[162:165], v2 offset:3072
	ds_read_b128 v[166:169], v227 offset:32768
	ds_read_b128 v[170:173], v227 offset:33792
	ds_read_b128 v[174:177], v227 offset:34816
	ds_read_b128 v[178:181], v227 offset:35840
	ds_read_b128 v[182:185], v227 offset:36864
	ds_read_b128 v[186:189], v227 offset:37888
	ds_read_b128 v[190:193], v227 offset:38912
	ds_read_b128 v[194:197], v227 offset:39936
	s_waitcnt lgkmcnt(0)
	s_barrier
	s_setprio 1
	v_mfma_f32_16x16x32_bf16 v[82:85], v[134:137], v[166:169], v[82:85]
	v_mfma_f32_16x16x32_bf16 v[8:11], v[142:145], v[166:169], v[10:13]
	v_mfma_f32_16x16x32_bf16 v[130:133], v[134:137], v[174:177], v[130:133]
	v_mfma_f32_16x16x32_bf16 v[66:69], v[142:145], v[174:177], v[66:69]
	v_mfma_f32_16x16x32_bf16 v[126:129], v[134:137], v[182:185], v[126:129]
	v_mfma_f32_16x16x32_bf16 v[62:65], v[142:145], v[182:185], v[62:65]
	v_mfma_f32_16x16x32_bf16 v[122:125], v[134:137], v[190:193], v[122:125]
	v_mfma_f32_16x16x32_bf16 v[58:61], v[142:145], v[190:193], v[58:61]
	v_mfma_f32_16x16x32_bf16 v[82:85], v[138:141], v[170:173], v[82:85]
	v_mfma_f32_16x16x32_bf16 v[10:13], v[146:149], v[170:173], v[8:11]
	v_mfma_f32_16x16x32_bf16 v[130:133], v[138:141], v[178:181], v[130:133]
	v_mfma_f32_16x16x32_bf16 v[66:69], v[146:149], v[178:181], v[66:69]
	v_mfma_f32_16x16x32_bf16 v[126:129], v[138:141], v[186:189], v[126:129]
	v_mfma_f32_16x16x32_bf16 v[62:65], v[146:149], v[186:189], v[62:65]
	v_mfma_f32_16x16x32_bf16 v[122:125], v[138:141], v[194:197], v[122:125]
	v_mfma_f32_16x16x32_bf16 v[58:61], v[146:149], v[194:197], v[58:61]
	v_mfma_f32_16x16x32_bf16 v[70:73], v[150:153], v[166:169], v[70:73]
	v_mfma_f32_16x16x32_bf16 v[4:7], v[158:161], v[166:169], v[4:7]
	v_mfma_f32_16x16x32_bf16 v[118:121], v[150:153], v[174:177], v[118:121]
	v_mfma_f32_16x16x32_bf16 v[54:57], v[158:161], v[174:177], v[54:57]
	v_mfma_f32_16x16x32_bf16 v[114:117], v[150:153], v[182:185], v[114:117]
	v_mfma_f32_16x16x32_bf16 v[50:53], v[158:161], v[182:185], v[50:53]
	v_mfma_f32_16x16x32_bf16 v[110:113], v[150:153], v[190:193], v[110:113]
	v_mfma_f32_16x16x32_bf16 v[46:49], v[158:161], v[190:193], v[46:49]
	v_mfma_f32_16x16x32_bf16 v[70:73], v[154:157], v[170:173], v[70:73]
	v_mfma_f32_16x16x32_bf16 v[6:9], v[162:165], v[170:173], v[4:7]
	v_mfma_f32_16x16x32_bf16 v[118:121], v[154:157], v[178:181], v[118:121]
	v_mfma_f32_16x16x32_bf16 v[54:57], v[162:165], v[178:181], v[54:57]
	v_mfma_f32_16x16x32_bf16 v[114:117], v[154:157], v[186:189], v[114:117]
	v_mfma_f32_16x16x32_bf16 v[50:53], v[162:165], v[186:189], v[50:53]
	v_mfma_f32_16x16x32_bf16 v[110:113], v[154:157], v[194:197], v[110:113]
	v_mfma_f32_16x16x32_bf16 v[46:49], v[162:165], v[194:197], v[46:49]
	s_setprio 0
	s_barrier
	ds_read_b128 v[166:169], v227 offset:49152
	ds_read_b128 v[170:173], v227 offset:50176
	ds_read_b128 v[174:177], v227 offset:51200
	ds_read_b128 v[178:181], v227 offset:52224
	ds_read_b128 v[182:185], v227 offset:53248
	ds_read_b128 v[186:189], v227 offset:54272
	ds_read_b128 v[190:193], v227 offset:55296
	ds_read_b128 v[194:197], v227 offset:56320
	s_waitcnt lgkmcnt(0)
	s_barrier
	s_setprio 1
	v_mfma_f32_16x16x32_bf16 v[102:105], v[134:137], v[166:169], v[102:105]
	v_mfma_f32_16x16x32_bf16 v[30:33], v[142:145], v[166:169], v[30:33]
	v_mfma_f32_16x16x32_bf16 v[106:109], v[134:137], v[174:177], v[106:109]
	v_mfma_f32_16x16x32_bf16 v[42:45], v[142:145], v[174:177], v[42:45]
	v_mfma_f32_16x16x32_bf16 v[98:101], v[134:137], v[182:185], v[98:101]
	v_mfma_f32_16x16x32_bf16 v[38:41], v[142:145], v[182:185], v[38:41]
	v_mfma_f32_16x16x32_bf16 v[94:97], v[134:137], v[190:193], v[94:97]
	v_mfma_f32_16x16x32_bf16 v[34:37], v[142:145], v[190:193], v[34:37]
	v_mfma_f32_16x16x32_bf16 v[102:105], v[138:141], v[170:173], v[102:105]
	v_mfma_f32_16x16x32_bf16 v[30:33], v[146:149], v[170:173], v[30:33]
	v_mfma_f32_16x16x32_bf16 v[106:109], v[138:141], v[178:181], v[106:109]
	v_mfma_f32_16x16x32_bf16 v[42:45], v[146:149], v[178:181], v[42:45]
	v_mfma_f32_16x16x32_bf16 v[98:101], v[138:141], v[186:189], v[98:101]
	v_mfma_f32_16x16x32_bf16 v[38:41], v[146:149], v[186:189], v[38:41]
	v_mfma_f32_16x16x32_bf16 v[94:97], v[138:141], v[194:197], v[94:97]
	v_mfma_f32_16x16x32_bf16 v[34:37], v[146:149], v[194:197], v[34:37]
	v_mfma_f32_16x16x32_bf16 v[74:77], v[150:153], v[166:169], v[74:77]
	v_mfma_f32_16x16x32_bf16 v[14:17], v[158:161], v[166:169], v[14:17]
	v_mfma_f32_16x16x32_bf16 v[90:93], v[150:153], v[174:177], v[90:93]
	v_mfma_f32_16x16x32_bf16 v[26:29], v[158:161], v[174:177], v[26:29]
	v_mfma_f32_16x16x32_bf16 v[86:89], v[150:153], v[182:185], v[86:89]
	v_mfma_f32_16x16x32_bf16 v[22:25], v[158:161], v[182:185], v[22:25]
	v_mfma_f32_16x16x32_bf16 v[78:81], v[150:153], v[190:193], v[78:81]
	v_mfma_f32_16x16x32_bf16 v[18:21], v[158:161], v[190:193], v[18:21]
	v_mfma_f32_16x16x32_bf16 v[74:77], v[154:157], v[170:173], v[74:77]
	v_mfma_f32_16x16x32_bf16 v[14:17], v[162:165], v[170:173], v[14:17]
	v_mfma_f32_16x16x32_bf16 v[90:93], v[154:157], v[178:181], v[90:93]
	v_mfma_f32_16x16x32_bf16 v[26:29], v[162:165], v[178:181], v[26:29]
	v_mfma_f32_16x16x32_bf16 v[86:89], v[154:157], v[186:189], v[86:89]
	v_mfma_f32_16x16x32_bf16 v[22:25], v[162:165], v[186:189], v[22:25]
	v_mfma_f32_16x16x32_bf16 v[78:81], v[154:157], v[194:197], v[78:81]
	v_mfma_f32_16x16x32_bf16 v[18:21], v[162:165], v[194:197], v[18:21]
	s_setprio 0
	s_barrier

.LBB0_1582:
	v_add_u32_e32 v11, s58, v152
	s_add_i32 s24, s24, 2
	ds_read_b128 v[156:159], v11
	ds_read_b128 v[160:163], v11 offset:1024
	ds_read_b128 v[164:167], v11 offset:2048
	ds_read_b128 v[168:171], v11 offset:3072
	v_add_u32_e32 v11, s59, v152
	s_add_u32 s25, s12, s38
	ds_read_b128 v[172:175], v11
	ds_read_b128 v[176:179], v11 offset:1024
	ds_read_b128 v[180:183], v11 offset:2048
	ds_read_b128 v[188:191], v11 offset:3072
	s_addc_u32 s40, s13, s39
	s_add_u32 s25, s25, 0x100
	s_addc_u32 s42, s40, 0
	s_add_u32 s40, s31, s38
	s_addc_u32 s41, s44, s39
	s_cmpk_eq_i32 s38, 0x1500
	s_cselect_b32 s41, s37, s41
	s_cselect_b32 s40, s36, s40
	s_cselect_b32 s43, s35, s42
	s_cselect_b32 s42, s34, s25
	v_lshl_add_u64 v[184:185], v[150:151], 0, s[38:39]
	s_add_i32 s64, s52, 0x8000
	v_lshl_add_u64 v[226:227], v[184:185], 0, s[20:21]
	s_mov_b32 m0, s64
	ds_read_b128 v[192:195], v154
	ds_read_b128 v[196:199], v154 offset:1024
	ds_read_b128 v[200:203], v154 offset:2048
	ds_read_b128 v[206:209], v154 offset:3072
	ds_read_b128 v[210:213], v154 offset:4096
	ds_read_b128 v[214:217], v154 offset:5120
	ds_read_b128 v[218:221], v154 offset:6144
	ds_read_b128 v[222:225], v154 offset:7168
	global_load_lds_dwordx4 v[226:227], off
	v_lshl_add_u64 v[226:227], v[12:13], 0, s[38:39]
	s_add_i32 s63, s52, 0xa000
	v_lshl_add_u64 v[228:229], v[226:227], 0, s[20:21]
	s_mov_b32 m0, s63
	s_add_i32 s25, s52, 0xc000
	global_load_lds_dwordx4 v[228:229], off
	v_lshl_add_u64 v[184:185], v[184:185], 0, s[22:23]
	s_mov_b32 m0, s25
	s_add_i32 s45, s52, 0xe000
	global_load_lds_dwordx4 v[184:185], off
	v_lshl_add_u64 v[184:185], v[226:227], 0, s[22:23]
	s_mov_b32 m0, s45
	s_nop 0
	global_load_lds_dwordx4 v[184:185], off
	s_waitcnt vmcnt(8)
	s_waitcnt lgkmcnt(0)
	s_barrier
	s_setprio 1
	v_mfma_f32_16x16x32_bf16 v[90:93], v[156:159], v[192:195], v[90:93]
	v_mfma_f32_16x16x32_bf16 v[94:97], v[164:167], v[192:195], v[94:97]
	v_mfma_f32_16x16x32_bf16 v[82:85], v[156:159], v[200:203], v[82:85]
	v_mfma_f32_16x16x32_bf16 v[86:89], v[164:167], v[200:203], v[86:89]
	v_mfma_f32_16x16x32_bf16 v[74:77], v[156:159], v[210:213], v[74:77]
	v_mfma_f32_16x16x32_bf16 v[78:81], v[164:167], v[210:213], v[78:81]
	v_mfma_f32_16x16x32_bf16 v[66:69], v[156:159], v[218:221], v[66:69]
	v_mfma_f32_16x16x32_bf16 v[70:73], v[164:167], v[218:221], v[70:73]
	v_mfma_f32_16x16x32_bf16 v[90:93], v[160:163], v[196:199], v[90:93]
	v_mfma_f32_16x16x32_bf16 v[94:97], v[168:171], v[196:199], v[94:97]
	v_mfma_f32_16x16x32_bf16 v[82:85], v[160:163], v[206:209], v[82:85]
	v_mfma_f32_16x16x32_bf16 v[86:89], v[168:171], v[206:209], v[86:89]
	v_mfma_f32_16x16x32_bf16 v[74:77], v[160:163], v[214:217], v[74:77]
	v_mfma_f32_16x16x32_bf16 v[78:81], v[168:171], v[214:217], v[78:81]
	v_mfma_f32_16x16x32_bf16 v[66:69], v[160:163], v[222:225], v[66:69]
	v_mfma_f32_16x16x32_bf16 v[70:73], v[168:171], v[222:225], v[70:73]
	v_mfma_f32_16x16x32_bf16 v[26:29], v[172:175], v[192:195], v[26:29]
	v_mfma_f32_16x16x32_bf16 v[30:33], v[180:183], v[192:195], v[30:33]
	v_mfma_f32_16x16x32_bf16 v[18:21], v[172:175], v[200:203], v[18:21]
	v_mfma_f32_16x16x32_bf16 v[22:25], v[180:183], v[200:203], v[22:25]
	v_mfma_f32_16x16x32_bf16 v[130:133], v[172:175], v[210:213], v[130:133]
	v_mfma_f32_16x16x32_bf16 v[14:17], v[180:183], v[210:213], v[14:17]
	v_mfma_f32_16x16x32_bf16 v[2:5], v[172:175], v[218:221], v[2:5]
	v_mfma_f32_16x16x32_bf16 v[6:9], v[180:183], v[218:221], v[6:9]
	v_mfma_f32_16x16x32_bf16 v[26:29], v[176:179], v[196:199], v[26:29]
	v_mfma_f32_16x16x32_bf16 v[30:33], v[188:191], v[196:199], v[30:33]
	v_mfma_f32_16x16x32_bf16 v[18:21], v[176:179], v[206:209], v[18:21]
	v_mfma_f32_16x16x32_bf16 v[22:25], v[188:191], v[206:209], v[22:25]
	v_mfma_f32_16x16x32_bf16 v[130:133], v[176:179], v[214:217], v[130:133]
	v_mfma_f32_16x16x32_bf16 v[14:17], v[188:191], v[214:217], v[14:17]
	v_mfma_f32_16x16x32_bf16 v[2:5], v[176:179], v[222:225], v[2:5]
	v_mfma_f32_16x16x32_bf16 v[6:9], v[188:191], v[222:225], v[6:9]
	s_setprio 0
	s_barrier
	s_add_i32 s65, s58, s51
	v_lshl_add_u64 v[184:185], s[40:41], 0, v[136:137]
	s_mov_b32 m0, s65
	ds_read_b128 v[192:195], v154 offset:16384
	ds_read_b128 v[196:199], v154 offset:17408
	ds_read_b128 v[200:203], v154 offset:18432
	ds_read_b128 v[206:209], v154 offset:19456
	ds_read_b128 v[210:213], v154 offset:20480
	ds_read_b128 v[214:217], v154 offset:21504
	ds_read_b128 v[218:221], v154 offset:22528
	ds_read_b128 v[222:225], v154 offset:23552
	global_load_lds_dwordx4 v[184:185], off
	s_add_i32 m0, s65, 0x2000
	s_add_u32 s66, s40, 0xb0000
	v_lshl_add_u64 v[226:227], s[40:41], 0, v[140:141]
	s_addc_u32 s67, s41, 0
	s_add_i32 s65, s59, s51
	global_load_lds_dwordx4 v[226:227], off
	v_lshl_add_u64 v[228:229], s[66:67], 0, v[136:137]
	s_mov_b32 m0, s65
	s_nop 0
	global_load_lds_dwordx4 v[228:229], off
	v_lshl_add_u64 v[228:229], s[66:67], 0, v[140:141]
	s_add_i32 m0, s65, 0x2000
	s_nop 0
	global_load_lds_dwordx4 v[228:229], off
	s_waitcnt vmcnt(4)
	s_waitcnt lgkmcnt(0)
	s_barrier
	s_setprio 1
	v_mfma_f32_16x16x32_bf16 v[122:125], v[156:159], v[192:195], v[122:125]
	v_mfma_f32_16x16x32_bf16 v[126:129], v[164:167], v[192:195], v[126:129]
	v_mfma_f32_16x16x32_bf16 v[114:117], v[156:159], v[200:203], v[114:117]
	v_mfma_f32_16x16x32_bf16 v[118:121], v[164:167], v[200:203], v[118:121]
	v_mfma_f32_16x16x32_bf16 v[106:109], v[156:159], v[210:213], v[106:109]
	v_mfma_f32_16x16x32_bf16 v[110:113], v[164:167], v[210:213], v[110:113]
	v_mfma_f32_16x16x32_bf16 v[98:101], v[156:159], v[218:221], v[98:101]
	v_mfma_f32_16x16x32_bf16 v[102:105], v[164:167], v[218:221], v[102:105]
	v_mfma_f32_16x16x32_bf16 v[122:125], v[160:163], v[196:199], v[122:125]
	v_mfma_f32_16x16x32_bf16 v[126:129], v[168:171], v[196:199], v[126:129]
	v_mfma_f32_16x16x32_bf16 v[114:117], v[160:163], v[206:209], v[114:117]
	v_mfma_f32_16x16x32_bf16 v[118:121], v[168:171], v[206:209], v[118:121]
	v_mfma_f32_16x16x32_bf16 v[106:109], v[160:163], v[214:217], v[106:109]
	v_mfma_f32_16x16x32_bf16 v[110:113], v[168:171], v[214:217], v[110:113]
	v_mfma_f32_16x16x32_bf16 v[98:101], v[160:163], v[222:225], v[98:101]
	v_mfma_f32_16x16x32_bf16 v[102:105], v[168:171], v[222:225], v[102:105]
	v_mfma_f32_16x16x32_bf16 v[58:61], v[172:175], v[192:195], v[58:61]
	v_mfma_f32_16x16x32_bf16 v[62:65], v[180:183], v[192:195], v[62:65]
	v_mfma_f32_16x16x32_bf16 v[50:53], v[172:175], v[200:203], v[50:53]
	v_mfma_f32_16x16x32_bf16 v[54:57], v[180:183], v[200:203], v[54:57]
	v_mfma_f32_16x16x32_bf16 v[42:45], v[172:175], v[210:213], v[42:45]
	v_mfma_f32_16x16x32_bf16 v[46:49], v[180:183], v[210:213], v[46:49]
	v_mfma_f32_16x16x32_bf16 v[38:41], v[172:175], v[218:221], v[38:41]
	v_mfma_f32_16x16x32_bf16 v[34:37], v[180:183], v[218:221], v[34:37]
	v_mfma_f32_16x16x32_bf16 v[58:61], v[176:179], v[196:199], v[58:61]
	v_mfma_f32_16x16x32_bf16 v[62:65], v[188:191], v[196:199], v[62:65]
	v_mfma_f32_16x16x32_bf16 v[50:53], v[176:179], v[206:209], v[50:53]
	v_mfma_f32_16x16x32_bf16 v[54:57], v[188:191], v[206:209], v[54:57]
	v_mfma_f32_16x16x32_bf16 v[42:45], v[176:179], v[214:217], v[42:45]
	v_mfma_f32_16x16x32_bf16 v[46:49], v[188:191], v[214:217], v[46:49]
	v_mfma_f32_16x16x32_bf16 v[38:41], v[176:179], v[222:225], v[38:41]
	v_mfma_f32_16x16x32_bf16 v[34:37], v[188:191], v[222:225], v[34:37]
	s_setprio 0
	s_barrier
	s_add_i32 s65, 0, 0x18000
	v_add_u32_e32 v11, s65, v152
	s_add_i32 s66, 0, 0x1c000
	ds_read_b128 v[156:159], v11
	ds_read_b128 v[160:163], v11 offset:1024
	ds_read_b128 v[164:167], v11 offset:2048
	ds_read_b128 v[168:171], v11 offset:3072
	v_add_u32_e32 v11, s66, v152
	ds_read_b128 v[172:175], v11
	ds_read_b128 v[176:179], v11 offset:1024
	ds_read_b128 v[180:183], v11 offset:2048
	ds_read_b128 v[188:191], v11 offset:3072
	s_mov_b32 m0, s52
	v_lshl_add_u64 v[228:229], s[42:43], 0, v[134:135]
	ds_read_b128 v[192:195], v154 offset:32768
	ds_read_b128 v[196:199], v154 offset:33792
	ds_read_b128 v[200:203], v154 offset:34816
	ds_read_b128 v[206:209], v154 offset:35840
	ds_read_b128 v[210:213], v154 offset:36864
	ds_read_b128 v[214:217], v154 offset:37888
	ds_read_b128 v[218:221], v154 offset:38912
	ds_read_b128 v[222:225], v154 offset:39936
	global_load_lds_dwordx4 v[228:229], off
	v_lshl_add_u64 v[228:229], s[42:43], 0, v[138:139]
	s_add_u32 s42, s42, 0xb0000
	s_mov_b32 m0, s53
	s_addc_u32 s43, s43, 0
	global_load_lds_dwordx4 v[228:229], off
	v_lshl_add_u64 v[228:229], s[42:43], 0, v[134:135]
	s_mov_b32 m0, s54
	s_nop 0
	global_load_lds_dwordx4 v[228:229], off
	v_lshl_add_u64 v[228:229], s[42:43], 0, v[138:139]
	s_mov_b32 m0, s55
	s_nop 0
	global_load_lds_dwordx4 v[228:229], off
	s_waitcnt vmcnt(8)
	s_waitcnt lgkmcnt(0)
	s_barrier
	s_setprio 1
	v_mfma_f32_16x16x32_bf16 v[90:93], v[156:159], v[192:195], v[90:93]
	v_mfma_f32_16x16x32_bf16 v[94:97], v[164:167], v[192:195], v[94:97]
	v_mfma_f32_16x16x32_bf16 v[82:85], v[156:159], v[200:203], v[82:85]
	v_mfma_f32_16x16x32_bf16 v[86:89], v[164:167], v[200:203], v[86:89]
	v_mfma_f32_16x16x32_bf16 v[74:77], v[156:159], v[210:213], v[74:77]
	v_mfma_f32_16x16x32_bf16 v[78:81], v[164:167], v[210:213], v[78:81]
	v_mfma_f32_16x16x32_bf16 v[66:69], v[156:159], v[218:221], v[66:69]
	v_mfma_f32_16x16x32_bf16 v[70:73], v[164:167], v[218:221], v[70:73]
	v_mfma_f32_16x16x32_bf16 v[90:93], v[160:163], v[196:199], v[90:93]
	v_mfma_f32_16x16x32_bf16 v[94:97], v[168:171], v[196:199], v[94:97]
	v_mfma_f32_16x16x32_bf16 v[82:85], v[160:163], v[206:209], v[82:85]
	v_mfma_f32_16x16x32_bf16 v[86:89], v[168:171], v[206:209], v[86:89]
	v_mfma_f32_16x16x32_bf16 v[74:77], v[160:163], v[214:217], v[74:77]
	v_mfma_f32_16x16x32_bf16 v[78:81], v[168:171], v[214:217], v[78:81]
	v_mfma_f32_16x16x32_bf16 v[66:69], v[160:163], v[222:225], v[66:69]
	v_mfma_f32_16x16x32_bf16 v[70:73], v[168:171], v[222:225], v[70:73]
	v_mfma_f32_16x16x32_bf16 v[26:29], v[172:175], v[192:195], v[26:29]
	v_mfma_f32_16x16x32_bf16 v[30:33], v[180:183], v[192:195], v[30:33]
	v_mfma_f32_16x16x32_bf16 v[18:21], v[172:175], v[200:203], v[18:21]
	v_mfma_f32_16x16x32_bf16 v[22:25], v[180:183], v[200:203], v[22:25]
	v_mfma_f32_16x16x32_bf16 v[130:133], v[172:175], v[210:213], v[130:133]
	v_mfma_f32_16x16x32_bf16 v[14:17], v[180:183], v[210:213], v[14:17]
	v_mfma_f32_16x16x32_bf16 v[2:5], v[172:175], v[218:221], v[2:5]
	v_mfma_f32_16x16x32_bf16 v[6:9], v[180:183], v[218:221], v[6:9]
	v_mfma_f32_16x16x32_bf16 v[26:29], v[176:179], v[196:199], v[26:29]
	v_mfma_f32_16x16x32_bf16 v[30:33], v[188:191], v[196:199], v[30:33]
	v_mfma_f32_16x16x32_bf16 v[18:21], v[176:179], v[206:209], v[18:21]
	v_mfma_f32_16x16x32_bf16 v[22:25], v[188:191], v[206:209], v[22:25]
	v_mfma_f32_16x16x32_bf16 v[130:133], v[176:179], v[214:217], v[130:133]
	v_mfma_f32_16x16x32_bf16 v[14:17], v[188:191], v[214:217], v[14:17]
	v_mfma_f32_16x16x32_bf16 v[2:5], v[176:179], v[222:225], v[2:5]
	v_mfma_f32_16x16x32_bf16 v[6:9], v[188:191], v[222:225], v[6:9]
	s_setprio 0
	s_barrier
	s_add_i32 s42, s65, s51
	v_lshl_add_u64 v[184:185], v[184:185], 0, s[20:21]
	s_mov_b32 m0, s42
	ds_read_b128 v[192:195], v154 offset:49152
	ds_read_b128 v[196:199], v154 offset:50176
	ds_read_b128 v[200:203], v154 offset:51200
	ds_read_b128 v[206:209], v154 offset:52224
	ds_read_b128 v[210:213], v154 offset:53248
	ds_read_b128 v[214:217], v154 offset:54272
	ds_read_b128 v[218:221], v154 offset:55296
	ds_read_b128 v[222:225], v154 offset:56320
	global_load_lds_dwordx4 v[184:185], off
	s_add_i32 m0, s42, 0x2000
	s_add_u32 s40, s40, 0xb0080
	v_lshl_add_u64 v[184:185], v[226:227], 0, s[20:21]
	s_addc_u32 s41, s41, 0
	s_add_i32 s42, s66, s51
	global_load_lds_dwordx4 v[184:185], off
	v_lshl_add_u64 v[184:185], s[40:41], 0, v[136:137]
	s_mov_b32 m0, s42
	s_nop 0
	global_load_lds_dwordx4 v[184:185], off
	v_lshl_add_u64 v[184:185], s[40:41], 0, v[140:141]
	s_add_i32 m0, s42, 0x2000
	s_nop 0
	global_load_lds_dwordx4 v[184:185], off
	s_waitcnt vmcnt(4)
	s_waitcnt lgkmcnt(0)
	s_barrier
	s_setprio 1
	v_mfma_f32_16x16x32_bf16 v[122:125], v[156:159], v[192:195], v[122:125]
	v_mfma_f32_16x16x32_bf16 v[126:129], v[164:167], v[192:195], v[126:129]
	v_mfma_f32_16x16x32_bf16 v[114:117], v[156:159], v[200:203], v[114:117]
	v_mfma_f32_16x16x32_bf16 v[118:121], v[164:167], v[200:203], v[118:121]
	v_mfma_f32_16x16x32_bf16 v[106:109], v[156:159], v[210:213], v[106:109]
	v_mfma_f32_16x16x32_bf16 v[110:113], v[164:167], v[210:213], v[110:113]
	v_mfma_f32_16x16x32_bf16 v[98:101], v[156:159], v[218:221], v[98:101]
	v_mfma_f32_16x16x32_bf16 v[102:105], v[164:167], v[218:221], v[102:105]
	v_mfma_f32_16x16x32_bf16 v[122:125], v[160:163], v[196:199], v[122:125]
	v_mfma_f32_16x16x32_bf16 v[126:129], v[168:171], v[196:199], v[126:129]
	v_mfma_f32_16x16x32_bf16 v[114:117], v[160:163], v[206:209], v[114:117]
	v_mfma_f32_16x16x32_bf16 v[118:121], v[168:171], v[206:209], v[118:121]
	v_mfma_f32_16x16x32_bf16 v[106:109], v[160:163], v[214:217], v[106:109]
	v_mfma_f32_16x16x32_bf16 v[110:113], v[168:171], v[214:217], v[110:113]
	v_mfma_f32_16x16x32_bf16 v[98:101], v[160:163], v[222:225], v[98:101]
	v_mfma_f32_16x16x32_bf16 v[102:105], v[168:171], v[222:225], v[102:105]
	v_mfma_f32_16x16x32_bf16 v[58:61], v[172:175], v[192:195], v[58:61]
	v_mfma_f32_16x16x32_bf16 v[62:65], v[180:183], v[192:195], v[62:65]
	v_mfma_f32_16x16x32_bf16 v[50:53], v[172:175], v[200:203], v[50:53]
	v_mfma_f32_16x16x32_bf16 v[54:57], v[180:183], v[200:203], v[54:57]
	v_mfma_f32_16x16x32_bf16 v[42:45], v[172:175], v[210:213], v[42:45]
	v_mfma_f32_16x16x32_bf16 v[46:49], v[180:183], v[210:213], v[46:49]
	v_mfma_f32_16x16x32_bf16 v[38:41], v[172:175], v[218:221], v[38:41]
	v_mfma_f32_16x16x32_bf16 v[34:37], v[180:183], v[218:221], v[34:37]
	v_mfma_f32_16x16x32_bf16 v[58:61], v[176:179], v[196:199], v[58:61]
	v_mfma_f32_16x16x32_bf16 v[62:65], v[188:191], v[196:199], v[62:65]
	v_mfma_f32_16x16x32_bf16 v[50:53], v[176:179], v[206:209], v[50:53]
	v_mfma_f32_16x16x32_bf16 v[54:57], v[188:191], v[206:209], v[54:57]
	v_mfma_f32_16x16x32_bf16 v[42:45], v[176:179], v[214:217], v[42:45]
	v_mfma_f32_16x16x32_bf16 v[46:49], v[188:191], v[214:217], v[46:49]
	v_mfma_f32_16x16x32_bf16 v[38:41], v[176:179], v[222:225], v[38:41]
	v_mfma_f32_16x16x32_bf16 v[34:37], v[188:191], v[222:225], v[34:37]
	s_setprio 0
	s_barrier
	s_add_u32 s38, s38, 0x100
	s_addc_u32 s39, s39, 0
	s_cmp_ge_u32 s24, s3
	s_cbranch_scc0 .LBB0_1582
	s_and_b64 vcc, exec, s[0:1]
	s_cbranch_vccz .LBB0_1586
	v_add_u32_e32 v11, 0, v152
	v_add_u32_e32 v12, 0x10000, v11
	ds_read_b128 v[156:159], v12
	ds_read_b128 v[160:163], v12 offset:1024
	ds_read_b128 v[164:167], v12 offset:2048
	ds_read_b128 v[168:171], v12 offset:3072
	v_add_u32_e32 v12, 0x14000, v11
	ds_read_b128 v[172:175], v12
	ds_read_b128 v[176:179], v12 offset:1024
	ds_read_b128 v[180:183], v12 offset:2048
	ds_read_b128 v[188:191], v12 offset:3072
	s_add_u32 s38, s12, 0x1580
	s_addc_u32 s39, s13, 0
	s_mov_b32 m0, s64
	v_lshl_add_u64 v[12:13], s[38:39], 0, v[134:135]
	ds_read_b128 v[192:195], v154
	ds_read_b128 v[196:199], v154 offset:1024
	ds_read_b128 v[200:203], v154 offset:2048
	ds_read_b128 v[206:209], v154 offset:3072
	ds_read_b128 v[210:213], v154 offset:4096
	ds_read_b128 v[214:217], v154 offset:5120
	ds_read_b128 v[218:221], v154 offset:6144
	ds_read_b128 v[222:225], v154 offset:7168
	global_load_lds_dwordx4 v[12:13], off
	v_lshl_add_u64 v[12:13], s[38:39], 0, v[138:139]
	s_add_u32 s38, s12, 0xb1580
	s_mov_b32 m0, s63
	s_addc_u32 s39, s13, 0
	global_load_lds_dwordx4 v[12:13], off
	v_lshl_add_u64 v[12:13], s[38:39], 0, v[134:135]
	s_mov_b32 m0, s25
	s_nop 0
	global_load_lds_dwordx4 v[12:13], off
	v_lshl_add_u64 v[12:13], s[38:39], 0, v[138:139]
	s_mov_b32 m0, s45
	s_nop 0
	global_load_lds_dwordx4 v[12:13], off
	s_waitcnt vmcnt(8)
	s_waitcnt lgkmcnt(0)
	s_barrier
	s_setprio 1
	v_mfma_f32_16x16x32_bf16 v[90:93], v[156:159], v[192:195], v[90:93]
	v_mfma_f32_16x16x32_bf16 v[94:97], v[164:167], v[192:195], v[94:97]
	v_mfma_f32_16x16x32_bf16 v[82:85], v[156:159], v[200:203], v[82:85]
	v_mfma_f32_16x16x32_bf16 v[86:89], v[164:167], v[200:203], v[86:89]
	v_mfma_f32_16x16x32_bf16 v[74:77], v[156:159], v[210:213], v[74:77]
	v_mfma_f32_16x16x32_bf16 v[78:81], v[164:167], v[210:213], v[78:81]
	v_mfma_f32_16x16x32_bf16 v[66:69], v[156:159], v[218:221], v[66:69]
	v_mfma_f32_16x16x32_bf16 v[70:73], v[164:167], v[218:221], v[70:73]
	v_mfma_f32_16x16x32_bf16 v[90:93], v[160:163], v[196:199], v[90:93]
	v_mfma_f32_16x16x32_bf16 v[94:97], v[168:171], v[196:199], v[94:97]
	v_mfma_f32_16x16x32_bf16 v[82:85], v[160:163], v[206:209], v[82:85]
	v_mfma_f32_16x16x32_bf16 v[86:89], v[168:171], v[206:209], v[86:89]
	v_mfma_f32_16x16x32_bf16 v[74:77], v[160:163], v[214:217], v[74:77]
	v_mfma_f32_16x16x32_bf16 v[78:81], v[168:171], v[214:217], v[78:81]
	v_mfma_f32_16x16x32_bf16 v[66:69], v[160:163], v[222:225], v[66:69]
	v_mfma_f32_16x16x32_bf16 v[70:73], v[168:171], v[222:225], v[70:73]
	v_mfma_f32_16x16x32_bf16 v[26:29], v[172:175], v[192:195], v[26:29]
	v_mfma_f32_16x16x32_bf16 v[30:33], v[180:183], v[192:195], v[30:33]
	v_mfma_f32_16x16x32_bf16 v[18:21], v[172:175], v[200:203], v[18:21]
	v_mfma_f32_16x16x32_bf16 v[22:25], v[180:183], v[200:203], v[22:25]
	v_mfma_f32_16x16x32_bf16 v[130:133], v[172:175], v[210:213], v[130:133]
	v_mfma_f32_16x16x32_bf16 v[12:15], v[180:183], v[210:213], v[14:17]
	v_mfma_f32_16x16x32_bf16 v[2:5], v[172:175], v[218:221], v[2:5]
	v_mfma_f32_16x16x32_bf16 v[6:9], v[180:183], v[218:221], v[6:9]
	v_mfma_f32_16x16x32_bf16 v[26:29], v[176:179], v[196:199], v[26:29]
	v_mfma_f32_16x16x32_bf16 v[30:33], v[188:191], v[196:199], v[30:33]
	v_mfma_f32_16x16x32_bf16 v[18:21], v[176:179], v[206:209], v[18:21]
	v_mfma_f32_16x16x32_bf16 v[22:25], v[188:191], v[206:209], v[22:25]
	v_mfma_f32_16x16x32_bf16 v[130:133], v[176:179], v[214:217], v[130:133]
	v_mfma_f32_16x16x32_bf16 v[12:15], v[188:191], v[214:217], v[12:15]
	v_mfma_f32_16x16x32_bf16 v[2:5], v[176:179], v[222:225], v[2:5]
	v_mfma_f32_16x16x32_bf16 v[6:9], v[188:191], v[222:225], v[6:9]
	s_setprio 0
	s_barrier
	ds_read_b128 v[192:195], v154 offset:16384
	ds_read_b128 v[196:199], v154 offset:17408
	ds_read_b128 v[200:203], v154 offset:18432
	ds_read_b128 v[206:209], v154 offset:19456
	ds_read_b128 v[210:213], v154 offset:20480
	ds_read_b128 v[214:217], v154 offset:21504
	ds_read_b128 v[218:221], v154 offset:22528
	ds_read_b128 v[222:225], v154 offset:23552
	s_waitcnt vmcnt(0)
	s_waitcnt lgkmcnt(0)
	s_barrier
	s_setprio 1
	v_mfma_f32_16x16x32_bf16 v[122:125], v[156:159], v[192:195], v[122:125]
	v_mfma_f32_16x16x32_bf16 v[126:129], v[164:167], v[192:195], v[126:129]
	v_mfma_f32_16x16x32_bf16 v[114:117], v[156:159], v[200:203], v[114:117]
	v_mfma_f32_16x16x32_bf16 v[118:121], v[164:167], v[200:203], v[118:121]
	v_mfma_f32_16x16x32_bf16 v[106:109], v[156:159], v[210:213], v[106:109]
	v_mfma_f32_16x16x32_bf16 v[110:113], v[164:167], v[210:213], v[110:113]
	v_mfma_f32_16x16x32_bf16 v[98:101], v[156:159], v[218:221], v[98:101]
	v_mfma_f32_16x16x32_bf16 v[102:105], v[164:167], v[218:221], v[102:105]
	v_mfma_f32_16x16x32_bf16 v[122:125], v[160:163], v[196:199], v[122:125]
	v_mfma_f32_16x16x32_bf16 v[126:129], v[168:171], v[196:199], v[126:129]
	v_mfma_f32_16x16x32_bf16 v[114:117], v[160:163], v[206:209], v[114:117]
	v_mfma_f32_16x16x32_bf16 v[118:121], v[168:171], v[206:209], v[118:121]
	v_mfma_f32_16x16x32_bf16 v[106:109], v[160:163], v[214:217], v[106:109]
	v_mfma_f32_16x16x32_bf16 v[110:113], v[168:171], v[214:217], v[110:113]
	v_mfma_f32_16x16x32_bf16 v[98:101], v[160:163], v[222:225], v[98:101]
	v_mfma_f32_16x16x32_bf16 v[102:105], v[168:171], v[222:225], v[102:105]
	v_mfma_f32_16x16x32_bf16 v[58:61], v[172:175], v[192:195], v[58:61]
	v_mfma_f32_16x16x32_bf16 v[62:65], v[180:183], v[192:195], v[62:65]
	v_mfma_f32_16x16x32_bf16 v[50:53], v[172:175], v[200:203], v[50:53]
	v_mfma_f32_16x16x32_bf16 v[54:57], v[180:183], v[200:203], v[54:57]
	v_mfma_f32_16x16x32_bf16 v[42:45], v[172:175], v[210:213], v[42:45]
	v_mfma_f32_16x16x32_bf16 v[46:49], v[180:183], v[210:213], v[46:49]
	v_mfma_f32_16x16x32_bf16 v[38:41], v[172:175], v[218:221], v[38:41]
	v_mfma_f32_16x16x32_bf16 v[34:37], v[180:183], v[218:221], v[34:37]
	v_mfma_f32_16x16x32_bf16 v[58:61], v[176:179], v[196:199], v[58:61]
	v_mfma_f32_16x16x32_bf16 v[62:65], v[188:191], v[196:199], v[62:65]
	v_mfma_f32_16x16x32_bf16 v[50:53], v[176:179], v[206:209], v[50:53]
	v_mfma_f32_16x16x32_bf16 v[54:57], v[188:191], v[206:209], v[54:57]
	v_mfma_f32_16x16x32_bf16 v[42:45], v[176:179], v[214:217], v[42:45]
	v_mfma_f32_16x16x32_bf16 v[46:49], v[188:191], v[214:217], v[46:49]
	v_mfma_f32_16x16x32_bf16 v[38:41], v[176:179], v[222:225], v[38:41]
	v_mfma_f32_16x16x32_bf16 v[34:37], v[188:191], v[222:225], v[34:37]
	s_setprio 0
	s_barrier
	v_add_u32_e32 v16, 0x18000, v11
	v_add_u32_e32 v11, 0x1c000, v11
	ds_read_b128 v[156:159], v16
	ds_read_b128 v[160:163], v16 offset:1024
	ds_read_b128 v[164:167], v16 offset:2048
	ds_read_b128 v[168:171], v16 offset:3072
	ds_read_b128 v[172:175], v11
	ds_read_b128 v[176:179], v11 offset:1024
	ds_read_b128 v[180:183], v11 offset:2048
	ds_read_b128 v[188:191], v11 offset:3072
	ds_read_b128 v[192:195], v154 offset:32768
	ds_read_b128 v[196:199], v154 offset:33792
	ds_read_b128 v[200:203], v154 offset:34816
	ds_read_b128 v[206:209], v154 offset:35840
	ds_read_b128 v[210:213], v154 offset:36864
	ds_read_b128 v[214:217], v154 offset:37888
	ds_read_b128 v[218:221], v154 offset:38912
	ds_read_b128 v[222:225], v154 offset:39936
	s_waitcnt lgkmcnt(0)
	s_barrier
	s_setprio 1
	v_mfma_f32_16x16x32_bf16 v[90:93], v[156:159], v[192:195], v[90:93]
	v_mfma_f32_16x16x32_bf16 v[94:97], v[164:167], v[192:195], v[94:97]
	v_mfma_f32_16x16x32_bf16 v[82:85], v[156:159], v[200:203], v[82:85]
	v_mfma_f32_16x16x32_bf16 v[86:89], v[164:167], v[200:203], v[86:89]
	v_mfma_f32_16x16x32_bf16 v[74:77], v[156:159], v[210:213], v[74:77]
	v_mfma_f32_16x16x32_bf16 v[78:81], v[164:167], v[210:213], v[78:81]
	v_mfma_f32_16x16x32_bf16 v[66:69], v[156:159], v[218:221], v[66:69]
	v_mfma_f32_16x16x32_bf16 v[70:73], v[164:167], v[218:221], v[70:73]
	v_mfma_f32_16x16x32_bf16 v[90:93], v[160:163], v[196:199], v[90:93]
	v_mfma_f32_16x16x32_bf16 v[94:97], v[168:171], v[196:199], v[94:97]
	v_mfma_f32_16x16x32_bf16 v[82:85], v[160:163], v[206:209], v[82:85]
	v_mfma_f32_16x16x32_bf16 v[86:89], v[168:171], v[206:209], v[86:89]
	v_mfma_f32_16x16x32_bf16 v[74:77], v[160:163], v[214:217], v[74:77]
	v_mfma_f32_16x16x32_bf16 v[78:81], v[168:171], v[214:217], v[78:81]
	v_mfma_f32_16x16x32_bf16 v[66:69], v[160:163], v[222:225], v[66:69]
	v_mfma_f32_16x16x32_bf16 v[70:73], v[168:171], v[222:225], v[70:73]
	v_mfma_f32_16x16x32_bf16 v[26:29], v[172:175], v[192:195], v[26:29]
	v_mfma_f32_16x16x32_bf16 v[30:33], v[180:183], v[192:195], v[30:33]
	v_mfma_f32_16x16x32_bf16 v[16:19], v[172:175], v[200:203], v[18:21]
	v_mfma_f32_16x16x32_bf16 v[22:25], v[180:183], v[200:203], v[22:25]
	v_mfma_f32_16x16x32_bf16 v[130:133], v[172:175], v[210:213], v[130:133]
	v_mfma_f32_16x16x32_bf16 v[12:15], v[180:183], v[210:213], v[12:15]
	v_mfma_f32_16x16x32_bf16 v[2:5], v[172:175], v[218:221], v[2:5]
	v_mfma_f32_16x16x32_bf16 v[6:9], v[180:183], v[218:221], v[6:9]
	v_mfma_f32_16x16x32_bf16 v[26:29], v[176:179], v[196:199], v[26:29]
	v_mfma_f32_16x16x32_bf16 v[30:33], v[188:191], v[196:199], v[30:33]
	v_mfma_f32_16x16x32_bf16 v[18:21], v[176:179], v[206:209], v[16:19]
	v_mfma_f32_16x16x32_bf16 v[22:25], v[188:191], v[206:209], v[22:25]
	v_mfma_f32_16x16x32_bf16 v[130:133], v[176:179], v[214:217], v[130:133]
	v_mfma_f32_16x16x32_bf16 v[14:17], v[188:191], v[214:217], v[12:15]
	v_mfma_f32_16x16x32_bf16 v[2:5], v[176:179], v[222:225], v[2:5]
	v_mfma_f32_16x16x32_bf16 v[6:9], v[188:191], v[222:225], v[6:9]
	s_setprio 0
	s_barrier
	ds_read_b128 v[192:195], v154 offset:49152
	ds_read_b128 v[196:199], v154 offset:50176
	ds_read_b128 v[200:203], v154 offset:51200
	ds_read_b128 v[206:209], v154 offset:52224
	ds_read_b128 v[210:213], v154 offset:53248
	ds_read_b128 v[214:217], v154 offset:54272
	ds_read_b128 v[218:221], v154 offset:55296
	ds_read_b128 v[222:225], v154 offset:56320
	s_waitcnt lgkmcnt(0)
	s_barrier
	s_setprio 1
	v_mfma_f32_16x16x32_bf16 v[122:125], v[156:159], v[192:195], v[122:125]
	v_mfma_f32_16x16x32_bf16 v[126:129], v[164:167], v[192:195], v[126:129]
	v_mfma_f32_16x16x32_bf16 v[114:117], v[156:159], v[200:203], v[114:117]
	v_mfma_f32_16x16x32_bf16 v[118:121], v[164:167], v[200:203], v[118:121]
	v_mfma_f32_16x16x32_bf16 v[106:109], v[156:159], v[210:213], v[106:109]
	v_mfma_f32_16x16x32_bf16 v[110:113], v[164:167], v[210:213], v[110:113]
	v_mfma_f32_16x16x32_bf16 v[98:101], v[156:159], v[218:221], v[98:101]
	v_mfma_f32_16x16x32_bf16 v[102:105], v[164:167], v[218:221], v[102:105]
	v_mfma_f32_16x16x32_bf16 v[122:125], v[160:163], v[196:199], v[122:125]
	v_mfma_f32_16x16x32_bf16 v[126:129], v[168:171], v[196:199], v[126:129]
	v_mfma_f32_16x16x32_bf16 v[114:117], v[160:163], v[206:209], v[114:117]
	v_mfma_f32_16x16x32_bf16 v[118:121], v[168:171], v[206:209], v[118:121]
	v_mfma_f32_16x16x32_bf16 v[106:109], v[160:163], v[214:217], v[106:109]
	v_mfma_f32_16x16x32_bf16 v[110:113], v[168:171], v[214:217], v[110:113]
	v_mfma_f32_16x16x32_bf16 v[98:101], v[160:163], v[222:225], v[98:101]
	v_mfma_f32_16x16x32_bf16 v[102:105], v[168:171], v[222:225], v[102:105]
	v_mfma_f32_16x16x32_bf16 v[58:61], v[172:175], v[192:195], v[58:61]
	v_mfma_f32_16x16x32_bf16 v[62:65], v[180:183], v[192:195], v[62:65]
	v_mfma_f32_16x16x32_bf16 v[50:53], v[172:175], v[200:203], v[50:53]
	v_mfma_f32_16x16x32_bf16 v[54:57], v[180:183], v[200:203], v[54:57]
	v_mfma_f32_16x16x32_bf16 v[42:45], v[172:175], v[210:213], v[42:45]
	v_mfma_f32_16x16x32_bf16 v[46:49], v[180:183], v[210:213], v[46:49]
	v_mfma_f32_16x16x32_bf16 v[38:41], v[172:175], v[218:221], v[38:41]
	v_mfma_f32_16x16x32_bf16 v[34:37], v[180:183], v[218:221], v[34:37]
	v_mfma_f32_16x16x32_bf16 v[58:61], v[176:179], v[196:199], v[58:61]
	v_mfma_f32_16x16x32_bf16 v[62:65], v[188:191], v[196:199], v[62:65]
	v_mfma_f32_16x16x32_bf16 v[50:53], v[176:179], v[206:209], v[50:53]
	v_mfma_f32_16x16x32_bf16 v[54:57], v[188:191], v[206:209], v[54:57]
	v_mfma_f32_16x16x32_bf16 v[42:45], v[176:179], v[214:217], v[42:45]
	v_mfma_f32_16x16x32_bf16 v[46:49], v[188:191], v[214:217], v[46:49]
	v_mfma_f32_16x16x32_bf16 v[38:41], v[176:179], v[222:225], v[38:41]
	v_mfma_f32_16x16x32_bf16 v[34:37], v[188:191], v[222:225], v[34:37]
	s_setprio 0
	s_barrier
	s_andn2_b64 vcc, exec, s[28:29]
	s_cbranch_vccz .LBB0_1587
